# early barrier: s_barrier ending each MFMA block moved before the last 2 MFMAs (handoff overlap), on top of pair order
# baseline (speedup 1.0000x reference)
.LBB0_183:
	s_ashr_i32 s13, s12, 31
	s_lshl_b64 s[24:25], s[12:13], 19
	s_add_u32 s24, s80, s24
	s_addc_u32 s25, s81, s25
	s_and_b64 s[30:31], s[4:5], exec
	s_cselect_b32 s13, s25, s45
	s_cselect_b32 s66, s24, s44
	s_ashr_i32 s11, s10, 31
	s_lshl_b64 s[30:31], s[10:11], 19
	s_add_u32 s30, s52, s30
	s_addc_u32 s31, s53, s31
	s_and_b64 s[48:49], s[4:5], exec
	s_cselect_b32 s11, s31, s47
	s_cselect_b32 s67, s30, s46
	s_add_u32 s44, s44, 0x40080
	s_addc_u32 s45, s45, 0
	s_add_u32 s68, s46, 0x100
	s_addc_u32 s69, s47, 0
	s_mov_b32 s70, -2
	ds_read_b128 v[140:143], v147
	ds_read_b128 v[150:153], v147 offset:1024
	ds_read_b128 v[154:157], v147 offset:2048
	ds_read_b128 v[158:161], v147 offset:3072
	ds_read_b128 v[162:165], v148
	ds_read_b128 v[166:169], v148 offset:1024
	ds_read_b128 v[170:173], v148 offset:2048
	ds_read_b128 v[174:177], v148 offset:3072
	s_add_u32 s18, s44, 0xfffc0080
	s_addc_u32 s19, s45, -1
	s_cmp_eq_u32 s70, 12
	s_cselect_b32 s49, s13, s19
	s_cselect_b32 s48, s66, s18
	s_cselect_b32 s47, s11, s69
	s_cselect_b32 s46, s67, s68
	v_lshl_add_u64 v[178:179], s[44:45], 0, v[132:133]
	s_add_i32 m0, s37, 0xc000
	ds_read_b128 v[184:187], v149
	ds_read_b128 v[188:191], v149 offset:1024
	ds_read_b128 v[192:195], v149 offset:2048
	ds_read_b128 v[196:199], v149 offset:3072
	ds_read_b128 v[200:203], v149 offset:4096
	ds_read_b128 v[204:207], v149 offset:5120
	ds_read_b128 v[208:211], v149 offset:6144
	ds_read_b128 v[212:215], v149 offset:7168
	global_load_lds_dwordx4 v[178:179], off
	v_lshl_add_u64 v[178:179], s[44:45], 0, v[134:135]
	s_add_i32 m0, s37, 0xe000
	s_nop 0
	global_load_lds_dwordx4 v[178:179], off
	s_waitcnt vmcnt(8)
	s_waitcnt lgkmcnt(0)
	s_barrier
	s_setprio 1
	s_waitcnt lgkmcnt(0)
	v_mfma_f32_16x16x32_bf16 v[124:127], v[140:143], v[184:187], 0
	v_mfma_f32_16x16x32_bf16 v[124:127], v[150:153], v[188:191], v[124:127]
	v_mfma_f32_16x16x32_bf16 v[120:123], v[154:157], v[184:187], 0
	v_mfma_f32_16x16x32_bf16 v[120:123], v[158:161], v[188:191], v[120:123]
	v_mfma_f32_16x16x32_bf16 v[108:111], v[140:143], v[192:195], 0
	v_mfma_f32_16x16x32_bf16 v[108:111], v[150:153], v[196:199], v[108:111]
	v_mfma_f32_16x16x32_bf16 v[104:107], v[154:157], v[192:195], 0
	v_mfma_f32_16x16x32_bf16 v[104:107], v[158:161], v[196:199], v[104:107]
	v_mfma_f32_16x16x32_bf16 v[92:95], v[140:143], v[200:203], 0
	v_mfma_f32_16x16x32_bf16 v[92:95], v[150:153], v[204:207], v[92:95]
	v_mfma_f32_16x16x32_bf16 v[88:91], v[154:157], v[200:203], 0
	v_mfma_f32_16x16x32_bf16 v[88:91], v[158:161], v[204:207], v[88:91]
	v_mfma_f32_16x16x32_bf16 v[76:79], v[140:143], v[208:211], 0
	v_mfma_f32_16x16x32_bf16 v[76:79], v[150:153], v[212:215], v[76:79]
	v_mfma_f32_16x16x32_bf16 v[72:75], v[154:157], v[208:211], 0
	v_mfma_f32_16x16x32_bf16 v[72:75], v[158:161], v[212:215], v[72:75]
	s_setprio 0
	s_setprio 1
	v_mfma_f32_16x16x32_bf16 v[116:119], v[162:165], v[184:187], 0
	v_mfma_f32_16x16x32_bf16 v[116:119], v[166:169], v[188:191], v[116:119]
	v_mfma_f32_16x16x32_bf16 v[112:115], v[170:173], v[184:187], 0
	v_mfma_f32_16x16x32_bf16 v[112:115], v[174:177], v[188:191], v[112:115]
	v_mfma_f32_16x16x32_bf16 v[100:103], v[162:165], v[192:195], 0
	v_mfma_f32_16x16x32_bf16 v[100:103], v[166:169], v[196:199], v[100:103]
	v_mfma_f32_16x16x32_bf16 v[96:99], v[170:173], v[192:195], 0
	v_mfma_f32_16x16x32_bf16 v[96:99], v[174:177], v[196:199], v[96:99]
	v_mfma_f32_16x16x32_bf16 v[84:87], v[162:165], v[200:203], 0
	v_mfma_f32_16x16x32_bf16 v[84:87], v[166:169], v[204:207], v[84:87]
	v_mfma_f32_16x16x32_bf16 v[80:83], v[170:173], v[200:203], 0
	v_mfma_f32_16x16x32_bf16 v[80:83], v[174:177], v[204:207], v[80:83]
	v_mfma_f32_16x16x32_bf16 v[68:71], v[162:165], v[208:211], 0
	v_mfma_f32_16x16x32_bf16 v[68:71], v[166:169], v[212:215], v[68:71]
	s_barrier
	v_mfma_f32_16x16x32_bf16 v[64:67], v[170:173], v[208:211], 0
	v_mfma_f32_16x16x32_bf16 v[64:67], v[174:177], v[212:215], v[64:67]
	s_setprio 0
	s_add_i32 s18, s62, s54
	v_lshl_add_u64 v[178:179], s[46:47], 0, v[130:131]
	s_mov_b32 m0, s18
	ds_read_b128 v[184:187], v149 offset:16384
	ds_read_b128 v[188:191], v149 offset:17408
	ds_read_b128 v[192:195], v149 offset:18432
	ds_read_b128 v[196:199], v149 offset:19456
	ds_read_b128 v[200:203], v149 offset:20480
	ds_read_b128 v[204:207], v149 offset:21504
	ds_read_b128 v[208:211], v149 offset:22528
	ds_read_b128 v[212:215], v149 offset:23552
	global_load_lds_dwordx4 v[178:179], off
	s_add_i32 m0, s18, 0x2000
	s_add_u32 s72, s46, 0x40000
	v_lshl_add_u64 v[216:217], s[46:47], 0, v[128:129]
	s_addc_u32 s73, s47, 0
	s_add_i32 s18, s63, s54
	global_load_lds_dwordx4 v[216:217], off
	v_lshl_add_u64 v[218:219], s[72:73], 0, v[130:131]
	s_mov_b32 m0, s18
	v_lshl_add_u64 v[220:221], s[48:49], 0, v[128:129]
	global_load_lds_dwordx4 v[218:219], off
	v_lshl_add_u64 v[218:219], s[72:73], 0, v[128:129]
	s_add_i32 m0, s18, 0x2000
	s_nop 0
	global_load_lds_dwordx4 v[218:219], off
	v_lshl_add_u64 v[218:219], s[48:49], 0, v[130:131]
	s_mov_b32 m0, s37
	s_nop 0
	global_load_lds_dwordx4 v[218:219], off
	s_mov_b32 m0, s56
	s_nop 0
	global_load_lds_dwordx4 v[220:221], off
	s_waitcnt vmcnt(8)
	s_waitcnt lgkmcnt(0)
	s_barrier
	s_setprio 1
	s_waitcnt lgkmcnt(0)
	v_mfma_f32_16x16x32_bf16 v[60:63], v[140:143], v[184:187], 0
	v_mfma_f32_16x16x32_bf16 v[60:63], v[150:153], v[188:191], v[60:63]
	v_mfma_f32_16x16x32_bf16 v[56:59], v[154:157], v[184:187], 0
	v_mfma_f32_16x16x32_bf16 v[56:59], v[158:161], v[188:191], v[56:59]
	v_mfma_f32_16x16x32_bf16 v[44:47], v[140:143], v[192:195], 0
	v_mfma_f32_16x16x32_bf16 v[44:47], v[150:153], v[196:199], v[44:47]
	v_mfma_f32_16x16x32_bf16 v[40:43], v[154:157], v[192:195], 0
	v_mfma_f32_16x16x32_bf16 v[40:43], v[158:161], v[196:199], v[40:43]
	v_mfma_f32_16x16x32_bf16 v[28:31], v[140:143], v[200:203], 0
	v_mfma_f32_16x16x32_bf16 v[28:31], v[150:153], v[204:207], v[28:31]
	v_mfma_f32_16x16x32_bf16 v[24:27], v[154:157], v[200:203], 0
	v_mfma_f32_16x16x32_bf16 v[24:27], v[158:161], v[204:207], v[24:27]
	v_mfma_f32_16x16x32_bf16 v[12:15], v[140:143], v[208:211], 0
	v_mfma_f32_16x16x32_bf16 v[12:15], v[150:153], v[212:215], v[12:15]
	v_mfma_f32_16x16x32_bf16 v[8:11], v[154:157], v[208:211], 0
	v_mfma_f32_16x16x32_bf16 v[8:11], v[158:161], v[212:215], v[8:11]
	s_setprio 0
	s_setprio 1
	v_mfma_f32_16x16x32_bf16 v[52:55], v[162:165], v[184:187], 0
	v_mfma_f32_16x16x32_bf16 v[52:55], v[166:169], v[188:191], v[52:55]
	v_mfma_f32_16x16x32_bf16 v[48:51], v[170:173], v[184:187], 0
	v_mfma_f32_16x16x32_bf16 v[48:51], v[174:177], v[188:191], v[48:51]
	v_mfma_f32_16x16x32_bf16 v[36:39], v[162:165], v[192:195], 0
	v_mfma_f32_16x16x32_bf16 v[36:39], v[166:169], v[196:199], v[36:39]
	v_mfma_f32_16x16x32_bf16 v[32:35], v[170:173], v[192:195], 0
	v_mfma_f32_16x16x32_bf16 v[32:35], v[174:177], v[196:199], v[32:35]
	v_mfma_f32_16x16x32_bf16 v[20:23], v[162:165], v[200:203], 0
	v_mfma_f32_16x16x32_bf16 v[20:23], v[166:169], v[204:207], v[20:23]
	v_mfma_f32_16x16x32_bf16 v[16:19], v[170:173], v[200:203], 0
	v_mfma_f32_16x16x32_bf16 v[16:19], v[174:177], v[204:207], v[16:19]
	v_mfma_f32_16x16x32_bf16 v[4:7], v[162:165], v[208:211], 0
	v_mfma_f32_16x16x32_bf16 v[4:7], v[166:169], v[212:215], v[4:7]
	s_barrier
	v_mfma_f32_16x16x32_bf16 v[0:3], v[170:173], v[208:211], 0
	v_mfma_f32_16x16x32_bf16 v[0:3], v[174:177], v[212:215], v[0:3]
	s_setprio 0
	s_branch .Lmid_gemm0
.LBB0_184:
	ds_read_b128 v[140:143], v147
	ds_read_b128 v[150:153], v147 offset:1024
	ds_read_b128 v[154:157], v147 offset:2048
	ds_read_b128 v[158:161], v147 offset:3072
	ds_read_b128 v[162:165], v148
	ds_read_b128 v[166:169], v148 offset:1024
	ds_read_b128 v[170:173], v148 offset:2048
	ds_read_b128 v[174:177], v148 offset:3072
	s_add_u32 s18, s44, 0xfffc0080
	s_addc_u32 s19, s45, -1
	s_cmp_eq_u32 s70, 12
	s_cselect_b32 s49, s13, s19
	s_cselect_b32 s48, s66, s18
	s_cselect_b32 s47, s11, s69
	s_cselect_b32 s46, s67, s68
	v_lshl_add_u64 v[178:179], s[44:45], 0, v[132:133]
	s_add_i32 m0, s37, 0xc000
	ds_read_b128 v[184:187], v149
	ds_read_b128 v[188:191], v149 offset:1024
	ds_read_b128 v[192:195], v149 offset:2048
	ds_read_b128 v[196:199], v149 offset:3072
	ds_read_b128 v[200:203], v149 offset:4096
	ds_read_b128 v[204:207], v149 offset:5120
	ds_read_b128 v[208:211], v149 offset:6144
	ds_read_b128 v[212:215], v149 offset:7168
	global_load_lds_dwordx4 v[178:179], off
	v_lshl_add_u64 v[178:179], s[44:45], 0, v[134:135]
	s_add_i32 m0, s37, 0xe000
	s_nop 0
	global_load_lds_dwordx4 v[178:179], off
	s_waitcnt vmcnt(8)
	s_waitcnt lgkmcnt(0)
	s_barrier
	s_setprio 1
	s_waitcnt lgkmcnt(0)
	v_mfma_f32_16x16x32_bf16 v[124:127], v[140:143], v[184:187], v[124:127]
	v_mfma_f32_16x16x32_bf16 v[124:127], v[150:153], v[188:191], v[124:127]
	v_mfma_f32_16x16x32_bf16 v[120:123], v[154:157], v[184:187], v[120:123]
	v_mfma_f32_16x16x32_bf16 v[120:123], v[158:161], v[188:191], v[120:123]
	v_mfma_f32_16x16x32_bf16 v[108:111], v[140:143], v[192:195], v[108:111]
	v_mfma_f32_16x16x32_bf16 v[108:111], v[150:153], v[196:199], v[108:111]
	v_mfma_f32_16x16x32_bf16 v[104:107], v[154:157], v[192:195], v[104:107]
	v_mfma_f32_16x16x32_bf16 v[104:107], v[158:161], v[196:199], v[104:107]
	v_mfma_f32_16x16x32_bf16 v[92:95], v[140:143], v[200:203], v[92:95]
	v_mfma_f32_16x16x32_bf16 v[92:95], v[150:153], v[204:207], v[92:95]
	v_mfma_f32_16x16x32_bf16 v[88:91], v[154:157], v[200:203], v[88:91]
	v_mfma_f32_16x16x32_bf16 v[88:91], v[158:161], v[204:207], v[88:91]
	v_mfma_f32_16x16x32_bf16 v[76:79], v[140:143], v[208:211], v[76:79]
	v_mfma_f32_16x16x32_bf16 v[76:79], v[150:153], v[212:215], v[76:79]
	v_mfma_f32_16x16x32_bf16 v[72:75], v[154:157], v[208:211], v[72:75]
	v_mfma_f32_16x16x32_bf16 v[72:75], v[158:161], v[212:215], v[72:75]
	s_setprio 0
	s_setprio 1
	v_mfma_f32_16x16x32_bf16 v[116:119], v[162:165], v[184:187], v[116:119]
	v_mfma_f32_16x16x32_bf16 v[116:119], v[166:169], v[188:191], v[116:119]
	v_mfma_f32_16x16x32_bf16 v[112:115], v[170:173], v[184:187], v[112:115]
	v_mfma_f32_16x16x32_bf16 v[112:115], v[174:177], v[188:191], v[112:115]
	v_mfma_f32_16x16x32_bf16 v[100:103], v[162:165], v[192:195], v[100:103]
	v_mfma_f32_16x16x32_bf16 v[100:103], v[166:169], v[196:199], v[100:103]
	v_mfma_f32_16x16x32_bf16 v[96:99], v[170:173], v[192:195], v[96:99]
	v_mfma_f32_16x16x32_bf16 v[96:99], v[174:177], v[196:199], v[96:99]
	v_mfma_f32_16x16x32_bf16 v[84:87], v[162:165], v[200:203], v[84:87]
	v_mfma_f32_16x16x32_bf16 v[84:87], v[166:169], v[204:207], v[84:87]
	v_mfma_f32_16x16x32_bf16 v[80:83], v[170:173], v[200:203], v[80:83]
	v_mfma_f32_16x16x32_bf16 v[80:83], v[174:177], v[204:207], v[80:83]
	v_mfma_f32_16x16x32_bf16 v[68:71], v[162:165], v[208:211], v[68:71]
	v_mfma_f32_16x16x32_bf16 v[68:71], v[166:169], v[212:215], v[68:71]
	s_barrier
	v_mfma_f32_16x16x32_bf16 v[64:67], v[170:173], v[208:211], v[64:67]
	v_mfma_f32_16x16x32_bf16 v[64:67], v[174:177], v[212:215], v[64:67]
	s_setprio 0
	s_add_i32 s18, s62, s54
	v_lshl_add_u64 v[178:179], s[46:47], 0, v[130:131]
	s_mov_b32 m0, s18
	ds_read_b128 v[184:187], v149 offset:16384
	ds_read_b128 v[188:191], v149 offset:17408
	ds_read_b128 v[192:195], v149 offset:18432
	ds_read_b128 v[196:199], v149 offset:19456
	ds_read_b128 v[200:203], v149 offset:20480
	ds_read_b128 v[204:207], v149 offset:21504
	ds_read_b128 v[208:211], v149 offset:22528
	ds_read_b128 v[212:215], v149 offset:23552
	global_load_lds_dwordx4 v[178:179], off
	s_add_i32 m0, s18, 0x2000
	s_add_u32 s72, s46, 0x40000
	v_lshl_add_u64 v[216:217], s[46:47], 0, v[128:129]
	s_addc_u32 s73, s47, 0
	s_add_i32 s18, s63, s54
	global_load_lds_dwordx4 v[216:217], off
	v_lshl_add_u64 v[218:219], s[72:73], 0, v[130:131]
	s_mov_b32 m0, s18
	v_lshl_add_u64 v[220:221], s[48:49], 0, v[128:129]
	global_load_lds_dwordx4 v[218:219], off
	v_lshl_add_u64 v[218:219], s[72:73], 0, v[128:129]
	s_add_i32 m0, s18, 0x2000
	s_nop 0
	global_load_lds_dwordx4 v[218:219], off
	v_lshl_add_u64 v[218:219], s[48:49], 0, v[130:131]
	s_mov_b32 m0, s37
	s_nop 0
	global_load_lds_dwordx4 v[218:219], off
	s_mov_b32 m0, s56
	s_nop 0
	global_load_lds_dwordx4 v[220:221], off
	s_waitcnt vmcnt(8)
	s_waitcnt lgkmcnt(0)
	s_barrier
	s_setprio 1
	s_waitcnt lgkmcnt(0)
	v_mfma_f32_16x16x32_bf16 v[60:63], v[140:143], v[184:187], v[60:63]
	v_mfma_f32_16x16x32_bf16 v[60:63], v[150:153], v[188:191], v[60:63]
	v_mfma_f32_16x16x32_bf16 v[56:59], v[154:157], v[184:187], v[56:59]
	v_mfma_f32_16x16x32_bf16 v[56:59], v[158:161], v[188:191], v[56:59]
	v_mfma_f32_16x16x32_bf16 v[44:47], v[140:143], v[192:195], v[44:47]
	v_mfma_f32_16x16x32_bf16 v[44:47], v[150:153], v[196:199], v[44:47]
	v_mfma_f32_16x16x32_bf16 v[40:43], v[154:157], v[192:195], v[40:43]
	v_mfma_f32_16x16x32_bf16 v[40:43], v[158:161], v[196:199], v[40:43]
	v_mfma_f32_16x16x32_bf16 v[28:31], v[140:143], v[200:203], v[28:31]
	v_mfma_f32_16x16x32_bf16 v[28:31], v[150:153], v[204:207], v[28:31]
	v_mfma_f32_16x16x32_bf16 v[24:27], v[154:157], v[200:203], v[24:27]
	v_mfma_f32_16x16x32_bf16 v[24:27], v[158:161], v[204:207], v[24:27]
	v_mfma_f32_16x16x32_bf16 v[12:15], v[140:143], v[208:211], v[12:15]
	v_mfma_f32_16x16x32_bf16 v[12:15], v[150:153], v[212:215], v[12:15]
	v_mfma_f32_16x16x32_bf16 v[8:11], v[154:157], v[208:211], v[8:11]
	v_mfma_f32_16x16x32_bf16 v[8:11], v[158:161], v[212:215], v[8:11]
	s_setprio 0
	s_setprio 1
	v_mfma_f32_16x16x32_bf16 v[52:55], v[162:165], v[184:187], v[52:55]
	v_mfma_f32_16x16x32_bf16 v[52:55], v[166:169], v[188:191], v[52:55]
	v_mfma_f32_16x16x32_bf16 v[48:51], v[170:173], v[184:187], v[48:51]
	v_mfma_f32_16x16x32_bf16 v[48:51], v[174:177], v[188:191], v[48:51]
	v_mfma_f32_16x16x32_bf16 v[36:39], v[162:165], v[192:195], v[36:39]
	v_mfma_f32_16x16x32_bf16 v[36:39], v[166:169], v[196:199], v[36:39]
	v_mfma_f32_16x16x32_bf16 v[32:35], v[170:173], v[192:195], v[32:35]
	v_mfma_f32_16x16x32_bf16 v[32:35], v[174:177], v[196:199], v[32:35]
	v_mfma_f32_16x16x32_bf16 v[20:23], v[162:165], v[200:203], v[20:23]
	v_mfma_f32_16x16x32_bf16 v[20:23], v[166:169], v[204:207], v[20:23]
	v_mfma_f32_16x16x32_bf16 v[16:19], v[170:173], v[200:203], v[16:19]
	v_mfma_f32_16x16x32_bf16 v[16:19], v[174:177], v[204:207], v[16:19]
	v_mfma_f32_16x16x32_bf16 v[4:7], v[162:165], v[208:211], v[4:7]
	v_mfma_f32_16x16x32_bf16 v[4:7], v[166:169], v[212:215], v[4:7]
	s_barrier
	v_mfma_f32_16x16x32_bf16 v[0:3], v[170:173], v[208:211], v[0:3]
	v_mfma_f32_16x16x32_bf16 v[0:3], v[174:177], v[212:215], v[0:3]
	s_setprio 0
.Lmid_gemm0:
	s_add_i32 s18, 0, 0x18000
	s_add_i32 s19, 0, 0x1c000
	v_add_u32_e32 v158, s18, v145
	v_add_u32_e32 v174, s19, v145
	ds_read_b128 v[140:143], v158
	ds_read_b128 v[150:153], v158 offset:1024
	ds_read_b128 v[154:157], v158 offset:2048
	ds_read_b128 v[158:161], v158 offset:3072
	ds_read_b128 v[162:165], v174
	ds_read_b128 v[166:169], v174 offset:1024
	ds_read_b128 v[170:173], v174 offset:2048
	ds_read_b128 v[174:177], v174 offset:3072
	s_add_u32 s48, s48, 0x40000
	s_addc_u32 s49, s49, 0
	s_mov_b32 m0, s57
	v_lshl_add_u64 v[222:223], s[48:49], 0, v[130:131]
	ds_read_b128 v[184:187], v149 offset:32768
	ds_read_b128 v[188:191], v149 offset:33792
	ds_read_b128 v[192:195], v149 offset:34816
	ds_read_b128 v[196:199], v149 offset:35840
	ds_read_b128 v[200:203], v149 offset:36864
	ds_read_b128 v[204:207], v149 offset:37888
	ds_read_b128 v[208:211], v149 offset:38912
	ds_read_b128 v[212:215], v149 offset:39936
	global_load_lds_dwordx4 v[222:223], off
	v_lshl_add_u64 v[222:223], s[48:49], 0, v[128:129]
	s_mov_b32 m0, s58
	s_nop 0
	global_load_lds_dwordx4 v[222:223], off
	s_waitcnt vmcnt(8)
	s_waitcnt lgkmcnt(0)
	s_barrier
	s_setprio 1
	s_waitcnt lgkmcnt(0)
	v_mfma_f32_16x16x32_bf16 v[124:127], v[140:143], v[184:187], v[124:127]
	v_mfma_f32_16x16x32_bf16 v[124:127], v[150:153], v[188:191], v[124:127]
	v_mfma_f32_16x16x32_bf16 v[120:123], v[154:157], v[184:187], v[120:123]
	v_mfma_f32_16x16x32_bf16 v[120:123], v[158:161], v[188:191], v[120:123]
	v_mfma_f32_16x16x32_bf16 v[108:111], v[140:143], v[192:195], v[108:111]
	v_mfma_f32_16x16x32_bf16 v[108:111], v[150:153], v[196:199], v[108:111]
	v_mfma_f32_16x16x32_bf16 v[104:107], v[154:157], v[192:195], v[104:107]
	v_mfma_f32_16x16x32_bf16 v[104:107], v[158:161], v[196:199], v[104:107]
	v_mfma_f32_16x16x32_bf16 v[92:95], v[140:143], v[200:203], v[92:95]
	v_mfma_f32_16x16x32_bf16 v[92:95], v[150:153], v[204:207], v[92:95]
	v_mfma_f32_16x16x32_bf16 v[88:91], v[154:157], v[200:203], v[88:91]
	v_mfma_f32_16x16x32_bf16 v[88:91], v[158:161], v[204:207], v[88:91]
	v_mfma_f32_16x16x32_bf16 v[76:79], v[140:143], v[208:211], v[76:79]
	v_mfma_f32_16x16x32_bf16 v[76:79], v[150:153], v[212:215], v[76:79]
	v_mfma_f32_16x16x32_bf16 v[72:75], v[154:157], v[208:211], v[72:75]
	v_mfma_f32_16x16x32_bf16 v[72:75], v[158:161], v[212:215], v[72:75]
	s_setprio 0
	s_setprio 1
	v_mfma_f32_16x16x32_bf16 v[116:119], v[162:165], v[184:187], v[116:119]
	v_mfma_f32_16x16x32_bf16 v[116:119], v[166:169], v[188:191], v[116:119]
	v_mfma_f32_16x16x32_bf16 v[112:115], v[170:173], v[184:187], v[112:115]
	v_mfma_f32_16x16x32_bf16 v[112:115], v[174:177], v[188:191], v[112:115]
	v_mfma_f32_16x16x32_bf16 v[100:103], v[162:165], v[192:195], v[100:103]
	v_mfma_f32_16x16x32_bf16 v[100:103], v[166:169], v[196:199], v[100:103]
	v_mfma_f32_16x16x32_bf16 v[96:99], v[170:173], v[192:195], v[96:99]
	v_mfma_f32_16x16x32_bf16 v[96:99], v[174:177], v[196:199], v[96:99]
	v_mfma_f32_16x16x32_bf16 v[84:87], v[162:165], v[200:203], v[84:87]
	v_mfma_f32_16x16x32_bf16 v[84:87], v[166:169], v[204:207], v[84:87]
	v_mfma_f32_16x16x32_bf16 v[80:83], v[170:173], v[200:203], v[80:83]
	v_mfma_f32_16x16x32_bf16 v[80:83], v[174:177], v[204:207], v[80:83]
	v_mfma_f32_16x16x32_bf16 v[68:71], v[162:165], v[208:211], v[68:71]
	v_mfma_f32_16x16x32_bf16 v[68:71], v[166:169], v[212:215], v[68:71]
	s_barrier
	v_mfma_f32_16x16x32_bf16 v[64:67], v[170:173], v[208:211], v[64:67]
	v_mfma_f32_16x16x32_bf16 v[64:67], v[174:177], v[212:215], v[64:67]
	s_setprio 0
	s_add_i32 s18, s18, s54
	v_lshl_add_u64 v[178:179], v[178:179], 0, s[6:7]
	s_mov_b32 m0, s18
	ds_read_b128 v[184:187], v149 offset:49152
	ds_read_b128 v[188:191], v149 offset:50176
	ds_read_b128 v[192:195], v149 offset:51200
	ds_read_b128 v[196:199], v149 offset:52224
	ds_read_b128 v[200:203], v149 offset:53248
	ds_read_b128 v[204:207], v149 offset:54272
	ds_read_b128 v[208:211], v149 offset:55296
	ds_read_b128 v[212:215], v149 offset:56320
	global_load_lds_dwordx4 v[178:179], off
	s_add_i32 m0, s18, 0x2000
	s_add_u32 s46, s46, 0x40080
	v_lshl_add_u64 v[178:179], v[216:217], 0, s[6:7]
	s_addc_u32 s47, s47, 0
	s_add_i32 s18, s19, s54
	global_load_lds_dwordx4 v[178:179], off
	v_lshl_add_u64 v[178:179], s[46:47], 0, v[130:131]
	s_mov_b32 m0, s18
	s_nop 0
	global_load_lds_dwordx4 v[178:179], off
	v_lshl_add_u64 v[178:179], s[46:47], 0, v[128:129]
	s_add_i32 m0, s18, 0x2000
	s_nop 0
	global_load_lds_dwordx4 v[178:179], off
	v_lshl_add_u64 v[178:179], v[218:219], 0, s[6:7]
	s_mov_b32 m0, s60
	s_nop 0
	global_load_lds_dwordx4 v[178:179], off
	v_lshl_add_u64 v[178:179], v[220:221], 0, s[6:7]
	s_mov_b32 m0, s61
	s_nop 0
	global_load_lds_dwordx4 v[178:179], off
	s_waitcnt vmcnt(8)
	s_waitcnt lgkmcnt(0)
	s_barrier
	s_setprio 1
	s_waitcnt lgkmcnt(0)
	v_mfma_f32_16x16x32_bf16 v[60:63], v[140:143], v[184:187], v[60:63]
	v_mfma_f32_16x16x32_bf16 v[60:63], v[150:153], v[188:191], v[60:63]
	v_mfma_f32_16x16x32_bf16 v[56:59], v[154:157], v[184:187], v[56:59]
	v_mfma_f32_16x16x32_bf16 v[56:59], v[158:161], v[188:191], v[56:59]
	v_mfma_f32_16x16x32_bf16 v[44:47], v[140:143], v[192:195], v[44:47]
	v_mfma_f32_16x16x32_bf16 v[44:47], v[150:153], v[196:199], v[44:47]
	v_mfma_f32_16x16x32_bf16 v[40:43], v[154:157], v[192:195], v[40:43]
	v_mfma_f32_16x16x32_bf16 v[40:43], v[158:161], v[196:199], v[40:43]
	v_mfma_f32_16x16x32_bf16 v[28:31], v[140:143], v[200:203], v[28:31]
	v_mfma_f32_16x16x32_bf16 v[28:31], v[150:153], v[204:207], v[28:31]
	v_mfma_f32_16x16x32_bf16 v[24:27], v[154:157], v[200:203], v[24:27]
	v_mfma_f32_16x16x32_bf16 v[24:27], v[158:161], v[204:207], v[24:27]
	v_mfma_f32_16x16x32_bf16 v[12:15], v[140:143], v[208:211], v[12:15]
	v_mfma_f32_16x16x32_bf16 v[12:15], v[150:153], v[212:215], v[12:15]
	v_mfma_f32_16x16x32_bf16 v[8:11], v[154:157], v[208:211], v[8:11]
	v_mfma_f32_16x16x32_bf16 v[8:11], v[158:161], v[212:215], v[8:11]
	s_setprio 0
	s_setprio 1
	v_mfma_f32_16x16x32_bf16 v[52:55], v[162:165], v[184:187], v[52:55]
	v_mfma_f32_16x16x32_bf16 v[52:55], v[166:169], v[188:191], v[52:55]
	v_mfma_f32_16x16x32_bf16 v[48:51], v[170:173], v[184:187], v[48:51]
	v_mfma_f32_16x16x32_bf16 v[48:51], v[174:177], v[188:191], v[48:51]
	v_mfma_f32_16x16x32_bf16 v[36:39], v[162:165], v[192:195], v[36:39]
	v_mfma_f32_16x16x32_bf16 v[36:39], v[166:169], v[196:199], v[36:39]
	v_mfma_f32_16x16x32_bf16 v[32:35], v[170:173], v[192:195], v[32:35]
	v_mfma_f32_16x16x32_bf16 v[32:35], v[174:177], v[196:199], v[32:35]
	v_mfma_f32_16x16x32_bf16 v[20:23], v[162:165], v[200:203], v[20:23]
	v_mfma_f32_16x16x32_bf16 v[20:23], v[166:169], v[204:207], v[20:23]
	v_mfma_f32_16x16x32_bf16 v[16:19], v[170:173], v[200:203], v[16:19]
	v_mfma_f32_16x16x32_bf16 v[16:19], v[174:177], v[204:207], v[16:19]
	v_mfma_f32_16x16x32_bf16 v[4:7], v[162:165], v[208:211], v[4:7]
	v_mfma_f32_16x16x32_bf16 v[4:7], v[166:169], v[212:215], v[4:7]
	s_barrier
	v_mfma_f32_16x16x32_bf16 v[0:3], v[170:173], v[208:211], v[0:3]
	v_mfma_f32_16x16x32_bf16 v[0:3], v[174:177], v[212:215], v[0:3]
	s_setprio 0
	s_add_i32 s70, s70, 2
	s_add_u32 s44, s44, 0x100
	s_addc_u32 s45, s45, 0
	s_add_u32 s68, s68, 0x100
	s_addc_u32 s69, s69, 0
	s_cmp_gt_u32 s70, 13
	s_cbranch_scc0 .LBB0_184
	s_and_b64 vcc, exec, s[8:9]
	s_cbranch_vccz .LBB0_187
	s_barrier

.LBB0_263:
	s_add_u32 s84, s54, 0x100
	s_addc_u32 s85, s55, 0
	s_mov_b32 s86, -2
	ds_read_b128 v[152:155], v149
	ds_read_b128 v[156:159], v149 offset:1024
	ds_read_b128 v[160:163], v149 offset:2048
	ds_read_b128 v[164:167], v149 offset:3072
	ds_read_b128 v[168:171], v150
	ds_read_b128 v[172:175], v150 offset:1024
	ds_read_b128 v[176:179], v150 offset:2048
	ds_read_b128 v[184:187], v150 offset:3072
	s_add_u32 s54, s52, 0x100
	s_addc_u32 s55, s53, 0
	s_cmp_eq_u32 s86, 40
	s_cselect_b32 s59, s7, s55
	s_cselect_b32 s58, s6, s54
	s_cselect_b32 s57, s49, s85
	s_cselect_b32 s56, s48, s84
	v_lshl_add_u64 v[144:145], s[52:53], 0, v[136:137]
	s_add_i32 m0, s63, 0xc000
	ds_read_b128 v[188:191], v151
	ds_read_b128 v[192:195], v151 offset:1024
	ds_read_b128 v[196:199], v151 offset:2048
	ds_read_b128 v[200:203], v151 offset:3072
	ds_read_b128 v[204:207], v151 offset:4096
	ds_read_b128 v[208:211], v151 offset:5120
	ds_read_b128 v[212:215], v151 offset:6144
	ds_read_b128 v[216:219], v151 offset:7168
	global_load_lds_dwordx4 v[144:145], off
	v_lshl_add_u64 v[144:145], s[52:53], 0, v[138:139]
	s_add_i32 m0, s63, 0xe000
	s_nop 0
	global_load_lds_dwordx4 v[144:145], off
	s_waitcnt vmcnt(8)
	s_waitcnt lgkmcnt(0)
	s_barrier
	s_setprio 1
	s_waitcnt lgkmcnt(0)
	v_mfma_f32_16x16x32_bf16 v[124:127], v[152:155], v[188:191], 0
	v_mfma_f32_16x16x32_bf16 v[124:127], v[156:159], v[192:195], v[124:127]
	v_mfma_f32_16x16x32_bf16 v[120:123], v[160:163], v[188:191], 0
	v_mfma_f32_16x16x32_bf16 v[120:123], v[164:167], v[192:195], v[120:123]
	v_mfma_f32_16x16x32_bf16 v[116:119], v[152:155], v[196:199], 0
	v_mfma_f32_16x16x32_bf16 v[116:119], v[156:159], v[200:203], v[116:119]
	v_mfma_f32_16x16x32_bf16 v[108:111], v[160:163], v[196:199], 0
	v_mfma_f32_16x16x32_bf16 v[108:111], v[164:167], v[200:203], v[108:111]
	v_mfma_f32_16x16x32_bf16 v[100:103], v[152:155], v[204:207], 0
	v_mfma_f32_16x16x32_bf16 v[100:103], v[156:159], v[208:211], v[100:103]
	v_mfma_f32_16x16x32_bf16 v[92:95], v[160:163], v[204:207], 0
	v_mfma_f32_16x16x32_bf16 v[92:95], v[164:167], v[208:211], v[92:95]
	v_mfma_f32_16x16x32_bf16 v[84:87], v[152:155], v[212:215], 0
	v_mfma_f32_16x16x32_bf16 v[84:87], v[156:159], v[216:219], v[84:87]
	v_mfma_f32_16x16x32_bf16 v[76:79], v[160:163], v[212:215], 0
	v_mfma_f32_16x16x32_bf16 v[76:79], v[164:167], v[216:219], v[76:79]
	s_setprio 0
	s_setprio 1
	v_mfma_f32_16x16x32_bf16 v[112:115], v[168:171], v[188:191], 0
	v_mfma_f32_16x16x32_bf16 v[112:115], v[172:175], v[192:195], v[112:115]
	v_mfma_f32_16x16x32_bf16 v[104:107], v[176:179], v[188:191], 0
	v_mfma_f32_16x16x32_bf16 v[104:107], v[184:187], v[192:195], v[104:107]
	v_mfma_f32_16x16x32_bf16 v[96:99], v[168:171], v[196:199], 0
	v_mfma_f32_16x16x32_bf16 v[96:99], v[172:175], v[200:203], v[96:99]
	v_mfma_f32_16x16x32_bf16 v[88:91], v[176:179], v[196:199], 0
	v_mfma_f32_16x16x32_bf16 v[88:91], v[184:187], v[200:203], v[88:91]
	v_mfma_f32_16x16x32_bf16 v[80:83], v[168:171], v[204:207], 0
	v_mfma_f32_16x16x32_bf16 v[80:83], v[172:175], v[208:211], v[80:83]
	v_mfma_f32_16x16x32_bf16 v[72:75], v[176:179], v[204:207], 0
	v_mfma_f32_16x16x32_bf16 v[72:75], v[184:187], v[208:211], v[72:75]
	v_mfma_f32_16x16x32_bf16 v[68:71], v[168:171], v[212:215], 0
	v_mfma_f32_16x16x32_bf16 v[68:71], v[172:175], v[216:219], v[68:71]
	s_barrier
	v_mfma_f32_16x16x32_bf16 v[64:67], v[176:179], v[212:215], 0
	v_mfma_f32_16x16x32_bf16 v[64:67], v[184:187], v[216:219], v[64:67]
	s_setprio 0
	s_add_i32 s18, s70, s62
	v_lshl_add_u64 v[144:145], s[56:57], 0, v[130:131]
	s_mov_b32 m0, s18
	ds_read_b128 v[188:191], v151 offset:16384
	ds_read_b128 v[192:195], v151 offset:17408
	ds_read_b128 v[196:199], v151 offset:18432
	ds_read_b128 v[200:203], v151 offset:19456
	ds_read_b128 v[204:207], v151 offset:20480
	ds_read_b128 v[208:211], v151 offset:21504
	ds_read_b128 v[212:215], v151 offset:22528
	ds_read_b128 v[216:219], v151 offset:23552
	global_load_lds_dwordx4 v[144:145], off
	s_add_i32 m0, s18, 0x2000
	s_add_u32 s52, s56, 0xb0000
	v_lshl_add_u64 v[220:221], s[56:57], 0, v[134:135]
	s_addc_u32 s53, s57, 0
	s_add_i32 s18, s71, s62
	global_load_lds_dwordx4 v[220:221], off
	v_lshl_add_u64 v[222:223], s[52:53], 0, v[130:131]
	s_mov_b32 m0, s18
	v_lshl_add_u64 v[224:225], s[58:59], 0, v[132:133]
	global_load_lds_dwordx4 v[222:223], off
	v_lshl_add_u64 v[222:223], s[52:53], 0, v[134:135]
	s_add_i32 m0, s18, 0x2000
	s_nop 0
	global_load_lds_dwordx4 v[222:223], off
	v_lshl_add_u64 v[222:223], s[58:59], 0, v[128:129]
	s_mov_b32 m0, s63
	s_nop 0
	global_load_lds_dwordx4 v[222:223], off
	s_mov_b32 m0, s64
	s_nop 0
	global_load_lds_dwordx4 v[224:225], off
	s_waitcnt vmcnt(8)
	s_waitcnt lgkmcnt(0)
	s_barrier
	s_setprio 1
	s_waitcnt lgkmcnt(0)
	v_mfma_f32_16x16x32_bf16 v[60:63], v[152:155], v[188:191], 0
	v_mfma_f32_16x16x32_bf16 v[60:63], v[156:159], v[192:195], v[60:63]
	v_mfma_f32_16x16x32_bf16 v[56:59], v[160:163], v[188:191], 0
	v_mfma_f32_16x16x32_bf16 v[56:59], v[164:167], v[192:195], v[56:59]
	v_mfma_f32_16x16x32_bf16 v[52:55], v[152:155], v[196:199], 0
	v_mfma_f32_16x16x32_bf16 v[52:55], v[156:159], v[200:203], v[52:55]
	v_mfma_f32_16x16x32_bf16 v[44:47], v[160:163], v[196:199], 0
	v_mfma_f32_16x16x32_bf16 v[44:47], v[164:167], v[200:203], v[44:47]
	v_mfma_f32_16x16x32_bf16 v[36:39], v[152:155], v[204:207], 0
	v_mfma_f32_16x16x32_bf16 v[36:39], v[156:159], v[208:211], v[36:39]
	v_mfma_f32_16x16x32_bf16 v[28:31], v[160:163], v[204:207], 0
	v_mfma_f32_16x16x32_bf16 v[28:31], v[164:167], v[208:211], v[28:31]
	v_mfma_f32_16x16x32_bf16 v[20:23], v[152:155], v[212:215], 0
	v_mfma_f32_16x16x32_bf16 v[20:23], v[156:159], v[216:219], v[20:23]
	v_mfma_f32_16x16x32_bf16 v[12:15], v[160:163], v[212:215], 0
	v_mfma_f32_16x16x32_bf16 v[12:15], v[164:167], v[216:219], v[12:15]
	s_setprio 0
	s_setprio 1
	v_mfma_f32_16x16x32_bf16 v[48:51], v[168:171], v[188:191], 0
	v_mfma_f32_16x16x32_bf16 v[48:51], v[172:175], v[192:195], v[48:51]
	v_mfma_f32_16x16x32_bf16 v[40:43], v[176:179], v[188:191], 0
	v_mfma_f32_16x16x32_bf16 v[40:43], v[184:187], v[192:195], v[40:43]
	v_mfma_f32_16x16x32_bf16 v[32:35], v[168:171], v[196:199], 0
	v_mfma_f32_16x16x32_bf16 v[32:35], v[172:175], v[200:203], v[32:35]
	v_mfma_f32_16x16x32_bf16 v[24:27], v[176:179], v[196:199], 0
	v_mfma_f32_16x16x32_bf16 v[24:27], v[184:187], v[200:203], v[24:27]
	v_mfma_f32_16x16x32_bf16 v[16:19], v[168:171], v[204:207], 0
	v_mfma_f32_16x16x32_bf16 v[16:19], v[172:175], v[208:211], v[16:19]
	v_mfma_f32_16x16x32_bf16 v[8:11], v[176:179], v[204:207], 0
	v_mfma_f32_16x16x32_bf16 v[8:11], v[184:187], v[208:211], v[8:11]
	v_mfma_f32_16x16x32_bf16 v[4:7], v[168:171], v[212:215], 0
	v_mfma_f32_16x16x32_bf16 v[4:7], v[172:175], v[216:219], v[4:7]
	s_barrier
	v_mfma_f32_16x16x32_bf16 v[0:3], v[176:179], v[212:215], 0
	v_mfma_f32_16x16x32_bf16 v[0:3], v[184:187], v[216:219], v[0:3]
	s_setprio 0
	s_branch .Lmid_gemm1
.LBB0_264:
	ds_read_b128 v[152:155], v149
	ds_read_b128 v[156:159], v149 offset:1024
	ds_read_b128 v[160:163], v149 offset:2048
	ds_read_b128 v[164:167], v149 offset:3072
	ds_read_b128 v[168:171], v150
	ds_read_b128 v[172:175], v150 offset:1024
	ds_read_b128 v[176:179], v150 offset:2048
	ds_read_b128 v[184:187], v150 offset:3072
	s_add_u32 s54, s52, 0x100
	s_addc_u32 s55, s53, 0
	s_cmp_eq_u32 s86, 40
	s_cselect_b32 s59, s7, s55
	s_cselect_b32 s58, s6, s54
	s_cselect_b32 s57, s49, s85
	s_cselect_b32 s56, s48, s84
	v_lshl_add_u64 v[144:145], s[52:53], 0, v[136:137]
	s_add_i32 m0, s63, 0xc000
	ds_read_b128 v[188:191], v151
	ds_read_b128 v[192:195], v151 offset:1024
	ds_read_b128 v[196:199], v151 offset:2048
	ds_read_b128 v[200:203], v151 offset:3072
	ds_read_b128 v[204:207], v151 offset:4096
	ds_read_b128 v[208:211], v151 offset:5120
	ds_read_b128 v[212:215], v151 offset:6144
	ds_read_b128 v[216:219], v151 offset:7168
	global_load_lds_dwordx4 v[144:145], off
	v_lshl_add_u64 v[144:145], s[52:53], 0, v[138:139]
	s_add_i32 m0, s63, 0xe000
	s_nop 0
	global_load_lds_dwordx4 v[144:145], off
	s_waitcnt vmcnt(8)
	s_waitcnt lgkmcnt(0)
	s_barrier
	s_setprio 1
	s_waitcnt lgkmcnt(0)
	v_mfma_f32_16x16x32_bf16 v[124:127], v[152:155], v[188:191], v[124:127]
	v_mfma_f32_16x16x32_bf16 v[124:127], v[156:159], v[192:195], v[124:127]
	v_mfma_f32_16x16x32_bf16 v[120:123], v[160:163], v[188:191], v[120:123]
	v_mfma_f32_16x16x32_bf16 v[120:123], v[164:167], v[192:195], v[120:123]
	v_mfma_f32_16x16x32_bf16 v[116:119], v[152:155], v[196:199], v[116:119]
	v_mfma_f32_16x16x32_bf16 v[116:119], v[156:159], v[200:203], v[116:119]
	v_mfma_f32_16x16x32_bf16 v[108:111], v[160:163], v[196:199], v[108:111]
	v_mfma_f32_16x16x32_bf16 v[108:111], v[164:167], v[200:203], v[108:111]
	v_mfma_f32_16x16x32_bf16 v[100:103], v[152:155], v[204:207], v[100:103]
	v_mfma_f32_16x16x32_bf16 v[100:103], v[156:159], v[208:211], v[100:103]
	v_mfma_f32_16x16x32_bf16 v[92:95], v[160:163], v[204:207], v[92:95]
	v_mfma_f32_16x16x32_bf16 v[92:95], v[164:167], v[208:211], v[92:95]
	v_mfma_f32_16x16x32_bf16 v[84:87], v[152:155], v[212:215], v[84:87]
	v_mfma_f32_16x16x32_bf16 v[84:87], v[156:159], v[216:219], v[84:87]
	v_mfma_f32_16x16x32_bf16 v[76:79], v[160:163], v[212:215], v[76:79]
	v_mfma_f32_16x16x32_bf16 v[76:79], v[164:167], v[216:219], v[76:79]
	s_setprio 0
	s_setprio 1
	v_mfma_f32_16x16x32_bf16 v[112:115], v[168:171], v[188:191], v[112:115]
	v_mfma_f32_16x16x32_bf16 v[112:115], v[172:175], v[192:195], v[112:115]
	v_mfma_f32_16x16x32_bf16 v[104:107], v[176:179], v[188:191], v[104:107]
	v_mfma_f32_16x16x32_bf16 v[104:107], v[184:187], v[192:195], v[104:107]
	v_mfma_f32_16x16x32_bf16 v[96:99], v[168:171], v[196:199], v[96:99]
	v_mfma_f32_16x16x32_bf16 v[96:99], v[172:175], v[200:203], v[96:99]
	v_mfma_f32_16x16x32_bf16 v[88:91], v[176:179], v[196:199], v[88:91]
	v_mfma_f32_16x16x32_bf16 v[88:91], v[184:187], v[200:203], v[88:91]
	v_mfma_f32_16x16x32_bf16 v[80:83], v[168:171], v[204:207], v[80:83]
	v_mfma_f32_16x16x32_bf16 v[80:83], v[172:175], v[208:211], v[80:83]
	v_mfma_f32_16x16x32_bf16 v[72:75], v[176:179], v[204:207], v[72:75]
	v_mfma_f32_16x16x32_bf16 v[72:75], v[184:187], v[208:211], v[72:75]
	v_mfma_f32_16x16x32_bf16 v[68:71], v[168:171], v[212:215], v[68:71]
	v_mfma_f32_16x16x32_bf16 v[68:71], v[172:175], v[216:219], v[68:71]
	s_barrier
	v_mfma_f32_16x16x32_bf16 v[64:67], v[176:179], v[212:215], v[64:67]
	v_mfma_f32_16x16x32_bf16 v[64:67], v[184:187], v[216:219], v[64:67]
	s_setprio 0
	s_add_i32 s18, s70, s62
	v_lshl_add_u64 v[144:145], s[56:57], 0, v[130:131]
	s_mov_b32 m0, s18
	ds_read_b128 v[188:191], v151 offset:16384
	ds_read_b128 v[192:195], v151 offset:17408
	ds_read_b128 v[196:199], v151 offset:18432
	ds_read_b128 v[200:203], v151 offset:19456
	ds_read_b128 v[204:207], v151 offset:20480
	ds_read_b128 v[208:211], v151 offset:21504
	ds_read_b128 v[212:215], v151 offset:22528
	ds_read_b128 v[216:219], v151 offset:23552
	global_load_lds_dwordx4 v[144:145], off
	s_add_i32 m0, s18, 0x2000
	s_add_u32 s52, s56, 0xb0000
	v_lshl_add_u64 v[220:221], s[56:57], 0, v[134:135]
	s_addc_u32 s53, s57, 0
	s_add_i32 s18, s71, s62
	global_load_lds_dwordx4 v[220:221], off
	v_lshl_add_u64 v[222:223], s[52:53], 0, v[130:131]
	s_mov_b32 m0, s18
	v_lshl_add_u64 v[224:225], s[58:59], 0, v[132:133]
	global_load_lds_dwordx4 v[222:223], off
	v_lshl_add_u64 v[222:223], s[52:53], 0, v[134:135]
	s_add_i32 m0, s18, 0x2000
	s_nop 0
	global_load_lds_dwordx4 v[222:223], off
	v_lshl_add_u64 v[222:223], s[58:59], 0, v[128:129]
	s_mov_b32 m0, s63
	s_nop 0
	global_load_lds_dwordx4 v[222:223], off
	s_mov_b32 m0, s64
	s_nop 0
	global_load_lds_dwordx4 v[224:225], off
	s_waitcnt vmcnt(8)
	s_waitcnt lgkmcnt(0)
	s_barrier
	s_setprio 1
	s_waitcnt lgkmcnt(0)
	v_mfma_f32_16x16x32_bf16 v[60:63], v[152:155], v[188:191], v[60:63]
	v_mfma_f32_16x16x32_bf16 v[60:63], v[156:159], v[192:195], v[60:63]
	v_mfma_f32_16x16x32_bf16 v[56:59], v[160:163], v[188:191], v[56:59]
	v_mfma_f32_16x16x32_bf16 v[56:59], v[164:167], v[192:195], v[56:59]
	v_mfma_f32_16x16x32_bf16 v[52:55], v[152:155], v[196:199], v[52:55]
	v_mfma_f32_16x16x32_bf16 v[52:55], v[156:159], v[200:203], v[52:55]
	v_mfma_f32_16x16x32_bf16 v[44:47], v[160:163], v[196:199], v[44:47]
	v_mfma_f32_16x16x32_bf16 v[44:47], v[164:167], v[200:203], v[44:47]
	v_mfma_f32_16x16x32_bf16 v[36:39], v[152:155], v[204:207], v[36:39]
	v_mfma_f32_16x16x32_bf16 v[36:39], v[156:159], v[208:211], v[36:39]
	v_mfma_f32_16x16x32_bf16 v[28:31], v[160:163], v[204:207], v[28:31]
	v_mfma_f32_16x16x32_bf16 v[28:31], v[164:167], v[208:211], v[28:31]
	v_mfma_f32_16x16x32_bf16 v[20:23], v[152:155], v[212:215], v[20:23]
	v_mfma_f32_16x16x32_bf16 v[20:23], v[156:159], v[216:219], v[20:23]
	v_mfma_f32_16x16x32_bf16 v[12:15], v[160:163], v[212:215], v[12:15]
	v_mfma_f32_16x16x32_bf16 v[12:15], v[164:167], v[216:219], v[12:15]
	s_setprio 0
	s_setprio 1
	v_mfma_f32_16x16x32_bf16 v[48:51], v[168:171], v[188:191], v[48:51]
	v_mfma_f32_16x16x32_bf16 v[48:51], v[172:175], v[192:195], v[48:51]
	v_mfma_f32_16x16x32_bf16 v[40:43], v[176:179], v[188:191], v[40:43]
	v_mfma_f32_16x16x32_bf16 v[40:43], v[184:187], v[192:195], v[40:43]
	v_mfma_f32_16x16x32_bf16 v[32:35], v[168:171], v[196:199], v[32:35]
	v_mfma_f32_16x16x32_bf16 v[32:35], v[172:175], v[200:203], v[32:35]
	v_mfma_f32_16x16x32_bf16 v[24:27], v[176:179], v[196:199], v[24:27]
	v_mfma_f32_16x16x32_bf16 v[24:27], v[184:187], v[200:203], v[24:27]
	v_mfma_f32_16x16x32_bf16 v[16:19], v[168:171], v[204:207], v[16:19]
	v_mfma_f32_16x16x32_bf16 v[16:19], v[172:175], v[208:211], v[16:19]
	v_mfma_f32_16x16x32_bf16 v[8:11], v[176:179], v[204:207], v[8:11]
	v_mfma_f32_16x16x32_bf16 v[8:11], v[184:187], v[208:211], v[8:11]
	v_mfma_f32_16x16x32_bf16 v[4:7], v[168:171], v[212:215], v[4:7]
	v_mfma_f32_16x16x32_bf16 v[4:7], v[172:175], v[216:219], v[4:7]
	s_barrier
	v_mfma_f32_16x16x32_bf16 v[0:3], v[176:179], v[212:215], v[0:3]
	v_mfma_f32_16x16x32_bf16 v[0:3], v[184:187], v[216:219], v[0:3]
	s_setprio 0
.Lmid_gemm1:
	s_add_i32 s18, 0, 0x18000
	s_add_i32 s19, 0, 0x1c000
	v_add_u32_e32 v164, s18, v147
	v_add_u32_e32 v181, s19, v147
	ds_read_b128 v[152:155], v164
	ds_read_b128 v[156:159], v164 offset:1024
	ds_read_b128 v[160:163], v164 offset:2048
	ds_read_b128 v[164:167], v164 offset:3072
	ds_read_b128 v[168:171], v181
	ds_read_b128 v[172:175], v181 offset:1024
	ds_read_b128 v[176:179], v181 offset:2048
	ds_read_b128 v[184:187], v181 offset:3072
	s_add_u32 s52, s58, 0xb0000
	s_addc_u32 s53, s59, 0
	s_mov_b32 m0, s65
	v_lshl_add_u64 v[226:227], s[52:53], 0, v[128:129]
	ds_read_b128 v[188:191], v151 offset:32768
	ds_read_b128 v[192:195], v151 offset:33792
	ds_read_b128 v[196:199], v151 offset:34816
	ds_read_b128 v[200:203], v151 offset:35840
	ds_read_b128 v[204:207], v151 offset:36864
	ds_read_b128 v[208:211], v151 offset:37888
	ds_read_b128 v[212:215], v151 offset:38912
	ds_read_b128 v[216:219], v151 offset:39936
	global_load_lds_dwordx4 v[226:227], off
	v_lshl_add_u64 v[226:227], s[52:53], 0, v[132:133]
	s_mov_b32 m0, s66
	s_nop 0
	global_load_lds_dwordx4 v[226:227], off
	s_waitcnt vmcnt(8)
	s_waitcnt lgkmcnt(0)
	s_barrier
	s_setprio 1
	s_waitcnt lgkmcnt(0)
	v_mfma_f32_16x16x32_bf16 v[124:127], v[152:155], v[188:191], v[124:127]
	v_mfma_f32_16x16x32_bf16 v[124:127], v[156:159], v[192:195], v[124:127]
	v_mfma_f32_16x16x32_bf16 v[120:123], v[160:163], v[188:191], v[120:123]
	v_mfma_f32_16x16x32_bf16 v[120:123], v[164:167], v[192:195], v[120:123]
	v_mfma_f32_16x16x32_bf16 v[116:119], v[152:155], v[196:199], v[116:119]
	v_mfma_f32_16x16x32_bf16 v[116:119], v[156:159], v[200:203], v[116:119]
	v_mfma_f32_16x16x32_bf16 v[108:111], v[160:163], v[196:199], v[108:111]
	v_mfma_f32_16x16x32_bf16 v[108:111], v[164:167], v[200:203], v[108:111]
	v_mfma_f32_16x16x32_bf16 v[100:103], v[152:155], v[204:207], v[100:103]
	v_mfma_f32_16x16x32_bf16 v[100:103], v[156:159], v[208:211], v[100:103]
	v_mfma_f32_16x16x32_bf16 v[92:95], v[160:163], v[204:207], v[92:95]
	v_mfma_f32_16x16x32_bf16 v[92:95], v[164:167], v[208:211], v[92:95]
	v_mfma_f32_16x16x32_bf16 v[84:87], v[152:155], v[212:215], v[84:87]
	v_mfma_f32_16x16x32_bf16 v[84:87], v[156:159], v[216:219], v[84:87]
	v_mfma_f32_16x16x32_bf16 v[76:79], v[160:163], v[212:215], v[76:79]
	v_mfma_f32_16x16x32_bf16 v[76:79], v[164:167], v[216:219], v[76:79]
	s_setprio 0
	s_setprio 1
	v_mfma_f32_16x16x32_bf16 v[112:115], v[168:171], v[188:191], v[112:115]
	v_mfma_f32_16x16x32_bf16 v[112:115], v[172:175], v[192:195], v[112:115]
	v_mfma_f32_16x16x32_bf16 v[104:107], v[176:179], v[188:191], v[104:107]
	v_mfma_f32_16x16x32_bf16 v[104:107], v[184:187], v[192:195], v[104:107]
	v_mfma_f32_16x16x32_bf16 v[96:99], v[168:171], v[196:199], v[96:99]
	v_mfma_f32_16x16x32_bf16 v[96:99], v[172:175], v[200:203], v[96:99]
	v_mfma_f32_16x16x32_bf16 v[88:91], v[176:179], v[196:199], v[88:91]
	v_mfma_f32_16x16x32_bf16 v[88:91], v[184:187], v[200:203], v[88:91]
	v_mfma_f32_16x16x32_bf16 v[80:83], v[168:171], v[204:207], v[80:83]
	v_mfma_f32_16x16x32_bf16 v[80:83], v[172:175], v[208:211], v[80:83]
	v_mfma_f32_16x16x32_bf16 v[72:75], v[176:179], v[204:207], v[72:75]
	v_mfma_f32_16x16x32_bf16 v[72:75], v[184:187], v[208:211], v[72:75]
	v_mfma_f32_16x16x32_bf16 v[68:71], v[168:171], v[212:215], v[68:71]
	v_mfma_f32_16x16x32_bf16 v[68:71], v[172:175], v[216:219], v[68:71]
	s_barrier
	v_mfma_f32_16x16x32_bf16 v[64:67], v[176:179], v[212:215], v[64:67]
	v_mfma_f32_16x16x32_bf16 v[64:67], v[184:187], v[216:219], v[64:67]
	s_setprio 0
	s_add_i32 s18, s18, s62
	v_lshl_add_u64 v[144:145], v[144:145], 0, s[8:9]
	s_mov_b32 m0, s18
	ds_read_b128 v[188:191], v151 offset:49152
	ds_read_b128 v[192:195], v151 offset:50176
	ds_read_b128 v[196:199], v151 offset:51200
	ds_read_b128 v[200:203], v151 offset:52224
	ds_read_b128 v[204:207], v151 offset:53248
	ds_read_b128 v[208:211], v151 offset:54272
	ds_read_b128 v[212:215], v151 offset:55296
	ds_read_b128 v[216:219], v151 offset:56320
	global_load_lds_dwordx4 v[144:145], off
	s_add_i32 m0, s18, 0x2000
	s_add_u32 s52, s56, 0xb0080
	v_lshl_add_u64 v[144:145], v[220:221], 0, s[8:9]
	s_addc_u32 s53, s57, 0
	s_add_i32 s18, s19, s62
	global_load_lds_dwordx4 v[144:145], off
	v_lshl_add_u64 v[144:145], s[52:53], 0, v[130:131]
	s_mov_b32 m0, s18
	s_nop 0
	global_load_lds_dwordx4 v[144:145], off
	v_lshl_add_u64 v[144:145], s[52:53], 0, v[134:135]
	s_add_i32 m0, s18, 0x2000
	s_nop 0
	global_load_lds_dwordx4 v[144:145], off
	v_lshl_add_u64 v[144:145], v[222:223], 0, s[8:9]
	s_mov_b32 m0, s68
	s_nop 0
	global_load_lds_dwordx4 v[144:145], off
	v_lshl_add_u64 v[144:145], v[224:225], 0, s[8:9]
	s_mov_b32 m0, s69
	s_nop 0
	global_load_lds_dwordx4 v[144:145], off
	s_waitcnt vmcnt(8)
	s_waitcnt lgkmcnt(0)
	s_barrier
	s_setprio 1
	s_waitcnt lgkmcnt(0)
	v_mfma_f32_16x16x32_bf16 v[60:63], v[152:155], v[188:191], v[60:63]
	v_mfma_f32_16x16x32_bf16 v[60:63], v[156:159], v[192:195], v[60:63]
	v_mfma_f32_16x16x32_bf16 v[56:59], v[160:163], v[188:191], v[56:59]
	v_mfma_f32_16x16x32_bf16 v[56:59], v[164:167], v[192:195], v[56:59]
	v_mfma_f32_16x16x32_bf16 v[52:55], v[152:155], v[196:199], v[52:55]
	v_mfma_f32_16x16x32_bf16 v[52:55], v[156:159], v[200:203], v[52:55]
	v_mfma_f32_16x16x32_bf16 v[44:47], v[160:163], v[196:199], v[44:47]
	v_mfma_f32_16x16x32_bf16 v[44:47], v[164:167], v[200:203], v[44:47]
	v_mfma_f32_16x16x32_bf16 v[36:39], v[152:155], v[204:207], v[36:39]
	v_mfma_f32_16x16x32_bf16 v[36:39], v[156:159], v[208:211], v[36:39]
	v_mfma_f32_16x16x32_bf16 v[28:31], v[160:163], v[204:207], v[28:31]
	v_mfma_f32_16x16x32_bf16 v[28:31], v[164:167], v[208:211], v[28:31]
	v_mfma_f32_16x16x32_bf16 v[20:23], v[152:155], v[212:215], v[20:23]
	v_mfma_f32_16x16x32_bf16 v[20:23], v[156:159], v[216:219], v[20:23]
	v_mfma_f32_16x16x32_bf16 v[12:15], v[160:163], v[212:215], v[12:15]
	v_mfma_f32_16x16x32_bf16 v[12:15], v[164:167], v[216:219], v[12:15]
	s_setprio 0
	s_setprio 1
	v_mfma_f32_16x16x32_bf16 v[48:51], v[168:171], v[188:191], v[48:51]
	v_mfma_f32_16x16x32_bf16 v[48:51], v[172:175], v[192:195], v[48:51]
	v_mfma_f32_16x16x32_bf16 v[40:43], v[176:179], v[188:191], v[40:43]
	v_mfma_f32_16x16x32_bf16 v[40:43], v[184:187], v[192:195], v[40:43]
	v_mfma_f32_16x16x32_bf16 v[32:35], v[168:171], v[196:199], v[32:35]
	v_mfma_f32_16x16x32_bf16 v[32:35], v[172:175], v[200:203], v[32:35]
	v_mfma_f32_16x16x32_bf16 v[24:27], v[176:179], v[196:199], v[24:27]
	v_mfma_f32_16x16x32_bf16 v[24:27], v[184:187], v[200:203], v[24:27]
	v_mfma_f32_16x16x32_bf16 v[16:19], v[168:171], v[204:207], v[16:19]
	v_mfma_f32_16x16x32_bf16 v[16:19], v[172:175], v[208:211], v[16:19]
	v_mfma_f32_16x16x32_bf16 v[8:11], v[176:179], v[204:207], v[8:11]
	v_mfma_f32_16x16x32_bf16 v[8:11], v[184:187], v[208:211], v[8:11]
	v_mfma_f32_16x16x32_bf16 v[4:7], v[168:171], v[212:215], v[4:7]
	v_mfma_f32_16x16x32_bf16 v[4:7], v[172:175], v[216:219], v[4:7]
	s_barrier
	v_mfma_f32_16x16x32_bf16 v[0:3], v[176:179], v[212:215], v[0:3]
	v_mfma_f32_16x16x32_bf16 v[0:3], v[184:187], v[216:219], v[0:3]
	s_setprio 0
	s_add_i32 s86, s86, 2
	s_add_u32 s84, s84, 0x100
	s_addc_u32 s85, s85, 0
	s_cmp_gt_u32 s86, 41
	s_mov_b64 s[52:53], s[54:55]
	s_cbranch_scc0 .LBB0_264
	s_and_b64 vcc, exec, s[10:11]
	s_cbranch_vccz .LBB0_267
	s_barrier

.LBB0_386:
	s_ashr_i32 s49, s48, 31
	s_lshl_b64 s[52:53], s[48:49], 19
	s_add_u32 s52, s80, s52
	s_addc_u32 s53, s81, s53
	s_and_b64 s[54:55], s[4:5], exec
	s_cselect_b32 s49, s53, s59
	s_cselect_b32 s82, s52, s58
	s_ashr_i32 s47, s46, 31
	s_lshl_b64 s[54:55], s[46:47], 19
	s_add_u32 s54, s64, s54
	s_addc_u32 s55, s65, s55
	s_and_b64 s[62:63], s[4:5], exec
	s_cselect_b32 s47, s55, s61
	s_cselect_b32 s83, s54, s60
	s_add_u32 s58, s58, 0x40080
	s_addc_u32 s59, s59, 0
	s_add_u32 s84, s60, 0x100
	s_addc_u32 s85, s61, 0
	s_mov_b32 s86, -2
	ds_read_b128 v[152:155], v148
	ds_read_b128 v[156:159], v148 offset:1024
	ds_read_b128 v[160:163], v148 offset:2048
	ds_read_b128 v[164:167], v148 offset:3072
	ds_read_b128 v[168:171], v149
	ds_read_b128 v[172:175], v149 offset:1024
	ds_read_b128 v[176:179], v149 offset:2048
	ds_read_b128 v[184:187], v149 offset:3072
	s_add_u32 s18, s58, 0xfffc0080
	s_addc_u32 s19, s59, -1
	s_cmp_eq_u32 s86, 12
	s_cselect_b32 s63, s49, s19
	s_cselect_b32 s62, s82, s18
	s_cselect_b32 s61, s47, s85
	s_cselect_b32 s60, s83, s84
	v_lshl_add_u64 v[220:221], s[58:59], 0, v[138:139]
	s_add_i32 m0, s68, 0xc000
	ds_read_b128 v[188:191], v150
	ds_read_b128 v[192:195], v150 offset:1024
	ds_read_b128 v[196:199], v150 offset:2048
	ds_read_b128 v[200:203], v150 offset:3072
	ds_read_b128 v[204:207], v150 offset:4096
	ds_read_b128 v[208:211], v150 offset:5120
	ds_read_b128 v[212:215], v150 offset:6144
	ds_read_b128 v[216:219], v150 offset:7168
	global_load_lds_dwordx4 v[220:221], off
	v_lshl_add_u64 v[220:221], s[58:59], 0, v[140:141]
	s_add_i32 m0, s68, 0xe000
	s_nop 0
	global_load_lds_dwordx4 v[220:221], off
	s_waitcnt vmcnt(8)
	s_waitcnt lgkmcnt(0)
	s_barrier
	s_setprio 1
	s_waitcnt lgkmcnt(0)
	v_mfma_f32_16x16x32_bf16 v[124:127], v[152:155], v[188:191], 0
	v_mfma_f32_16x16x32_bf16 v[124:127], v[156:159], v[192:195], v[124:127]
	v_mfma_f32_16x16x32_bf16 v[120:123], v[160:163], v[188:191], 0
	v_mfma_f32_16x16x32_bf16 v[120:123], v[164:167], v[192:195], v[120:123]
	v_mfma_f32_16x16x32_bf16 v[116:119], v[152:155], v[196:199], 0
	v_mfma_f32_16x16x32_bf16 v[116:119], v[156:159], v[200:203], v[116:119]
	v_mfma_f32_16x16x32_bf16 v[112:115], v[160:163], v[196:199], 0
	v_mfma_f32_16x16x32_bf16 v[112:115], v[164:167], v[200:203], v[112:115]
	v_mfma_f32_16x16x32_bf16 v[108:111], v[152:155], v[204:207], 0
	v_mfma_f32_16x16x32_bf16 v[108:111], v[156:159], v[208:211], v[108:111]
	v_mfma_f32_16x16x32_bf16 v[104:107], v[160:163], v[204:207], 0
	v_mfma_f32_16x16x32_bf16 v[104:107], v[164:167], v[208:211], v[104:107]
	v_mfma_f32_16x16x32_bf16 v[100:103], v[152:155], v[212:215], 0
	v_mfma_f32_16x16x32_bf16 v[100:103], v[156:159], v[216:219], v[100:103]
	v_mfma_f32_16x16x32_bf16 v[96:99], v[160:163], v[212:215], 0
	v_mfma_f32_16x16x32_bf16 v[96:99], v[164:167], v[216:219], v[96:99]
	s_setprio 0
	s_setprio 1
	v_mfma_f32_16x16x32_bf16 v[68:71], v[168:171], v[188:191], 0
	v_mfma_f32_16x16x32_bf16 v[68:71], v[172:175], v[192:195], v[68:71]
	v_mfma_f32_16x16x32_bf16 v[64:67], v[176:179], v[188:191], 0
	v_mfma_f32_16x16x32_bf16 v[64:67], v[184:187], v[192:195], v[64:67]
	v_mfma_f32_16x16x32_bf16 v[52:55], v[168:171], v[196:199], 0
	v_mfma_f32_16x16x32_bf16 v[52:55], v[172:175], v[200:203], v[52:55]
	v_mfma_f32_16x16x32_bf16 v[48:51], v[176:179], v[196:199], 0
	v_mfma_f32_16x16x32_bf16 v[48:51], v[184:187], v[200:203], v[48:51]
	v_mfma_f32_16x16x32_bf16 v[44:47], v[168:171], v[204:207], 0
	v_mfma_f32_16x16x32_bf16 v[44:47], v[172:175], v[208:211], v[44:47]
	v_mfma_f32_16x16x32_bf16 v[40:43], v[176:179], v[204:207], 0
	v_mfma_f32_16x16x32_bf16 v[40:43], v[184:187], v[208:211], v[40:43]
	v_mfma_f32_16x16x32_bf16 v[36:39], v[168:171], v[212:215], 0
	v_mfma_f32_16x16x32_bf16 v[36:39], v[172:175], v[216:219], v[36:39]
	s_barrier
	v_mfma_f32_16x16x32_bf16 v[32:35], v[176:179], v[212:215], 0
	v_mfma_f32_16x16x32_bf16 v[32:35], v[184:187], v[216:219], v[32:35]
	s_setprio 0
	s_add_i32 s18, s76, s66
	v_lshl_add_u64 v[220:221], s[60:61], 0, v[132:133]
	s_mov_b32 m0, s18
	ds_read_b128 v[188:191], v150 offset:16384
	ds_read_b128 v[192:195], v150 offset:17408
	ds_read_b128 v[196:199], v150 offset:18432
	ds_read_b128 v[200:203], v150 offset:19456
	ds_read_b128 v[204:207], v150 offset:20480
	ds_read_b128 v[208:211], v150 offset:21504
	ds_read_b128 v[212:215], v150 offset:22528
	ds_read_b128 v[216:219], v150 offset:23552
	global_load_lds_dwordx4 v[220:221], off
	s_add_i32 m0, s18, 0x2000
	s_add_u32 s88, s60, 0x40000
	v_lshl_add_u64 v[222:223], s[60:61], 0, v[128:129]
	s_addc_u32 s89, s61, 0
	s_add_i32 s18, s77, s66
	global_load_lds_dwordx4 v[222:223], off
	v_lshl_add_u64 v[224:225], s[88:89], 0, v[132:133]
	s_mov_b32 m0, s18
	v_lshl_add_u64 v[226:227], s[62:63], 0, v[130:131]
	global_load_lds_dwordx4 v[224:225], off
	v_lshl_add_u64 v[224:225], s[88:89], 0, v[128:129]
	s_add_i32 m0, s18, 0x2000
	s_nop 0
	global_load_lds_dwordx4 v[224:225], off
	v_lshl_add_u64 v[224:225], s[62:63], 0, v[134:135]
	s_mov_b32 m0, s68
	s_nop 0
	global_load_lds_dwordx4 v[224:225], off
	s_mov_b32 m0, s69
	s_nop 0
	global_load_lds_dwordx4 v[226:227], off
	s_waitcnt vmcnt(8)
	s_waitcnt lgkmcnt(0)
	s_barrier
	s_setprio 1
	s_waitcnt lgkmcnt(0)
	v_mfma_f32_16x16x32_bf16 v[92:95], v[152:155], v[188:191], 0
	v_mfma_f32_16x16x32_bf16 v[92:95], v[156:159], v[192:195], v[92:95]
	v_mfma_f32_16x16x32_bf16 v[88:91], v[160:163], v[188:191], 0
	v_mfma_f32_16x16x32_bf16 v[88:91], v[164:167], v[192:195], v[88:91]
	v_mfma_f32_16x16x32_bf16 v[84:87], v[152:155], v[196:199], 0
	v_mfma_f32_16x16x32_bf16 v[84:87], v[156:159], v[200:203], v[84:87]
	v_mfma_f32_16x16x32_bf16 v[80:83], v[160:163], v[196:199], 0
	v_mfma_f32_16x16x32_bf16 v[80:83], v[164:167], v[200:203], v[80:83]
	v_mfma_f32_16x16x32_bf16 v[76:79], v[152:155], v[204:207], 0
	v_mfma_f32_16x16x32_bf16 v[76:79], v[156:159], v[208:211], v[76:79]
	v_mfma_f32_16x16x32_bf16 v[72:75], v[160:163], v[204:207], 0
	v_mfma_f32_16x16x32_bf16 v[72:75], v[164:167], v[208:211], v[72:75]
	v_mfma_f32_16x16x32_bf16 v[60:63], v[152:155], v[212:215], 0
	v_mfma_f32_16x16x32_bf16 v[60:63], v[156:159], v[216:219], v[60:63]
	v_mfma_f32_16x16x32_bf16 v[56:59], v[160:163], v[212:215], 0
	v_mfma_f32_16x16x32_bf16 v[56:59], v[164:167], v[216:219], v[56:59]
	s_setprio 0
	s_setprio 1
	v_mfma_f32_16x16x32_bf16 v[28:31], v[168:171], v[188:191], 0
	v_mfma_f32_16x16x32_bf16 v[28:31], v[172:175], v[192:195], v[28:31]
	v_mfma_f32_16x16x32_bf16 v[24:27], v[176:179], v[188:191], 0
	v_mfma_f32_16x16x32_bf16 v[24:27], v[184:187], v[192:195], v[24:27]
	v_mfma_f32_16x16x32_bf16 v[20:23], v[168:171], v[196:199], 0
	v_mfma_f32_16x16x32_bf16 v[20:23], v[172:175], v[200:203], v[20:23]
	v_mfma_f32_16x16x32_bf16 v[16:19], v[176:179], v[196:199], 0
	v_mfma_f32_16x16x32_bf16 v[16:19], v[184:187], v[200:203], v[16:19]
	v_mfma_f32_16x16x32_bf16 v[12:15], v[168:171], v[204:207], 0
	v_mfma_f32_16x16x32_bf16 v[12:15], v[172:175], v[208:211], v[12:15]
	v_mfma_f32_16x16x32_bf16 v[8:11], v[176:179], v[204:207], 0
	v_mfma_f32_16x16x32_bf16 v[8:11], v[184:187], v[208:211], v[8:11]
	v_mfma_f32_16x16x32_bf16 v[4:7], v[168:171], v[212:215], 0
	v_mfma_f32_16x16x32_bf16 v[4:7], v[172:175], v[216:219], v[4:7]
	s_barrier
	v_mfma_f32_16x16x32_bf16 v[0:3], v[176:179], v[212:215], 0
	v_mfma_f32_16x16x32_bf16 v[0:3], v[184:187], v[216:219], v[0:3]
	s_setprio 0
	s_branch .Lmid_gemm2
.LBB0_387:
	ds_read_b128 v[152:155], v148
	ds_read_b128 v[156:159], v148 offset:1024
	ds_read_b128 v[160:163], v148 offset:2048
	ds_read_b128 v[164:167], v148 offset:3072
	ds_read_b128 v[168:171], v149
	ds_read_b128 v[172:175], v149 offset:1024
	ds_read_b128 v[176:179], v149 offset:2048
	ds_read_b128 v[184:187], v149 offset:3072
	s_add_u32 s18, s58, 0xfffc0080
	s_addc_u32 s19, s59, -1
	s_cmp_eq_u32 s86, 12
	s_cselect_b32 s63, s49, s19
	s_cselect_b32 s62, s82, s18
	s_cselect_b32 s61, s47, s85
	s_cselect_b32 s60, s83, s84
	v_lshl_add_u64 v[220:221], s[58:59], 0, v[138:139]
	s_add_i32 m0, s68, 0xc000
	ds_read_b128 v[188:191], v150
	ds_read_b128 v[192:195], v150 offset:1024
	ds_read_b128 v[196:199], v150 offset:2048
	ds_read_b128 v[200:203], v150 offset:3072
	ds_read_b128 v[204:207], v150 offset:4096
	ds_read_b128 v[208:211], v150 offset:5120
	ds_read_b128 v[212:215], v150 offset:6144
	ds_read_b128 v[216:219], v150 offset:7168
	global_load_lds_dwordx4 v[220:221], off
	v_lshl_add_u64 v[220:221], s[58:59], 0, v[140:141]
	s_add_i32 m0, s68, 0xe000
	s_nop 0
	global_load_lds_dwordx4 v[220:221], off
	s_waitcnt vmcnt(8)
	s_waitcnt lgkmcnt(0)
	s_barrier
	s_setprio 1
	s_waitcnt lgkmcnt(0)
	v_mfma_f32_16x16x32_bf16 v[124:127], v[152:155], v[188:191], v[124:127]
	v_mfma_f32_16x16x32_bf16 v[124:127], v[156:159], v[192:195], v[124:127]
	v_mfma_f32_16x16x32_bf16 v[120:123], v[160:163], v[188:191], v[120:123]
	v_mfma_f32_16x16x32_bf16 v[120:123], v[164:167], v[192:195], v[120:123]
	v_mfma_f32_16x16x32_bf16 v[116:119], v[152:155], v[196:199], v[116:119]
	v_mfma_f32_16x16x32_bf16 v[116:119], v[156:159], v[200:203], v[116:119]
	v_mfma_f32_16x16x32_bf16 v[112:115], v[160:163], v[196:199], v[112:115]
	v_mfma_f32_16x16x32_bf16 v[112:115], v[164:167], v[200:203], v[112:115]
	v_mfma_f32_16x16x32_bf16 v[108:111], v[152:155], v[204:207], v[108:111]
	v_mfma_f32_16x16x32_bf16 v[108:111], v[156:159], v[208:211], v[108:111]
	v_mfma_f32_16x16x32_bf16 v[104:107], v[160:163], v[204:207], v[104:107]
	v_mfma_f32_16x16x32_bf16 v[104:107], v[164:167], v[208:211], v[104:107]
	v_mfma_f32_16x16x32_bf16 v[100:103], v[152:155], v[212:215], v[100:103]
	v_mfma_f32_16x16x32_bf16 v[100:103], v[156:159], v[216:219], v[100:103]
	v_mfma_f32_16x16x32_bf16 v[96:99], v[160:163], v[212:215], v[96:99]
	v_mfma_f32_16x16x32_bf16 v[96:99], v[164:167], v[216:219], v[96:99]
	s_setprio 0
	s_setprio 1
	v_mfma_f32_16x16x32_bf16 v[68:71], v[168:171], v[188:191], v[68:71]
	v_mfma_f32_16x16x32_bf16 v[68:71], v[172:175], v[192:195], v[68:71]
	v_mfma_f32_16x16x32_bf16 v[64:67], v[176:179], v[188:191], v[64:67]
	v_mfma_f32_16x16x32_bf16 v[64:67], v[184:187], v[192:195], v[64:67]
	v_mfma_f32_16x16x32_bf16 v[52:55], v[168:171], v[196:199], v[52:55]
	v_mfma_f32_16x16x32_bf16 v[52:55], v[172:175], v[200:203], v[52:55]
	v_mfma_f32_16x16x32_bf16 v[48:51], v[176:179], v[196:199], v[48:51]
	v_mfma_f32_16x16x32_bf16 v[48:51], v[184:187], v[200:203], v[48:51]
	v_mfma_f32_16x16x32_bf16 v[44:47], v[168:171], v[204:207], v[44:47]
	v_mfma_f32_16x16x32_bf16 v[44:47], v[172:175], v[208:211], v[44:47]
	v_mfma_f32_16x16x32_bf16 v[40:43], v[176:179], v[204:207], v[40:43]
	v_mfma_f32_16x16x32_bf16 v[40:43], v[184:187], v[208:211], v[40:43]
	v_mfma_f32_16x16x32_bf16 v[36:39], v[168:171], v[212:215], v[36:39]
	v_mfma_f32_16x16x32_bf16 v[36:39], v[172:175], v[216:219], v[36:39]
	s_barrier
	v_mfma_f32_16x16x32_bf16 v[32:35], v[176:179], v[212:215], v[32:35]
	v_mfma_f32_16x16x32_bf16 v[32:35], v[184:187], v[216:219], v[32:35]
	s_setprio 0
	s_add_i32 s18, s76, s66
	v_lshl_add_u64 v[220:221], s[60:61], 0, v[132:133]
	s_mov_b32 m0, s18
	ds_read_b128 v[188:191], v150 offset:16384
	ds_read_b128 v[192:195], v150 offset:17408
	ds_read_b128 v[196:199], v150 offset:18432
	ds_read_b128 v[200:203], v150 offset:19456
	ds_read_b128 v[204:207], v150 offset:20480
	ds_read_b128 v[208:211], v150 offset:21504
	ds_read_b128 v[212:215], v150 offset:22528
	ds_read_b128 v[216:219], v150 offset:23552
	global_load_lds_dwordx4 v[220:221], off
	s_add_i32 m0, s18, 0x2000
	s_add_u32 s88, s60, 0x40000
	v_lshl_add_u64 v[222:223], s[60:61], 0, v[128:129]
	s_addc_u32 s89, s61, 0
	s_add_i32 s18, s77, s66
	global_load_lds_dwordx4 v[222:223], off
	v_lshl_add_u64 v[224:225], s[88:89], 0, v[132:133]
	s_mov_b32 m0, s18
	v_lshl_add_u64 v[226:227], s[62:63], 0, v[130:131]
	global_load_lds_dwordx4 v[224:225], off
	v_lshl_add_u64 v[224:225], s[88:89], 0, v[128:129]
	s_add_i32 m0, s18, 0x2000
	s_nop 0
	global_load_lds_dwordx4 v[224:225], off
	v_lshl_add_u64 v[224:225], s[62:63], 0, v[134:135]
	s_mov_b32 m0, s68
	s_nop 0
	global_load_lds_dwordx4 v[224:225], off
	s_mov_b32 m0, s69
	s_nop 0
	global_load_lds_dwordx4 v[226:227], off
	s_waitcnt vmcnt(8)
	s_waitcnt lgkmcnt(0)
	s_barrier
	s_setprio 1
	s_waitcnt lgkmcnt(0)
	v_mfma_f32_16x16x32_bf16 v[92:95], v[152:155], v[188:191], v[92:95]
	v_mfma_f32_16x16x32_bf16 v[92:95], v[156:159], v[192:195], v[92:95]
	v_mfma_f32_16x16x32_bf16 v[88:91], v[160:163], v[188:191], v[88:91]
	v_mfma_f32_16x16x32_bf16 v[88:91], v[164:167], v[192:195], v[88:91]
	v_mfma_f32_16x16x32_bf16 v[84:87], v[152:155], v[196:199], v[84:87]
	v_mfma_f32_16x16x32_bf16 v[84:87], v[156:159], v[200:203], v[84:87]
	v_mfma_f32_16x16x32_bf16 v[80:83], v[160:163], v[196:199], v[80:83]
	v_mfma_f32_16x16x32_bf16 v[80:83], v[164:167], v[200:203], v[80:83]
	v_mfma_f32_16x16x32_bf16 v[76:79], v[152:155], v[204:207], v[76:79]
	v_mfma_f32_16x16x32_bf16 v[76:79], v[156:159], v[208:211], v[76:79]
	v_mfma_f32_16x16x32_bf16 v[72:75], v[160:163], v[204:207], v[72:75]
	v_mfma_f32_16x16x32_bf16 v[72:75], v[164:167], v[208:211], v[72:75]
	v_mfma_f32_16x16x32_bf16 v[60:63], v[152:155], v[212:215], v[60:63]
	v_mfma_f32_16x16x32_bf16 v[60:63], v[156:159], v[216:219], v[60:63]
	v_mfma_f32_16x16x32_bf16 v[56:59], v[160:163], v[212:215], v[56:59]
	v_mfma_f32_16x16x32_bf16 v[56:59], v[164:167], v[216:219], v[56:59]
	s_setprio 0
	s_setprio 1
	v_mfma_f32_16x16x32_bf16 v[28:31], v[168:171], v[188:191], v[28:31]
	v_mfma_f32_16x16x32_bf16 v[28:31], v[172:175], v[192:195], v[28:31]
	v_mfma_f32_16x16x32_bf16 v[24:27], v[176:179], v[188:191], v[24:27]
	v_mfma_f32_16x16x32_bf16 v[24:27], v[184:187], v[192:195], v[24:27]
	v_mfma_f32_16x16x32_bf16 v[20:23], v[168:171], v[196:199], v[20:23]
	v_mfma_f32_16x16x32_bf16 v[20:23], v[172:175], v[200:203], v[20:23]
	v_mfma_f32_16x16x32_bf16 v[16:19], v[176:179], v[196:199], v[16:19]
	v_mfma_f32_16x16x32_bf16 v[16:19], v[184:187], v[200:203], v[16:19]
	v_mfma_f32_16x16x32_bf16 v[12:15], v[168:171], v[204:207], v[12:15]
	v_mfma_f32_16x16x32_bf16 v[12:15], v[172:175], v[208:211], v[12:15]
	v_mfma_f32_16x16x32_bf16 v[8:11], v[176:179], v[204:207], v[8:11]
	v_mfma_f32_16x16x32_bf16 v[8:11], v[184:187], v[208:211], v[8:11]
	v_mfma_f32_16x16x32_bf16 v[4:7], v[168:171], v[212:215], v[4:7]
	v_mfma_f32_16x16x32_bf16 v[4:7], v[172:175], v[216:219], v[4:7]
	s_barrier
	v_mfma_f32_16x16x32_bf16 v[0:3], v[176:179], v[212:215], v[0:3]
	v_mfma_f32_16x16x32_bf16 v[0:3], v[184:187], v[216:219], v[0:3]
	s_setprio 0
.Lmid_gemm2:
	s_add_i32 s18, 0, 0x18000
	s_add_i32 s19, 0, 0x1c000
	v_add_u32_e32 v164, s18, v147
	v_add_u32_e32 v181, s19, v147
	ds_read_b128 v[152:155], v164
	ds_read_b128 v[156:159], v164 offset:1024
	ds_read_b128 v[160:163], v164 offset:2048
	ds_read_b128 v[164:167], v164 offset:3072
	ds_read_b128 v[168:171], v181
	ds_read_b128 v[172:175], v181 offset:1024
	ds_read_b128 v[176:179], v181 offset:2048
	ds_read_b128 v[184:187], v181 offset:3072
	s_add_u32 s62, s62, 0x40000
	s_addc_u32 s63, s63, 0
	s_mov_b32 m0, s70
	v_lshl_add_u64 v[228:229], s[62:63], 0, v[134:135]
	ds_read_b128 v[188:191], v150 offset:32768
	ds_read_b128 v[192:195], v150 offset:33792
	ds_read_b128 v[196:199], v150 offset:34816
	ds_read_b128 v[200:203], v150 offset:35840
	ds_read_b128 v[204:207], v150 offset:36864
	ds_read_b128 v[208:211], v150 offset:37888
	ds_read_b128 v[212:215], v150 offset:38912
	ds_read_b128 v[216:219], v150 offset:39936
	global_load_lds_dwordx4 v[228:229], off
	v_lshl_add_u64 v[228:229], s[62:63], 0, v[130:131]
	s_mov_b32 m0, s71
	s_nop 0
	global_load_lds_dwordx4 v[228:229], off
	s_waitcnt vmcnt(8)
	s_waitcnt lgkmcnt(0)
	s_barrier
	s_setprio 1
	s_waitcnt lgkmcnt(0)
	v_mfma_f32_16x16x32_bf16 v[124:127], v[152:155], v[188:191], v[124:127]
	v_mfma_f32_16x16x32_bf16 v[124:127], v[156:159], v[192:195], v[124:127]
	v_mfma_f32_16x16x32_bf16 v[120:123], v[160:163], v[188:191], v[120:123]
	v_mfma_f32_16x16x32_bf16 v[120:123], v[164:167], v[192:195], v[120:123]
	v_mfma_f32_16x16x32_bf16 v[116:119], v[152:155], v[196:199], v[116:119]
	v_mfma_f32_16x16x32_bf16 v[116:119], v[156:159], v[200:203], v[116:119]
	v_mfma_f32_16x16x32_bf16 v[112:115], v[160:163], v[196:199], v[112:115]
	v_mfma_f32_16x16x32_bf16 v[112:115], v[164:167], v[200:203], v[112:115]
	v_mfma_f32_16x16x32_bf16 v[108:111], v[152:155], v[204:207], v[108:111]
	v_mfma_f32_16x16x32_bf16 v[108:111], v[156:159], v[208:211], v[108:111]
	v_mfma_f32_16x16x32_bf16 v[104:107], v[160:163], v[204:207], v[104:107]
	v_mfma_f32_16x16x32_bf16 v[104:107], v[164:167], v[208:211], v[104:107]
	v_mfma_f32_16x16x32_bf16 v[100:103], v[152:155], v[212:215], v[100:103]
	v_mfma_f32_16x16x32_bf16 v[100:103], v[156:159], v[216:219], v[100:103]
	v_mfma_f32_16x16x32_bf16 v[96:99], v[160:163], v[212:215], v[96:99]
	v_mfma_f32_16x16x32_bf16 v[96:99], v[164:167], v[216:219], v[96:99]
	s_setprio 0
	s_setprio 1
	v_mfma_f32_16x16x32_bf16 v[68:71], v[168:171], v[188:191], v[68:71]
	v_mfma_f32_16x16x32_bf16 v[68:71], v[172:175], v[192:195], v[68:71]
	v_mfma_f32_16x16x32_bf16 v[64:67], v[176:179], v[188:191], v[64:67]
	v_mfma_f32_16x16x32_bf16 v[64:67], v[184:187], v[192:195], v[64:67]
	v_mfma_f32_16x16x32_bf16 v[52:55], v[168:171], v[196:199], v[52:55]
	v_mfma_f32_16x16x32_bf16 v[52:55], v[172:175], v[200:203], v[52:55]
	v_mfma_f32_16x16x32_bf16 v[48:51], v[176:179], v[196:199], v[48:51]
	v_mfma_f32_16x16x32_bf16 v[48:51], v[184:187], v[200:203], v[48:51]
	v_mfma_f32_16x16x32_bf16 v[44:47], v[168:171], v[204:207], v[44:47]
	v_mfma_f32_16x16x32_bf16 v[44:47], v[172:175], v[208:211], v[44:47]
	v_mfma_f32_16x16x32_bf16 v[40:43], v[176:179], v[204:207], v[40:43]
	v_mfma_f32_16x16x32_bf16 v[40:43], v[184:187], v[208:211], v[40:43]
	v_mfma_f32_16x16x32_bf16 v[36:39], v[168:171], v[212:215], v[36:39]
	v_mfma_f32_16x16x32_bf16 v[36:39], v[172:175], v[216:219], v[36:39]
	s_barrier
	v_mfma_f32_16x16x32_bf16 v[32:35], v[176:179], v[212:215], v[32:35]
	v_mfma_f32_16x16x32_bf16 v[32:35], v[184:187], v[216:219], v[32:35]
	s_setprio 0
	s_add_i32 s18, s18, s66
	v_lshl_add_u64 v[220:221], v[220:221], 0, s[6:7]
	s_mov_b32 m0, s18
	ds_read_b128 v[188:191], v150 offset:49152
	ds_read_b128 v[192:195], v150 offset:50176
	ds_read_b128 v[196:199], v150 offset:51200
	ds_read_b128 v[200:203], v150 offset:52224
	ds_read_b128 v[204:207], v150 offset:53248
	ds_read_b128 v[208:211], v150 offset:54272
	ds_read_b128 v[212:215], v150 offset:55296
	ds_read_b128 v[216:219], v150 offset:56320
	global_load_lds_dwordx4 v[220:221], off
	s_add_i32 m0, s18, 0x2000
	s_add_u32 s60, s60, 0x40080
	v_lshl_add_u64 v[220:221], v[222:223], 0, s[6:7]
	s_addc_u32 s61, s61, 0
	s_add_i32 s18, s19, s66
	global_load_lds_dwordx4 v[220:221], off
	v_lshl_add_u64 v[220:221], s[60:61], 0, v[132:133]
	s_mov_b32 m0, s18
	s_nop 0
	global_load_lds_dwordx4 v[220:221], off
	v_lshl_add_u64 v[220:221], s[60:61], 0, v[128:129]
	s_add_i32 m0, s18, 0x2000
	s_nop 0
	global_load_lds_dwordx4 v[220:221], off
	v_lshl_add_u64 v[220:221], v[224:225], 0, s[6:7]
	s_mov_b32 m0, s74
	s_nop 0
	global_load_lds_dwordx4 v[220:221], off
	v_lshl_add_u64 v[220:221], v[226:227], 0, s[6:7]
	s_mov_b32 m0, s75
	s_nop 0
	global_load_lds_dwordx4 v[220:221], off
	s_waitcnt vmcnt(8)
	s_waitcnt lgkmcnt(0)
	s_barrier
	s_setprio 1
	s_waitcnt lgkmcnt(0)
	v_mfma_f32_16x16x32_bf16 v[92:95], v[152:155], v[188:191], v[92:95]
	v_mfma_f32_16x16x32_bf16 v[92:95], v[156:159], v[192:195], v[92:95]
	v_mfma_f32_16x16x32_bf16 v[88:91], v[160:163], v[188:191], v[88:91]
	v_mfma_f32_16x16x32_bf16 v[88:91], v[164:167], v[192:195], v[88:91]
	v_mfma_f32_16x16x32_bf16 v[84:87], v[152:155], v[196:199], v[84:87]
	v_mfma_f32_16x16x32_bf16 v[84:87], v[156:159], v[200:203], v[84:87]
	v_mfma_f32_16x16x32_bf16 v[80:83], v[160:163], v[196:199], v[80:83]
	v_mfma_f32_16x16x32_bf16 v[80:83], v[164:167], v[200:203], v[80:83]
	v_mfma_f32_16x16x32_bf16 v[76:79], v[152:155], v[204:207], v[76:79]
	v_mfma_f32_16x16x32_bf16 v[76:79], v[156:159], v[208:211], v[76:79]
	v_mfma_f32_16x16x32_bf16 v[72:75], v[160:163], v[204:207], v[72:75]
	v_mfma_f32_16x16x32_bf16 v[72:75], v[164:167], v[208:211], v[72:75]
	v_mfma_f32_16x16x32_bf16 v[60:63], v[152:155], v[212:215], v[60:63]
	v_mfma_f32_16x16x32_bf16 v[60:63], v[156:159], v[216:219], v[60:63]
	v_mfma_f32_16x16x32_bf16 v[56:59], v[160:163], v[212:215], v[56:59]
	v_mfma_f32_16x16x32_bf16 v[56:59], v[164:167], v[216:219], v[56:59]
	s_setprio 0
	s_setprio 1
	v_mfma_f32_16x16x32_bf16 v[28:31], v[168:171], v[188:191], v[28:31]
	v_mfma_f32_16x16x32_bf16 v[28:31], v[172:175], v[192:195], v[28:31]
	v_mfma_f32_16x16x32_bf16 v[24:27], v[176:179], v[188:191], v[24:27]
	v_mfma_f32_16x16x32_bf16 v[24:27], v[184:187], v[192:195], v[24:27]
	v_mfma_f32_16x16x32_bf16 v[20:23], v[168:171], v[196:199], v[20:23]
	v_mfma_f32_16x16x32_bf16 v[20:23], v[172:175], v[200:203], v[20:23]
	v_mfma_f32_16x16x32_bf16 v[16:19], v[176:179], v[196:199], v[16:19]
	v_mfma_f32_16x16x32_bf16 v[16:19], v[184:187], v[200:203], v[16:19]
	v_mfma_f32_16x16x32_bf16 v[12:15], v[168:171], v[204:207], v[12:15]
	v_mfma_f32_16x16x32_bf16 v[12:15], v[172:175], v[208:211], v[12:15]
	v_mfma_f32_16x16x32_bf16 v[8:11], v[176:179], v[204:207], v[8:11]
	v_mfma_f32_16x16x32_bf16 v[8:11], v[184:187], v[208:211], v[8:11]
	v_mfma_f32_16x16x32_bf16 v[4:7], v[168:171], v[212:215], v[4:7]
	v_mfma_f32_16x16x32_bf16 v[4:7], v[172:175], v[216:219], v[4:7]
	s_barrier
	v_mfma_f32_16x16x32_bf16 v[0:3], v[176:179], v[212:215], v[0:3]
	v_mfma_f32_16x16x32_bf16 v[0:3], v[184:187], v[216:219], v[0:3]
	s_setprio 0
	s_add_i32 s86, s86, 2
	s_add_u32 s58, s58, 0x100
	s_addc_u32 s59, s59, 0
	s_add_u32 s84, s84, 0x100
	s_addc_u32 s85, s85, 0
	s_cmp_gt_u32 s86, 13
	s_cbranch_scc0 .LBB0_387
	s_and_b64 vcc, exec, s[8:9]
	s_cbranch_vccz .LBB0_390
	s_barrier

.LBB0_600:
	s_ashr_i32 s49, s48, 31
	s_lshl_b64 s[18:19], s[48:49], 19
	s_add_u32 s52, s38, s18
	s_addc_u32 s53, s39, s19
	s_and_b64 s[18:19], s[4:5], exec
	s_cselect_b32 s49, s53, s59
	s_cselect_b32 s84, s52, s58
	s_ashr_i32 s47, s46, 31
	s_lshl_b64 s[18:19], s[46:47], 19
	s_add_u32 s54, s64, s18
	s_addc_u32 s55, s65, s19
	s_and_b64 s[18:19], s[4:5], exec
	s_cselect_b32 s47, s55, s61
	s_cselect_b32 s85, s54, s60
	s_add_u32 s58, s58, 0x40080
	s_addc_u32 s59, s59, 0
	s_add_u32 s86, s60, 0x100
	s_addc_u32 s87, s61, 0
	s_mov_b32 s88, -2
	ds_read_b128 v[152:155], v149
	ds_read_b128 v[156:159], v149 offset:1024
	ds_read_b128 v[160:163], v149 offset:2048
	ds_read_b128 v[164:167], v149 offset:3072
	ds_read_b128 v[168:171], v150
	ds_read_b128 v[172:175], v150 offset:1024
	ds_read_b128 v[176:179], v150 offset:2048
	ds_read_b128 v[184:187], v150 offset:3072
	s_add_u32 s18, s58, 0xfffc0080
	s_addc_u32 s19, s59, -1
	s_cmp_eq_u32 s88, 12
	s_cselect_b32 s63, s49, s19
	s_cselect_b32 s62, s84, s18
	s_cselect_b32 s61, s47, s87
	s_cselect_b32 s60, s85, s86
	v_lshl_add_u64 v[144:145], s[58:59], 0, v[136:137]
	s_add_i32 m0, s57, 0xc000
	ds_read_b128 v[188:191], v151
	ds_read_b128 v[192:195], v151 offset:1024
	ds_read_b128 v[196:199], v151 offset:2048
	ds_read_b128 v[200:203], v151 offset:3072
	ds_read_b128 v[204:207], v151 offset:4096
	ds_read_b128 v[208:211], v151 offset:5120
	ds_read_b128 v[212:215], v151 offset:6144
	ds_read_b128 v[216:219], v151 offset:7168
	global_load_lds_dwordx4 v[144:145], off
	v_lshl_add_u64 v[144:145], s[58:59], 0, v[138:139]
	s_add_i32 m0, s57, 0xe000
	s_nop 0
	global_load_lds_dwordx4 v[144:145], off
	s_waitcnt vmcnt(8)
	s_waitcnt lgkmcnt(0)
	s_barrier
	s_setprio 1
	s_waitcnt lgkmcnt(0)
	v_mfma_f32_16x16x32_bf16 v[124:127], v[152:155], v[188:191], 0
	v_mfma_f32_16x16x32_bf16 v[124:127], v[156:159], v[192:195], v[124:127]
	v_mfma_f32_16x16x32_bf16 v[120:123], v[160:163], v[188:191], 0
	v_mfma_f32_16x16x32_bf16 v[120:123], v[164:167], v[192:195], v[120:123]
	v_mfma_f32_16x16x32_bf16 v[116:119], v[152:155], v[196:199], 0
	v_mfma_f32_16x16x32_bf16 v[116:119], v[156:159], v[200:203], v[116:119]
	v_mfma_f32_16x16x32_bf16 v[108:111], v[160:163], v[196:199], 0
	v_mfma_f32_16x16x32_bf16 v[108:111], v[164:167], v[200:203], v[108:111]
	v_mfma_f32_16x16x32_bf16 v[100:103], v[152:155], v[204:207], 0
	v_mfma_f32_16x16x32_bf16 v[100:103], v[156:159], v[208:211], v[100:103]
	v_mfma_f32_16x16x32_bf16 v[92:95], v[160:163], v[204:207], 0
	v_mfma_f32_16x16x32_bf16 v[92:95], v[164:167], v[208:211], v[92:95]
	v_mfma_f32_16x16x32_bf16 v[84:87], v[152:155], v[212:215], 0
	v_mfma_f32_16x16x32_bf16 v[84:87], v[156:159], v[216:219], v[84:87]
	v_mfma_f32_16x16x32_bf16 v[76:79], v[160:163], v[212:215], 0
	v_mfma_f32_16x16x32_bf16 v[76:79], v[164:167], v[216:219], v[76:79]
	s_setprio 0
	s_setprio 1
	v_mfma_f32_16x16x32_bf16 v[112:115], v[168:171], v[188:191], 0
	v_mfma_f32_16x16x32_bf16 v[112:115], v[172:175], v[192:195], v[112:115]
	v_mfma_f32_16x16x32_bf16 v[104:107], v[176:179], v[188:191], 0
	v_mfma_f32_16x16x32_bf16 v[104:107], v[184:187], v[192:195], v[104:107]
	v_mfma_f32_16x16x32_bf16 v[96:99], v[168:171], v[196:199], 0
	v_mfma_f32_16x16x32_bf16 v[96:99], v[172:175], v[200:203], v[96:99]
	v_mfma_f32_16x16x32_bf16 v[88:91], v[176:179], v[196:199], 0
	v_mfma_f32_16x16x32_bf16 v[88:91], v[184:187], v[200:203], v[88:91]
	v_mfma_f32_16x16x32_bf16 v[80:83], v[168:171], v[204:207], 0
	v_mfma_f32_16x16x32_bf16 v[80:83], v[172:175], v[208:211], v[80:83]
	v_mfma_f32_16x16x32_bf16 v[72:75], v[176:179], v[204:207], 0
	v_mfma_f32_16x16x32_bf16 v[72:75], v[184:187], v[208:211], v[72:75]
	v_mfma_f32_16x16x32_bf16 v[68:71], v[168:171], v[212:215], 0
	v_mfma_f32_16x16x32_bf16 v[68:71], v[172:175], v[216:219], v[68:71]
	s_barrier
	v_mfma_f32_16x16x32_bf16 v[64:67], v[176:179], v[212:215], 0
	v_mfma_f32_16x16x32_bf16 v[64:67], v[184:187], v[216:219], v[64:67]
	s_setprio 0
	s_add_i32 s18, s73, s66
	v_lshl_add_u64 v[144:145], s[60:61], 0, v[130:131]
	s_mov_b32 m0, s18
	ds_read_b128 v[188:191], v151 offset:16384
	ds_read_b128 v[192:195], v151 offset:17408
	ds_read_b128 v[196:199], v151 offset:18432
	ds_read_b128 v[200:203], v151 offset:19456
	ds_read_b128 v[204:207], v151 offset:20480
	ds_read_b128 v[208:211], v151 offset:21504
	ds_read_b128 v[212:215], v151 offset:22528
	ds_read_b128 v[216:219], v151 offset:23552
	global_load_lds_dwordx4 v[144:145], off
	s_add_i32 m0, s18, 0x2000
	s_add_u32 s18, s60, 0x40000
	v_lshl_add_u64 v[220:221], s[60:61], 0, v[134:135]
	s_addc_u32 s19, s61, 0
	s_add_i32 s79, s74, s66
	global_load_lds_dwordx4 v[220:221], off
	v_lshl_add_u64 v[222:223], s[18:19], 0, v[130:131]
	s_mov_b32 m0, s79
	v_lshl_add_u64 v[224:225], s[62:63], 0, v[132:133]
	global_load_lds_dwordx4 v[222:223], off
	v_lshl_add_u64 v[222:223], s[18:19], 0, v[134:135]
	s_add_i32 m0, s79, 0x2000
	s_nop 0
	global_load_lds_dwordx4 v[222:223], off
	v_lshl_add_u64 v[222:223], s[62:63], 0, v[128:129]
	s_mov_b32 m0, s57
	s_nop 0
	global_load_lds_dwordx4 v[222:223], off
	s_mov_b32 m0, s67
	s_nop 0
	global_load_lds_dwordx4 v[224:225], off
	s_waitcnt vmcnt(8)
	s_waitcnt lgkmcnt(0)
	s_barrier
	s_setprio 1
	s_waitcnt lgkmcnt(0)
	v_mfma_f32_16x16x32_bf16 v[60:63], v[152:155], v[188:191], 0
	v_mfma_f32_16x16x32_bf16 v[60:63], v[156:159], v[192:195], v[60:63]
	v_mfma_f32_16x16x32_bf16 v[56:59], v[160:163], v[188:191], 0
	v_mfma_f32_16x16x32_bf16 v[56:59], v[164:167], v[192:195], v[56:59]
	v_mfma_f32_16x16x32_bf16 v[52:55], v[152:155], v[196:199], 0
	v_mfma_f32_16x16x32_bf16 v[52:55], v[156:159], v[200:203], v[52:55]
	v_mfma_f32_16x16x32_bf16 v[44:47], v[160:163], v[196:199], 0
	v_mfma_f32_16x16x32_bf16 v[44:47], v[164:167], v[200:203], v[44:47]
	v_mfma_f32_16x16x32_bf16 v[36:39], v[152:155], v[204:207], 0
	v_mfma_f32_16x16x32_bf16 v[36:39], v[156:159], v[208:211], v[36:39]
	v_mfma_f32_16x16x32_bf16 v[28:31], v[160:163], v[204:207], 0
	v_mfma_f32_16x16x32_bf16 v[28:31], v[164:167], v[208:211], v[28:31]
	v_mfma_f32_16x16x32_bf16 v[20:23], v[152:155], v[212:215], 0
	v_mfma_f32_16x16x32_bf16 v[20:23], v[156:159], v[216:219], v[20:23]
	v_mfma_f32_16x16x32_bf16 v[12:15], v[160:163], v[212:215], 0
	v_mfma_f32_16x16x32_bf16 v[12:15], v[164:167], v[216:219], v[12:15]
	s_setprio 0
	s_setprio 1
	v_mfma_f32_16x16x32_bf16 v[48:51], v[168:171], v[188:191], 0
	v_mfma_f32_16x16x32_bf16 v[48:51], v[172:175], v[192:195], v[48:51]
	v_mfma_f32_16x16x32_bf16 v[40:43], v[176:179], v[188:191], 0
	v_mfma_f32_16x16x32_bf16 v[40:43], v[184:187], v[192:195], v[40:43]
	v_mfma_f32_16x16x32_bf16 v[32:35], v[168:171], v[196:199], 0
	v_mfma_f32_16x16x32_bf16 v[32:35], v[172:175], v[200:203], v[32:35]
	v_mfma_f32_16x16x32_bf16 v[24:27], v[176:179], v[196:199], 0
	v_mfma_f32_16x16x32_bf16 v[24:27], v[184:187], v[200:203], v[24:27]
	v_mfma_f32_16x16x32_bf16 v[16:19], v[168:171], v[204:207], 0
	v_mfma_f32_16x16x32_bf16 v[16:19], v[172:175], v[208:211], v[16:19]
	v_mfma_f32_16x16x32_bf16 v[8:11], v[176:179], v[204:207], 0
	v_mfma_f32_16x16x32_bf16 v[8:11], v[184:187], v[208:211], v[8:11]
	v_mfma_f32_16x16x32_bf16 v[4:7], v[168:171], v[212:215], 0
	v_mfma_f32_16x16x32_bf16 v[4:7], v[172:175], v[216:219], v[4:7]
	s_barrier
	v_mfma_f32_16x16x32_bf16 v[0:3], v[176:179], v[212:215], 0
	v_mfma_f32_16x16x32_bf16 v[0:3], v[184:187], v[216:219], v[0:3]
	s_setprio 0
	s_branch .Lmid_gemm3
.LBB0_601:
	ds_read_b128 v[152:155], v149
	ds_read_b128 v[156:159], v149 offset:1024
	ds_read_b128 v[160:163], v149 offset:2048
	ds_read_b128 v[164:167], v149 offset:3072
	ds_read_b128 v[168:171], v150
	ds_read_b128 v[172:175], v150 offset:1024
	ds_read_b128 v[176:179], v150 offset:2048
	ds_read_b128 v[184:187], v150 offset:3072
	s_add_u32 s18, s58, 0xfffc0080
	s_addc_u32 s19, s59, -1
	s_cmp_eq_u32 s88, 12
	s_cselect_b32 s63, s49, s19
	s_cselect_b32 s62, s84, s18
	s_cselect_b32 s61, s47, s87
	s_cselect_b32 s60, s85, s86
	v_lshl_add_u64 v[144:145], s[58:59], 0, v[136:137]
	s_add_i32 m0, s57, 0xc000
	ds_read_b128 v[188:191], v151
	ds_read_b128 v[192:195], v151 offset:1024
	ds_read_b128 v[196:199], v151 offset:2048
	ds_read_b128 v[200:203], v151 offset:3072
	ds_read_b128 v[204:207], v151 offset:4096
	ds_read_b128 v[208:211], v151 offset:5120
	ds_read_b128 v[212:215], v151 offset:6144
	ds_read_b128 v[216:219], v151 offset:7168
	global_load_lds_dwordx4 v[144:145], off
	v_lshl_add_u64 v[144:145], s[58:59], 0, v[138:139]
	s_add_i32 m0, s57, 0xe000
	s_nop 0
	global_load_lds_dwordx4 v[144:145], off
	s_waitcnt vmcnt(8)
	s_waitcnt lgkmcnt(0)
	s_barrier
	s_setprio 1
	s_waitcnt lgkmcnt(0)
	v_mfma_f32_16x16x32_bf16 v[124:127], v[152:155], v[188:191], v[124:127]
	v_mfma_f32_16x16x32_bf16 v[124:127], v[156:159], v[192:195], v[124:127]
	v_mfma_f32_16x16x32_bf16 v[120:123], v[160:163], v[188:191], v[120:123]
	v_mfma_f32_16x16x32_bf16 v[120:123], v[164:167], v[192:195], v[120:123]
	v_mfma_f32_16x16x32_bf16 v[116:119], v[152:155], v[196:199], v[116:119]
	v_mfma_f32_16x16x32_bf16 v[116:119], v[156:159], v[200:203], v[116:119]
	v_mfma_f32_16x16x32_bf16 v[108:111], v[160:163], v[196:199], v[108:111]
	v_mfma_f32_16x16x32_bf16 v[108:111], v[164:167], v[200:203], v[108:111]
	v_mfma_f32_16x16x32_bf16 v[100:103], v[152:155], v[204:207], v[100:103]
	v_mfma_f32_16x16x32_bf16 v[100:103], v[156:159], v[208:211], v[100:103]
	v_mfma_f32_16x16x32_bf16 v[92:95], v[160:163], v[204:207], v[92:95]
	v_mfma_f32_16x16x32_bf16 v[92:95], v[164:167], v[208:211], v[92:95]
	v_mfma_f32_16x16x32_bf16 v[84:87], v[152:155], v[212:215], v[84:87]
	v_mfma_f32_16x16x32_bf16 v[84:87], v[156:159], v[216:219], v[84:87]
	v_mfma_f32_16x16x32_bf16 v[76:79], v[160:163], v[212:215], v[76:79]
	v_mfma_f32_16x16x32_bf16 v[76:79], v[164:167], v[216:219], v[76:79]
	s_setprio 0
	s_setprio 1
	v_mfma_f32_16x16x32_bf16 v[112:115], v[168:171], v[188:191], v[112:115]
	v_mfma_f32_16x16x32_bf16 v[112:115], v[172:175], v[192:195], v[112:115]
	v_mfma_f32_16x16x32_bf16 v[104:107], v[176:179], v[188:191], v[104:107]
	v_mfma_f32_16x16x32_bf16 v[104:107], v[184:187], v[192:195], v[104:107]
	v_mfma_f32_16x16x32_bf16 v[96:99], v[168:171], v[196:199], v[96:99]
	v_mfma_f32_16x16x32_bf16 v[96:99], v[172:175], v[200:203], v[96:99]
	v_mfma_f32_16x16x32_bf16 v[88:91], v[176:179], v[196:199], v[88:91]
	v_mfma_f32_16x16x32_bf16 v[88:91], v[184:187], v[200:203], v[88:91]
	v_mfma_f32_16x16x32_bf16 v[80:83], v[168:171], v[204:207], v[80:83]
	v_mfma_f32_16x16x32_bf16 v[80:83], v[172:175], v[208:211], v[80:83]
	v_mfma_f32_16x16x32_bf16 v[72:75], v[176:179], v[204:207], v[72:75]
	v_mfma_f32_16x16x32_bf16 v[72:75], v[184:187], v[208:211], v[72:75]
	v_mfma_f32_16x16x32_bf16 v[68:71], v[168:171], v[212:215], v[68:71]
	v_mfma_f32_16x16x32_bf16 v[68:71], v[172:175], v[216:219], v[68:71]
	s_barrier
	v_mfma_f32_16x16x32_bf16 v[64:67], v[176:179], v[212:215], v[64:67]
	v_mfma_f32_16x16x32_bf16 v[64:67], v[184:187], v[216:219], v[64:67]
	s_setprio 0
	s_add_i32 s18, s73, s66
	v_lshl_add_u64 v[144:145], s[60:61], 0, v[130:131]
	s_mov_b32 m0, s18
	ds_read_b128 v[188:191], v151 offset:16384
	ds_read_b128 v[192:195], v151 offset:17408
	ds_read_b128 v[196:199], v151 offset:18432
	ds_read_b128 v[200:203], v151 offset:19456
	ds_read_b128 v[204:207], v151 offset:20480
	ds_read_b128 v[208:211], v151 offset:21504
	ds_read_b128 v[212:215], v151 offset:22528
	ds_read_b128 v[216:219], v151 offset:23552
	global_load_lds_dwordx4 v[144:145], off
	s_add_i32 m0, s18, 0x2000
	s_add_u32 s18, s60, 0x40000
	v_lshl_add_u64 v[220:221], s[60:61], 0, v[134:135]
	s_addc_u32 s19, s61, 0
	s_add_i32 s79, s74, s66
	global_load_lds_dwordx4 v[220:221], off
	v_lshl_add_u64 v[222:223], s[18:19], 0, v[130:131]
	s_mov_b32 m0, s79
	v_lshl_add_u64 v[224:225], s[62:63], 0, v[132:133]
	global_load_lds_dwordx4 v[222:223], off
	v_lshl_add_u64 v[222:223], s[18:19], 0, v[134:135]
	s_add_i32 m0, s79, 0x2000
	s_nop 0
	global_load_lds_dwordx4 v[222:223], off
	v_lshl_add_u64 v[222:223], s[62:63], 0, v[128:129]
	s_mov_b32 m0, s57
	s_nop 0
	global_load_lds_dwordx4 v[222:223], off
	s_mov_b32 m0, s67
	s_nop 0
	global_load_lds_dwordx4 v[224:225], off
	s_waitcnt vmcnt(8)
	s_waitcnt lgkmcnt(0)
	s_barrier
	s_setprio 1
	s_waitcnt lgkmcnt(0)
	v_mfma_f32_16x16x32_bf16 v[60:63], v[152:155], v[188:191], v[60:63]
	v_mfma_f32_16x16x32_bf16 v[60:63], v[156:159], v[192:195], v[60:63]
	v_mfma_f32_16x16x32_bf16 v[56:59], v[160:163], v[188:191], v[56:59]
	v_mfma_f32_16x16x32_bf16 v[56:59], v[164:167], v[192:195], v[56:59]
	v_mfma_f32_16x16x32_bf16 v[52:55], v[152:155], v[196:199], v[52:55]
	v_mfma_f32_16x16x32_bf16 v[52:55], v[156:159], v[200:203], v[52:55]
	v_mfma_f32_16x16x32_bf16 v[44:47], v[160:163], v[196:199], v[44:47]
	v_mfma_f32_16x16x32_bf16 v[44:47], v[164:167], v[200:203], v[44:47]
	v_mfma_f32_16x16x32_bf16 v[36:39], v[152:155], v[204:207], v[36:39]
	v_mfma_f32_16x16x32_bf16 v[36:39], v[156:159], v[208:211], v[36:39]
	v_mfma_f32_16x16x32_bf16 v[28:31], v[160:163], v[204:207], v[28:31]
	v_mfma_f32_16x16x32_bf16 v[28:31], v[164:167], v[208:211], v[28:31]
	v_mfma_f32_16x16x32_bf16 v[20:23], v[152:155], v[212:215], v[20:23]
	v_mfma_f32_16x16x32_bf16 v[20:23], v[156:159], v[216:219], v[20:23]
	v_mfma_f32_16x16x32_bf16 v[12:15], v[160:163], v[212:215], v[12:15]
	v_mfma_f32_16x16x32_bf16 v[12:15], v[164:167], v[216:219], v[12:15]
	s_setprio 0
	s_setprio 1
	v_mfma_f32_16x16x32_bf16 v[48:51], v[168:171], v[188:191], v[48:51]
	v_mfma_f32_16x16x32_bf16 v[48:51], v[172:175], v[192:195], v[48:51]
	v_mfma_f32_16x16x32_bf16 v[40:43], v[176:179], v[188:191], v[40:43]
	v_mfma_f32_16x16x32_bf16 v[40:43], v[184:187], v[192:195], v[40:43]
	v_mfma_f32_16x16x32_bf16 v[32:35], v[168:171], v[196:199], v[32:35]
	v_mfma_f32_16x16x32_bf16 v[32:35], v[172:175], v[200:203], v[32:35]
	v_mfma_f32_16x16x32_bf16 v[24:27], v[176:179], v[196:199], v[24:27]
	v_mfma_f32_16x16x32_bf16 v[24:27], v[184:187], v[200:203], v[24:27]
	v_mfma_f32_16x16x32_bf16 v[16:19], v[168:171], v[204:207], v[16:19]
	v_mfma_f32_16x16x32_bf16 v[16:19], v[172:175], v[208:211], v[16:19]
	v_mfma_f32_16x16x32_bf16 v[8:11], v[176:179], v[204:207], v[8:11]
	v_mfma_f32_16x16x32_bf16 v[8:11], v[184:187], v[208:211], v[8:11]
	v_mfma_f32_16x16x32_bf16 v[4:7], v[168:171], v[212:215], v[4:7]
	v_mfma_f32_16x16x32_bf16 v[4:7], v[172:175], v[216:219], v[4:7]
	s_barrier
	v_mfma_f32_16x16x32_bf16 v[0:3], v[176:179], v[212:215], v[0:3]
	v_mfma_f32_16x16x32_bf16 v[0:3], v[184:187], v[216:219], v[0:3]
	s_setprio 0
.Lmid_gemm3:
	s_add_i32 s79, 0, 0x18000
	s_add_i32 s89, 0, 0x1c000
	v_add_u32_e32 v164, s79, v147
	v_add_u32_e32 v181, s89, v147
	ds_read_b128 v[152:155], v164
	ds_read_b128 v[156:159], v164 offset:1024
	ds_read_b128 v[160:163], v164 offset:2048
	ds_read_b128 v[164:167], v164 offset:3072
	ds_read_b128 v[168:171], v181
	ds_read_b128 v[172:175], v181 offset:1024
	ds_read_b128 v[176:179], v181 offset:2048
	ds_read_b128 v[184:187], v181 offset:3072
	s_add_u32 s18, s62, 0x40000
	s_addc_u32 s19, s63, 0
	s_mov_b32 m0, s68
	v_lshl_add_u64 v[226:227], s[18:19], 0, v[128:129]
	ds_read_b128 v[188:191], v151 offset:32768
	ds_read_b128 v[192:195], v151 offset:33792
	ds_read_b128 v[196:199], v151 offset:34816
	ds_read_b128 v[200:203], v151 offset:35840
	ds_read_b128 v[204:207], v151 offset:36864
	ds_read_b128 v[208:211], v151 offset:37888
	ds_read_b128 v[212:215], v151 offset:38912
	ds_read_b128 v[216:219], v151 offset:39936
	global_load_lds_dwordx4 v[226:227], off
	v_lshl_add_u64 v[226:227], s[18:19], 0, v[132:133]
	s_mov_b32 m0, s69
	s_nop 0
	global_load_lds_dwordx4 v[226:227], off
	s_waitcnt vmcnt(8)
	s_waitcnt lgkmcnt(0)
	s_barrier
	s_setprio 1
	s_waitcnt lgkmcnt(0)
	v_mfma_f32_16x16x32_bf16 v[124:127], v[152:155], v[188:191], v[124:127]
	v_mfma_f32_16x16x32_bf16 v[124:127], v[156:159], v[192:195], v[124:127]
	v_mfma_f32_16x16x32_bf16 v[120:123], v[160:163], v[188:191], v[120:123]
	v_mfma_f32_16x16x32_bf16 v[120:123], v[164:167], v[192:195], v[120:123]
	v_mfma_f32_16x16x32_bf16 v[116:119], v[152:155], v[196:199], v[116:119]
	v_mfma_f32_16x16x32_bf16 v[116:119], v[156:159], v[200:203], v[116:119]
	v_mfma_f32_16x16x32_bf16 v[108:111], v[160:163], v[196:199], v[108:111]
	v_mfma_f32_16x16x32_bf16 v[108:111], v[164:167], v[200:203], v[108:111]
	v_mfma_f32_16x16x32_bf16 v[100:103], v[152:155], v[204:207], v[100:103]
	v_mfma_f32_16x16x32_bf16 v[100:103], v[156:159], v[208:211], v[100:103]
	v_mfma_f32_16x16x32_bf16 v[92:95], v[160:163], v[204:207], v[92:95]
	v_mfma_f32_16x16x32_bf16 v[92:95], v[164:167], v[208:211], v[92:95]
	v_mfma_f32_16x16x32_bf16 v[84:87], v[152:155], v[212:215], v[84:87]
	v_mfma_f32_16x16x32_bf16 v[84:87], v[156:159], v[216:219], v[84:87]
	v_mfma_f32_16x16x32_bf16 v[76:79], v[160:163], v[212:215], v[76:79]
	v_mfma_f32_16x16x32_bf16 v[76:79], v[164:167], v[216:219], v[76:79]
	s_setprio 0
	s_setprio 1
	v_mfma_f32_16x16x32_bf16 v[112:115], v[168:171], v[188:191], v[112:115]
	v_mfma_f32_16x16x32_bf16 v[112:115], v[172:175], v[192:195], v[112:115]
	v_mfma_f32_16x16x32_bf16 v[104:107], v[176:179], v[188:191], v[104:107]
	v_mfma_f32_16x16x32_bf16 v[104:107], v[184:187], v[192:195], v[104:107]
	v_mfma_f32_16x16x32_bf16 v[96:99], v[168:171], v[196:199], v[96:99]
	v_mfma_f32_16x16x32_bf16 v[96:99], v[172:175], v[200:203], v[96:99]
	v_mfma_f32_16x16x32_bf16 v[88:91], v[176:179], v[196:199], v[88:91]
	v_mfma_f32_16x16x32_bf16 v[88:91], v[184:187], v[200:203], v[88:91]
	v_mfma_f32_16x16x32_bf16 v[80:83], v[168:171], v[204:207], v[80:83]
	v_mfma_f32_16x16x32_bf16 v[80:83], v[172:175], v[208:211], v[80:83]
	v_mfma_f32_16x16x32_bf16 v[72:75], v[176:179], v[204:207], v[72:75]
	v_mfma_f32_16x16x32_bf16 v[72:75], v[184:187], v[208:211], v[72:75]
	v_mfma_f32_16x16x32_bf16 v[68:71], v[168:171], v[212:215], v[68:71]
	v_mfma_f32_16x16x32_bf16 v[68:71], v[172:175], v[216:219], v[68:71]
	s_barrier
	v_mfma_f32_16x16x32_bf16 v[64:67], v[176:179], v[212:215], v[64:67]
	v_mfma_f32_16x16x32_bf16 v[64:67], v[184:187], v[216:219], v[64:67]
	s_setprio 0
	s_add_i32 s18, s79, s66
	v_lshl_add_u64 v[144:145], v[144:145], 0, s[10:11]
	s_mov_b32 m0, s18
	ds_read_b128 v[188:191], v151 offset:49152
	ds_read_b128 v[192:195], v151 offset:50176
	ds_read_b128 v[196:199], v151 offset:51200
	ds_read_b128 v[200:203], v151 offset:52224
	ds_read_b128 v[204:207], v151 offset:53248
	ds_read_b128 v[208:211], v151 offset:54272
	ds_read_b128 v[212:215], v151 offset:55296
	ds_read_b128 v[216:219], v151 offset:56320
	global_load_lds_dwordx4 v[144:145], off
	s_add_i32 m0, s18, 0x2000
	s_add_u32 s18, s60, 0x40080
	v_lshl_add_u64 v[144:145], v[220:221], 0, s[10:11]
	s_addc_u32 s19, s61, 0
	s_add_i32 s60, s89, s66
	global_load_lds_dwordx4 v[144:145], off
	v_lshl_add_u64 v[144:145], s[18:19], 0, v[130:131]
	s_mov_b32 m0, s60
	s_nop 0
	global_load_lds_dwordx4 v[144:145], off
	v_lshl_add_u64 v[144:145], s[18:19], 0, v[134:135]
	s_add_i32 m0, s60, 0x2000
	s_nop 0
	global_load_lds_dwordx4 v[144:145], off
	v_lshl_add_u64 v[144:145], v[222:223], 0, s[10:11]
	s_mov_b32 m0, s71
	s_nop 0
	global_load_lds_dwordx4 v[144:145], off
	v_lshl_add_u64 v[144:145], v[224:225], 0, s[10:11]
	s_mov_b32 m0, s72
	s_nop 0
	global_load_lds_dwordx4 v[144:145], off
	s_waitcnt vmcnt(8)
	s_waitcnt lgkmcnt(0)
	s_barrier
	s_setprio 1
	s_waitcnt lgkmcnt(0)
	v_mfma_f32_16x16x32_bf16 v[60:63], v[152:155], v[188:191], v[60:63]
	v_mfma_f32_16x16x32_bf16 v[60:63], v[156:159], v[192:195], v[60:63]
	v_mfma_f32_16x16x32_bf16 v[56:59], v[160:163], v[188:191], v[56:59]
	v_mfma_f32_16x16x32_bf16 v[56:59], v[164:167], v[192:195], v[56:59]
	v_mfma_f32_16x16x32_bf16 v[52:55], v[152:155], v[196:199], v[52:55]
	v_mfma_f32_16x16x32_bf16 v[52:55], v[156:159], v[200:203], v[52:55]
	v_mfma_f32_16x16x32_bf16 v[44:47], v[160:163], v[196:199], v[44:47]
	v_mfma_f32_16x16x32_bf16 v[44:47], v[164:167], v[200:203], v[44:47]
	v_mfma_f32_16x16x32_bf16 v[36:39], v[152:155], v[204:207], v[36:39]
	v_mfma_f32_16x16x32_bf16 v[36:39], v[156:159], v[208:211], v[36:39]
	v_mfma_f32_16x16x32_bf16 v[28:31], v[160:163], v[204:207], v[28:31]
	v_mfma_f32_16x16x32_bf16 v[28:31], v[164:167], v[208:211], v[28:31]
	v_mfma_f32_16x16x32_bf16 v[20:23], v[152:155], v[212:215], v[20:23]
	v_mfma_f32_16x16x32_bf16 v[20:23], v[156:159], v[216:219], v[20:23]
	v_mfma_f32_16x16x32_bf16 v[12:15], v[160:163], v[212:215], v[12:15]
	v_mfma_f32_16x16x32_bf16 v[12:15], v[164:167], v[216:219], v[12:15]
	s_setprio 0
	s_setprio 1
	v_mfma_f32_16x16x32_bf16 v[48:51], v[168:171], v[188:191], v[48:51]
	v_mfma_f32_16x16x32_bf16 v[48:51], v[172:175], v[192:195], v[48:51]
	v_mfma_f32_16x16x32_bf16 v[40:43], v[176:179], v[188:191], v[40:43]
	v_mfma_f32_16x16x32_bf16 v[40:43], v[184:187], v[192:195], v[40:43]
	v_mfma_f32_16x16x32_bf16 v[32:35], v[168:171], v[196:199], v[32:35]
	v_mfma_f32_16x16x32_bf16 v[32:35], v[172:175], v[200:203], v[32:35]
	v_mfma_f32_16x16x32_bf16 v[24:27], v[176:179], v[196:199], v[24:27]
	v_mfma_f32_16x16x32_bf16 v[24:27], v[184:187], v[200:203], v[24:27]
	v_mfma_f32_16x16x32_bf16 v[16:19], v[168:171], v[204:207], v[16:19]
	v_mfma_f32_16x16x32_bf16 v[16:19], v[172:175], v[208:211], v[16:19]
	v_mfma_f32_16x16x32_bf16 v[8:11], v[176:179], v[204:207], v[8:11]
	v_mfma_f32_16x16x32_bf16 v[8:11], v[184:187], v[208:211], v[8:11]
	v_mfma_f32_16x16x32_bf16 v[4:7], v[168:171], v[212:215], v[4:7]
	v_mfma_f32_16x16x32_bf16 v[4:7], v[172:175], v[216:219], v[4:7]
	s_barrier
	v_mfma_f32_16x16x32_bf16 v[0:3], v[176:179], v[212:215], v[0:3]
	v_mfma_f32_16x16x32_bf16 v[0:3], v[184:187], v[216:219], v[0:3]
	s_setprio 0
	s_add_i32 s88, s88, 2
	s_add_u32 s58, s58, 0x100
	s_addc_u32 s59, s59, 0
	s_add_u32 s86, s86, 0x100
	s_addc_u32 s87, s87, 0
	s_cmp_gt_u32 s88, 13
	s_cbranch_scc0 .LBB0_601
	s_and_b64 vcc, exec, s[12:13]
	s_cbranch_vccz .LBB0_604
	s_barrier

.LBB0_723:
	s_ashr_i32 s31, s30, 31
	s_lshl_b64 s[36:37], s[30:31], 19
	s_add_u32 s36, s80, s36
	s_addc_u32 s37, s81, s37
	s_and_b64 s[44:45], s[10:11], exec
	s_cselect_b32 s31, s37, s49
	s_cselect_b32 s70, s36, s48
	s_ashr_i32 s19, s18, 31
	s_lshl_b64 s[44:45], s[18:19], 19
	s_add_u32 s44, s56, s44
	s_addc_u32 s45, s57, s45
	s_and_b64 s[54:55], s[10:11], exec
	s_cselect_b32 s19, s45, s53
	s_cselect_b32 s71, s44, s52
	s_add_u32 s48, s48, 0x40080
	s_addc_u32 s49, s49, 0
	s_add_u32 s72, s52, 0x100
	s_addc_u32 s73, s53, 0
	s_mov_b32 s74, -2
	ds_read_b128 v[140:143], v147
	ds_read_b128 v[150:153], v147 offset:1024
	ds_read_b128 v[154:157], v147 offset:2048
	ds_read_b128 v[158:161], v147 offset:3072
	ds_read_b128 v[162:165], v148
	ds_read_b128 v[166:169], v148 offset:1024
	ds_read_b128 v[170:173], v148 offset:2048
	ds_read_b128 v[174:177], v148 offset:3072
	s_add_u32 s52, s48, 0xfffc0080
	s_addc_u32 s53, s49, -1
	s_cmp_eq_u32 s74, 12
	s_cselect_b32 s55, s31, s53
	s_cselect_b32 s54, s70, s52
	s_cselect_b32 s53, s19, s73
	s_cselect_b32 s52, s71, s72
	v_lshl_add_u64 v[178:179], s[48:49], 0, v[132:133]
	s_add_i32 m0, s47, 0xc000
	ds_read_b128 v[184:187], v149
	ds_read_b128 v[188:191], v149 offset:1024
	ds_read_b128 v[192:195], v149 offset:2048
	ds_read_b128 v[196:199], v149 offset:3072
	ds_read_b128 v[200:203], v149 offset:4096
	ds_read_b128 v[204:207], v149 offset:5120
	ds_read_b128 v[208:211], v149 offset:6144
	ds_read_b128 v[212:215], v149 offset:7168
	global_load_lds_dwordx4 v[178:179], off
	v_lshl_add_u64 v[178:179], s[48:49], 0, v[134:135]
	s_add_i32 m0, s47, 0xe000
	s_nop 0
	global_load_lds_dwordx4 v[178:179], off
	s_waitcnt vmcnt(8)
	s_waitcnt lgkmcnt(0)
	s_barrier
	s_setprio 1
	s_waitcnt lgkmcnt(0)
	v_mfma_f32_16x16x32_bf16 v[124:127], v[140:143], v[184:187], 0
	v_mfma_f32_16x16x32_bf16 v[124:127], v[150:153], v[188:191], v[124:127]
	v_mfma_f32_16x16x32_bf16 v[120:123], v[154:157], v[184:187], 0
	v_mfma_f32_16x16x32_bf16 v[120:123], v[158:161], v[188:191], v[120:123]
	v_mfma_f32_16x16x32_bf16 v[108:111], v[140:143], v[192:195], 0
	v_mfma_f32_16x16x32_bf16 v[108:111], v[150:153], v[196:199], v[108:111]
	v_mfma_f32_16x16x32_bf16 v[104:107], v[154:157], v[192:195], 0
	v_mfma_f32_16x16x32_bf16 v[104:107], v[158:161], v[196:199], v[104:107]
	v_mfma_f32_16x16x32_bf16 v[92:95], v[140:143], v[200:203], 0
	v_mfma_f32_16x16x32_bf16 v[92:95], v[150:153], v[204:207], v[92:95]
	v_mfma_f32_16x16x32_bf16 v[88:91], v[154:157], v[200:203], 0
	v_mfma_f32_16x16x32_bf16 v[88:91], v[158:161], v[204:207], v[88:91]
	v_mfma_f32_16x16x32_bf16 v[76:79], v[140:143], v[208:211], 0
	v_mfma_f32_16x16x32_bf16 v[76:79], v[150:153], v[212:215], v[76:79]
	v_mfma_f32_16x16x32_bf16 v[72:75], v[154:157], v[208:211], 0
	v_mfma_f32_16x16x32_bf16 v[72:75], v[158:161], v[212:215], v[72:75]
	s_setprio 0
	s_setprio 1
	v_mfma_f32_16x16x32_bf16 v[116:119], v[162:165], v[184:187], 0
	v_mfma_f32_16x16x32_bf16 v[116:119], v[166:169], v[188:191], v[116:119]
	v_mfma_f32_16x16x32_bf16 v[112:115], v[170:173], v[184:187], 0
	v_mfma_f32_16x16x32_bf16 v[112:115], v[174:177], v[188:191], v[112:115]
	v_mfma_f32_16x16x32_bf16 v[100:103], v[162:165], v[192:195], 0
	v_mfma_f32_16x16x32_bf16 v[100:103], v[166:169], v[196:199], v[100:103]
	v_mfma_f32_16x16x32_bf16 v[96:99], v[170:173], v[192:195], 0
	v_mfma_f32_16x16x32_bf16 v[96:99], v[174:177], v[196:199], v[96:99]
	v_mfma_f32_16x16x32_bf16 v[84:87], v[162:165], v[200:203], 0
	v_mfma_f32_16x16x32_bf16 v[84:87], v[166:169], v[204:207], v[84:87]
	v_mfma_f32_16x16x32_bf16 v[80:83], v[170:173], v[200:203], 0
	v_mfma_f32_16x16x32_bf16 v[80:83], v[174:177], v[204:207], v[80:83]
	v_mfma_f32_16x16x32_bf16 v[68:71], v[162:165], v[208:211], 0
	v_mfma_f32_16x16x32_bf16 v[68:71], v[166:169], v[212:215], v[68:71]
	s_barrier
	v_mfma_f32_16x16x32_bf16 v[64:67], v[170:173], v[208:211], 0
	v_mfma_f32_16x16x32_bf16 v[64:67], v[174:177], v[212:215], v[64:67]
	s_setprio 0
	s_add_i32 s75, s66, s58
	v_lshl_add_u64 v[178:179], s[52:53], 0, v[130:131]
	s_mov_b32 m0, s75
	ds_read_b128 v[184:187], v149 offset:16384
	ds_read_b128 v[188:191], v149 offset:17408
	ds_read_b128 v[192:195], v149 offset:18432
	ds_read_b128 v[196:199], v149 offset:19456
	ds_read_b128 v[200:203], v149 offset:20480
	ds_read_b128 v[204:207], v149 offset:21504
	ds_read_b128 v[208:211], v149 offset:22528
	ds_read_b128 v[212:215], v149 offset:23552
	global_load_lds_dwordx4 v[178:179], off
	s_add_i32 m0, s75, 0x2000
	s_add_u32 s76, s52, 0x40000
	v_lshl_add_u64 v[216:217], s[52:53], 0, v[128:129]
	s_addc_u32 s77, s53, 0
	s_add_i32 s75, s67, s58
	global_load_lds_dwordx4 v[216:217], off
	v_lshl_add_u64 v[218:219], s[76:77], 0, v[130:131]
	s_mov_b32 m0, s75
	v_lshl_add_u64 v[220:221], s[54:55], 0, v[128:129]
	global_load_lds_dwordx4 v[218:219], off
	v_lshl_add_u64 v[218:219], s[76:77], 0, v[128:129]
	s_add_i32 m0, s75, 0x2000
	s_nop 0
	global_load_lds_dwordx4 v[218:219], off
	v_lshl_add_u64 v[218:219], s[54:55], 0, v[130:131]
	s_mov_b32 m0, s47
	s_nop 0
	global_load_lds_dwordx4 v[218:219], off
	s_mov_b32 m0, s60
	s_nop 0
	global_load_lds_dwordx4 v[220:221], off
	s_waitcnt vmcnt(8)
	s_waitcnt lgkmcnt(0)
	s_barrier
	s_setprio 1
	s_waitcnt lgkmcnt(0)
	v_mfma_f32_16x16x32_bf16 v[60:63], v[140:143], v[184:187], 0
	v_mfma_f32_16x16x32_bf16 v[60:63], v[150:153], v[188:191], v[60:63]
	v_mfma_f32_16x16x32_bf16 v[56:59], v[154:157], v[184:187], 0
	v_mfma_f32_16x16x32_bf16 v[56:59], v[158:161], v[188:191], v[56:59]
	v_mfma_f32_16x16x32_bf16 v[44:47], v[140:143], v[192:195], 0
	v_mfma_f32_16x16x32_bf16 v[44:47], v[150:153], v[196:199], v[44:47]
	v_mfma_f32_16x16x32_bf16 v[40:43], v[154:157], v[192:195], 0
	v_mfma_f32_16x16x32_bf16 v[40:43], v[158:161], v[196:199], v[40:43]
	v_mfma_f32_16x16x32_bf16 v[28:31], v[140:143], v[200:203], 0
	v_mfma_f32_16x16x32_bf16 v[28:31], v[150:153], v[204:207], v[28:31]
	v_mfma_f32_16x16x32_bf16 v[24:27], v[154:157], v[200:203], 0
	v_mfma_f32_16x16x32_bf16 v[24:27], v[158:161], v[204:207], v[24:27]
	v_mfma_f32_16x16x32_bf16 v[12:15], v[140:143], v[208:211], 0
	v_mfma_f32_16x16x32_bf16 v[12:15], v[150:153], v[212:215], v[12:15]
	v_mfma_f32_16x16x32_bf16 v[8:11], v[154:157], v[208:211], 0
	v_mfma_f32_16x16x32_bf16 v[8:11], v[158:161], v[212:215], v[8:11]
	s_setprio 0
	s_setprio 1
	v_mfma_f32_16x16x32_bf16 v[52:55], v[162:165], v[184:187], 0
	v_mfma_f32_16x16x32_bf16 v[52:55], v[166:169], v[188:191], v[52:55]
	v_mfma_f32_16x16x32_bf16 v[48:51], v[170:173], v[184:187], 0
	v_mfma_f32_16x16x32_bf16 v[48:51], v[174:177], v[188:191], v[48:51]
	v_mfma_f32_16x16x32_bf16 v[36:39], v[162:165], v[192:195], 0
	v_mfma_f32_16x16x32_bf16 v[36:39], v[166:169], v[196:199], v[36:39]
	v_mfma_f32_16x16x32_bf16 v[32:35], v[170:173], v[192:195], 0
	v_mfma_f32_16x16x32_bf16 v[32:35], v[174:177], v[196:199], v[32:35]
	v_mfma_f32_16x16x32_bf16 v[20:23], v[162:165], v[200:203], 0
	v_mfma_f32_16x16x32_bf16 v[20:23], v[166:169], v[204:207], v[20:23]
	v_mfma_f32_16x16x32_bf16 v[16:19], v[170:173], v[200:203], 0
	v_mfma_f32_16x16x32_bf16 v[16:19], v[174:177], v[204:207], v[16:19]
	v_mfma_f32_16x16x32_bf16 v[4:7], v[162:165], v[208:211], 0
	v_mfma_f32_16x16x32_bf16 v[4:7], v[166:169], v[212:215], v[4:7]
	s_barrier
	v_mfma_f32_16x16x32_bf16 v[0:3], v[170:173], v[208:211], 0
	v_mfma_f32_16x16x32_bf16 v[0:3], v[174:177], v[212:215], v[0:3]
	s_setprio 0
	s_branch .Lmid_gemm4
.LBB0_724:
	ds_read_b128 v[140:143], v147
	ds_read_b128 v[150:153], v147 offset:1024
	ds_read_b128 v[154:157], v147 offset:2048
	ds_read_b128 v[158:161], v147 offset:3072
	ds_read_b128 v[162:165], v148
	ds_read_b128 v[166:169], v148 offset:1024
	ds_read_b128 v[170:173], v148 offset:2048
	ds_read_b128 v[174:177], v148 offset:3072
	s_add_u32 s52, s48, 0xfffc0080
	s_addc_u32 s53, s49, -1
	s_cmp_eq_u32 s74, 12
	s_cselect_b32 s55, s31, s53
	s_cselect_b32 s54, s70, s52
	s_cselect_b32 s53, s19, s73
	s_cselect_b32 s52, s71, s72
	v_lshl_add_u64 v[178:179], s[48:49], 0, v[132:133]
	s_add_i32 m0, s47, 0xc000
	ds_read_b128 v[184:187], v149
	ds_read_b128 v[188:191], v149 offset:1024
	ds_read_b128 v[192:195], v149 offset:2048
	ds_read_b128 v[196:199], v149 offset:3072
	ds_read_b128 v[200:203], v149 offset:4096
	ds_read_b128 v[204:207], v149 offset:5120
	ds_read_b128 v[208:211], v149 offset:6144
	ds_read_b128 v[212:215], v149 offset:7168
	global_load_lds_dwordx4 v[178:179], off
	v_lshl_add_u64 v[178:179], s[48:49], 0, v[134:135]
	s_add_i32 m0, s47, 0xe000
	s_nop 0
	global_load_lds_dwordx4 v[178:179], off
	s_waitcnt vmcnt(8)
	s_waitcnt lgkmcnt(0)
	s_barrier
	s_setprio 1
	s_waitcnt lgkmcnt(0)
	v_mfma_f32_16x16x32_bf16 v[124:127], v[140:143], v[184:187], v[124:127]
	v_mfma_f32_16x16x32_bf16 v[124:127], v[150:153], v[188:191], v[124:127]
	v_mfma_f32_16x16x32_bf16 v[120:123], v[154:157], v[184:187], v[120:123]
	v_mfma_f32_16x16x32_bf16 v[120:123], v[158:161], v[188:191], v[120:123]
	v_mfma_f32_16x16x32_bf16 v[108:111], v[140:143], v[192:195], v[108:111]
	v_mfma_f32_16x16x32_bf16 v[108:111], v[150:153], v[196:199], v[108:111]
	v_mfma_f32_16x16x32_bf16 v[104:107], v[154:157], v[192:195], v[104:107]
	v_mfma_f32_16x16x32_bf16 v[104:107], v[158:161], v[196:199], v[104:107]
	v_mfma_f32_16x16x32_bf16 v[92:95], v[140:143], v[200:203], v[92:95]
	v_mfma_f32_16x16x32_bf16 v[92:95], v[150:153], v[204:207], v[92:95]
	v_mfma_f32_16x16x32_bf16 v[88:91], v[154:157], v[200:203], v[88:91]
	v_mfma_f32_16x16x32_bf16 v[88:91], v[158:161], v[204:207], v[88:91]
	v_mfma_f32_16x16x32_bf16 v[76:79], v[140:143], v[208:211], v[76:79]
	v_mfma_f32_16x16x32_bf16 v[76:79], v[150:153], v[212:215], v[76:79]
	v_mfma_f32_16x16x32_bf16 v[72:75], v[154:157], v[208:211], v[72:75]
	v_mfma_f32_16x16x32_bf16 v[72:75], v[158:161], v[212:215], v[72:75]
	s_setprio 0
	s_setprio 1
	v_mfma_f32_16x16x32_bf16 v[116:119], v[162:165], v[184:187], v[116:119]
	v_mfma_f32_16x16x32_bf16 v[116:119], v[166:169], v[188:191], v[116:119]
	v_mfma_f32_16x16x32_bf16 v[112:115], v[170:173], v[184:187], v[112:115]
	v_mfma_f32_16x16x32_bf16 v[112:115], v[174:177], v[188:191], v[112:115]
	v_mfma_f32_16x16x32_bf16 v[100:103], v[162:165], v[192:195], v[100:103]
	v_mfma_f32_16x16x32_bf16 v[100:103], v[166:169], v[196:199], v[100:103]
	v_mfma_f32_16x16x32_bf16 v[96:99], v[170:173], v[192:195], v[96:99]
	v_mfma_f32_16x16x32_bf16 v[96:99], v[174:177], v[196:199], v[96:99]
	v_mfma_f32_16x16x32_bf16 v[84:87], v[162:165], v[200:203], v[84:87]
	v_mfma_f32_16x16x32_bf16 v[84:87], v[166:169], v[204:207], v[84:87]
	v_mfma_f32_16x16x32_bf16 v[80:83], v[170:173], v[200:203], v[80:83]
	v_mfma_f32_16x16x32_bf16 v[80:83], v[174:177], v[204:207], v[80:83]
	v_mfma_f32_16x16x32_bf16 v[68:71], v[162:165], v[208:211], v[68:71]
	v_mfma_f32_16x16x32_bf16 v[68:71], v[166:169], v[212:215], v[68:71]
	s_barrier
	v_mfma_f32_16x16x32_bf16 v[64:67], v[170:173], v[208:211], v[64:67]
	v_mfma_f32_16x16x32_bf16 v[64:67], v[174:177], v[212:215], v[64:67]
	s_setprio 0
	s_add_i32 s75, s66, s58
	v_lshl_add_u64 v[178:179], s[52:53], 0, v[130:131]
	s_mov_b32 m0, s75
	ds_read_b128 v[184:187], v149 offset:16384
	ds_read_b128 v[188:191], v149 offset:17408
	ds_read_b128 v[192:195], v149 offset:18432
	ds_read_b128 v[196:199], v149 offset:19456
	ds_read_b128 v[200:203], v149 offset:20480
	ds_read_b128 v[204:207], v149 offset:21504
	ds_read_b128 v[208:211], v149 offset:22528
	ds_read_b128 v[212:215], v149 offset:23552
	global_load_lds_dwordx4 v[178:179], off
	s_add_i32 m0, s75, 0x2000
	s_add_u32 s76, s52, 0x40000
	v_lshl_add_u64 v[216:217], s[52:53], 0, v[128:129]
	s_addc_u32 s77, s53, 0
	s_add_i32 s75, s67, s58
	global_load_lds_dwordx4 v[216:217], off
	v_lshl_add_u64 v[218:219], s[76:77], 0, v[130:131]
	s_mov_b32 m0, s75
	v_lshl_add_u64 v[220:221], s[54:55], 0, v[128:129]
	global_load_lds_dwordx4 v[218:219], off
	v_lshl_add_u64 v[218:219], s[76:77], 0, v[128:129]
	s_add_i32 m0, s75, 0x2000
	s_nop 0
	global_load_lds_dwordx4 v[218:219], off
	v_lshl_add_u64 v[218:219], s[54:55], 0, v[130:131]
	s_mov_b32 m0, s47
	s_nop 0
	global_load_lds_dwordx4 v[218:219], off
	s_mov_b32 m0, s60
	s_nop 0
	global_load_lds_dwordx4 v[220:221], off
	s_waitcnt vmcnt(8)
	s_waitcnt lgkmcnt(0)
	s_barrier
	s_setprio 1
	s_waitcnt lgkmcnt(0)
	v_mfma_f32_16x16x32_bf16 v[60:63], v[140:143], v[184:187], v[60:63]
	v_mfma_f32_16x16x32_bf16 v[60:63], v[150:153], v[188:191], v[60:63]
	v_mfma_f32_16x16x32_bf16 v[56:59], v[154:157], v[184:187], v[56:59]
	v_mfma_f32_16x16x32_bf16 v[56:59], v[158:161], v[188:191], v[56:59]
	v_mfma_f32_16x16x32_bf16 v[44:47], v[140:143], v[192:195], v[44:47]
	v_mfma_f32_16x16x32_bf16 v[44:47], v[150:153], v[196:199], v[44:47]
	v_mfma_f32_16x16x32_bf16 v[40:43], v[154:157], v[192:195], v[40:43]
	v_mfma_f32_16x16x32_bf16 v[40:43], v[158:161], v[196:199], v[40:43]
	v_mfma_f32_16x16x32_bf16 v[28:31], v[140:143], v[200:203], v[28:31]
	v_mfma_f32_16x16x32_bf16 v[28:31], v[150:153], v[204:207], v[28:31]
	v_mfma_f32_16x16x32_bf16 v[24:27], v[154:157], v[200:203], v[24:27]
	v_mfma_f32_16x16x32_bf16 v[24:27], v[158:161], v[204:207], v[24:27]
	v_mfma_f32_16x16x32_bf16 v[12:15], v[140:143], v[208:211], v[12:15]
	v_mfma_f32_16x16x32_bf16 v[12:15], v[150:153], v[212:215], v[12:15]
	v_mfma_f32_16x16x32_bf16 v[8:11], v[154:157], v[208:211], v[8:11]
	v_mfma_f32_16x16x32_bf16 v[8:11], v[158:161], v[212:215], v[8:11]
	s_setprio 0
	s_setprio 1
	v_mfma_f32_16x16x32_bf16 v[52:55], v[162:165], v[184:187], v[52:55]
	v_mfma_f32_16x16x32_bf16 v[52:55], v[166:169], v[188:191], v[52:55]
	v_mfma_f32_16x16x32_bf16 v[48:51], v[170:173], v[184:187], v[48:51]
	v_mfma_f32_16x16x32_bf16 v[48:51], v[174:177], v[188:191], v[48:51]
	v_mfma_f32_16x16x32_bf16 v[36:39], v[162:165], v[192:195], v[36:39]
	v_mfma_f32_16x16x32_bf16 v[36:39], v[166:169], v[196:199], v[36:39]
	v_mfma_f32_16x16x32_bf16 v[32:35], v[170:173], v[192:195], v[32:35]
	v_mfma_f32_16x16x32_bf16 v[32:35], v[174:177], v[196:199], v[32:35]
	v_mfma_f32_16x16x32_bf16 v[20:23], v[162:165], v[200:203], v[20:23]
	v_mfma_f32_16x16x32_bf16 v[20:23], v[166:169], v[204:207], v[20:23]
	v_mfma_f32_16x16x32_bf16 v[16:19], v[170:173], v[200:203], v[16:19]
	v_mfma_f32_16x16x32_bf16 v[16:19], v[174:177], v[204:207], v[16:19]
	v_mfma_f32_16x16x32_bf16 v[4:7], v[162:165], v[208:211], v[4:7]
	v_mfma_f32_16x16x32_bf16 v[4:7], v[166:169], v[212:215], v[4:7]
	s_barrier
	v_mfma_f32_16x16x32_bf16 v[0:3], v[170:173], v[208:211], v[0:3]
	v_mfma_f32_16x16x32_bf16 v[0:3], v[174:177], v[212:215], v[0:3]
	s_setprio 0
.Lmid_gemm4:
	s_add_i32 s75, 0, 0x18000
	s_add_i32 s76, 0, 0x1c000
	v_add_u32_e32 v158, s75, v145
	v_add_u32_e32 v174, s76, v145
	ds_read_b128 v[140:143], v158
	ds_read_b128 v[150:153], v158 offset:1024
	ds_read_b128 v[154:157], v158 offset:2048
	ds_read_b128 v[158:161], v158 offset:3072
	ds_read_b128 v[162:165], v174
	ds_read_b128 v[166:169], v174 offset:1024
	ds_read_b128 v[170:173], v174 offset:2048
	ds_read_b128 v[174:177], v174 offset:3072
	s_add_u32 s54, s54, 0x40000
	s_addc_u32 s55, s55, 0
	s_mov_b32 m0, s61
	v_lshl_add_u64 v[222:223], s[54:55], 0, v[130:131]
	ds_read_b128 v[184:187], v149 offset:32768
	ds_read_b128 v[188:191], v149 offset:33792
	ds_read_b128 v[192:195], v149 offset:34816
	ds_read_b128 v[196:199], v149 offset:35840
	ds_read_b128 v[200:203], v149 offset:36864
	ds_read_b128 v[204:207], v149 offset:37888
	ds_read_b128 v[208:211], v149 offset:38912
	ds_read_b128 v[212:215], v149 offset:39936
	global_load_lds_dwordx4 v[222:223], off
	v_lshl_add_u64 v[222:223], s[54:55], 0, v[128:129]
	s_mov_b32 m0, s62
	s_nop 0
	global_load_lds_dwordx4 v[222:223], off
	s_waitcnt vmcnt(8)
	s_waitcnt lgkmcnt(0)
	s_barrier
	s_setprio 1
	s_waitcnt lgkmcnt(0)
	v_mfma_f32_16x16x32_bf16 v[124:127], v[140:143], v[184:187], v[124:127]
	v_mfma_f32_16x16x32_bf16 v[124:127], v[150:153], v[188:191], v[124:127]
	v_mfma_f32_16x16x32_bf16 v[120:123], v[154:157], v[184:187], v[120:123]
	v_mfma_f32_16x16x32_bf16 v[120:123], v[158:161], v[188:191], v[120:123]
	v_mfma_f32_16x16x32_bf16 v[108:111], v[140:143], v[192:195], v[108:111]
	v_mfma_f32_16x16x32_bf16 v[108:111], v[150:153], v[196:199], v[108:111]
	v_mfma_f32_16x16x32_bf16 v[104:107], v[154:157], v[192:195], v[104:107]
	v_mfma_f32_16x16x32_bf16 v[104:107], v[158:161], v[196:199], v[104:107]
	v_mfma_f32_16x16x32_bf16 v[92:95], v[140:143], v[200:203], v[92:95]
	v_mfma_f32_16x16x32_bf16 v[92:95], v[150:153], v[204:207], v[92:95]
	v_mfma_f32_16x16x32_bf16 v[88:91], v[154:157], v[200:203], v[88:91]
	v_mfma_f32_16x16x32_bf16 v[88:91], v[158:161], v[204:207], v[88:91]
	v_mfma_f32_16x16x32_bf16 v[76:79], v[140:143], v[208:211], v[76:79]
	v_mfma_f32_16x16x32_bf16 v[76:79], v[150:153], v[212:215], v[76:79]
	v_mfma_f32_16x16x32_bf16 v[72:75], v[154:157], v[208:211], v[72:75]
	v_mfma_f32_16x16x32_bf16 v[72:75], v[158:161], v[212:215], v[72:75]
	s_setprio 0
	s_setprio 1
	v_mfma_f32_16x16x32_bf16 v[116:119], v[162:165], v[184:187], v[116:119]
	v_mfma_f32_16x16x32_bf16 v[116:119], v[166:169], v[188:191], v[116:119]
	v_mfma_f32_16x16x32_bf16 v[112:115], v[170:173], v[184:187], v[112:115]
	v_mfma_f32_16x16x32_bf16 v[112:115], v[174:177], v[188:191], v[112:115]
	v_mfma_f32_16x16x32_bf16 v[100:103], v[162:165], v[192:195], v[100:103]
	v_mfma_f32_16x16x32_bf16 v[100:103], v[166:169], v[196:199], v[100:103]
	v_mfma_f32_16x16x32_bf16 v[96:99], v[170:173], v[192:195], v[96:99]
	v_mfma_f32_16x16x32_bf16 v[96:99], v[174:177], v[196:199], v[96:99]
	v_mfma_f32_16x16x32_bf16 v[84:87], v[162:165], v[200:203], v[84:87]
	v_mfma_f32_16x16x32_bf16 v[84:87], v[166:169], v[204:207], v[84:87]
	v_mfma_f32_16x16x32_bf16 v[80:83], v[170:173], v[200:203], v[80:83]
	v_mfma_f32_16x16x32_bf16 v[80:83], v[174:177], v[204:207], v[80:83]
	v_mfma_f32_16x16x32_bf16 v[68:71], v[162:165], v[208:211], v[68:71]
	v_mfma_f32_16x16x32_bf16 v[68:71], v[166:169], v[212:215], v[68:71]
	s_barrier
	v_mfma_f32_16x16x32_bf16 v[64:67], v[170:173], v[208:211], v[64:67]
	v_mfma_f32_16x16x32_bf16 v[64:67], v[174:177], v[212:215], v[64:67]
	s_setprio 0
	s_add_i32 s54, s75, s58
	v_lshl_add_u64 v[178:179], v[178:179], 0, s[12:13]
	s_mov_b32 m0, s54
	ds_read_b128 v[184:187], v149 offset:49152
	ds_read_b128 v[188:191], v149 offset:50176
	ds_read_b128 v[192:195], v149 offset:51200
	ds_read_b128 v[196:199], v149 offset:52224
	ds_read_b128 v[200:203], v149 offset:53248
	ds_read_b128 v[204:207], v149 offset:54272
	ds_read_b128 v[208:211], v149 offset:55296
	ds_read_b128 v[212:215], v149 offset:56320
	global_load_lds_dwordx4 v[178:179], off
	s_add_i32 m0, s54, 0x2000
	s_add_u32 s52, s52, 0x40080
	v_lshl_add_u64 v[178:179], v[216:217], 0, s[12:13]
	s_addc_u32 s53, s53, 0
	s_add_i32 s54, s76, s58
	global_load_lds_dwordx4 v[178:179], off
	v_lshl_add_u64 v[178:179], s[52:53], 0, v[130:131]
	s_mov_b32 m0, s54
	s_nop 0
	global_load_lds_dwordx4 v[178:179], off
	v_lshl_add_u64 v[178:179], s[52:53], 0, v[128:129]
	s_add_i32 m0, s54, 0x2000
	s_nop 0
	global_load_lds_dwordx4 v[178:179], off
	v_lshl_add_u64 v[178:179], v[218:219], 0, s[12:13]
	s_mov_b32 m0, s64
	s_nop 0
	global_load_lds_dwordx4 v[178:179], off
	v_lshl_add_u64 v[178:179], v[220:221], 0, s[12:13]
	s_mov_b32 m0, s65
	s_nop 0
	global_load_lds_dwordx4 v[178:179], off
	s_waitcnt vmcnt(8)
	s_waitcnt lgkmcnt(0)
	s_barrier
	s_setprio 1
	s_waitcnt lgkmcnt(0)
	v_mfma_f32_16x16x32_bf16 v[60:63], v[140:143], v[184:187], v[60:63]
	v_mfma_f32_16x16x32_bf16 v[60:63], v[150:153], v[188:191], v[60:63]
	v_mfma_f32_16x16x32_bf16 v[56:59], v[154:157], v[184:187], v[56:59]
	v_mfma_f32_16x16x32_bf16 v[56:59], v[158:161], v[188:191], v[56:59]
	v_mfma_f32_16x16x32_bf16 v[44:47], v[140:143], v[192:195], v[44:47]
	v_mfma_f32_16x16x32_bf16 v[44:47], v[150:153], v[196:199], v[44:47]
	v_mfma_f32_16x16x32_bf16 v[40:43], v[154:157], v[192:195], v[40:43]
	v_mfma_f32_16x16x32_bf16 v[40:43], v[158:161], v[196:199], v[40:43]
	v_mfma_f32_16x16x32_bf16 v[28:31], v[140:143], v[200:203], v[28:31]
	v_mfma_f32_16x16x32_bf16 v[28:31], v[150:153], v[204:207], v[28:31]
	v_mfma_f32_16x16x32_bf16 v[24:27], v[154:157], v[200:203], v[24:27]
	v_mfma_f32_16x16x32_bf16 v[24:27], v[158:161], v[204:207], v[24:27]
	v_mfma_f32_16x16x32_bf16 v[12:15], v[140:143], v[208:211], v[12:15]
	v_mfma_f32_16x16x32_bf16 v[12:15], v[150:153], v[212:215], v[12:15]
	v_mfma_f32_16x16x32_bf16 v[8:11], v[154:157], v[208:211], v[8:11]
	v_mfma_f32_16x16x32_bf16 v[8:11], v[158:161], v[212:215], v[8:11]
	s_setprio 0
	s_setprio 1
	v_mfma_f32_16x16x32_bf16 v[52:55], v[162:165], v[184:187], v[52:55]
	v_mfma_f32_16x16x32_bf16 v[52:55], v[166:169], v[188:191], v[52:55]
	v_mfma_f32_16x16x32_bf16 v[48:51], v[170:173], v[184:187], v[48:51]
	v_mfma_f32_16x16x32_bf16 v[48:51], v[174:177], v[188:191], v[48:51]
	v_mfma_f32_16x16x32_bf16 v[36:39], v[162:165], v[192:195], v[36:39]
	v_mfma_f32_16x16x32_bf16 v[36:39], v[166:169], v[196:199], v[36:39]
	v_mfma_f32_16x16x32_bf16 v[32:35], v[170:173], v[192:195], v[32:35]
	v_mfma_f32_16x16x32_bf16 v[32:35], v[174:177], v[196:199], v[32:35]
	v_mfma_f32_16x16x32_bf16 v[20:23], v[162:165], v[200:203], v[20:23]
	v_mfma_f32_16x16x32_bf16 v[20:23], v[166:169], v[204:207], v[20:23]
	v_mfma_f32_16x16x32_bf16 v[16:19], v[170:173], v[200:203], v[16:19]
	v_mfma_f32_16x16x32_bf16 v[16:19], v[174:177], v[204:207], v[16:19]
	v_mfma_f32_16x16x32_bf16 v[4:7], v[162:165], v[208:211], v[4:7]
	v_mfma_f32_16x16x32_bf16 v[4:7], v[166:169], v[212:215], v[4:7]
	s_barrier
	v_mfma_f32_16x16x32_bf16 v[0:3], v[170:173], v[208:211], v[0:3]
	v_mfma_f32_16x16x32_bf16 v[0:3], v[174:177], v[212:215], v[0:3]
	s_setprio 0
	s_add_i32 s74, s74, 2
	s_add_u32 s48, s48, 0x100
	s_addc_u32 s49, s49, 0
	s_add_u32 s72, s72, 0x100
	s_addc_u32 s73, s73, 0
	s_cmp_gt_u32 s74, 13
	s_cbranch_scc0 .LBB0_724
	s_and_b64 vcc, exec, s[16:17]
	s_cbranch_vccz .LBB0_727
	s_barrier

.LBB0_803:
	s_add_u32 s84, s54, 0x100
	s_addc_u32 s85, s55, 0
	s_mov_b32 s86, -2
	ds_read_b128 v[152:155], v149
	ds_read_b128 v[156:159], v149 offset:1024
	ds_read_b128 v[160:163], v149 offset:2048
	ds_read_b128 v[164:167], v149 offset:3072
	ds_read_b128 v[168:171], v150
	ds_read_b128 v[172:175], v150 offset:1024
	ds_read_b128 v[176:179], v150 offset:2048
	ds_read_b128 v[184:187], v150 offset:3072
	s_add_u32 s54, s52, 0x100
	s_addc_u32 s55, s53, 0
	s_cmp_eq_u32 s86, 40
	s_cselect_b32 s59, s13, s55
	s_cselect_b32 s58, s12, s54
	s_cselect_b32 s57, s49, s85
	s_cselect_b32 s56, s48, s84
	v_lshl_add_u64 v[144:145], s[52:53], 0, v[136:137]
	s_add_i32 m0, s63, 0xc000
	ds_read_b128 v[188:191], v151
	ds_read_b128 v[192:195], v151 offset:1024
	ds_read_b128 v[196:199], v151 offset:2048
	ds_read_b128 v[200:203], v151 offset:3072
	ds_read_b128 v[204:207], v151 offset:4096
	ds_read_b128 v[208:211], v151 offset:5120
	ds_read_b128 v[212:215], v151 offset:6144
	ds_read_b128 v[216:219], v151 offset:7168
	global_load_lds_dwordx4 v[144:145], off
	v_lshl_add_u64 v[144:145], s[52:53], 0, v[138:139]
	s_add_i32 m0, s63, 0xe000
	s_nop 0
	global_load_lds_dwordx4 v[144:145], off
	s_waitcnt vmcnt(8)
	s_waitcnt lgkmcnt(0)
	s_barrier
	s_setprio 1
	s_waitcnt lgkmcnt(0)
	v_mfma_f32_16x16x32_bf16 v[124:127], v[152:155], v[188:191], 0
	v_mfma_f32_16x16x32_bf16 v[124:127], v[156:159], v[192:195], v[124:127]
	v_mfma_f32_16x16x32_bf16 v[120:123], v[160:163], v[188:191], 0
	v_mfma_f32_16x16x32_bf16 v[120:123], v[164:167], v[192:195], v[120:123]
	v_mfma_f32_16x16x32_bf16 v[116:119], v[152:155], v[196:199], 0
	v_mfma_f32_16x16x32_bf16 v[116:119], v[156:159], v[200:203], v[116:119]
	v_mfma_f32_16x16x32_bf16 v[108:111], v[160:163], v[196:199], 0
	v_mfma_f32_16x16x32_bf16 v[108:111], v[164:167], v[200:203], v[108:111]
	v_mfma_f32_16x16x32_bf16 v[100:103], v[152:155], v[204:207], 0
	v_mfma_f32_16x16x32_bf16 v[100:103], v[156:159], v[208:211], v[100:103]
	v_mfma_f32_16x16x32_bf16 v[92:95], v[160:163], v[204:207], 0
	v_mfma_f32_16x16x32_bf16 v[92:95], v[164:167], v[208:211], v[92:95]
	v_mfma_f32_16x16x32_bf16 v[84:87], v[152:155], v[212:215], 0
	v_mfma_f32_16x16x32_bf16 v[84:87], v[156:159], v[216:219], v[84:87]
	v_mfma_f32_16x16x32_bf16 v[76:79], v[160:163], v[212:215], 0
	v_mfma_f32_16x16x32_bf16 v[76:79], v[164:167], v[216:219], v[76:79]
	s_setprio 0
	s_setprio 1
	v_mfma_f32_16x16x32_bf16 v[112:115], v[168:171], v[188:191], 0
	v_mfma_f32_16x16x32_bf16 v[112:115], v[172:175], v[192:195], v[112:115]
	v_mfma_f32_16x16x32_bf16 v[104:107], v[176:179], v[188:191], 0
	v_mfma_f32_16x16x32_bf16 v[104:107], v[184:187], v[192:195], v[104:107]
	v_mfma_f32_16x16x32_bf16 v[96:99], v[168:171], v[196:199], 0
	v_mfma_f32_16x16x32_bf16 v[96:99], v[172:175], v[200:203], v[96:99]
	v_mfma_f32_16x16x32_bf16 v[88:91], v[176:179], v[196:199], 0
	v_mfma_f32_16x16x32_bf16 v[88:91], v[184:187], v[200:203], v[88:91]
	v_mfma_f32_16x16x32_bf16 v[80:83], v[168:171], v[204:207], 0
	v_mfma_f32_16x16x32_bf16 v[80:83], v[172:175], v[208:211], v[80:83]
	v_mfma_f32_16x16x32_bf16 v[72:75], v[176:179], v[204:207], 0
	v_mfma_f32_16x16x32_bf16 v[72:75], v[184:187], v[208:211], v[72:75]
	v_mfma_f32_16x16x32_bf16 v[68:71], v[168:171], v[212:215], 0
	v_mfma_f32_16x16x32_bf16 v[68:71], v[172:175], v[216:219], v[68:71]
	s_barrier
	v_mfma_f32_16x16x32_bf16 v[64:67], v[176:179], v[212:215], 0
	v_mfma_f32_16x16x32_bf16 v[64:67], v[184:187], v[216:219], v[64:67]
	s_setprio 0
	s_add_i32 s52, s70, s62
	v_lshl_add_u64 v[144:145], s[56:57], 0, v[130:131]
	s_mov_b32 m0, s52
	ds_read_b128 v[188:191], v151 offset:16384
	ds_read_b128 v[192:195], v151 offset:17408
	ds_read_b128 v[196:199], v151 offset:18432
	ds_read_b128 v[200:203], v151 offset:19456
	ds_read_b128 v[204:207], v151 offset:20480
	ds_read_b128 v[208:211], v151 offset:21504
	ds_read_b128 v[212:215], v151 offset:22528
	ds_read_b128 v[216:219], v151 offset:23552
	global_load_lds_dwordx4 v[144:145], off
	s_add_i32 m0, s52, 0x2000
	s_add_u32 s52, s56, 0xb0000
	v_lshl_add_u64 v[220:221], s[56:57], 0, v[134:135]
	s_addc_u32 s53, s57, 0
	s_add_i32 s79, s71, s62
	global_load_lds_dwordx4 v[220:221], off
	v_lshl_add_u64 v[222:223], s[52:53], 0, v[130:131]
	s_mov_b32 m0, s79
	v_lshl_add_u64 v[224:225], s[58:59], 0, v[132:133]
	global_load_lds_dwordx4 v[222:223], off
	v_lshl_add_u64 v[222:223], s[52:53], 0, v[134:135]
	s_add_i32 m0, s79, 0x2000
	s_nop 0
	global_load_lds_dwordx4 v[222:223], off
	v_lshl_add_u64 v[222:223], s[58:59], 0, v[128:129]
	s_mov_b32 m0, s63
	s_nop 0
	global_load_lds_dwordx4 v[222:223], off
	s_mov_b32 m0, s64
	s_nop 0
	global_load_lds_dwordx4 v[224:225], off
	s_waitcnt vmcnt(8)
	s_waitcnt lgkmcnt(0)
	s_barrier
	s_setprio 1
	s_waitcnt lgkmcnt(0)
	v_mfma_f32_16x16x32_bf16 v[60:63], v[152:155], v[188:191], 0
	v_mfma_f32_16x16x32_bf16 v[60:63], v[156:159], v[192:195], v[60:63]
	v_mfma_f32_16x16x32_bf16 v[56:59], v[160:163], v[188:191], 0
	v_mfma_f32_16x16x32_bf16 v[56:59], v[164:167], v[192:195], v[56:59]
	v_mfma_f32_16x16x32_bf16 v[52:55], v[152:155], v[196:199], 0
	v_mfma_f32_16x16x32_bf16 v[52:55], v[156:159], v[200:203], v[52:55]
	v_mfma_f32_16x16x32_bf16 v[44:47], v[160:163], v[196:199], 0
	v_mfma_f32_16x16x32_bf16 v[44:47], v[164:167], v[200:203], v[44:47]
	v_mfma_f32_16x16x32_bf16 v[36:39], v[152:155], v[204:207], 0
	v_mfma_f32_16x16x32_bf16 v[36:39], v[156:159], v[208:211], v[36:39]
	v_mfma_f32_16x16x32_bf16 v[28:31], v[160:163], v[204:207], 0
	v_mfma_f32_16x16x32_bf16 v[28:31], v[164:167], v[208:211], v[28:31]
	v_mfma_f32_16x16x32_bf16 v[20:23], v[152:155], v[212:215], 0
	v_mfma_f32_16x16x32_bf16 v[20:23], v[156:159], v[216:219], v[20:23]
	v_mfma_f32_16x16x32_bf16 v[12:15], v[160:163], v[212:215], 0
	v_mfma_f32_16x16x32_bf16 v[12:15], v[164:167], v[216:219], v[12:15]
	s_setprio 0
	s_setprio 1
	v_mfma_f32_16x16x32_bf16 v[48:51], v[168:171], v[188:191], 0
	v_mfma_f32_16x16x32_bf16 v[48:51], v[172:175], v[192:195], v[48:51]
	v_mfma_f32_16x16x32_bf16 v[40:43], v[176:179], v[188:191], 0
	v_mfma_f32_16x16x32_bf16 v[40:43], v[184:187], v[192:195], v[40:43]
	v_mfma_f32_16x16x32_bf16 v[32:35], v[168:171], v[196:199], 0
	v_mfma_f32_16x16x32_bf16 v[32:35], v[172:175], v[200:203], v[32:35]
	v_mfma_f32_16x16x32_bf16 v[24:27], v[176:179], v[196:199], 0
	v_mfma_f32_16x16x32_bf16 v[24:27], v[184:187], v[200:203], v[24:27]
	v_mfma_f32_16x16x32_bf16 v[16:19], v[168:171], v[204:207], 0
	v_mfma_f32_16x16x32_bf16 v[16:19], v[172:175], v[208:211], v[16:19]
	v_mfma_f32_16x16x32_bf16 v[8:11], v[176:179], v[204:207], 0
	v_mfma_f32_16x16x32_bf16 v[8:11], v[184:187], v[208:211], v[8:11]
	v_mfma_f32_16x16x32_bf16 v[4:7], v[168:171], v[212:215], 0
	v_mfma_f32_16x16x32_bf16 v[4:7], v[172:175], v[216:219], v[4:7]
	s_barrier
	v_mfma_f32_16x16x32_bf16 v[0:3], v[176:179], v[212:215], 0
	v_mfma_f32_16x16x32_bf16 v[0:3], v[184:187], v[216:219], v[0:3]
	s_setprio 0
	s_branch .Lmid_gemm5
.LBB0_804:
	ds_read_b128 v[152:155], v149
	ds_read_b128 v[156:159], v149 offset:1024
	ds_read_b128 v[160:163], v149 offset:2048
	ds_read_b128 v[164:167], v149 offset:3072
	ds_read_b128 v[168:171], v150
	ds_read_b128 v[172:175], v150 offset:1024
	ds_read_b128 v[176:179], v150 offset:2048
	ds_read_b128 v[184:187], v150 offset:3072
	s_add_u32 s54, s52, 0x100
	s_addc_u32 s55, s53, 0
	s_cmp_eq_u32 s86, 40
	s_cselect_b32 s59, s13, s55
	s_cselect_b32 s58, s12, s54
	s_cselect_b32 s57, s49, s85
	s_cselect_b32 s56, s48, s84
	v_lshl_add_u64 v[144:145], s[52:53], 0, v[136:137]
	s_add_i32 m0, s63, 0xc000
	ds_read_b128 v[188:191], v151
	ds_read_b128 v[192:195], v151 offset:1024
	ds_read_b128 v[196:199], v151 offset:2048
	ds_read_b128 v[200:203], v151 offset:3072
	ds_read_b128 v[204:207], v151 offset:4096
	ds_read_b128 v[208:211], v151 offset:5120
	ds_read_b128 v[212:215], v151 offset:6144
	ds_read_b128 v[216:219], v151 offset:7168
	global_load_lds_dwordx4 v[144:145], off
	v_lshl_add_u64 v[144:145], s[52:53], 0, v[138:139]
	s_add_i32 m0, s63, 0xe000
	s_nop 0
	global_load_lds_dwordx4 v[144:145], off
	s_waitcnt vmcnt(8)
	s_waitcnt lgkmcnt(0)
	s_barrier
	s_setprio 1
	s_waitcnt lgkmcnt(0)
	v_mfma_f32_16x16x32_bf16 v[124:127], v[152:155], v[188:191], v[124:127]
	v_mfma_f32_16x16x32_bf16 v[124:127], v[156:159], v[192:195], v[124:127]
	v_mfma_f32_16x16x32_bf16 v[120:123], v[160:163], v[188:191], v[120:123]
	v_mfma_f32_16x16x32_bf16 v[120:123], v[164:167], v[192:195], v[120:123]
	v_mfma_f32_16x16x32_bf16 v[116:119], v[152:155], v[196:199], v[116:119]
	v_mfma_f32_16x16x32_bf16 v[116:119], v[156:159], v[200:203], v[116:119]
	v_mfma_f32_16x16x32_bf16 v[108:111], v[160:163], v[196:199], v[108:111]
	v_mfma_f32_16x16x32_bf16 v[108:111], v[164:167], v[200:203], v[108:111]
	v_mfma_f32_16x16x32_bf16 v[100:103], v[152:155], v[204:207], v[100:103]
	v_mfma_f32_16x16x32_bf16 v[100:103], v[156:159], v[208:211], v[100:103]
	v_mfma_f32_16x16x32_bf16 v[92:95], v[160:163], v[204:207], v[92:95]
	v_mfma_f32_16x16x32_bf16 v[92:95], v[164:167], v[208:211], v[92:95]
	v_mfma_f32_16x16x32_bf16 v[84:87], v[152:155], v[212:215], v[84:87]
	v_mfma_f32_16x16x32_bf16 v[84:87], v[156:159], v[216:219], v[84:87]
	v_mfma_f32_16x16x32_bf16 v[76:79], v[160:163], v[212:215], v[76:79]
	v_mfma_f32_16x16x32_bf16 v[76:79], v[164:167], v[216:219], v[76:79]
	s_setprio 0
	s_setprio 1
	v_mfma_f32_16x16x32_bf16 v[112:115], v[168:171], v[188:191], v[112:115]
	v_mfma_f32_16x16x32_bf16 v[112:115], v[172:175], v[192:195], v[112:115]
	v_mfma_f32_16x16x32_bf16 v[104:107], v[176:179], v[188:191], v[104:107]
	v_mfma_f32_16x16x32_bf16 v[104:107], v[184:187], v[192:195], v[104:107]
	v_mfma_f32_16x16x32_bf16 v[96:99], v[168:171], v[196:199], v[96:99]
	v_mfma_f32_16x16x32_bf16 v[96:99], v[172:175], v[200:203], v[96:99]
	v_mfma_f32_16x16x32_bf16 v[88:91], v[176:179], v[196:199], v[88:91]
	v_mfma_f32_16x16x32_bf16 v[88:91], v[184:187], v[200:203], v[88:91]
	v_mfma_f32_16x16x32_bf16 v[80:83], v[168:171], v[204:207], v[80:83]
	v_mfma_f32_16x16x32_bf16 v[80:83], v[172:175], v[208:211], v[80:83]
	v_mfma_f32_16x16x32_bf16 v[72:75], v[176:179], v[204:207], v[72:75]
	v_mfma_f32_16x16x32_bf16 v[72:75], v[184:187], v[208:211], v[72:75]
	v_mfma_f32_16x16x32_bf16 v[68:71], v[168:171], v[212:215], v[68:71]
	v_mfma_f32_16x16x32_bf16 v[68:71], v[172:175], v[216:219], v[68:71]
	s_barrier
	v_mfma_f32_16x16x32_bf16 v[64:67], v[176:179], v[212:215], v[64:67]
	v_mfma_f32_16x16x32_bf16 v[64:67], v[184:187], v[216:219], v[64:67]
	s_setprio 0
	s_add_i32 s52, s70, s62
	v_lshl_add_u64 v[144:145], s[56:57], 0, v[130:131]
	s_mov_b32 m0, s52
	ds_read_b128 v[188:191], v151 offset:16384
	ds_read_b128 v[192:195], v151 offset:17408
	ds_read_b128 v[196:199], v151 offset:18432
	ds_read_b128 v[200:203], v151 offset:19456
	ds_read_b128 v[204:207], v151 offset:20480
	ds_read_b128 v[208:211], v151 offset:21504
	ds_read_b128 v[212:215], v151 offset:22528
	ds_read_b128 v[216:219], v151 offset:23552
	global_load_lds_dwordx4 v[144:145], off
	s_add_i32 m0, s52, 0x2000
	s_add_u32 s52, s56, 0xb0000
	v_lshl_add_u64 v[220:221], s[56:57], 0, v[134:135]
	s_addc_u32 s53, s57, 0
	s_add_i32 s79, s71, s62
	global_load_lds_dwordx4 v[220:221], off
	v_lshl_add_u64 v[222:223], s[52:53], 0, v[130:131]
	s_mov_b32 m0, s79
	v_lshl_add_u64 v[224:225], s[58:59], 0, v[132:133]
	global_load_lds_dwordx4 v[222:223], off
	v_lshl_add_u64 v[222:223], s[52:53], 0, v[134:135]
	s_add_i32 m0, s79, 0x2000
	s_nop 0
	global_load_lds_dwordx4 v[222:223], off
	v_lshl_add_u64 v[222:223], s[58:59], 0, v[128:129]
	s_mov_b32 m0, s63
	s_nop 0
	global_load_lds_dwordx4 v[222:223], off
	s_mov_b32 m0, s64
	s_nop 0
	global_load_lds_dwordx4 v[224:225], off
	s_waitcnt vmcnt(8)
	s_waitcnt lgkmcnt(0)
	s_barrier
	s_setprio 1
	s_waitcnt lgkmcnt(0)
	v_mfma_f32_16x16x32_bf16 v[60:63], v[152:155], v[188:191], v[60:63]
	v_mfma_f32_16x16x32_bf16 v[60:63], v[156:159], v[192:195], v[60:63]
	v_mfma_f32_16x16x32_bf16 v[56:59], v[160:163], v[188:191], v[56:59]
	v_mfma_f32_16x16x32_bf16 v[56:59], v[164:167], v[192:195], v[56:59]
	v_mfma_f32_16x16x32_bf16 v[52:55], v[152:155], v[196:199], v[52:55]
	v_mfma_f32_16x16x32_bf16 v[52:55], v[156:159], v[200:203], v[52:55]
	v_mfma_f32_16x16x32_bf16 v[44:47], v[160:163], v[196:199], v[44:47]
	v_mfma_f32_16x16x32_bf16 v[44:47], v[164:167], v[200:203], v[44:47]
	v_mfma_f32_16x16x32_bf16 v[36:39], v[152:155], v[204:207], v[36:39]
	v_mfma_f32_16x16x32_bf16 v[36:39], v[156:159], v[208:211], v[36:39]
	v_mfma_f32_16x16x32_bf16 v[28:31], v[160:163], v[204:207], v[28:31]
	v_mfma_f32_16x16x32_bf16 v[28:31], v[164:167], v[208:211], v[28:31]
	v_mfma_f32_16x16x32_bf16 v[20:23], v[152:155], v[212:215], v[20:23]
	v_mfma_f32_16x16x32_bf16 v[20:23], v[156:159], v[216:219], v[20:23]
	v_mfma_f32_16x16x32_bf16 v[12:15], v[160:163], v[212:215], v[12:15]
	v_mfma_f32_16x16x32_bf16 v[12:15], v[164:167], v[216:219], v[12:15]
	s_setprio 0
	s_setprio 1
	v_mfma_f32_16x16x32_bf16 v[48:51], v[168:171], v[188:191], v[48:51]
	v_mfma_f32_16x16x32_bf16 v[48:51], v[172:175], v[192:195], v[48:51]
	v_mfma_f32_16x16x32_bf16 v[40:43], v[176:179], v[188:191], v[40:43]
	v_mfma_f32_16x16x32_bf16 v[40:43], v[184:187], v[192:195], v[40:43]
	v_mfma_f32_16x16x32_bf16 v[32:35], v[168:171], v[196:199], v[32:35]
	v_mfma_f32_16x16x32_bf16 v[32:35], v[172:175], v[200:203], v[32:35]
	v_mfma_f32_16x16x32_bf16 v[24:27], v[176:179], v[196:199], v[24:27]
	v_mfma_f32_16x16x32_bf16 v[24:27], v[184:187], v[200:203], v[24:27]
	v_mfma_f32_16x16x32_bf16 v[16:19], v[168:171], v[204:207], v[16:19]
	v_mfma_f32_16x16x32_bf16 v[16:19], v[172:175], v[208:211], v[16:19]
	v_mfma_f32_16x16x32_bf16 v[8:11], v[176:179], v[204:207], v[8:11]
	v_mfma_f32_16x16x32_bf16 v[8:11], v[184:187], v[208:211], v[8:11]
	v_mfma_f32_16x16x32_bf16 v[4:7], v[168:171], v[212:215], v[4:7]
	v_mfma_f32_16x16x32_bf16 v[4:7], v[172:175], v[216:219], v[4:7]
	s_barrier
	v_mfma_f32_16x16x32_bf16 v[0:3], v[176:179], v[212:215], v[0:3]
	v_mfma_f32_16x16x32_bf16 v[0:3], v[184:187], v[216:219], v[0:3]
	s_setprio 0
.Lmid_gemm5:
	s_add_i32 s79, 0, 0x18000
	s_add_i32 s87, 0, 0x1c000
	v_add_u32_e32 v164, s79, v147
	v_add_u32_e32 v181, s87, v147
	ds_read_b128 v[152:155], v164
	ds_read_b128 v[156:159], v164 offset:1024
	ds_read_b128 v[160:163], v164 offset:2048
	ds_read_b128 v[164:167], v164 offset:3072
	ds_read_b128 v[168:171], v181
	ds_read_b128 v[172:175], v181 offset:1024
	ds_read_b128 v[176:179], v181 offset:2048
	ds_read_b128 v[184:187], v181 offset:3072
	s_add_u32 s52, s58, 0xb0000
	s_addc_u32 s53, s59, 0
	s_mov_b32 m0, s65
	v_lshl_add_u64 v[226:227], s[52:53], 0, v[128:129]
	ds_read_b128 v[188:191], v151 offset:32768
	ds_read_b128 v[192:195], v151 offset:33792
	ds_read_b128 v[196:199], v151 offset:34816
	ds_read_b128 v[200:203], v151 offset:35840
	ds_read_b128 v[204:207], v151 offset:36864
	ds_read_b128 v[208:211], v151 offset:37888
	ds_read_b128 v[212:215], v151 offset:38912
	ds_read_b128 v[216:219], v151 offset:39936
	global_load_lds_dwordx4 v[226:227], off
	v_lshl_add_u64 v[226:227], s[52:53], 0, v[132:133]
	s_mov_b32 m0, s66
	s_nop 0
	global_load_lds_dwordx4 v[226:227], off
	s_waitcnt vmcnt(8)
	s_waitcnt lgkmcnt(0)
	s_barrier
	s_setprio 1
	s_waitcnt lgkmcnt(0)
	v_mfma_f32_16x16x32_bf16 v[124:127], v[152:155], v[188:191], v[124:127]
	v_mfma_f32_16x16x32_bf16 v[124:127], v[156:159], v[192:195], v[124:127]
	v_mfma_f32_16x16x32_bf16 v[120:123], v[160:163], v[188:191], v[120:123]
	v_mfma_f32_16x16x32_bf16 v[120:123], v[164:167], v[192:195], v[120:123]
	v_mfma_f32_16x16x32_bf16 v[116:119], v[152:155], v[196:199], v[116:119]
	v_mfma_f32_16x16x32_bf16 v[116:119], v[156:159], v[200:203], v[116:119]
	v_mfma_f32_16x16x32_bf16 v[108:111], v[160:163], v[196:199], v[108:111]
	v_mfma_f32_16x16x32_bf16 v[108:111], v[164:167], v[200:203], v[108:111]
	v_mfma_f32_16x16x32_bf16 v[100:103], v[152:155], v[204:207], v[100:103]
	v_mfma_f32_16x16x32_bf16 v[100:103], v[156:159], v[208:211], v[100:103]
	v_mfma_f32_16x16x32_bf16 v[92:95], v[160:163], v[204:207], v[92:95]
	v_mfma_f32_16x16x32_bf16 v[92:95], v[164:167], v[208:211], v[92:95]
	v_mfma_f32_16x16x32_bf16 v[84:87], v[152:155], v[212:215], v[84:87]
	v_mfma_f32_16x16x32_bf16 v[84:87], v[156:159], v[216:219], v[84:87]
	v_mfma_f32_16x16x32_bf16 v[76:79], v[160:163], v[212:215], v[76:79]
	v_mfma_f32_16x16x32_bf16 v[76:79], v[164:167], v[216:219], v[76:79]
	s_setprio 0
	s_setprio 1
	v_mfma_f32_16x16x32_bf16 v[112:115], v[168:171], v[188:191], v[112:115]
	v_mfma_f32_16x16x32_bf16 v[112:115], v[172:175], v[192:195], v[112:115]
	v_mfma_f32_16x16x32_bf16 v[104:107], v[176:179], v[188:191], v[104:107]
	v_mfma_f32_16x16x32_bf16 v[104:107], v[184:187], v[192:195], v[104:107]
	v_mfma_f32_16x16x32_bf16 v[96:99], v[168:171], v[196:199], v[96:99]
	v_mfma_f32_16x16x32_bf16 v[96:99], v[172:175], v[200:203], v[96:99]
	v_mfma_f32_16x16x32_bf16 v[88:91], v[176:179], v[196:199], v[88:91]
	v_mfma_f32_16x16x32_bf16 v[88:91], v[184:187], v[200:203], v[88:91]
	v_mfma_f32_16x16x32_bf16 v[80:83], v[168:171], v[204:207], v[80:83]
	v_mfma_f32_16x16x32_bf16 v[80:83], v[172:175], v[208:211], v[80:83]
	v_mfma_f32_16x16x32_bf16 v[72:75], v[176:179], v[204:207], v[72:75]
	v_mfma_f32_16x16x32_bf16 v[72:75], v[184:187], v[208:211], v[72:75]
	v_mfma_f32_16x16x32_bf16 v[68:71], v[168:171], v[212:215], v[68:71]
	v_mfma_f32_16x16x32_bf16 v[68:71], v[172:175], v[216:219], v[68:71]
	s_barrier
	v_mfma_f32_16x16x32_bf16 v[64:67], v[176:179], v[212:215], v[64:67]
	v_mfma_f32_16x16x32_bf16 v[64:67], v[184:187], v[216:219], v[64:67]
	s_setprio 0
	s_add_i32 s52, s79, s62
	v_lshl_add_u64 v[144:145], v[144:145], 0, s[16:17]
	s_mov_b32 m0, s52
	ds_read_b128 v[188:191], v151 offset:49152
	ds_read_b128 v[192:195], v151 offset:50176
	ds_read_b128 v[196:199], v151 offset:51200
	ds_read_b128 v[200:203], v151 offset:52224
	ds_read_b128 v[204:207], v151 offset:53248
	ds_read_b128 v[208:211], v151 offset:54272
	ds_read_b128 v[212:215], v151 offset:55296
	ds_read_b128 v[216:219], v151 offset:56320
	global_load_lds_dwordx4 v[144:145], off
	s_add_i32 m0, s52, 0x2000
	s_add_u32 s52, s56, 0xb0080
	v_lshl_add_u64 v[144:145], v[220:221], 0, s[16:17]
	s_addc_u32 s53, s57, 0
	s_add_i32 s56, s87, s62
	global_load_lds_dwordx4 v[144:145], off
	v_lshl_add_u64 v[144:145], s[52:53], 0, v[130:131]
	s_mov_b32 m0, s56
	s_nop 0
	global_load_lds_dwordx4 v[144:145], off
	v_lshl_add_u64 v[144:145], s[52:53], 0, v[134:135]
	s_add_i32 m0, s56, 0x2000
	s_nop 0
	global_load_lds_dwordx4 v[144:145], off
	v_lshl_add_u64 v[144:145], v[222:223], 0, s[16:17]
	s_mov_b32 m0, s68
	s_nop 0
	global_load_lds_dwordx4 v[144:145], off
	v_lshl_add_u64 v[144:145], v[224:225], 0, s[16:17]
	s_mov_b32 m0, s69
	s_nop 0
	global_load_lds_dwordx4 v[144:145], off
	s_waitcnt vmcnt(8)
	s_waitcnt lgkmcnt(0)
	s_barrier
	s_setprio 1
	s_waitcnt lgkmcnt(0)
	v_mfma_f32_16x16x32_bf16 v[60:63], v[152:155], v[188:191], v[60:63]
	v_mfma_f32_16x16x32_bf16 v[60:63], v[156:159], v[192:195], v[60:63]
	v_mfma_f32_16x16x32_bf16 v[56:59], v[160:163], v[188:191], v[56:59]
	v_mfma_f32_16x16x32_bf16 v[56:59], v[164:167], v[192:195], v[56:59]
	v_mfma_f32_16x16x32_bf16 v[52:55], v[152:155], v[196:199], v[52:55]
	v_mfma_f32_16x16x32_bf16 v[52:55], v[156:159], v[200:203], v[52:55]
	v_mfma_f32_16x16x32_bf16 v[44:47], v[160:163], v[196:199], v[44:47]
	v_mfma_f32_16x16x32_bf16 v[44:47], v[164:167], v[200:203], v[44:47]
	v_mfma_f32_16x16x32_bf16 v[36:39], v[152:155], v[204:207], v[36:39]
	v_mfma_f32_16x16x32_bf16 v[36:39], v[156:159], v[208:211], v[36:39]
	v_mfma_f32_16x16x32_bf16 v[28:31], v[160:163], v[204:207], v[28:31]
	v_mfma_f32_16x16x32_bf16 v[28:31], v[164:167], v[208:211], v[28:31]
	v_mfma_f32_16x16x32_bf16 v[20:23], v[152:155], v[212:215], v[20:23]
	v_mfma_f32_16x16x32_bf16 v[20:23], v[156:159], v[216:219], v[20:23]
	v_mfma_f32_16x16x32_bf16 v[12:15], v[160:163], v[212:215], v[12:15]
	v_mfma_f32_16x16x32_bf16 v[12:15], v[164:167], v[216:219], v[12:15]
	s_setprio 0
	s_setprio 1
	v_mfma_f32_16x16x32_bf16 v[48:51], v[168:171], v[188:191], v[48:51]
	v_mfma_f32_16x16x32_bf16 v[48:51], v[172:175], v[192:195], v[48:51]
	v_mfma_f32_16x16x32_bf16 v[40:43], v[176:179], v[188:191], v[40:43]
	v_mfma_f32_16x16x32_bf16 v[40:43], v[184:187], v[192:195], v[40:43]
	v_mfma_f32_16x16x32_bf16 v[32:35], v[168:171], v[196:199], v[32:35]
	v_mfma_f32_16x16x32_bf16 v[32:35], v[172:175], v[200:203], v[32:35]
	v_mfma_f32_16x16x32_bf16 v[24:27], v[176:179], v[196:199], v[24:27]
	v_mfma_f32_16x16x32_bf16 v[24:27], v[184:187], v[200:203], v[24:27]
	v_mfma_f32_16x16x32_bf16 v[16:19], v[168:171], v[204:207], v[16:19]
	v_mfma_f32_16x16x32_bf16 v[16:19], v[172:175], v[208:211], v[16:19]
	v_mfma_f32_16x16x32_bf16 v[8:11], v[176:179], v[204:207], v[8:11]
	v_mfma_f32_16x16x32_bf16 v[8:11], v[184:187], v[208:211], v[8:11]
	v_mfma_f32_16x16x32_bf16 v[4:7], v[168:171], v[212:215], v[4:7]
	v_mfma_f32_16x16x32_bf16 v[4:7], v[172:175], v[216:219], v[4:7]
	s_barrier
	v_mfma_f32_16x16x32_bf16 v[0:3], v[176:179], v[212:215], v[0:3]
	v_mfma_f32_16x16x32_bf16 v[0:3], v[184:187], v[216:219], v[0:3]
	s_setprio 0
	s_add_i32 s86, s86, 2
	s_add_u32 s84, s84, 0x100
	s_addc_u32 s85, s85, 0
	s_cmp_gt_u32 s86, 41
	s_mov_b64 s[52:53], s[54:55]
	s_cbranch_scc0 .LBB0_804
	s_and_b64 vcc, exec, s[18:19]
	s_cbranch_vccz .LBB0_807
	s_barrier

.LBB0_934:
	s_ashr_i32 s53, s52, 31
	s_lshl_b64 s[54:55], s[52:53], 19
	s_add_u32 s54, s80, s54
	s_addc_u32 s55, s81, s55
	s_and_b64 s[56:57], s[10:11], exec
	s_cselect_b32 s53, s55, s61
	s_cselect_b32 s83, s54, s60
	s_ashr_i32 s49, s48, 31
	s_lshl_b64 s[56:57], s[48:49], 19
	s_add_u32 s56, s66, s56
	s_addc_u32 s57, s67, s57
	s_and_b64 s[64:65], s[10:11], exec
	s_cselect_b32 s49, s57, s63
	s_cselect_b32 s84, s56, s62
	s_add_u32 s60, s60, 0x40080
	s_addc_u32 s61, s61, 0
	s_add_u32 s85, s62, 0x100
	s_addc_u32 s86, s63, 0
	s_mov_b32 s87, -2
	ds_read_b128 v[152:155], v148
	ds_read_b128 v[156:159], v148 offset:1024
	ds_read_b128 v[160:163], v148 offset:2048
	ds_read_b128 v[164:167], v148 offset:3072
	ds_read_b128 v[168:171], v149
	ds_read_b128 v[172:175], v149 offset:1024
	ds_read_b128 v[176:179], v149 offset:2048
	ds_read_b128 v[184:187], v149 offset:3072
	s_add_u32 s62, s60, 0xfffc0080
	s_addc_u32 s63, s61, -1
	s_cmp_eq_u32 s87, 12
	s_cselect_b32 s65, s53, s63
	s_cselect_b32 s64, s83, s62
	s_cselect_b32 s63, s49, s86
	s_cselect_b32 s62, s84, s85
	v_lshl_add_u64 v[220:221], s[60:61], 0, v[138:139]
	s_add_i32 m0, s69, 0xc000
	ds_read_b128 v[188:191], v150
	ds_read_b128 v[192:195], v150 offset:1024
	ds_read_b128 v[196:199], v150 offset:2048
	ds_read_b128 v[200:203], v150 offset:3072
	ds_read_b128 v[204:207], v150 offset:4096
	ds_read_b128 v[208:211], v150 offset:5120
	ds_read_b128 v[212:215], v150 offset:6144
	ds_read_b128 v[216:219], v150 offset:7168
	global_load_lds_dwordx4 v[220:221], off
	v_lshl_add_u64 v[220:221], s[60:61], 0, v[140:141]
	s_add_i32 m0, s69, 0xe000
	s_nop 0
	global_load_lds_dwordx4 v[220:221], off
	s_waitcnt vmcnt(8)
	s_waitcnt lgkmcnt(0)
	s_barrier
	s_setprio 1
	s_waitcnt lgkmcnt(0)
	v_mfma_f32_16x16x32_bf16 v[124:127], v[152:155], v[188:191], 0
	v_mfma_f32_16x16x32_bf16 v[124:127], v[156:159], v[192:195], v[124:127]
	v_mfma_f32_16x16x32_bf16 v[120:123], v[160:163], v[188:191], 0
	v_mfma_f32_16x16x32_bf16 v[120:123], v[164:167], v[192:195], v[120:123]
	v_mfma_f32_16x16x32_bf16 v[116:119], v[152:155], v[196:199], 0
	v_mfma_f32_16x16x32_bf16 v[116:119], v[156:159], v[200:203], v[116:119]
	v_mfma_f32_16x16x32_bf16 v[112:115], v[160:163], v[196:199], 0
	v_mfma_f32_16x16x32_bf16 v[112:115], v[164:167], v[200:203], v[112:115]
	v_mfma_f32_16x16x32_bf16 v[108:111], v[152:155], v[204:207], 0
	v_mfma_f32_16x16x32_bf16 v[108:111], v[156:159], v[208:211], v[108:111]
	v_mfma_f32_16x16x32_bf16 v[104:107], v[160:163], v[204:207], 0
	v_mfma_f32_16x16x32_bf16 v[104:107], v[164:167], v[208:211], v[104:107]
	v_mfma_f32_16x16x32_bf16 v[100:103], v[152:155], v[212:215], 0
	v_mfma_f32_16x16x32_bf16 v[100:103], v[156:159], v[216:219], v[100:103]
	v_mfma_f32_16x16x32_bf16 v[96:99], v[160:163], v[212:215], 0
	v_mfma_f32_16x16x32_bf16 v[96:99], v[164:167], v[216:219], v[96:99]
	s_setprio 0
	s_setprio 1
	v_mfma_f32_16x16x32_bf16 v[76:79], v[168:171], v[188:191], 0
	v_mfma_f32_16x16x32_bf16 v[76:79], v[172:175], v[192:195], v[76:79]
	v_mfma_f32_16x16x32_bf16 v[68:71], v[176:179], v[188:191], 0
	v_mfma_f32_16x16x32_bf16 v[68:71], v[184:187], v[192:195], v[68:71]
	v_mfma_f32_16x16x32_bf16 v[60:63], v[168:171], v[196:199], 0
	v_mfma_f32_16x16x32_bf16 v[60:63], v[172:175], v[200:203], v[60:63]
	v_mfma_f32_16x16x32_bf16 v[52:55], v[176:179], v[196:199], 0
	v_mfma_f32_16x16x32_bf16 v[52:55], v[184:187], v[200:203], v[52:55]
	v_mfma_f32_16x16x32_bf16 v[44:47], v[168:171], v[204:207], 0
	v_mfma_f32_16x16x32_bf16 v[44:47], v[172:175], v[208:211], v[44:47]
	v_mfma_f32_16x16x32_bf16 v[40:43], v[176:179], v[204:207], 0
	v_mfma_f32_16x16x32_bf16 v[40:43], v[184:187], v[208:211], v[40:43]
	v_mfma_f32_16x16x32_bf16 v[36:39], v[168:171], v[212:215], 0
	v_mfma_f32_16x16x32_bf16 v[36:39], v[172:175], v[216:219], v[36:39]
	s_barrier
	v_mfma_f32_16x16x32_bf16 v[32:35], v[176:179], v[212:215], 0
	v_mfma_f32_16x16x32_bf16 v[32:35], v[184:187], v[216:219], v[32:35]
	s_setprio 0
	s_add_i32 s79, s77, s68
	v_lshl_add_u64 v[220:221], s[62:63], 0, v[130:131]
	s_mov_b32 m0, s79
	ds_read_b128 v[188:191], v150 offset:16384
	ds_read_b128 v[192:195], v150 offset:17408
	ds_read_b128 v[196:199], v150 offset:18432
	ds_read_b128 v[200:203], v150 offset:19456
	ds_read_b128 v[204:207], v150 offset:20480
	ds_read_b128 v[208:211], v150 offset:21504
	ds_read_b128 v[212:215], v150 offset:22528
	ds_read_b128 v[216:219], v150 offset:23552
	global_load_lds_dwordx4 v[220:221], off
	s_add_i32 m0, s79, 0x2000
	s_add_u32 s88, s62, 0x40000
	v_lshl_add_u64 v[222:223], s[62:63], 0, v[134:135]
	s_addc_u32 s89, s63, 0
	s_add_i32 s79, s82, s68
	global_load_lds_dwordx4 v[222:223], off
	v_lshl_add_u64 v[224:225], s[88:89], 0, v[130:131]
	s_mov_b32 m0, s79
	v_lshl_add_u64 v[226:227], s[64:65], 0, v[132:133]
	global_load_lds_dwordx4 v[224:225], off
	v_lshl_add_u64 v[224:225], s[88:89], 0, v[134:135]
	s_add_i32 m0, s79, 0x2000
	s_nop 0
	global_load_lds_dwordx4 v[224:225], off
	v_lshl_add_u64 v[224:225], s[64:65], 0, v[128:129]
	s_mov_b32 m0, s69
	s_nop 0
	global_load_lds_dwordx4 v[224:225], off
	s_mov_b32 m0, s70
	s_nop 0
	global_load_lds_dwordx4 v[226:227], off
	s_waitcnt vmcnt(8)
	s_waitcnt lgkmcnt(0)
	s_barrier
	s_setprio 1
	s_waitcnt lgkmcnt(0)
	v_mfma_f32_16x16x32_bf16 v[92:95], v[152:155], v[188:191], 0
	v_mfma_f32_16x16x32_bf16 v[92:95], v[156:159], v[192:195], v[92:95]
	v_mfma_f32_16x16x32_bf16 v[88:91], v[160:163], v[188:191], 0
	v_mfma_f32_16x16x32_bf16 v[88:91], v[164:167], v[192:195], v[88:91]
	v_mfma_f32_16x16x32_bf16 v[84:87], v[152:155], v[196:199], 0
	v_mfma_f32_16x16x32_bf16 v[84:87], v[156:159], v[200:203], v[84:87]
	v_mfma_f32_16x16x32_bf16 v[80:83], v[160:163], v[196:199], 0
	v_mfma_f32_16x16x32_bf16 v[80:83], v[164:167], v[200:203], v[80:83]
	v_mfma_f32_16x16x32_bf16 v[72:75], v[152:155], v[204:207], 0
	v_mfma_f32_16x16x32_bf16 v[72:75], v[156:159], v[208:211], v[72:75]
	v_mfma_f32_16x16x32_bf16 v[64:67], v[160:163], v[204:207], 0
	v_mfma_f32_16x16x32_bf16 v[64:67], v[164:167], v[208:211], v[64:67]
	v_mfma_f32_16x16x32_bf16 v[56:59], v[152:155], v[212:215], 0
	v_mfma_f32_16x16x32_bf16 v[56:59], v[156:159], v[216:219], v[56:59]
	v_mfma_f32_16x16x32_bf16 v[48:51], v[160:163], v[212:215], 0
	v_mfma_f32_16x16x32_bf16 v[48:51], v[164:167], v[216:219], v[48:51]
	s_setprio 0
	s_setprio 1
	v_mfma_f32_16x16x32_bf16 v[28:31], v[168:171], v[188:191], 0
	v_mfma_f32_16x16x32_bf16 v[28:31], v[172:175], v[192:195], v[28:31]
	v_mfma_f32_16x16x32_bf16 v[24:27], v[176:179], v[188:191], 0
	v_mfma_f32_16x16x32_bf16 v[24:27], v[184:187], v[192:195], v[24:27]
	v_mfma_f32_16x16x32_bf16 v[20:23], v[168:171], v[196:199], 0
	v_mfma_f32_16x16x32_bf16 v[20:23], v[172:175], v[200:203], v[20:23]
	v_mfma_f32_16x16x32_bf16 v[16:19], v[176:179], v[196:199], 0
	v_mfma_f32_16x16x32_bf16 v[16:19], v[184:187], v[200:203], v[16:19]
	v_mfma_f32_16x16x32_bf16 v[12:15], v[168:171], v[204:207], 0
	v_mfma_f32_16x16x32_bf16 v[12:15], v[172:175], v[208:211], v[12:15]
	v_mfma_f32_16x16x32_bf16 v[8:11], v[176:179], v[204:207], 0
	v_mfma_f32_16x16x32_bf16 v[8:11], v[184:187], v[208:211], v[8:11]
	v_mfma_f32_16x16x32_bf16 v[4:7], v[168:171], v[212:215], 0
	v_mfma_f32_16x16x32_bf16 v[4:7], v[172:175], v[216:219], v[4:7]
	s_barrier
	v_mfma_f32_16x16x32_bf16 v[0:3], v[176:179], v[212:215], 0
	v_mfma_f32_16x16x32_bf16 v[0:3], v[184:187], v[216:219], v[0:3]
	s_setprio 0
	s_branch .Lmid_gemm6
.LBB0_935:
	ds_read_b128 v[152:155], v148
	ds_read_b128 v[156:159], v148 offset:1024
	ds_read_b128 v[160:163], v148 offset:2048
	ds_read_b128 v[164:167], v148 offset:3072
	ds_read_b128 v[168:171], v149
	ds_read_b128 v[172:175], v149 offset:1024
	ds_read_b128 v[176:179], v149 offset:2048
	ds_read_b128 v[184:187], v149 offset:3072
	s_add_u32 s62, s60, 0xfffc0080
	s_addc_u32 s63, s61, -1
	s_cmp_eq_u32 s87, 12
	s_cselect_b32 s65, s53, s63
	s_cselect_b32 s64, s83, s62
	s_cselect_b32 s63, s49, s86
	s_cselect_b32 s62, s84, s85
	v_lshl_add_u64 v[220:221], s[60:61], 0, v[138:139]
	s_add_i32 m0, s69, 0xc000
	ds_read_b128 v[188:191], v150
	ds_read_b128 v[192:195], v150 offset:1024
	ds_read_b128 v[196:199], v150 offset:2048
	ds_read_b128 v[200:203], v150 offset:3072
	ds_read_b128 v[204:207], v150 offset:4096
	ds_read_b128 v[208:211], v150 offset:5120
	ds_read_b128 v[212:215], v150 offset:6144
	ds_read_b128 v[216:219], v150 offset:7168
	global_load_lds_dwordx4 v[220:221], off
	v_lshl_add_u64 v[220:221], s[60:61], 0, v[140:141]
	s_add_i32 m0, s69, 0xe000
	s_nop 0
	global_load_lds_dwordx4 v[220:221], off
	s_waitcnt vmcnt(8)
	s_waitcnt lgkmcnt(0)
	s_barrier
	s_setprio 1
	s_waitcnt lgkmcnt(0)
	v_mfma_f32_16x16x32_bf16 v[124:127], v[152:155], v[188:191], v[124:127]
	v_mfma_f32_16x16x32_bf16 v[124:127], v[156:159], v[192:195], v[124:127]
	v_mfma_f32_16x16x32_bf16 v[120:123], v[160:163], v[188:191], v[120:123]
	v_mfma_f32_16x16x32_bf16 v[120:123], v[164:167], v[192:195], v[120:123]
	v_mfma_f32_16x16x32_bf16 v[116:119], v[152:155], v[196:199], v[116:119]
	v_mfma_f32_16x16x32_bf16 v[116:119], v[156:159], v[200:203], v[116:119]
	v_mfma_f32_16x16x32_bf16 v[112:115], v[160:163], v[196:199], v[112:115]
	v_mfma_f32_16x16x32_bf16 v[112:115], v[164:167], v[200:203], v[112:115]
	v_mfma_f32_16x16x32_bf16 v[108:111], v[152:155], v[204:207], v[108:111]
	v_mfma_f32_16x16x32_bf16 v[108:111], v[156:159], v[208:211], v[108:111]
	v_mfma_f32_16x16x32_bf16 v[104:107], v[160:163], v[204:207], v[104:107]
	v_mfma_f32_16x16x32_bf16 v[104:107], v[164:167], v[208:211], v[104:107]
	v_mfma_f32_16x16x32_bf16 v[100:103], v[152:155], v[212:215], v[100:103]
	v_mfma_f32_16x16x32_bf16 v[100:103], v[156:159], v[216:219], v[100:103]
	v_mfma_f32_16x16x32_bf16 v[96:99], v[160:163], v[212:215], v[96:99]
	v_mfma_f32_16x16x32_bf16 v[96:99], v[164:167], v[216:219], v[96:99]
	s_setprio 0
	s_setprio 1
	v_mfma_f32_16x16x32_bf16 v[76:79], v[168:171], v[188:191], v[76:79]
	v_mfma_f32_16x16x32_bf16 v[76:79], v[172:175], v[192:195], v[76:79]
	v_mfma_f32_16x16x32_bf16 v[68:71], v[176:179], v[188:191], v[68:71]
	v_mfma_f32_16x16x32_bf16 v[68:71], v[184:187], v[192:195], v[68:71]
	v_mfma_f32_16x16x32_bf16 v[60:63], v[168:171], v[196:199], v[60:63]
	v_mfma_f32_16x16x32_bf16 v[60:63], v[172:175], v[200:203], v[60:63]
	v_mfma_f32_16x16x32_bf16 v[52:55], v[176:179], v[196:199], v[52:55]
	v_mfma_f32_16x16x32_bf16 v[52:55], v[184:187], v[200:203], v[52:55]
	v_mfma_f32_16x16x32_bf16 v[44:47], v[168:171], v[204:207], v[44:47]
	v_mfma_f32_16x16x32_bf16 v[44:47], v[172:175], v[208:211], v[44:47]
	v_mfma_f32_16x16x32_bf16 v[40:43], v[176:179], v[204:207], v[40:43]
	v_mfma_f32_16x16x32_bf16 v[40:43], v[184:187], v[208:211], v[40:43]
	v_mfma_f32_16x16x32_bf16 v[36:39], v[168:171], v[212:215], v[36:39]
	v_mfma_f32_16x16x32_bf16 v[36:39], v[172:175], v[216:219], v[36:39]
	s_barrier
	v_mfma_f32_16x16x32_bf16 v[32:35], v[176:179], v[212:215], v[32:35]
	v_mfma_f32_16x16x32_bf16 v[32:35], v[184:187], v[216:219], v[32:35]
	s_setprio 0
	s_add_i32 s79, s77, s68
	v_lshl_add_u64 v[220:221], s[62:63], 0, v[130:131]
	s_mov_b32 m0, s79
	ds_read_b128 v[188:191], v150 offset:16384
	ds_read_b128 v[192:195], v150 offset:17408
	ds_read_b128 v[196:199], v150 offset:18432
	ds_read_b128 v[200:203], v150 offset:19456
	ds_read_b128 v[204:207], v150 offset:20480
	ds_read_b128 v[208:211], v150 offset:21504
	ds_read_b128 v[212:215], v150 offset:22528
	ds_read_b128 v[216:219], v150 offset:23552
	global_load_lds_dwordx4 v[220:221], off
	s_add_i32 m0, s79, 0x2000
	s_add_u32 s88, s62, 0x40000
	v_lshl_add_u64 v[222:223], s[62:63], 0, v[134:135]
	s_addc_u32 s89, s63, 0
	s_add_i32 s79, s82, s68
	global_load_lds_dwordx4 v[222:223], off
	v_lshl_add_u64 v[224:225], s[88:89], 0, v[130:131]
	s_mov_b32 m0, s79
	v_lshl_add_u64 v[226:227], s[64:65], 0, v[132:133]
	global_load_lds_dwordx4 v[224:225], off
	v_lshl_add_u64 v[224:225], s[88:89], 0, v[134:135]
	s_add_i32 m0, s79, 0x2000
	s_nop 0
	global_load_lds_dwordx4 v[224:225], off
	v_lshl_add_u64 v[224:225], s[64:65], 0, v[128:129]
	s_mov_b32 m0, s69
	s_nop 0
	global_load_lds_dwordx4 v[224:225], off
	s_mov_b32 m0, s70
	s_nop 0
	global_load_lds_dwordx4 v[226:227], off
	s_waitcnt vmcnt(8)
	s_waitcnt lgkmcnt(0)
	s_barrier
	s_setprio 1
	s_waitcnt lgkmcnt(0)
	v_mfma_f32_16x16x32_bf16 v[92:95], v[152:155], v[188:191], v[92:95]
	v_mfma_f32_16x16x32_bf16 v[92:95], v[156:159], v[192:195], v[92:95]
	v_mfma_f32_16x16x32_bf16 v[88:91], v[160:163], v[188:191], v[88:91]
	v_mfma_f32_16x16x32_bf16 v[88:91], v[164:167], v[192:195], v[88:91]
	v_mfma_f32_16x16x32_bf16 v[84:87], v[152:155], v[196:199], v[84:87]
	v_mfma_f32_16x16x32_bf16 v[84:87], v[156:159], v[200:203], v[84:87]
	v_mfma_f32_16x16x32_bf16 v[80:83], v[160:163], v[196:199], v[80:83]
	v_mfma_f32_16x16x32_bf16 v[80:83], v[164:167], v[200:203], v[80:83]
	v_mfma_f32_16x16x32_bf16 v[72:75], v[152:155], v[204:207], v[72:75]
	v_mfma_f32_16x16x32_bf16 v[72:75], v[156:159], v[208:211], v[72:75]
	v_mfma_f32_16x16x32_bf16 v[64:67], v[160:163], v[204:207], v[64:67]
	v_mfma_f32_16x16x32_bf16 v[64:67], v[164:167], v[208:211], v[64:67]
	v_mfma_f32_16x16x32_bf16 v[56:59], v[152:155], v[212:215], v[56:59]
	v_mfma_f32_16x16x32_bf16 v[56:59], v[156:159], v[216:219], v[56:59]
	v_mfma_f32_16x16x32_bf16 v[48:51], v[160:163], v[212:215], v[48:51]
	v_mfma_f32_16x16x32_bf16 v[48:51], v[164:167], v[216:219], v[48:51]
	s_setprio 0
	s_setprio 1
	v_mfma_f32_16x16x32_bf16 v[28:31], v[168:171], v[188:191], v[28:31]
	v_mfma_f32_16x16x32_bf16 v[28:31], v[172:175], v[192:195], v[28:31]
	v_mfma_f32_16x16x32_bf16 v[24:27], v[176:179], v[188:191], v[24:27]
	v_mfma_f32_16x16x32_bf16 v[24:27], v[184:187], v[192:195], v[24:27]
	v_mfma_f32_16x16x32_bf16 v[20:23], v[168:171], v[196:199], v[20:23]
	v_mfma_f32_16x16x32_bf16 v[20:23], v[172:175], v[200:203], v[20:23]
	v_mfma_f32_16x16x32_bf16 v[16:19], v[176:179], v[196:199], v[16:19]
	v_mfma_f32_16x16x32_bf16 v[16:19], v[184:187], v[200:203], v[16:19]
	v_mfma_f32_16x16x32_bf16 v[12:15], v[168:171], v[204:207], v[12:15]
	v_mfma_f32_16x16x32_bf16 v[12:15], v[172:175], v[208:211], v[12:15]
	v_mfma_f32_16x16x32_bf16 v[8:11], v[176:179], v[204:207], v[8:11]
	v_mfma_f32_16x16x32_bf16 v[8:11], v[184:187], v[208:211], v[8:11]
	v_mfma_f32_16x16x32_bf16 v[4:7], v[168:171], v[212:215], v[4:7]
	v_mfma_f32_16x16x32_bf16 v[4:7], v[172:175], v[216:219], v[4:7]
	s_barrier
	v_mfma_f32_16x16x32_bf16 v[0:3], v[176:179], v[212:215], v[0:3]
	v_mfma_f32_16x16x32_bf16 v[0:3], v[184:187], v[216:219], v[0:3]
	s_setprio 0
.Lmid_gemm6:
	s_add_i32 s79, 0, 0x18000
	v_add_u32_e32 v151, s79, v147
	s_add_i32 s88, 0, 0x1c000
	ds_read_b128 v[152:155], v151
	ds_read_b128 v[156:159], v151 offset:1024
	ds_read_b128 v[160:163], v151 offset:2048
	ds_read_b128 v[164:167], v151 offset:3072
	v_add_u32_e32 v151, s88, v147
	ds_read_b128 v[168:171], v151
	ds_read_b128 v[172:175], v151 offset:1024
	ds_read_b128 v[176:179], v151 offset:2048
	ds_read_b128 v[184:187], v151 offset:3072
	s_add_u32 s64, s64, 0x40000
	s_addc_u32 s65, s65, 0
	s_mov_b32 m0, s71
	v_lshl_add_u64 v[228:229], s[64:65], 0, v[128:129]
	ds_read_b128 v[188:191], v150 offset:32768
	ds_read_b128 v[192:195], v150 offset:33792
	ds_read_b128 v[196:199], v150 offset:34816
	ds_read_b128 v[200:203], v150 offset:35840
	ds_read_b128 v[204:207], v150 offset:36864
	ds_read_b128 v[208:211], v150 offset:37888
	ds_read_b128 v[212:215], v150 offset:38912
	ds_read_b128 v[216:219], v150 offset:39936
	global_load_lds_dwordx4 v[228:229], off
	v_lshl_add_u64 v[228:229], s[64:65], 0, v[132:133]
	s_mov_b32 m0, s72
	s_nop 0
	global_load_lds_dwordx4 v[228:229], off
	s_waitcnt vmcnt(8)
	s_waitcnt lgkmcnt(0)
	s_barrier
	s_setprio 1
	s_waitcnt lgkmcnt(0)
	v_mfma_f32_16x16x32_bf16 v[124:127], v[152:155], v[188:191], v[124:127]
	v_mfma_f32_16x16x32_bf16 v[124:127], v[156:159], v[192:195], v[124:127]
	v_mfma_f32_16x16x32_bf16 v[120:123], v[160:163], v[188:191], v[120:123]
	v_mfma_f32_16x16x32_bf16 v[120:123], v[164:167], v[192:195], v[120:123]
	v_mfma_f32_16x16x32_bf16 v[116:119], v[152:155], v[196:199], v[116:119]
	v_mfma_f32_16x16x32_bf16 v[116:119], v[156:159], v[200:203], v[116:119]
	v_mfma_f32_16x16x32_bf16 v[112:115], v[160:163], v[196:199], v[112:115]
	v_mfma_f32_16x16x32_bf16 v[112:115], v[164:167], v[200:203], v[112:115]
	v_mfma_f32_16x16x32_bf16 v[108:111], v[152:155], v[204:207], v[108:111]
	v_mfma_f32_16x16x32_bf16 v[108:111], v[156:159], v[208:211], v[108:111]
	v_mfma_f32_16x16x32_bf16 v[104:107], v[160:163], v[204:207], v[104:107]
	v_mfma_f32_16x16x32_bf16 v[104:107], v[164:167], v[208:211], v[104:107]
	v_mfma_f32_16x16x32_bf16 v[100:103], v[152:155], v[212:215], v[100:103]
	v_mfma_f32_16x16x32_bf16 v[100:103], v[156:159], v[216:219], v[100:103]
	v_mfma_f32_16x16x32_bf16 v[96:99], v[160:163], v[212:215], v[96:99]
	v_mfma_f32_16x16x32_bf16 v[96:99], v[164:167], v[216:219], v[96:99]
	s_setprio 0
	s_setprio 1
	v_mfma_f32_16x16x32_bf16 v[76:79], v[168:171], v[188:191], v[76:79]
	v_mfma_f32_16x16x32_bf16 v[76:79], v[172:175], v[192:195], v[76:79]
	v_mfma_f32_16x16x32_bf16 v[68:71], v[176:179], v[188:191], v[68:71]
	v_mfma_f32_16x16x32_bf16 v[68:71], v[184:187], v[192:195], v[68:71]
	v_mfma_f32_16x16x32_bf16 v[60:63], v[168:171], v[196:199], v[60:63]
	v_mfma_f32_16x16x32_bf16 v[60:63], v[172:175], v[200:203], v[60:63]
	v_mfma_f32_16x16x32_bf16 v[52:55], v[176:179], v[196:199], v[52:55]
	v_mfma_f32_16x16x32_bf16 v[52:55], v[184:187], v[200:203], v[52:55]
	v_mfma_f32_16x16x32_bf16 v[44:47], v[168:171], v[204:207], v[44:47]
	v_mfma_f32_16x16x32_bf16 v[44:47], v[172:175], v[208:211], v[44:47]
	v_mfma_f32_16x16x32_bf16 v[40:43], v[176:179], v[204:207], v[40:43]
	v_mfma_f32_16x16x32_bf16 v[40:43], v[184:187], v[208:211], v[40:43]
	v_mfma_f32_16x16x32_bf16 v[36:39], v[168:171], v[212:215], v[36:39]
	v_mfma_f32_16x16x32_bf16 v[36:39], v[172:175], v[216:219], v[36:39]
	s_barrier
	v_mfma_f32_16x16x32_bf16 v[32:35], v[176:179], v[212:215], v[32:35]
	v_mfma_f32_16x16x32_bf16 v[32:35], v[184:187], v[216:219], v[32:35]
	s_setprio 0
	s_add_i32 s64, s79, s68
	v_lshl_add_u64 v[220:221], v[220:221], 0, s[12:13]
	s_mov_b32 m0, s64
	ds_read_b128 v[188:191], v150 offset:49152
	ds_read_b128 v[192:195], v150 offset:50176
	ds_read_b128 v[196:199], v150 offset:51200
	ds_read_b128 v[200:203], v150 offset:52224
	ds_read_b128 v[204:207], v150 offset:53248
	ds_read_b128 v[208:211], v150 offset:54272
	ds_read_b128 v[212:215], v150 offset:55296
	ds_read_b128 v[216:219], v150 offset:56320
	global_load_lds_dwordx4 v[220:221], off
	s_add_i32 m0, s64, 0x2000
	s_add_u32 s62, s62, 0x40080
	v_lshl_add_u64 v[220:221], v[222:223], 0, s[12:13]
	s_addc_u32 s63, s63, 0
	s_add_i32 s64, s88, s68
	global_load_lds_dwordx4 v[220:221], off
	v_lshl_add_u64 v[220:221], s[62:63], 0, v[130:131]
	s_mov_b32 m0, s64
	s_nop 0
	global_load_lds_dwordx4 v[220:221], off
	v_lshl_add_u64 v[220:221], s[62:63], 0, v[134:135]
	s_add_i32 m0, s64, 0x2000
	s_nop 0
	global_load_lds_dwordx4 v[220:221], off
	v_lshl_add_u64 v[220:221], v[224:225], 0, s[12:13]
	s_mov_b32 m0, s75
	s_nop 0
	global_load_lds_dwordx4 v[220:221], off
	v_lshl_add_u64 v[220:221], v[226:227], 0, s[12:13]
	s_mov_b32 m0, s76
	s_nop 0
	global_load_lds_dwordx4 v[220:221], off
	s_waitcnt vmcnt(8)
	s_waitcnt lgkmcnt(0)
	s_barrier
	s_setprio 1
	s_waitcnt lgkmcnt(0)
	v_mfma_f32_16x16x32_bf16 v[92:95], v[152:155], v[188:191], v[92:95]
	v_mfma_f32_16x16x32_bf16 v[92:95], v[156:159], v[192:195], v[92:95]
	v_mfma_f32_16x16x32_bf16 v[88:91], v[160:163], v[188:191], v[88:91]
	v_mfma_f32_16x16x32_bf16 v[88:91], v[164:167], v[192:195], v[88:91]
	v_mfma_f32_16x16x32_bf16 v[84:87], v[152:155], v[196:199], v[84:87]
	v_mfma_f32_16x16x32_bf16 v[84:87], v[156:159], v[200:203], v[84:87]
	v_mfma_f32_16x16x32_bf16 v[80:83], v[160:163], v[196:199], v[80:83]
	v_mfma_f32_16x16x32_bf16 v[80:83], v[164:167], v[200:203], v[80:83]
	v_mfma_f32_16x16x32_bf16 v[72:75], v[152:155], v[204:207], v[72:75]
	v_mfma_f32_16x16x32_bf16 v[72:75], v[156:159], v[208:211], v[72:75]
	v_mfma_f32_16x16x32_bf16 v[64:67], v[160:163], v[204:207], v[64:67]
	v_mfma_f32_16x16x32_bf16 v[64:67], v[164:167], v[208:211], v[64:67]
	v_mfma_f32_16x16x32_bf16 v[56:59], v[152:155], v[212:215], v[56:59]
	v_mfma_f32_16x16x32_bf16 v[56:59], v[156:159], v[216:219], v[56:59]
	v_mfma_f32_16x16x32_bf16 v[48:51], v[160:163], v[212:215], v[48:51]
	v_mfma_f32_16x16x32_bf16 v[48:51], v[164:167], v[216:219], v[48:51]
	s_setprio 0
	s_setprio 1
	v_mfma_f32_16x16x32_bf16 v[28:31], v[168:171], v[188:191], v[28:31]
	v_mfma_f32_16x16x32_bf16 v[28:31], v[172:175], v[192:195], v[28:31]
	v_mfma_f32_16x16x32_bf16 v[24:27], v[176:179], v[188:191], v[24:27]
	v_mfma_f32_16x16x32_bf16 v[24:27], v[184:187], v[192:195], v[24:27]
	v_mfma_f32_16x16x32_bf16 v[20:23], v[168:171], v[196:199], v[20:23]
	v_mfma_f32_16x16x32_bf16 v[20:23], v[172:175], v[200:203], v[20:23]
	v_mfma_f32_16x16x32_bf16 v[16:19], v[176:179], v[196:199], v[16:19]
	v_mfma_f32_16x16x32_bf16 v[16:19], v[184:187], v[200:203], v[16:19]
	v_mfma_f32_16x16x32_bf16 v[12:15], v[168:171], v[204:207], v[12:15]
	v_mfma_f32_16x16x32_bf16 v[12:15], v[172:175], v[208:211], v[12:15]
	v_mfma_f32_16x16x32_bf16 v[8:11], v[176:179], v[204:207], v[8:11]
	v_mfma_f32_16x16x32_bf16 v[8:11], v[184:187], v[208:211], v[8:11]
	v_mfma_f32_16x16x32_bf16 v[4:7], v[168:171], v[212:215], v[4:7]
	v_mfma_f32_16x16x32_bf16 v[4:7], v[172:175], v[216:219], v[4:7]
	s_barrier
	v_mfma_f32_16x16x32_bf16 v[0:3], v[176:179], v[212:215], v[0:3]
	v_mfma_f32_16x16x32_bf16 v[0:3], v[184:187], v[216:219], v[0:3]
	s_setprio 0
	s_add_i32 s87, s87, 2
	s_add_u32 s60, s60, 0x100
	s_addc_u32 s61, s61, 0
	s_add_u32 s85, s85, 0x100
	s_addc_u32 s86, s86, 0
	s_cmp_gt_u32 s87, 13
	s_cbranch_scc0 .LBB0_935
	s_and_b64 vcc, exec, s[16:17]
	s_cbranch_vccz .LBB0_938
	s_barrier

.LBB0_950:
	s_ashr_i32 s37, s36, 31
	s_lshl_b64 s[44:45], s[36:37], 19
	s_add_u32 s44, s80, s44
	s_addc_u32 s45, s81, s45
	s_and_b64 s[46:47], s[10:11], exec
	s_cselect_b32 s37, s45, s53
	s_cselect_b32 s72, s44, s52
	s_ashr_i32 s19, s18, 31
	s_lshl_b64 s[46:47], s[18:19], 19
	s_add_u32 s46, s58, s46
	s_addc_u32 s47, s59, s47
	s_and_b64 s[56:57], s[10:11], exec
	s_cselect_b32 s19, s47, s55
	s_cselect_b32 s73, s46, s54
	s_add_u32 s52, s52, 0x40080
	s_addc_u32 s53, s53, 0
	s_add_u32 s74, s54, 0x100
	s_addc_u32 s75, s55, 0
	s_mov_b32 s76, -2
	ds_read_b128 v[140:143], v147
	ds_read_b128 v[150:153], v147 offset:1024
	ds_read_b128 v[154:157], v147 offset:2048
	ds_read_b128 v[158:161], v147 offset:3072
	ds_read_b128 v[162:165], v148
	ds_read_b128 v[166:169], v148 offset:1024
	ds_read_b128 v[170:173], v148 offset:2048
	ds_read_b128 v[174:177], v148 offset:3072
	s_add_u32 s54, s52, 0xfffc0080
	s_addc_u32 s55, s53, -1
	s_cmp_eq_u32 s76, 12
	s_cselect_b32 s57, s37, s55
	s_cselect_b32 s56, s72, s54
	s_cselect_b32 s55, s19, s75
	s_cselect_b32 s54, s73, s74
	v_lshl_add_u64 v[178:179], s[52:53], 0, v[132:133]
	s_add_i32 m0, s49, 0xc000
	ds_read_b128 v[184:187], v149
	ds_read_b128 v[188:191], v149 offset:1024
	ds_read_b128 v[192:195], v149 offset:2048
	ds_read_b128 v[196:199], v149 offset:3072
	ds_read_b128 v[200:203], v149 offset:4096
	ds_read_b128 v[204:207], v149 offset:5120
	ds_read_b128 v[208:211], v149 offset:6144
	ds_read_b128 v[212:215], v149 offset:7168
	global_load_lds_dwordx4 v[178:179], off
	v_lshl_add_u64 v[178:179], s[52:53], 0, v[134:135]
	s_add_i32 m0, s49, 0xe000
	s_nop 0
	global_load_lds_dwordx4 v[178:179], off
	s_waitcnt vmcnt(8)
	s_waitcnt lgkmcnt(0)
	s_barrier
	s_setprio 1
	s_waitcnt lgkmcnt(0)
	v_mfma_f32_16x16x32_bf16 v[124:127], v[140:143], v[184:187], 0
	v_mfma_f32_16x16x32_bf16 v[124:127], v[150:153], v[188:191], v[124:127]
	v_mfma_f32_16x16x32_bf16 v[120:123], v[154:157], v[184:187], 0
	v_mfma_f32_16x16x32_bf16 v[120:123], v[158:161], v[188:191], v[120:123]
	v_mfma_f32_16x16x32_bf16 v[108:111], v[140:143], v[192:195], 0
	v_mfma_f32_16x16x32_bf16 v[108:111], v[150:153], v[196:199], v[108:111]
	v_mfma_f32_16x16x32_bf16 v[104:107], v[154:157], v[192:195], 0
	v_mfma_f32_16x16x32_bf16 v[104:107], v[158:161], v[196:199], v[104:107]
	v_mfma_f32_16x16x32_bf16 v[92:95], v[140:143], v[200:203], 0
	v_mfma_f32_16x16x32_bf16 v[92:95], v[150:153], v[204:207], v[92:95]
	v_mfma_f32_16x16x32_bf16 v[88:91], v[154:157], v[200:203], 0
	v_mfma_f32_16x16x32_bf16 v[88:91], v[158:161], v[204:207], v[88:91]
	v_mfma_f32_16x16x32_bf16 v[76:79], v[140:143], v[208:211], 0
	v_mfma_f32_16x16x32_bf16 v[76:79], v[150:153], v[212:215], v[76:79]
	v_mfma_f32_16x16x32_bf16 v[72:75], v[154:157], v[208:211], 0
	v_mfma_f32_16x16x32_bf16 v[72:75], v[158:161], v[212:215], v[72:75]
	s_setprio 0
	s_setprio 1
	v_mfma_f32_16x16x32_bf16 v[116:119], v[162:165], v[184:187], 0
	v_mfma_f32_16x16x32_bf16 v[116:119], v[166:169], v[188:191], v[116:119]
	v_mfma_f32_16x16x32_bf16 v[112:115], v[170:173], v[184:187], 0
	v_mfma_f32_16x16x32_bf16 v[112:115], v[174:177], v[188:191], v[112:115]
	v_mfma_f32_16x16x32_bf16 v[100:103], v[162:165], v[192:195], 0
	v_mfma_f32_16x16x32_bf16 v[100:103], v[166:169], v[196:199], v[100:103]
	v_mfma_f32_16x16x32_bf16 v[96:99], v[170:173], v[192:195], 0
	v_mfma_f32_16x16x32_bf16 v[96:99], v[174:177], v[196:199], v[96:99]
	v_mfma_f32_16x16x32_bf16 v[84:87], v[162:165], v[200:203], 0
	v_mfma_f32_16x16x32_bf16 v[84:87], v[166:169], v[204:207], v[84:87]
	v_mfma_f32_16x16x32_bf16 v[80:83], v[170:173], v[200:203], 0
	v_mfma_f32_16x16x32_bf16 v[80:83], v[174:177], v[204:207], v[80:83]
	v_mfma_f32_16x16x32_bf16 v[68:71], v[162:165], v[208:211], 0
	v_mfma_f32_16x16x32_bf16 v[68:71], v[166:169], v[212:215], v[68:71]
	s_barrier
	v_mfma_f32_16x16x32_bf16 v[64:67], v[170:173], v[208:211], 0
	v_mfma_f32_16x16x32_bf16 v[64:67], v[174:177], v[212:215], v[64:67]
	s_setprio 0
	s_add_i32 s77, s68, s60
	v_lshl_add_u64 v[178:179], s[54:55], 0, v[130:131]
	s_mov_b32 m0, s77
	ds_read_b128 v[184:187], v149 offset:16384
	ds_read_b128 v[188:191], v149 offset:17408
	ds_read_b128 v[192:195], v149 offset:18432
	ds_read_b128 v[196:199], v149 offset:19456
	ds_read_b128 v[200:203], v149 offset:20480
	ds_read_b128 v[204:207], v149 offset:21504
	ds_read_b128 v[208:211], v149 offset:22528
	ds_read_b128 v[212:215], v149 offset:23552
	global_load_lds_dwordx4 v[178:179], off
	s_add_i32 m0, s77, 0x2000
	s_add_u32 s82, s54, 0x40000
	v_lshl_add_u64 v[216:217], s[54:55], 0, v[128:129]
	s_addc_u32 s83, s55, 0
	s_add_i32 s77, s69, s60
	global_load_lds_dwordx4 v[216:217], off
	v_lshl_add_u64 v[218:219], s[82:83], 0, v[130:131]
	s_mov_b32 m0, s77
	v_lshl_add_u64 v[220:221], s[56:57], 0, v[128:129]
	global_load_lds_dwordx4 v[218:219], off
	v_lshl_add_u64 v[218:219], s[82:83], 0, v[128:129]
	s_add_i32 m0, s77, 0x2000
	s_nop 0
	global_load_lds_dwordx4 v[218:219], off
	v_lshl_add_u64 v[218:219], s[56:57], 0, v[130:131]
	s_mov_b32 m0, s49
	s_nop 0
	global_load_lds_dwordx4 v[218:219], off
	s_mov_b32 m0, s62
	s_nop 0
	global_load_lds_dwordx4 v[220:221], off
	s_waitcnt vmcnt(8)
	s_waitcnt lgkmcnt(0)
	s_barrier
	s_setprio 1
	s_waitcnt lgkmcnt(0)
	v_mfma_f32_16x16x32_bf16 v[60:63], v[140:143], v[184:187], 0
	v_mfma_f32_16x16x32_bf16 v[60:63], v[150:153], v[188:191], v[60:63]
	v_mfma_f32_16x16x32_bf16 v[56:59], v[154:157], v[184:187], 0
	v_mfma_f32_16x16x32_bf16 v[56:59], v[158:161], v[188:191], v[56:59]
	v_mfma_f32_16x16x32_bf16 v[44:47], v[140:143], v[192:195], 0
	v_mfma_f32_16x16x32_bf16 v[44:47], v[150:153], v[196:199], v[44:47]
	v_mfma_f32_16x16x32_bf16 v[40:43], v[154:157], v[192:195], 0
	v_mfma_f32_16x16x32_bf16 v[40:43], v[158:161], v[196:199], v[40:43]
	v_mfma_f32_16x16x32_bf16 v[28:31], v[140:143], v[200:203], 0
	v_mfma_f32_16x16x32_bf16 v[28:31], v[150:153], v[204:207], v[28:31]
	v_mfma_f32_16x16x32_bf16 v[24:27], v[154:157], v[200:203], 0
	v_mfma_f32_16x16x32_bf16 v[24:27], v[158:161], v[204:207], v[24:27]
	v_mfma_f32_16x16x32_bf16 v[12:15], v[140:143], v[208:211], 0
	v_mfma_f32_16x16x32_bf16 v[12:15], v[150:153], v[212:215], v[12:15]
	v_mfma_f32_16x16x32_bf16 v[8:11], v[154:157], v[208:211], 0
	v_mfma_f32_16x16x32_bf16 v[8:11], v[158:161], v[212:215], v[8:11]
	s_setprio 0
	s_setprio 1
	v_mfma_f32_16x16x32_bf16 v[52:55], v[162:165], v[184:187], 0
	v_mfma_f32_16x16x32_bf16 v[52:55], v[166:169], v[188:191], v[52:55]
	v_mfma_f32_16x16x32_bf16 v[48:51], v[170:173], v[184:187], 0
	v_mfma_f32_16x16x32_bf16 v[48:51], v[174:177], v[188:191], v[48:51]
	v_mfma_f32_16x16x32_bf16 v[36:39], v[162:165], v[192:195], 0
	v_mfma_f32_16x16x32_bf16 v[36:39], v[166:169], v[196:199], v[36:39]
	v_mfma_f32_16x16x32_bf16 v[32:35], v[170:173], v[192:195], 0
	v_mfma_f32_16x16x32_bf16 v[32:35], v[174:177], v[196:199], v[32:35]
	v_mfma_f32_16x16x32_bf16 v[20:23], v[162:165], v[200:203], 0
	v_mfma_f32_16x16x32_bf16 v[20:23], v[166:169], v[204:207], v[20:23]
	v_mfma_f32_16x16x32_bf16 v[16:19], v[170:173], v[200:203], 0
	v_mfma_f32_16x16x32_bf16 v[16:19], v[174:177], v[204:207], v[16:19]
	v_mfma_f32_16x16x32_bf16 v[4:7], v[162:165], v[208:211], 0
	v_mfma_f32_16x16x32_bf16 v[4:7], v[166:169], v[212:215], v[4:7]
	s_barrier
	v_mfma_f32_16x16x32_bf16 v[0:3], v[170:173], v[208:211], 0
	v_mfma_f32_16x16x32_bf16 v[0:3], v[174:177], v[212:215], v[0:3]
	s_setprio 0
	s_branch .Lmid_gemm7
.LBB0_951:
	ds_read_b128 v[140:143], v147
	ds_read_b128 v[150:153], v147 offset:1024
	ds_read_b128 v[154:157], v147 offset:2048
	ds_read_b128 v[158:161], v147 offset:3072
	ds_read_b128 v[162:165], v148
	ds_read_b128 v[166:169], v148 offset:1024
	ds_read_b128 v[170:173], v148 offset:2048
	ds_read_b128 v[174:177], v148 offset:3072
	s_add_u32 s54, s52, 0xfffc0080
	s_addc_u32 s55, s53, -1
	s_cmp_eq_u32 s76, 12
	s_cselect_b32 s57, s37, s55
	s_cselect_b32 s56, s72, s54
	s_cselect_b32 s55, s19, s75
	s_cselect_b32 s54, s73, s74
	v_lshl_add_u64 v[178:179], s[52:53], 0, v[132:133]
	s_add_i32 m0, s49, 0xc000
	ds_read_b128 v[184:187], v149
	ds_read_b128 v[188:191], v149 offset:1024
	ds_read_b128 v[192:195], v149 offset:2048
	ds_read_b128 v[196:199], v149 offset:3072
	ds_read_b128 v[200:203], v149 offset:4096
	ds_read_b128 v[204:207], v149 offset:5120
	ds_read_b128 v[208:211], v149 offset:6144
	ds_read_b128 v[212:215], v149 offset:7168
	global_load_lds_dwordx4 v[178:179], off
	v_lshl_add_u64 v[178:179], s[52:53], 0, v[134:135]
	s_add_i32 m0, s49, 0xe000
	s_nop 0
	global_load_lds_dwordx4 v[178:179], off
	s_waitcnt vmcnt(8)
	s_waitcnt lgkmcnt(0)
	s_barrier
	s_setprio 1
	s_waitcnt lgkmcnt(0)
	v_mfma_f32_16x16x32_bf16 v[124:127], v[140:143], v[184:187], v[124:127]
	v_mfma_f32_16x16x32_bf16 v[124:127], v[150:153], v[188:191], v[124:127]
	v_mfma_f32_16x16x32_bf16 v[120:123], v[154:157], v[184:187], v[120:123]
	v_mfma_f32_16x16x32_bf16 v[120:123], v[158:161], v[188:191], v[120:123]
	v_mfma_f32_16x16x32_bf16 v[108:111], v[140:143], v[192:195], v[108:111]
	v_mfma_f32_16x16x32_bf16 v[108:111], v[150:153], v[196:199], v[108:111]
	v_mfma_f32_16x16x32_bf16 v[104:107], v[154:157], v[192:195], v[104:107]
	v_mfma_f32_16x16x32_bf16 v[104:107], v[158:161], v[196:199], v[104:107]
	v_mfma_f32_16x16x32_bf16 v[92:95], v[140:143], v[200:203], v[92:95]
	v_mfma_f32_16x16x32_bf16 v[92:95], v[150:153], v[204:207], v[92:95]
	v_mfma_f32_16x16x32_bf16 v[88:91], v[154:157], v[200:203], v[88:91]
	v_mfma_f32_16x16x32_bf16 v[88:91], v[158:161], v[204:207], v[88:91]
	v_mfma_f32_16x16x32_bf16 v[76:79], v[140:143], v[208:211], v[76:79]
	v_mfma_f32_16x16x32_bf16 v[76:79], v[150:153], v[212:215], v[76:79]
	v_mfma_f32_16x16x32_bf16 v[72:75], v[154:157], v[208:211], v[72:75]
	v_mfma_f32_16x16x32_bf16 v[72:75], v[158:161], v[212:215], v[72:75]
	s_setprio 0
	s_setprio 1
	v_mfma_f32_16x16x32_bf16 v[116:119], v[162:165], v[184:187], v[116:119]
	v_mfma_f32_16x16x32_bf16 v[116:119], v[166:169], v[188:191], v[116:119]
	v_mfma_f32_16x16x32_bf16 v[112:115], v[170:173], v[184:187], v[112:115]
	v_mfma_f32_16x16x32_bf16 v[112:115], v[174:177], v[188:191], v[112:115]
	v_mfma_f32_16x16x32_bf16 v[100:103], v[162:165], v[192:195], v[100:103]
	v_mfma_f32_16x16x32_bf16 v[100:103], v[166:169], v[196:199], v[100:103]
	v_mfma_f32_16x16x32_bf16 v[96:99], v[170:173], v[192:195], v[96:99]
	v_mfma_f32_16x16x32_bf16 v[96:99], v[174:177], v[196:199], v[96:99]
	v_mfma_f32_16x16x32_bf16 v[84:87], v[162:165], v[200:203], v[84:87]
	v_mfma_f32_16x16x32_bf16 v[84:87], v[166:169], v[204:207], v[84:87]
	v_mfma_f32_16x16x32_bf16 v[80:83], v[170:173], v[200:203], v[80:83]
	v_mfma_f32_16x16x32_bf16 v[80:83], v[174:177], v[204:207], v[80:83]
	v_mfma_f32_16x16x32_bf16 v[68:71], v[162:165], v[208:211], v[68:71]
	v_mfma_f32_16x16x32_bf16 v[68:71], v[166:169], v[212:215], v[68:71]
	s_barrier
	v_mfma_f32_16x16x32_bf16 v[64:67], v[170:173], v[208:211], v[64:67]
	v_mfma_f32_16x16x32_bf16 v[64:67], v[174:177], v[212:215], v[64:67]
	s_setprio 0
	s_add_i32 s77, s68, s60
	v_lshl_add_u64 v[178:179], s[54:55], 0, v[130:131]
	s_mov_b32 m0, s77
	ds_read_b128 v[184:187], v149 offset:16384
	ds_read_b128 v[188:191], v149 offset:17408
	ds_read_b128 v[192:195], v149 offset:18432
	ds_read_b128 v[196:199], v149 offset:19456
	ds_read_b128 v[200:203], v149 offset:20480
	ds_read_b128 v[204:207], v149 offset:21504
	ds_read_b128 v[208:211], v149 offset:22528
	ds_read_b128 v[212:215], v149 offset:23552
	global_load_lds_dwordx4 v[178:179], off
	s_add_i32 m0, s77, 0x2000
	s_add_u32 s82, s54, 0x40000
	v_lshl_add_u64 v[216:217], s[54:55], 0, v[128:129]
	s_addc_u32 s83, s55, 0
	s_add_i32 s77, s69, s60
	global_load_lds_dwordx4 v[216:217], off
	v_lshl_add_u64 v[218:219], s[82:83], 0, v[130:131]
	s_mov_b32 m0, s77
	v_lshl_add_u64 v[220:221], s[56:57], 0, v[128:129]
	global_load_lds_dwordx4 v[218:219], off
	v_lshl_add_u64 v[218:219], s[82:83], 0, v[128:129]
	s_add_i32 m0, s77, 0x2000
	s_nop 0
	global_load_lds_dwordx4 v[218:219], off
	v_lshl_add_u64 v[218:219], s[56:57], 0, v[130:131]
	s_mov_b32 m0, s49
	s_nop 0
	global_load_lds_dwordx4 v[218:219], off
	s_mov_b32 m0, s62
	s_nop 0
	global_load_lds_dwordx4 v[220:221], off
	s_waitcnt vmcnt(8)
	s_waitcnt lgkmcnt(0)
	s_barrier
	s_setprio 1
	s_waitcnt lgkmcnt(0)
	v_mfma_f32_16x16x32_bf16 v[60:63], v[140:143], v[184:187], v[60:63]
	v_mfma_f32_16x16x32_bf16 v[60:63], v[150:153], v[188:191], v[60:63]
	v_mfma_f32_16x16x32_bf16 v[56:59], v[154:157], v[184:187], v[56:59]
	v_mfma_f32_16x16x32_bf16 v[56:59], v[158:161], v[188:191], v[56:59]
	v_mfma_f32_16x16x32_bf16 v[44:47], v[140:143], v[192:195], v[44:47]
	v_mfma_f32_16x16x32_bf16 v[44:47], v[150:153], v[196:199], v[44:47]
	v_mfma_f32_16x16x32_bf16 v[40:43], v[154:157], v[192:195], v[40:43]
	v_mfma_f32_16x16x32_bf16 v[40:43], v[158:161], v[196:199], v[40:43]
	v_mfma_f32_16x16x32_bf16 v[28:31], v[140:143], v[200:203], v[28:31]
	v_mfma_f32_16x16x32_bf16 v[28:31], v[150:153], v[204:207], v[28:31]
	v_mfma_f32_16x16x32_bf16 v[24:27], v[154:157], v[200:203], v[24:27]
	v_mfma_f32_16x16x32_bf16 v[24:27], v[158:161], v[204:207], v[24:27]
	v_mfma_f32_16x16x32_bf16 v[12:15], v[140:143], v[208:211], v[12:15]
	v_mfma_f32_16x16x32_bf16 v[12:15], v[150:153], v[212:215], v[12:15]
	v_mfma_f32_16x16x32_bf16 v[8:11], v[154:157], v[208:211], v[8:11]
	v_mfma_f32_16x16x32_bf16 v[8:11], v[158:161], v[212:215], v[8:11]
	s_setprio 0
	s_setprio 1
	v_mfma_f32_16x16x32_bf16 v[52:55], v[162:165], v[184:187], v[52:55]
	v_mfma_f32_16x16x32_bf16 v[52:55], v[166:169], v[188:191], v[52:55]
	v_mfma_f32_16x16x32_bf16 v[48:51], v[170:173], v[184:187], v[48:51]
	v_mfma_f32_16x16x32_bf16 v[48:51], v[174:177], v[188:191], v[48:51]
	v_mfma_f32_16x16x32_bf16 v[36:39], v[162:165], v[192:195], v[36:39]
	v_mfma_f32_16x16x32_bf16 v[36:39], v[166:169], v[196:199], v[36:39]
	v_mfma_f32_16x16x32_bf16 v[32:35], v[170:173], v[192:195], v[32:35]
	v_mfma_f32_16x16x32_bf16 v[32:35], v[174:177], v[196:199], v[32:35]
	v_mfma_f32_16x16x32_bf16 v[20:23], v[162:165], v[200:203], v[20:23]
	v_mfma_f32_16x16x32_bf16 v[20:23], v[166:169], v[204:207], v[20:23]
	v_mfma_f32_16x16x32_bf16 v[16:19], v[170:173], v[200:203], v[16:19]
	v_mfma_f32_16x16x32_bf16 v[16:19], v[174:177], v[204:207], v[16:19]
	v_mfma_f32_16x16x32_bf16 v[4:7], v[162:165], v[208:211], v[4:7]
	v_mfma_f32_16x16x32_bf16 v[4:7], v[166:169], v[212:215], v[4:7]
	s_barrier
	v_mfma_f32_16x16x32_bf16 v[0:3], v[170:173], v[208:211], v[0:3]
	v_mfma_f32_16x16x32_bf16 v[0:3], v[174:177], v[212:215], v[0:3]
	s_setprio 0
.Lmid_gemm7:
	s_add_i32 s77, 0, 0x18000
	s_add_i32 s79, 0, 0x1c000
	v_add_u32_e32 v158, s77, v145
	v_add_u32_e32 v174, s79, v145
	ds_read_b128 v[140:143], v158
	ds_read_b128 v[150:153], v158 offset:1024
	ds_read_b128 v[154:157], v158 offset:2048
	ds_read_b128 v[158:161], v158 offset:3072
	ds_read_b128 v[162:165], v174
	ds_read_b128 v[166:169], v174 offset:1024
	ds_read_b128 v[170:173], v174 offset:2048
	ds_read_b128 v[174:177], v174 offset:3072
	s_add_u32 s56, s56, 0x40000
	s_addc_u32 s57, s57, 0
	s_mov_b32 m0, s63
	v_lshl_add_u64 v[222:223], s[56:57], 0, v[130:131]
	ds_read_b128 v[184:187], v149 offset:32768
	ds_read_b128 v[188:191], v149 offset:33792
	ds_read_b128 v[192:195], v149 offset:34816
	ds_read_b128 v[196:199], v149 offset:35840
	ds_read_b128 v[200:203], v149 offset:36864
	ds_read_b128 v[204:207], v149 offset:37888
	ds_read_b128 v[208:211], v149 offset:38912
	ds_read_b128 v[212:215], v149 offset:39936
	global_load_lds_dwordx4 v[222:223], off
	v_lshl_add_u64 v[222:223], s[56:57], 0, v[128:129]
	s_mov_b32 m0, s64
	s_nop 0
	global_load_lds_dwordx4 v[222:223], off
	s_waitcnt vmcnt(8)
	s_waitcnt lgkmcnt(0)
	s_barrier
	s_setprio 1
	s_waitcnt lgkmcnt(0)
	v_mfma_f32_16x16x32_bf16 v[124:127], v[140:143], v[184:187], v[124:127]
	v_mfma_f32_16x16x32_bf16 v[124:127], v[150:153], v[188:191], v[124:127]
	v_mfma_f32_16x16x32_bf16 v[120:123], v[154:157], v[184:187], v[120:123]
	v_mfma_f32_16x16x32_bf16 v[120:123], v[158:161], v[188:191], v[120:123]
	v_mfma_f32_16x16x32_bf16 v[108:111], v[140:143], v[192:195], v[108:111]
	v_mfma_f32_16x16x32_bf16 v[108:111], v[150:153], v[196:199], v[108:111]
	v_mfma_f32_16x16x32_bf16 v[104:107], v[154:157], v[192:195], v[104:107]
	v_mfma_f32_16x16x32_bf16 v[104:107], v[158:161], v[196:199], v[104:107]
	v_mfma_f32_16x16x32_bf16 v[92:95], v[140:143], v[200:203], v[92:95]
	v_mfma_f32_16x16x32_bf16 v[92:95], v[150:153], v[204:207], v[92:95]
	v_mfma_f32_16x16x32_bf16 v[88:91], v[154:157], v[200:203], v[88:91]
	v_mfma_f32_16x16x32_bf16 v[88:91], v[158:161], v[204:207], v[88:91]
	v_mfma_f32_16x16x32_bf16 v[76:79], v[140:143], v[208:211], v[76:79]
	v_mfma_f32_16x16x32_bf16 v[76:79], v[150:153], v[212:215], v[76:79]
	v_mfma_f32_16x16x32_bf16 v[72:75], v[154:157], v[208:211], v[72:75]
	v_mfma_f32_16x16x32_bf16 v[72:75], v[158:161], v[212:215], v[72:75]
	s_setprio 0
	s_setprio 1
	v_mfma_f32_16x16x32_bf16 v[116:119], v[162:165], v[184:187], v[116:119]
	v_mfma_f32_16x16x32_bf16 v[116:119], v[166:169], v[188:191], v[116:119]
	v_mfma_f32_16x16x32_bf16 v[112:115], v[170:173], v[184:187], v[112:115]
	v_mfma_f32_16x16x32_bf16 v[112:115], v[174:177], v[188:191], v[112:115]
	v_mfma_f32_16x16x32_bf16 v[100:103], v[162:165], v[192:195], v[100:103]
	v_mfma_f32_16x16x32_bf16 v[100:103], v[166:169], v[196:199], v[100:103]
	v_mfma_f32_16x16x32_bf16 v[96:99], v[170:173], v[192:195], v[96:99]
	v_mfma_f32_16x16x32_bf16 v[96:99], v[174:177], v[196:199], v[96:99]
	v_mfma_f32_16x16x32_bf16 v[84:87], v[162:165], v[200:203], v[84:87]
	v_mfma_f32_16x16x32_bf16 v[84:87], v[166:169], v[204:207], v[84:87]
	v_mfma_f32_16x16x32_bf16 v[80:83], v[170:173], v[200:203], v[80:83]
	v_mfma_f32_16x16x32_bf16 v[80:83], v[174:177], v[204:207], v[80:83]
	v_mfma_f32_16x16x32_bf16 v[68:71], v[162:165], v[208:211], v[68:71]
	v_mfma_f32_16x16x32_bf16 v[68:71], v[166:169], v[212:215], v[68:71]
	s_barrier
	v_mfma_f32_16x16x32_bf16 v[64:67], v[170:173], v[208:211], v[64:67]
	v_mfma_f32_16x16x32_bf16 v[64:67], v[174:177], v[212:215], v[64:67]
	s_setprio 0
	s_add_i32 s56, s77, s60
	v_lshl_add_u64 v[178:179], v[178:179], 0, s[12:13]
	s_mov_b32 m0, s56
	ds_read_b128 v[184:187], v149 offset:49152
	ds_read_b128 v[188:191], v149 offset:50176
	ds_read_b128 v[192:195], v149 offset:51200
	ds_read_b128 v[196:199], v149 offset:52224
	ds_read_b128 v[200:203], v149 offset:53248
	ds_read_b128 v[204:207], v149 offset:54272
	ds_read_b128 v[208:211], v149 offset:55296
	ds_read_b128 v[212:215], v149 offset:56320
	global_load_lds_dwordx4 v[178:179], off
	s_add_i32 m0, s56, 0x2000
	s_add_u32 s54, s54, 0x40080
	v_lshl_add_u64 v[178:179], v[216:217], 0, s[12:13]
	s_addc_u32 s55, s55, 0
	s_add_i32 s56, s79, s60
	global_load_lds_dwordx4 v[178:179], off
	v_lshl_add_u64 v[178:179], s[54:55], 0, v[130:131]
	s_mov_b32 m0, s56
	s_nop 0
	global_load_lds_dwordx4 v[178:179], off
	v_lshl_add_u64 v[178:179], s[54:55], 0, v[128:129]
	s_add_i32 m0, s56, 0x2000
	s_nop 0
	global_load_lds_dwordx4 v[178:179], off
	v_lshl_add_u64 v[178:179], v[218:219], 0, s[12:13]
	s_mov_b32 m0, s66
	s_nop 0
	global_load_lds_dwordx4 v[178:179], off
	v_lshl_add_u64 v[178:179], v[220:221], 0, s[12:13]
	s_mov_b32 m0, s67
	s_nop 0
	global_load_lds_dwordx4 v[178:179], off
	s_waitcnt vmcnt(8)
	s_waitcnt lgkmcnt(0)
	s_barrier
	s_setprio 1
	s_waitcnt lgkmcnt(0)
	v_mfma_f32_16x16x32_bf16 v[60:63], v[140:143], v[184:187], v[60:63]
	v_mfma_f32_16x16x32_bf16 v[60:63], v[150:153], v[188:191], v[60:63]
	v_mfma_f32_16x16x32_bf16 v[56:59], v[154:157], v[184:187], v[56:59]
	v_mfma_f32_16x16x32_bf16 v[56:59], v[158:161], v[188:191], v[56:59]
	v_mfma_f32_16x16x32_bf16 v[44:47], v[140:143], v[192:195], v[44:47]
	v_mfma_f32_16x16x32_bf16 v[44:47], v[150:153], v[196:199], v[44:47]
	v_mfma_f32_16x16x32_bf16 v[40:43], v[154:157], v[192:195], v[40:43]
	v_mfma_f32_16x16x32_bf16 v[40:43], v[158:161], v[196:199], v[40:43]
	v_mfma_f32_16x16x32_bf16 v[28:31], v[140:143], v[200:203], v[28:31]
	v_mfma_f32_16x16x32_bf16 v[28:31], v[150:153], v[204:207], v[28:31]
	v_mfma_f32_16x16x32_bf16 v[24:27], v[154:157], v[200:203], v[24:27]
	v_mfma_f32_16x16x32_bf16 v[24:27], v[158:161], v[204:207], v[24:27]
	v_mfma_f32_16x16x32_bf16 v[12:15], v[140:143], v[208:211], v[12:15]
	v_mfma_f32_16x16x32_bf16 v[12:15], v[150:153], v[212:215], v[12:15]
	v_mfma_f32_16x16x32_bf16 v[8:11], v[154:157], v[208:211], v[8:11]
	v_mfma_f32_16x16x32_bf16 v[8:11], v[158:161], v[212:215], v[8:11]
	s_setprio 0
	s_setprio 1
	v_mfma_f32_16x16x32_bf16 v[52:55], v[162:165], v[184:187], v[52:55]
	v_mfma_f32_16x16x32_bf16 v[52:55], v[166:169], v[188:191], v[52:55]
	v_mfma_f32_16x16x32_bf16 v[48:51], v[170:173], v[184:187], v[48:51]
	v_mfma_f32_16x16x32_bf16 v[48:51], v[174:177], v[188:191], v[48:51]
	v_mfma_f32_16x16x32_bf16 v[36:39], v[162:165], v[192:195], v[36:39]
	v_mfma_f32_16x16x32_bf16 v[36:39], v[166:169], v[196:199], v[36:39]
	v_mfma_f32_16x16x32_bf16 v[32:35], v[170:173], v[192:195], v[32:35]
	v_mfma_f32_16x16x32_bf16 v[32:35], v[174:177], v[196:199], v[32:35]
	v_mfma_f32_16x16x32_bf16 v[20:23], v[162:165], v[200:203], v[20:23]
	v_mfma_f32_16x16x32_bf16 v[20:23], v[166:169], v[204:207], v[20:23]
	v_mfma_f32_16x16x32_bf16 v[16:19], v[170:173], v[200:203], v[16:19]
	v_mfma_f32_16x16x32_bf16 v[16:19], v[174:177], v[204:207], v[16:19]
	v_mfma_f32_16x16x32_bf16 v[4:7], v[162:165], v[208:211], v[4:7]
	v_mfma_f32_16x16x32_bf16 v[4:7], v[166:169], v[212:215], v[4:7]
	s_barrier
	v_mfma_f32_16x16x32_bf16 v[0:3], v[170:173], v[208:211], v[0:3]
	v_mfma_f32_16x16x32_bf16 v[0:3], v[174:177], v[212:215], v[0:3]
	s_setprio 0
	s_add_i32 s76, s76, 2
	s_add_u32 s52, s52, 0x100
	s_addc_u32 s53, s53, 0
	s_add_u32 s74, s74, 0x100
	s_addc_u32 s75, s75, 0
	s_cmp_gt_u32 s76, 13
	s_cbranch_scc0 .LBB0_951
	s_and_b64 vcc, exec, s[16:17]
	s_cbranch_vccz .LBB0_954
	s_barrier

.LBB0_1030:
	s_add_u32 s86, s56, 0x100
	s_addc_u32 s87, s57, 0
	s_mov_b32 s88, -2
	ds_read_b128 v[152:155], v149
	ds_read_b128 v[156:159], v149 offset:1024
	ds_read_b128 v[160:163], v149 offset:2048
	ds_read_b128 v[164:167], v149 offset:3072
	ds_read_b128 v[168:171], v150
	ds_read_b128 v[172:175], v150 offset:1024
	ds_read_b128 v[176:179], v150 offset:2048
	ds_read_b128 v[184:187], v150 offset:3072
	s_add_u32 s56, s54, 0x100
	s_addc_u32 s57, s55, 0
	s_cmp_eq_u32 s88, 40
	s_cselect_b32 s61, s13, s57
	s_cselect_b32 s60, s12, s56
	s_cselect_b32 s59, s53, s87
	s_cselect_b32 s58, s52, s86
	v_lshl_add_u64 v[144:145], s[54:55], 0, v[136:137]
	s_add_i32 m0, s65, 0xc000
	ds_read_b128 v[188:191], v151
	ds_read_b128 v[192:195], v151 offset:1024
	ds_read_b128 v[196:199], v151 offset:2048
	ds_read_b128 v[200:203], v151 offset:3072
	ds_read_b128 v[204:207], v151 offset:4096
	ds_read_b128 v[208:211], v151 offset:5120
	ds_read_b128 v[212:215], v151 offset:6144
	ds_read_b128 v[216:219], v151 offset:7168
	global_load_lds_dwordx4 v[144:145], off
	v_lshl_add_u64 v[144:145], s[54:55], 0, v[138:139]
	s_add_i32 m0, s65, 0xe000
	s_nop 0
	global_load_lds_dwordx4 v[144:145], off
	s_waitcnt vmcnt(8)
	s_waitcnt lgkmcnt(0)
	s_barrier
	s_setprio 1
	s_waitcnt lgkmcnt(0)
	v_mfma_f32_16x16x32_bf16 v[124:127], v[152:155], v[188:191], 0
	v_mfma_f32_16x16x32_bf16 v[124:127], v[156:159], v[192:195], v[124:127]
	v_mfma_f32_16x16x32_bf16 v[120:123], v[160:163], v[188:191], 0
	v_mfma_f32_16x16x32_bf16 v[120:123], v[164:167], v[192:195], v[120:123]
	v_mfma_f32_16x16x32_bf16 v[116:119], v[152:155], v[196:199], 0
	v_mfma_f32_16x16x32_bf16 v[116:119], v[156:159], v[200:203], v[116:119]
	v_mfma_f32_16x16x32_bf16 v[108:111], v[160:163], v[196:199], 0
	v_mfma_f32_16x16x32_bf16 v[108:111], v[164:167], v[200:203], v[108:111]
	v_mfma_f32_16x16x32_bf16 v[100:103], v[152:155], v[204:207], 0
	v_mfma_f32_16x16x32_bf16 v[100:103], v[156:159], v[208:211], v[100:103]
	v_mfma_f32_16x16x32_bf16 v[92:95], v[160:163], v[204:207], 0
	v_mfma_f32_16x16x32_bf16 v[92:95], v[164:167], v[208:211], v[92:95]
	v_mfma_f32_16x16x32_bf16 v[84:87], v[152:155], v[212:215], 0
	v_mfma_f32_16x16x32_bf16 v[84:87], v[156:159], v[216:219], v[84:87]
	v_mfma_f32_16x16x32_bf16 v[76:79], v[160:163], v[212:215], 0
	v_mfma_f32_16x16x32_bf16 v[76:79], v[164:167], v[216:219], v[76:79]
	s_setprio 0
	s_setprio 1
	v_mfma_f32_16x16x32_bf16 v[112:115], v[168:171], v[188:191], 0
	v_mfma_f32_16x16x32_bf16 v[112:115], v[172:175], v[192:195], v[112:115]
	v_mfma_f32_16x16x32_bf16 v[104:107], v[176:179], v[188:191], 0
	v_mfma_f32_16x16x32_bf16 v[104:107], v[184:187], v[192:195], v[104:107]
	v_mfma_f32_16x16x32_bf16 v[96:99], v[168:171], v[196:199], 0
	v_mfma_f32_16x16x32_bf16 v[96:99], v[172:175], v[200:203], v[96:99]
	v_mfma_f32_16x16x32_bf16 v[88:91], v[176:179], v[196:199], 0
	v_mfma_f32_16x16x32_bf16 v[88:91], v[184:187], v[200:203], v[88:91]
	v_mfma_f32_16x16x32_bf16 v[80:83], v[168:171], v[204:207], 0
	v_mfma_f32_16x16x32_bf16 v[80:83], v[172:175], v[208:211], v[80:83]
	v_mfma_f32_16x16x32_bf16 v[72:75], v[176:179], v[204:207], 0
	v_mfma_f32_16x16x32_bf16 v[72:75], v[184:187], v[208:211], v[72:75]
	v_mfma_f32_16x16x32_bf16 v[68:71], v[168:171], v[212:215], 0
	v_mfma_f32_16x16x32_bf16 v[68:71], v[172:175], v[216:219], v[68:71]
	s_barrier
	v_mfma_f32_16x16x32_bf16 v[64:67], v[176:179], v[212:215], 0
	v_mfma_f32_16x16x32_bf16 v[64:67], v[184:187], v[216:219], v[64:67]
	s_setprio 0
	s_add_i32 s54, s72, s64
	v_lshl_add_u64 v[144:145], s[58:59], 0, v[130:131]
	s_mov_b32 m0, s54
	ds_read_b128 v[188:191], v151 offset:16384
	ds_read_b128 v[192:195], v151 offset:17408
	ds_read_b128 v[196:199], v151 offset:18432
	ds_read_b128 v[200:203], v151 offset:19456
	ds_read_b128 v[204:207], v151 offset:20480
	ds_read_b128 v[208:211], v151 offset:21504
	ds_read_b128 v[212:215], v151 offset:22528
	ds_read_b128 v[216:219], v151 offset:23552
	global_load_lds_dwordx4 v[144:145], off
	s_add_i32 m0, s54, 0x2000
	s_add_u32 s54, s58, 0xb0000
	v_lshl_add_u64 v[220:221], s[58:59], 0, v[134:135]
	s_addc_u32 s55, s59, 0
	s_add_i32 s79, s73, s64
	global_load_lds_dwordx4 v[220:221], off
	v_lshl_add_u64 v[222:223], s[54:55], 0, v[130:131]
	s_mov_b32 m0, s79
	v_lshl_add_u64 v[224:225], s[60:61], 0, v[132:133]
	global_load_lds_dwordx4 v[222:223], off
	v_lshl_add_u64 v[222:223], s[54:55], 0, v[134:135]
	s_add_i32 m0, s79, 0x2000
	s_nop 0
	global_load_lds_dwordx4 v[222:223], off
	v_lshl_add_u64 v[222:223], s[60:61], 0, v[128:129]
	s_mov_b32 m0, s65
	s_nop 0
	global_load_lds_dwordx4 v[222:223], off
	s_mov_b32 m0, s66
	s_nop 0
	global_load_lds_dwordx4 v[224:225], off
	s_waitcnt vmcnt(8)
	s_waitcnt lgkmcnt(0)
	s_barrier
	s_setprio 1
	s_waitcnt lgkmcnt(0)
	v_mfma_f32_16x16x32_bf16 v[60:63], v[152:155], v[188:191], 0
	v_mfma_f32_16x16x32_bf16 v[60:63], v[156:159], v[192:195], v[60:63]
	v_mfma_f32_16x16x32_bf16 v[56:59], v[160:163], v[188:191], 0
	v_mfma_f32_16x16x32_bf16 v[56:59], v[164:167], v[192:195], v[56:59]
	v_mfma_f32_16x16x32_bf16 v[52:55], v[152:155], v[196:199], 0
	v_mfma_f32_16x16x32_bf16 v[52:55], v[156:159], v[200:203], v[52:55]
	v_mfma_f32_16x16x32_bf16 v[44:47], v[160:163], v[196:199], 0
	v_mfma_f32_16x16x32_bf16 v[44:47], v[164:167], v[200:203], v[44:47]
	v_mfma_f32_16x16x32_bf16 v[36:39], v[152:155], v[204:207], 0
	v_mfma_f32_16x16x32_bf16 v[36:39], v[156:159], v[208:211], v[36:39]
	v_mfma_f32_16x16x32_bf16 v[28:31], v[160:163], v[204:207], 0
	v_mfma_f32_16x16x32_bf16 v[28:31], v[164:167], v[208:211], v[28:31]
	v_mfma_f32_16x16x32_bf16 v[20:23], v[152:155], v[212:215], 0
	v_mfma_f32_16x16x32_bf16 v[20:23], v[156:159], v[216:219], v[20:23]
	v_mfma_f32_16x16x32_bf16 v[12:15], v[160:163], v[212:215], 0
	v_mfma_f32_16x16x32_bf16 v[12:15], v[164:167], v[216:219], v[12:15]
	s_setprio 0
	s_setprio 1
	v_mfma_f32_16x16x32_bf16 v[48:51], v[168:171], v[188:191], 0
	v_mfma_f32_16x16x32_bf16 v[48:51], v[172:175], v[192:195], v[48:51]
	v_mfma_f32_16x16x32_bf16 v[40:43], v[176:179], v[188:191], 0
	v_mfma_f32_16x16x32_bf16 v[40:43], v[184:187], v[192:195], v[40:43]
	v_mfma_f32_16x16x32_bf16 v[32:35], v[168:171], v[196:199], 0
	v_mfma_f32_16x16x32_bf16 v[32:35], v[172:175], v[200:203], v[32:35]
	v_mfma_f32_16x16x32_bf16 v[24:27], v[176:179], v[196:199], 0
	v_mfma_f32_16x16x32_bf16 v[24:27], v[184:187], v[200:203], v[24:27]
	v_mfma_f32_16x16x32_bf16 v[16:19], v[168:171], v[204:207], 0
	v_mfma_f32_16x16x32_bf16 v[16:19], v[172:175], v[208:211], v[16:19]
	v_mfma_f32_16x16x32_bf16 v[8:11], v[176:179], v[204:207], 0
	v_mfma_f32_16x16x32_bf16 v[8:11], v[184:187], v[208:211], v[8:11]
	v_mfma_f32_16x16x32_bf16 v[4:7], v[168:171], v[212:215], 0
	v_mfma_f32_16x16x32_bf16 v[4:7], v[172:175], v[216:219], v[4:7]
	s_barrier
	v_mfma_f32_16x16x32_bf16 v[0:3], v[176:179], v[212:215], 0
	v_mfma_f32_16x16x32_bf16 v[0:3], v[184:187], v[216:219], v[0:3]
	s_setprio 0
	s_branch .Lmid_gemm8
.LBB0_1031:
	ds_read_b128 v[152:155], v149
	ds_read_b128 v[156:159], v149 offset:1024
	ds_read_b128 v[160:163], v149 offset:2048
	ds_read_b128 v[164:167], v149 offset:3072
	ds_read_b128 v[168:171], v150
	ds_read_b128 v[172:175], v150 offset:1024
	ds_read_b128 v[176:179], v150 offset:2048
	ds_read_b128 v[184:187], v150 offset:3072
	s_add_u32 s56, s54, 0x100
	s_addc_u32 s57, s55, 0
	s_cmp_eq_u32 s88, 40
	s_cselect_b32 s61, s13, s57
	s_cselect_b32 s60, s12, s56
	s_cselect_b32 s59, s53, s87
	s_cselect_b32 s58, s52, s86
	v_lshl_add_u64 v[144:145], s[54:55], 0, v[136:137]
	s_add_i32 m0, s65, 0xc000
	ds_read_b128 v[188:191], v151
	ds_read_b128 v[192:195], v151 offset:1024
	ds_read_b128 v[196:199], v151 offset:2048
	ds_read_b128 v[200:203], v151 offset:3072
	ds_read_b128 v[204:207], v151 offset:4096
	ds_read_b128 v[208:211], v151 offset:5120
	ds_read_b128 v[212:215], v151 offset:6144
	ds_read_b128 v[216:219], v151 offset:7168
	global_load_lds_dwordx4 v[144:145], off
	v_lshl_add_u64 v[144:145], s[54:55], 0, v[138:139]
	s_add_i32 m0, s65, 0xe000
	s_nop 0
	global_load_lds_dwordx4 v[144:145], off
	s_waitcnt vmcnt(8)
	s_waitcnt lgkmcnt(0)
	s_barrier
	s_setprio 1
	s_waitcnt lgkmcnt(0)
	v_mfma_f32_16x16x32_bf16 v[124:127], v[152:155], v[188:191], v[124:127]
	v_mfma_f32_16x16x32_bf16 v[124:127], v[156:159], v[192:195], v[124:127]
	v_mfma_f32_16x16x32_bf16 v[120:123], v[160:163], v[188:191], v[120:123]
	v_mfma_f32_16x16x32_bf16 v[120:123], v[164:167], v[192:195], v[120:123]
	v_mfma_f32_16x16x32_bf16 v[116:119], v[152:155], v[196:199], v[116:119]
	v_mfma_f32_16x16x32_bf16 v[116:119], v[156:159], v[200:203], v[116:119]
	v_mfma_f32_16x16x32_bf16 v[108:111], v[160:163], v[196:199], v[108:111]
	v_mfma_f32_16x16x32_bf16 v[108:111], v[164:167], v[200:203], v[108:111]
	v_mfma_f32_16x16x32_bf16 v[100:103], v[152:155], v[204:207], v[100:103]
	v_mfma_f32_16x16x32_bf16 v[100:103], v[156:159], v[208:211], v[100:103]
	v_mfma_f32_16x16x32_bf16 v[92:95], v[160:163], v[204:207], v[92:95]
	v_mfma_f32_16x16x32_bf16 v[92:95], v[164:167], v[208:211], v[92:95]
	v_mfma_f32_16x16x32_bf16 v[84:87], v[152:155], v[212:215], v[84:87]
	v_mfma_f32_16x16x32_bf16 v[84:87], v[156:159], v[216:219], v[84:87]
	v_mfma_f32_16x16x32_bf16 v[76:79], v[160:163], v[212:215], v[76:79]
	v_mfma_f32_16x16x32_bf16 v[76:79], v[164:167], v[216:219], v[76:79]
	s_setprio 0
	s_setprio 1
	v_mfma_f32_16x16x32_bf16 v[112:115], v[168:171], v[188:191], v[112:115]
	v_mfma_f32_16x16x32_bf16 v[112:115], v[172:175], v[192:195], v[112:115]
	v_mfma_f32_16x16x32_bf16 v[104:107], v[176:179], v[188:191], v[104:107]
	v_mfma_f32_16x16x32_bf16 v[104:107], v[184:187], v[192:195], v[104:107]
	v_mfma_f32_16x16x32_bf16 v[96:99], v[168:171], v[196:199], v[96:99]
	v_mfma_f32_16x16x32_bf16 v[96:99], v[172:175], v[200:203], v[96:99]
	v_mfma_f32_16x16x32_bf16 v[88:91], v[176:179], v[196:199], v[88:91]
	v_mfma_f32_16x16x32_bf16 v[88:91], v[184:187], v[200:203], v[88:91]
	v_mfma_f32_16x16x32_bf16 v[80:83], v[168:171], v[204:207], v[80:83]
	v_mfma_f32_16x16x32_bf16 v[80:83], v[172:175], v[208:211], v[80:83]
	v_mfma_f32_16x16x32_bf16 v[72:75], v[176:179], v[204:207], v[72:75]
	v_mfma_f32_16x16x32_bf16 v[72:75], v[184:187], v[208:211], v[72:75]
	v_mfma_f32_16x16x32_bf16 v[68:71], v[168:171], v[212:215], v[68:71]
	v_mfma_f32_16x16x32_bf16 v[68:71], v[172:175], v[216:219], v[68:71]
	s_barrier
	v_mfma_f32_16x16x32_bf16 v[64:67], v[176:179], v[212:215], v[64:67]
	v_mfma_f32_16x16x32_bf16 v[64:67], v[184:187], v[216:219], v[64:67]
	s_setprio 0
	s_add_i32 s54, s72, s64
	v_lshl_add_u64 v[144:145], s[58:59], 0, v[130:131]
	s_mov_b32 m0, s54
	ds_read_b128 v[188:191], v151 offset:16384
	ds_read_b128 v[192:195], v151 offset:17408
	ds_read_b128 v[196:199], v151 offset:18432
	ds_read_b128 v[200:203], v151 offset:19456
	ds_read_b128 v[204:207], v151 offset:20480
	ds_read_b128 v[208:211], v151 offset:21504
	ds_read_b128 v[212:215], v151 offset:22528
	ds_read_b128 v[216:219], v151 offset:23552
	global_load_lds_dwordx4 v[144:145], off
	s_add_i32 m0, s54, 0x2000
	s_add_u32 s54, s58, 0xb0000
	v_lshl_add_u64 v[220:221], s[58:59], 0, v[134:135]
	s_addc_u32 s55, s59, 0
	s_add_i32 s79, s73, s64
	global_load_lds_dwordx4 v[220:221], off
	v_lshl_add_u64 v[222:223], s[54:55], 0, v[130:131]
	s_mov_b32 m0, s79
	v_lshl_add_u64 v[224:225], s[60:61], 0, v[132:133]
	global_load_lds_dwordx4 v[222:223], off
	v_lshl_add_u64 v[222:223], s[54:55], 0, v[134:135]
	s_add_i32 m0, s79, 0x2000
	s_nop 0
	global_load_lds_dwordx4 v[222:223], off
	v_lshl_add_u64 v[222:223], s[60:61], 0, v[128:129]
	s_mov_b32 m0, s65
	s_nop 0
	global_load_lds_dwordx4 v[222:223], off
	s_mov_b32 m0, s66
	s_nop 0
	global_load_lds_dwordx4 v[224:225], off
	s_waitcnt vmcnt(8)
	s_waitcnt lgkmcnt(0)
	s_barrier
	s_setprio 1
	s_waitcnt lgkmcnt(0)
	v_mfma_f32_16x16x32_bf16 v[60:63], v[152:155], v[188:191], v[60:63]
	v_mfma_f32_16x16x32_bf16 v[60:63], v[156:159], v[192:195], v[60:63]
	v_mfma_f32_16x16x32_bf16 v[56:59], v[160:163], v[188:191], v[56:59]
	v_mfma_f32_16x16x32_bf16 v[56:59], v[164:167], v[192:195], v[56:59]
	v_mfma_f32_16x16x32_bf16 v[52:55], v[152:155], v[196:199], v[52:55]
	v_mfma_f32_16x16x32_bf16 v[52:55], v[156:159], v[200:203], v[52:55]
	v_mfma_f32_16x16x32_bf16 v[44:47], v[160:163], v[196:199], v[44:47]
	v_mfma_f32_16x16x32_bf16 v[44:47], v[164:167], v[200:203], v[44:47]
	v_mfma_f32_16x16x32_bf16 v[36:39], v[152:155], v[204:207], v[36:39]
	v_mfma_f32_16x16x32_bf16 v[36:39], v[156:159], v[208:211], v[36:39]
	v_mfma_f32_16x16x32_bf16 v[28:31], v[160:163], v[204:207], v[28:31]
	v_mfma_f32_16x16x32_bf16 v[28:31], v[164:167], v[208:211], v[28:31]
	v_mfma_f32_16x16x32_bf16 v[20:23], v[152:155], v[212:215], v[20:23]
	v_mfma_f32_16x16x32_bf16 v[20:23], v[156:159], v[216:219], v[20:23]
	v_mfma_f32_16x16x32_bf16 v[12:15], v[160:163], v[212:215], v[12:15]
	v_mfma_f32_16x16x32_bf16 v[12:15], v[164:167], v[216:219], v[12:15]
	s_setprio 0
	s_setprio 1
	v_mfma_f32_16x16x32_bf16 v[48:51], v[168:171], v[188:191], v[48:51]
	v_mfma_f32_16x16x32_bf16 v[48:51], v[172:175], v[192:195], v[48:51]
	v_mfma_f32_16x16x32_bf16 v[40:43], v[176:179], v[188:191], v[40:43]
	v_mfma_f32_16x16x32_bf16 v[40:43], v[184:187], v[192:195], v[40:43]
	v_mfma_f32_16x16x32_bf16 v[32:35], v[168:171], v[196:199], v[32:35]
	v_mfma_f32_16x16x32_bf16 v[32:35], v[172:175], v[200:203], v[32:35]
	v_mfma_f32_16x16x32_bf16 v[24:27], v[176:179], v[196:199], v[24:27]
	v_mfma_f32_16x16x32_bf16 v[24:27], v[184:187], v[200:203], v[24:27]
	v_mfma_f32_16x16x32_bf16 v[16:19], v[168:171], v[204:207], v[16:19]
	v_mfma_f32_16x16x32_bf16 v[16:19], v[172:175], v[208:211], v[16:19]
	v_mfma_f32_16x16x32_bf16 v[8:11], v[176:179], v[204:207], v[8:11]
	v_mfma_f32_16x16x32_bf16 v[8:11], v[184:187], v[208:211], v[8:11]
	v_mfma_f32_16x16x32_bf16 v[4:7], v[168:171], v[212:215], v[4:7]
	v_mfma_f32_16x16x32_bf16 v[4:7], v[172:175], v[216:219], v[4:7]
	s_barrier
	v_mfma_f32_16x16x32_bf16 v[0:3], v[176:179], v[212:215], v[0:3]
	v_mfma_f32_16x16x32_bf16 v[0:3], v[184:187], v[216:219], v[0:3]
	s_setprio 0
.Lmid_gemm8:
	s_add_i32 s79, 0, 0x18000
	s_add_i32 s89, 0, 0x1c000
	v_add_u32_e32 v164, s79, v147
	v_add_u32_e32 v181, s89, v147
	ds_read_b128 v[152:155], v164
	ds_read_b128 v[156:159], v164 offset:1024
	ds_read_b128 v[160:163], v164 offset:2048
	ds_read_b128 v[164:167], v164 offset:3072
	ds_read_b128 v[168:171], v181
	ds_read_b128 v[172:175], v181 offset:1024
	ds_read_b128 v[176:179], v181 offset:2048
	ds_read_b128 v[184:187], v181 offset:3072
	s_add_u32 s54, s60, 0xb0000
	s_addc_u32 s55, s61, 0
	s_mov_b32 m0, s67
	v_lshl_add_u64 v[226:227], s[54:55], 0, v[128:129]
	ds_read_b128 v[188:191], v151 offset:32768
	ds_read_b128 v[192:195], v151 offset:33792
	ds_read_b128 v[196:199], v151 offset:34816
	ds_read_b128 v[200:203], v151 offset:35840
	ds_read_b128 v[204:207], v151 offset:36864
	ds_read_b128 v[208:211], v151 offset:37888
	ds_read_b128 v[212:215], v151 offset:38912
	ds_read_b128 v[216:219], v151 offset:39936
	global_load_lds_dwordx4 v[226:227], off
	v_lshl_add_u64 v[226:227], s[54:55], 0, v[132:133]
	s_mov_b32 m0, s68
	s_nop 0
	global_load_lds_dwordx4 v[226:227], off
	s_waitcnt vmcnt(8)
	s_waitcnt lgkmcnt(0)
	s_barrier
	s_setprio 1
	s_waitcnt lgkmcnt(0)
	v_mfma_f32_16x16x32_bf16 v[124:127], v[152:155], v[188:191], v[124:127]
	v_mfma_f32_16x16x32_bf16 v[124:127], v[156:159], v[192:195], v[124:127]
	v_mfma_f32_16x16x32_bf16 v[120:123], v[160:163], v[188:191], v[120:123]
	v_mfma_f32_16x16x32_bf16 v[120:123], v[164:167], v[192:195], v[120:123]
	v_mfma_f32_16x16x32_bf16 v[116:119], v[152:155], v[196:199], v[116:119]
	v_mfma_f32_16x16x32_bf16 v[116:119], v[156:159], v[200:203], v[116:119]
	v_mfma_f32_16x16x32_bf16 v[108:111], v[160:163], v[196:199], v[108:111]
	v_mfma_f32_16x16x32_bf16 v[108:111], v[164:167], v[200:203], v[108:111]
	v_mfma_f32_16x16x32_bf16 v[100:103], v[152:155], v[204:207], v[100:103]
	v_mfma_f32_16x16x32_bf16 v[100:103], v[156:159], v[208:211], v[100:103]
	v_mfma_f32_16x16x32_bf16 v[92:95], v[160:163], v[204:207], v[92:95]
	v_mfma_f32_16x16x32_bf16 v[92:95], v[164:167], v[208:211], v[92:95]
	v_mfma_f32_16x16x32_bf16 v[84:87], v[152:155], v[212:215], v[84:87]
	v_mfma_f32_16x16x32_bf16 v[84:87], v[156:159], v[216:219], v[84:87]
	v_mfma_f32_16x16x32_bf16 v[76:79], v[160:163], v[212:215], v[76:79]
	v_mfma_f32_16x16x32_bf16 v[76:79], v[164:167], v[216:219], v[76:79]
	s_setprio 0
	s_setprio 1
	v_mfma_f32_16x16x32_bf16 v[112:115], v[168:171], v[188:191], v[112:115]
	v_mfma_f32_16x16x32_bf16 v[112:115], v[172:175], v[192:195], v[112:115]
	v_mfma_f32_16x16x32_bf16 v[104:107], v[176:179], v[188:191], v[104:107]
	v_mfma_f32_16x16x32_bf16 v[104:107], v[184:187], v[192:195], v[104:107]
	v_mfma_f32_16x16x32_bf16 v[96:99], v[168:171], v[196:199], v[96:99]
	v_mfma_f32_16x16x32_bf16 v[96:99], v[172:175], v[200:203], v[96:99]
	v_mfma_f32_16x16x32_bf16 v[88:91], v[176:179], v[196:199], v[88:91]
	v_mfma_f32_16x16x32_bf16 v[88:91], v[184:187], v[200:203], v[88:91]
	v_mfma_f32_16x16x32_bf16 v[80:83], v[168:171], v[204:207], v[80:83]
	v_mfma_f32_16x16x32_bf16 v[80:83], v[172:175], v[208:211], v[80:83]
	v_mfma_f32_16x16x32_bf16 v[72:75], v[176:179], v[204:207], v[72:75]
	v_mfma_f32_16x16x32_bf16 v[72:75], v[184:187], v[208:211], v[72:75]
	v_mfma_f32_16x16x32_bf16 v[68:71], v[168:171], v[212:215], v[68:71]
	v_mfma_f32_16x16x32_bf16 v[68:71], v[172:175], v[216:219], v[68:71]
	s_barrier
	v_mfma_f32_16x16x32_bf16 v[64:67], v[176:179], v[212:215], v[64:67]
	v_mfma_f32_16x16x32_bf16 v[64:67], v[184:187], v[216:219], v[64:67]
	s_setprio 0
	s_add_i32 s54, s79, s64
	v_lshl_add_u64 v[144:145], v[144:145], 0, s[16:17]
	s_mov_b32 m0, s54
	ds_read_b128 v[188:191], v151 offset:49152
	ds_read_b128 v[192:195], v151 offset:50176
	ds_read_b128 v[196:199], v151 offset:51200
	ds_read_b128 v[200:203], v151 offset:52224
	ds_read_b128 v[204:207], v151 offset:53248
	ds_read_b128 v[208:211], v151 offset:54272
	ds_read_b128 v[212:215], v151 offset:55296
	ds_read_b128 v[216:219], v151 offset:56320
	global_load_lds_dwordx4 v[144:145], off
	s_add_i32 m0, s54, 0x2000
	s_add_u32 s54, s58, 0xb0080
	v_lshl_add_u64 v[144:145], v[220:221], 0, s[16:17]
	s_addc_u32 s55, s59, 0
	s_add_i32 s58, s89, s64
	global_load_lds_dwordx4 v[144:145], off
	v_lshl_add_u64 v[144:145], s[54:55], 0, v[130:131]
	s_mov_b32 m0, s58
	s_nop 0
	global_load_lds_dwordx4 v[144:145], off
	v_lshl_add_u64 v[144:145], s[54:55], 0, v[134:135]
	s_add_i32 m0, s58, 0x2000
	s_nop 0
	global_load_lds_dwordx4 v[144:145], off
	v_lshl_add_u64 v[144:145], v[222:223], 0, s[16:17]
	s_mov_b32 m0, s70
	s_nop 0
	global_load_lds_dwordx4 v[144:145], off
	v_lshl_add_u64 v[144:145], v[224:225], 0, s[16:17]
	s_mov_b32 m0, s71
	s_nop 0
	global_load_lds_dwordx4 v[144:145], off
	s_waitcnt vmcnt(8)
	s_waitcnt lgkmcnt(0)
	s_barrier
	s_setprio 1
	s_waitcnt lgkmcnt(0)
	v_mfma_f32_16x16x32_bf16 v[60:63], v[152:155], v[188:191], v[60:63]
	v_mfma_f32_16x16x32_bf16 v[60:63], v[156:159], v[192:195], v[60:63]
	v_mfma_f32_16x16x32_bf16 v[56:59], v[160:163], v[188:191], v[56:59]
	v_mfma_f32_16x16x32_bf16 v[56:59], v[164:167], v[192:195], v[56:59]
	v_mfma_f32_16x16x32_bf16 v[52:55], v[152:155], v[196:199], v[52:55]
	v_mfma_f32_16x16x32_bf16 v[52:55], v[156:159], v[200:203], v[52:55]
	v_mfma_f32_16x16x32_bf16 v[44:47], v[160:163], v[196:199], v[44:47]
	v_mfma_f32_16x16x32_bf16 v[44:47], v[164:167], v[200:203], v[44:47]
	v_mfma_f32_16x16x32_bf16 v[36:39], v[152:155], v[204:207], v[36:39]
	v_mfma_f32_16x16x32_bf16 v[36:39], v[156:159], v[208:211], v[36:39]
	v_mfma_f32_16x16x32_bf16 v[28:31], v[160:163], v[204:207], v[28:31]
	v_mfma_f32_16x16x32_bf16 v[28:31], v[164:167], v[208:211], v[28:31]
	v_mfma_f32_16x16x32_bf16 v[20:23], v[152:155], v[212:215], v[20:23]
	v_mfma_f32_16x16x32_bf16 v[20:23], v[156:159], v[216:219], v[20:23]
	v_mfma_f32_16x16x32_bf16 v[12:15], v[160:163], v[212:215], v[12:15]
	v_mfma_f32_16x16x32_bf16 v[12:15], v[164:167], v[216:219], v[12:15]
	s_setprio 0
	s_setprio 1
	v_mfma_f32_16x16x32_bf16 v[48:51], v[168:171], v[188:191], v[48:51]
	v_mfma_f32_16x16x32_bf16 v[48:51], v[172:175], v[192:195], v[48:51]
	v_mfma_f32_16x16x32_bf16 v[40:43], v[176:179], v[188:191], v[40:43]
	v_mfma_f32_16x16x32_bf16 v[40:43], v[184:187], v[192:195], v[40:43]
	v_mfma_f32_16x16x32_bf16 v[32:35], v[168:171], v[196:199], v[32:35]
	v_mfma_f32_16x16x32_bf16 v[32:35], v[172:175], v[200:203], v[32:35]
	v_mfma_f32_16x16x32_bf16 v[24:27], v[176:179], v[196:199], v[24:27]
	v_mfma_f32_16x16x32_bf16 v[24:27], v[184:187], v[200:203], v[24:27]
	v_mfma_f32_16x16x32_bf16 v[16:19], v[168:171], v[204:207], v[16:19]
	v_mfma_f32_16x16x32_bf16 v[16:19], v[172:175], v[208:211], v[16:19]
	v_mfma_f32_16x16x32_bf16 v[8:11], v[176:179], v[204:207], v[8:11]
	v_mfma_f32_16x16x32_bf16 v[8:11], v[184:187], v[208:211], v[8:11]
	v_mfma_f32_16x16x32_bf16 v[4:7], v[168:171], v[212:215], v[4:7]
	v_mfma_f32_16x16x32_bf16 v[4:7], v[172:175], v[216:219], v[4:7]
	s_barrier
	v_mfma_f32_16x16x32_bf16 v[0:3], v[176:179], v[212:215], v[0:3]
	v_mfma_f32_16x16x32_bf16 v[0:3], v[184:187], v[216:219], v[0:3]
	s_setprio 0
	s_add_i32 s88, s88, 2
	s_add_u32 s86, s86, 0x100
	s_addc_u32 s87, s87, 0
	s_cmp_gt_u32 s88, 41
	s_mov_b64 s[54:55], s[56:57]
	s_cbranch_scc0 .LBB0_1031
	s_and_b64 vcc, exec, s[18:19]
	s_cbranch_vccz .LBB0_1034
	s_barrier

.LBB0_1161:
	s_ashr_i32 s53, s52, 31
	s_lshl_b64 s[54:55], s[52:53], 19
	s_add_u32 s54, s80, s54
	s_addc_u32 s55, s81, s55
	s_and_b64 s[56:57], s[10:11], exec
	s_cselect_b32 s53, s55, s61
	s_cselect_b32 s83, s54, s60
	s_ashr_i32 s49, s48, 31
	s_lshl_b64 s[56:57], s[48:49], 19
	s_add_u32 s56, s66, s56
	s_addc_u32 s57, s67, s57
	s_and_b64 s[64:65], s[10:11], exec
	s_cselect_b32 s49, s57, s63
	s_cselect_b32 s84, s56, s62
	s_add_u32 s60, s60, 0x40080
	s_addc_u32 s61, s61, 0
	s_add_u32 s85, s62, 0x100
	s_addc_u32 s86, s63, 0
	s_mov_b32 s87, -2
	ds_read_b128 v[152:155], v148
	ds_read_b128 v[156:159], v148 offset:1024
	ds_read_b128 v[160:163], v148 offset:2048
	ds_read_b128 v[164:167], v148 offset:3072
	ds_read_b128 v[168:171], v149
	ds_read_b128 v[172:175], v149 offset:1024
	ds_read_b128 v[176:179], v149 offset:2048
	ds_read_b128 v[184:187], v149 offset:3072
	s_add_u32 s62, s60, 0xfffc0080
	s_addc_u32 s63, s61, -1
	s_cmp_eq_u32 s87, 12
	s_cselect_b32 s65, s53, s63
	s_cselect_b32 s64, s83, s62
	s_cselect_b32 s63, s49, s86
	s_cselect_b32 s62, s84, s85
	v_lshl_add_u64 v[220:221], s[60:61], 0, v[138:139]
	s_add_i32 m0, s69, 0xc000
	ds_read_b128 v[188:191], v150
	ds_read_b128 v[192:195], v150 offset:1024
	ds_read_b128 v[196:199], v150 offset:2048
	ds_read_b128 v[200:203], v150 offset:3072
	ds_read_b128 v[204:207], v150 offset:4096
	ds_read_b128 v[208:211], v150 offset:5120
	ds_read_b128 v[212:215], v150 offset:6144
	ds_read_b128 v[216:219], v150 offset:7168
	global_load_lds_dwordx4 v[220:221], off
	v_lshl_add_u64 v[220:221], s[60:61], 0, v[140:141]
	s_add_i32 m0, s69, 0xe000
	s_nop 0
	global_load_lds_dwordx4 v[220:221], off
	s_waitcnt vmcnt(8)
	s_waitcnt lgkmcnt(0)
	s_barrier
	s_setprio 1
	s_waitcnt lgkmcnt(0)
	v_mfma_f32_16x16x32_bf16 v[124:127], v[152:155], v[188:191], 0
	v_mfma_f32_16x16x32_bf16 v[124:127], v[156:159], v[192:195], v[124:127]
	v_mfma_f32_16x16x32_bf16 v[120:123], v[160:163], v[188:191], 0
	v_mfma_f32_16x16x32_bf16 v[120:123], v[164:167], v[192:195], v[120:123]
	v_mfma_f32_16x16x32_bf16 v[116:119], v[152:155], v[196:199], 0
	v_mfma_f32_16x16x32_bf16 v[116:119], v[156:159], v[200:203], v[116:119]
	v_mfma_f32_16x16x32_bf16 v[112:115], v[160:163], v[196:199], 0
	v_mfma_f32_16x16x32_bf16 v[112:115], v[164:167], v[200:203], v[112:115]
	v_mfma_f32_16x16x32_bf16 v[108:111], v[152:155], v[204:207], 0
	v_mfma_f32_16x16x32_bf16 v[108:111], v[156:159], v[208:211], v[108:111]
	v_mfma_f32_16x16x32_bf16 v[104:107], v[160:163], v[204:207], 0
	v_mfma_f32_16x16x32_bf16 v[104:107], v[164:167], v[208:211], v[104:107]
	v_mfma_f32_16x16x32_bf16 v[100:103], v[152:155], v[212:215], 0
	v_mfma_f32_16x16x32_bf16 v[100:103], v[156:159], v[216:219], v[100:103]
	v_mfma_f32_16x16x32_bf16 v[96:99], v[160:163], v[212:215], 0
	v_mfma_f32_16x16x32_bf16 v[96:99], v[164:167], v[216:219], v[96:99]
	s_setprio 0
	s_setprio 1
	v_mfma_f32_16x16x32_bf16 v[68:71], v[168:171], v[188:191], 0
	v_mfma_f32_16x16x32_bf16 v[68:71], v[172:175], v[192:195], v[68:71]
	v_mfma_f32_16x16x32_bf16 v[64:67], v[176:179], v[188:191], 0
	v_mfma_f32_16x16x32_bf16 v[64:67], v[184:187], v[192:195], v[64:67]
	v_mfma_f32_16x16x32_bf16 v[52:55], v[168:171], v[196:199], 0
	v_mfma_f32_16x16x32_bf16 v[52:55], v[172:175], v[200:203], v[52:55]
	v_mfma_f32_16x16x32_bf16 v[48:51], v[176:179], v[196:199], 0
	v_mfma_f32_16x16x32_bf16 v[48:51], v[184:187], v[200:203], v[48:51]
	v_mfma_f32_16x16x32_bf16 v[44:47], v[168:171], v[204:207], 0
	v_mfma_f32_16x16x32_bf16 v[44:47], v[172:175], v[208:211], v[44:47]
	v_mfma_f32_16x16x32_bf16 v[40:43], v[176:179], v[204:207], 0
	v_mfma_f32_16x16x32_bf16 v[40:43], v[184:187], v[208:211], v[40:43]
	v_mfma_f32_16x16x32_bf16 v[36:39], v[168:171], v[212:215], 0
	v_mfma_f32_16x16x32_bf16 v[36:39], v[172:175], v[216:219], v[36:39]
	s_barrier
	v_mfma_f32_16x16x32_bf16 v[32:35], v[176:179], v[212:215], 0
	v_mfma_f32_16x16x32_bf16 v[32:35], v[184:187], v[216:219], v[32:35]
	s_setprio 0
	s_add_i32 s79, s77, s68
	v_lshl_add_u64 v[220:221], s[62:63], 0, v[130:131]
	s_mov_b32 m0, s79
	ds_read_b128 v[188:191], v150 offset:16384
	ds_read_b128 v[192:195], v150 offset:17408
	ds_read_b128 v[196:199], v150 offset:18432
	ds_read_b128 v[200:203], v150 offset:19456
	ds_read_b128 v[204:207], v150 offset:20480
	ds_read_b128 v[208:211], v150 offset:21504
	ds_read_b128 v[212:215], v150 offset:22528
	ds_read_b128 v[216:219], v150 offset:23552
	global_load_lds_dwordx4 v[220:221], off
	s_add_i32 m0, s79, 0x2000
	s_add_u32 s88, s62, 0x40000
	v_lshl_add_u64 v[222:223], s[62:63], 0, v[134:135]
	s_addc_u32 s89, s63, 0
	s_add_i32 s79, s82, s68
	global_load_lds_dwordx4 v[222:223], off
	v_lshl_add_u64 v[224:225], s[88:89], 0, v[130:131]
	s_mov_b32 m0, s79
	v_lshl_add_u64 v[226:227], s[64:65], 0, v[132:133]
	global_load_lds_dwordx4 v[224:225], off
	v_lshl_add_u64 v[224:225], s[88:89], 0, v[134:135]
	s_add_i32 m0, s79, 0x2000
	s_nop 0
	global_load_lds_dwordx4 v[224:225], off
	v_lshl_add_u64 v[224:225], s[64:65], 0, v[128:129]
	s_mov_b32 m0, s69
	s_nop 0
	global_load_lds_dwordx4 v[224:225], off
	s_mov_b32 m0, s70
	s_nop 0
	global_load_lds_dwordx4 v[226:227], off
	s_waitcnt vmcnt(8)
	s_waitcnt lgkmcnt(0)
	s_barrier
	s_setprio 1
	s_waitcnt lgkmcnt(0)
	v_mfma_f32_16x16x32_bf16 v[92:95], v[152:155], v[188:191], 0
	v_mfma_f32_16x16x32_bf16 v[92:95], v[156:159], v[192:195], v[92:95]
	v_mfma_f32_16x16x32_bf16 v[88:91], v[160:163], v[188:191], 0
	v_mfma_f32_16x16x32_bf16 v[88:91], v[164:167], v[192:195], v[88:91]
	v_mfma_f32_16x16x32_bf16 v[84:87], v[152:155], v[196:199], 0
	v_mfma_f32_16x16x32_bf16 v[84:87], v[156:159], v[200:203], v[84:87]
	v_mfma_f32_16x16x32_bf16 v[80:83], v[160:163], v[196:199], 0
	v_mfma_f32_16x16x32_bf16 v[80:83], v[164:167], v[200:203], v[80:83]
	v_mfma_f32_16x16x32_bf16 v[76:79], v[152:155], v[204:207], 0
	v_mfma_f32_16x16x32_bf16 v[76:79], v[156:159], v[208:211], v[76:79]
	v_mfma_f32_16x16x32_bf16 v[72:75], v[160:163], v[204:207], 0
	v_mfma_f32_16x16x32_bf16 v[72:75], v[164:167], v[208:211], v[72:75]
	v_mfma_f32_16x16x32_bf16 v[60:63], v[152:155], v[212:215], 0
	v_mfma_f32_16x16x32_bf16 v[60:63], v[156:159], v[216:219], v[60:63]
	v_mfma_f32_16x16x32_bf16 v[56:59], v[160:163], v[212:215], 0
	v_mfma_f32_16x16x32_bf16 v[56:59], v[164:167], v[216:219], v[56:59]
	s_setprio 0
	s_setprio 1
	v_mfma_f32_16x16x32_bf16 v[28:31], v[168:171], v[188:191], 0
	v_mfma_f32_16x16x32_bf16 v[28:31], v[172:175], v[192:195], v[28:31]
	v_mfma_f32_16x16x32_bf16 v[24:27], v[176:179], v[188:191], 0
	v_mfma_f32_16x16x32_bf16 v[24:27], v[184:187], v[192:195], v[24:27]
	v_mfma_f32_16x16x32_bf16 v[20:23], v[168:171], v[196:199], 0
	v_mfma_f32_16x16x32_bf16 v[20:23], v[172:175], v[200:203], v[20:23]
	v_mfma_f32_16x16x32_bf16 v[16:19], v[176:179], v[196:199], 0
	v_mfma_f32_16x16x32_bf16 v[16:19], v[184:187], v[200:203], v[16:19]
	v_mfma_f32_16x16x32_bf16 v[12:15], v[168:171], v[204:207], 0
	v_mfma_f32_16x16x32_bf16 v[12:15], v[172:175], v[208:211], v[12:15]
	v_mfma_f32_16x16x32_bf16 v[8:11], v[176:179], v[204:207], 0
	v_mfma_f32_16x16x32_bf16 v[8:11], v[184:187], v[208:211], v[8:11]
	v_mfma_f32_16x16x32_bf16 v[4:7], v[168:171], v[212:215], 0
	v_mfma_f32_16x16x32_bf16 v[4:7], v[172:175], v[216:219], v[4:7]
	s_barrier
	v_mfma_f32_16x16x32_bf16 v[0:3], v[176:179], v[212:215], 0
	v_mfma_f32_16x16x32_bf16 v[0:3], v[184:187], v[216:219], v[0:3]
	s_setprio 0
	s_branch .Lmid_gemm9
.LBB0_1162:
	ds_read_b128 v[152:155], v148
	ds_read_b128 v[156:159], v148 offset:1024
	ds_read_b128 v[160:163], v148 offset:2048
	ds_read_b128 v[164:167], v148 offset:3072
	ds_read_b128 v[168:171], v149
	ds_read_b128 v[172:175], v149 offset:1024
	ds_read_b128 v[176:179], v149 offset:2048
	ds_read_b128 v[184:187], v149 offset:3072
	s_add_u32 s62, s60, 0xfffc0080
	s_addc_u32 s63, s61, -1
	s_cmp_eq_u32 s87, 12
	s_cselect_b32 s65, s53, s63
	s_cselect_b32 s64, s83, s62
	s_cselect_b32 s63, s49, s86
	s_cselect_b32 s62, s84, s85
	v_lshl_add_u64 v[220:221], s[60:61], 0, v[138:139]
	s_add_i32 m0, s69, 0xc000
	ds_read_b128 v[188:191], v150
	ds_read_b128 v[192:195], v150 offset:1024
	ds_read_b128 v[196:199], v150 offset:2048
	ds_read_b128 v[200:203], v150 offset:3072
	ds_read_b128 v[204:207], v150 offset:4096
	ds_read_b128 v[208:211], v150 offset:5120
	ds_read_b128 v[212:215], v150 offset:6144
	ds_read_b128 v[216:219], v150 offset:7168
	global_load_lds_dwordx4 v[220:221], off
	v_lshl_add_u64 v[220:221], s[60:61], 0, v[140:141]
	s_add_i32 m0, s69, 0xe000
	s_nop 0
	global_load_lds_dwordx4 v[220:221], off
	s_waitcnt vmcnt(8)
	s_waitcnt lgkmcnt(0)
	s_barrier
	s_setprio 1
	s_waitcnt lgkmcnt(0)
	v_mfma_f32_16x16x32_bf16 v[124:127], v[152:155], v[188:191], v[124:127]
	v_mfma_f32_16x16x32_bf16 v[124:127], v[156:159], v[192:195], v[124:127]
	v_mfma_f32_16x16x32_bf16 v[120:123], v[160:163], v[188:191], v[120:123]
	v_mfma_f32_16x16x32_bf16 v[120:123], v[164:167], v[192:195], v[120:123]
	v_mfma_f32_16x16x32_bf16 v[116:119], v[152:155], v[196:199], v[116:119]
	v_mfma_f32_16x16x32_bf16 v[116:119], v[156:159], v[200:203], v[116:119]
	v_mfma_f32_16x16x32_bf16 v[112:115], v[160:163], v[196:199], v[112:115]
	v_mfma_f32_16x16x32_bf16 v[112:115], v[164:167], v[200:203], v[112:115]
	v_mfma_f32_16x16x32_bf16 v[108:111], v[152:155], v[204:207], v[108:111]
	v_mfma_f32_16x16x32_bf16 v[108:111], v[156:159], v[208:211], v[108:111]
	v_mfma_f32_16x16x32_bf16 v[104:107], v[160:163], v[204:207], v[104:107]
	v_mfma_f32_16x16x32_bf16 v[104:107], v[164:167], v[208:211], v[104:107]
	v_mfma_f32_16x16x32_bf16 v[100:103], v[152:155], v[212:215], v[100:103]
	v_mfma_f32_16x16x32_bf16 v[100:103], v[156:159], v[216:219], v[100:103]
	v_mfma_f32_16x16x32_bf16 v[96:99], v[160:163], v[212:215], v[96:99]
	v_mfma_f32_16x16x32_bf16 v[96:99], v[164:167], v[216:219], v[96:99]
	s_setprio 0
	s_setprio 1
	v_mfma_f32_16x16x32_bf16 v[68:71], v[168:171], v[188:191], v[68:71]
	v_mfma_f32_16x16x32_bf16 v[68:71], v[172:175], v[192:195], v[68:71]
	v_mfma_f32_16x16x32_bf16 v[64:67], v[176:179], v[188:191], v[64:67]
	v_mfma_f32_16x16x32_bf16 v[64:67], v[184:187], v[192:195], v[64:67]
	v_mfma_f32_16x16x32_bf16 v[52:55], v[168:171], v[196:199], v[52:55]
	v_mfma_f32_16x16x32_bf16 v[52:55], v[172:175], v[200:203], v[52:55]
	v_mfma_f32_16x16x32_bf16 v[48:51], v[176:179], v[196:199], v[48:51]
	v_mfma_f32_16x16x32_bf16 v[48:51], v[184:187], v[200:203], v[48:51]
	v_mfma_f32_16x16x32_bf16 v[44:47], v[168:171], v[204:207], v[44:47]
	v_mfma_f32_16x16x32_bf16 v[44:47], v[172:175], v[208:211], v[44:47]
	v_mfma_f32_16x16x32_bf16 v[40:43], v[176:179], v[204:207], v[40:43]
	v_mfma_f32_16x16x32_bf16 v[40:43], v[184:187], v[208:211], v[40:43]
	v_mfma_f32_16x16x32_bf16 v[36:39], v[168:171], v[212:215], v[36:39]
	v_mfma_f32_16x16x32_bf16 v[36:39], v[172:175], v[216:219], v[36:39]
	s_barrier
	v_mfma_f32_16x16x32_bf16 v[32:35], v[176:179], v[212:215], v[32:35]
	v_mfma_f32_16x16x32_bf16 v[32:35], v[184:187], v[216:219], v[32:35]
	s_setprio 0
	s_add_i32 s79, s77, s68
	v_lshl_add_u64 v[220:221], s[62:63], 0, v[130:131]
	s_mov_b32 m0, s79
	ds_read_b128 v[188:191], v150 offset:16384
	ds_read_b128 v[192:195], v150 offset:17408
	ds_read_b128 v[196:199], v150 offset:18432
	ds_read_b128 v[200:203], v150 offset:19456
	ds_read_b128 v[204:207], v150 offset:20480
	ds_read_b128 v[208:211], v150 offset:21504
	ds_read_b128 v[212:215], v150 offset:22528
	ds_read_b128 v[216:219], v150 offset:23552
	global_load_lds_dwordx4 v[220:221], off
	s_add_i32 m0, s79, 0x2000
	s_add_u32 s88, s62, 0x40000
	v_lshl_add_u64 v[222:223], s[62:63], 0, v[134:135]
	s_addc_u32 s89, s63, 0
	s_add_i32 s79, s82, s68
	global_load_lds_dwordx4 v[222:223], off
	v_lshl_add_u64 v[224:225], s[88:89], 0, v[130:131]
	s_mov_b32 m0, s79
	v_lshl_add_u64 v[226:227], s[64:65], 0, v[132:133]
	global_load_lds_dwordx4 v[224:225], off
	v_lshl_add_u64 v[224:225], s[88:89], 0, v[134:135]
	s_add_i32 m0, s79, 0x2000
	s_nop 0
	global_load_lds_dwordx4 v[224:225], off
	v_lshl_add_u64 v[224:225], s[64:65], 0, v[128:129]
	s_mov_b32 m0, s69
	s_nop 0
	global_load_lds_dwordx4 v[224:225], off
	s_mov_b32 m0, s70
	s_nop 0
	global_load_lds_dwordx4 v[226:227], off
	s_waitcnt vmcnt(8)
	s_waitcnt lgkmcnt(0)
	s_barrier
	s_setprio 1
	s_waitcnt lgkmcnt(0)
	v_mfma_f32_16x16x32_bf16 v[92:95], v[152:155], v[188:191], v[92:95]
	v_mfma_f32_16x16x32_bf16 v[92:95], v[156:159], v[192:195], v[92:95]
	v_mfma_f32_16x16x32_bf16 v[88:91], v[160:163], v[188:191], v[88:91]
	v_mfma_f32_16x16x32_bf16 v[88:91], v[164:167], v[192:195], v[88:91]
	v_mfma_f32_16x16x32_bf16 v[84:87], v[152:155], v[196:199], v[84:87]
	v_mfma_f32_16x16x32_bf16 v[84:87], v[156:159], v[200:203], v[84:87]
	v_mfma_f32_16x16x32_bf16 v[80:83], v[160:163], v[196:199], v[80:83]
	v_mfma_f32_16x16x32_bf16 v[80:83], v[164:167], v[200:203], v[80:83]
	v_mfma_f32_16x16x32_bf16 v[76:79], v[152:155], v[204:207], v[76:79]
	v_mfma_f32_16x16x32_bf16 v[76:79], v[156:159], v[208:211], v[76:79]
	v_mfma_f32_16x16x32_bf16 v[72:75], v[160:163], v[204:207], v[72:75]
	v_mfma_f32_16x16x32_bf16 v[72:75], v[164:167], v[208:211], v[72:75]
	v_mfma_f32_16x16x32_bf16 v[60:63], v[152:155], v[212:215], v[60:63]
	v_mfma_f32_16x16x32_bf16 v[60:63], v[156:159], v[216:219], v[60:63]
	v_mfma_f32_16x16x32_bf16 v[56:59], v[160:163], v[212:215], v[56:59]
	v_mfma_f32_16x16x32_bf16 v[56:59], v[164:167], v[216:219], v[56:59]
	s_setprio 0
	s_setprio 1
	v_mfma_f32_16x16x32_bf16 v[28:31], v[168:171], v[188:191], v[28:31]
	v_mfma_f32_16x16x32_bf16 v[28:31], v[172:175], v[192:195], v[28:31]
	v_mfma_f32_16x16x32_bf16 v[24:27], v[176:179], v[188:191], v[24:27]
	v_mfma_f32_16x16x32_bf16 v[24:27], v[184:187], v[192:195], v[24:27]
	v_mfma_f32_16x16x32_bf16 v[20:23], v[168:171], v[196:199], v[20:23]
	v_mfma_f32_16x16x32_bf16 v[20:23], v[172:175], v[200:203], v[20:23]
	v_mfma_f32_16x16x32_bf16 v[16:19], v[176:179], v[196:199], v[16:19]
	v_mfma_f32_16x16x32_bf16 v[16:19], v[184:187], v[200:203], v[16:19]
	v_mfma_f32_16x16x32_bf16 v[12:15], v[168:171], v[204:207], v[12:15]
	v_mfma_f32_16x16x32_bf16 v[12:15], v[172:175], v[208:211], v[12:15]
	v_mfma_f32_16x16x32_bf16 v[8:11], v[176:179], v[204:207], v[8:11]
	v_mfma_f32_16x16x32_bf16 v[8:11], v[184:187], v[208:211], v[8:11]
	v_mfma_f32_16x16x32_bf16 v[4:7], v[168:171], v[212:215], v[4:7]
	v_mfma_f32_16x16x32_bf16 v[4:7], v[172:175], v[216:219], v[4:7]
	s_barrier
	v_mfma_f32_16x16x32_bf16 v[0:3], v[176:179], v[212:215], v[0:3]
	v_mfma_f32_16x16x32_bf16 v[0:3], v[184:187], v[216:219], v[0:3]
	s_setprio 0
.Lmid_gemm9:
	s_add_i32 s79, 0, 0x18000
	s_add_i32 s88, 0, 0x1c000
	v_add_u32_e32 v164, s79, v147
	v_add_u32_e32 v181, s88, v147
	ds_read_b128 v[152:155], v164
	ds_read_b128 v[156:159], v164 offset:1024
	ds_read_b128 v[160:163], v164 offset:2048
	ds_read_b128 v[164:167], v164 offset:3072
	ds_read_b128 v[168:171], v181
	ds_read_b128 v[172:175], v181 offset:1024
	ds_read_b128 v[176:179], v181 offset:2048
	ds_read_b128 v[184:187], v181 offset:3072
	s_add_u32 s64, s64, 0x40000
	s_addc_u32 s65, s65, 0
	s_mov_b32 m0, s71
	v_lshl_add_u64 v[228:229], s[64:65], 0, v[128:129]
	ds_read_b128 v[188:191], v150 offset:32768
	ds_read_b128 v[192:195], v150 offset:33792
	ds_read_b128 v[196:199], v150 offset:34816
	ds_read_b128 v[200:203], v150 offset:35840
	ds_read_b128 v[204:207], v150 offset:36864
	ds_read_b128 v[208:211], v150 offset:37888
	ds_read_b128 v[212:215], v150 offset:38912
	ds_read_b128 v[216:219], v150 offset:39936
	global_load_lds_dwordx4 v[228:229], off
	v_lshl_add_u64 v[228:229], s[64:65], 0, v[132:133]
	s_mov_b32 m0, s72
	s_nop 0
	global_load_lds_dwordx4 v[228:229], off
	s_waitcnt vmcnt(8)
	s_waitcnt lgkmcnt(0)
	s_barrier
	s_setprio 1
	s_waitcnt lgkmcnt(0)
	v_mfma_f32_16x16x32_bf16 v[124:127], v[152:155], v[188:191], v[124:127]
	v_mfma_f32_16x16x32_bf16 v[124:127], v[156:159], v[192:195], v[124:127]
	v_mfma_f32_16x16x32_bf16 v[120:123], v[160:163], v[188:191], v[120:123]
	v_mfma_f32_16x16x32_bf16 v[120:123], v[164:167], v[192:195], v[120:123]
	v_mfma_f32_16x16x32_bf16 v[116:119], v[152:155], v[196:199], v[116:119]
	v_mfma_f32_16x16x32_bf16 v[116:119], v[156:159], v[200:203], v[116:119]
	v_mfma_f32_16x16x32_bf16 v[112:115], v[160:163], v[196:199], v[112:115]
	v_mfma_f32_16x16x32_bf16 v[112:115], v[164:167], v[200:203], v[112:115]
	v_mfma_f32_16x16x32_bf16 v[108:111], v[152:155], v[204:207], v[108:111]
	v_mfma_f32_16x16x32_bf16 v[108:111], v[156:159], v[208:211], v[108:111]
	v_mfma_f32_16x16x32_bf16 v[104:107], v[160:163], v[204:207], v[104:107]
	v_mfma_f32_16x16x32_bf16 v[104:107], v[164:167], v[208:211], v[104:107]
	v_mfma_f32_16x16x32_bf16 v[100:103], v[152:155], v[212:215], v[100:103]
	v_mfma_f32_16x16x32_bf16 v[100:103], v[156:159], v[216:219], v[100:103]
	v_mfma_f32_16x16x32_bf16 v[96:99], v[160:163], v[212:215], v[96:99]
	v_mfma_f32_16x16x32_bf16 v[96:99], v[164:167], v[216:219], v[96:99]
	s_setprio 0
	s_setprio 1
	v_mfma_f32_16x16x32_bf16 v[68:71], v[168:171], v[188:191], v[68:71]
	v_mfma_f32_16x16x32_bf16 v[68:71], v[172:175], v[192:195], v[68:71]
	v_mfma_f32_16x16x32_bf16 v[64:67], v[176:179], v[188:191], v[64:67]
	v_mfma_f32_16x16x32_bf16 v[64:67], v[184:187], v[192:195], v[64:67]
	v_mfma_f32_16x16x32_bf16 v[52:55], v[168:171], v[196:199], v[52:55]
	v_mfma_f32_16x16x32_bf16 v[52:55], v[172:175], v[200:203], v[52:55]
	v_mfma_f32_16x16x32_bf16 v[48:51], v[176:179], v[196:199], v[48:51]
	v_mfma_f32_16x16x32_bf16 v[48:51], v[184:187], v[200:203], v[48:51]
	v_mfma_f32_16x16x32_bf16 v[44:47], v[168:171], v[204:207], v[44:47]
	v_mfma_f32_16x16x32_bf16 v[44:47], v[172:175], v[208:211], v[44:47]
	v_mfma_f32_16x16x32_bf16 v[40:43], v[176:179], v[204:207], v[40:43]
	v_mfma_f32_16x16x32_bf16 v[40:43], v[184:187], v[208:211], v[40:43]
	v_mfma_f32_16x16x32_bf16 v[36:39], v[168:171], v[212:215], v[36:39]
	v_mfma_f32_16x16x32_bf16 v[36:39], v[172:175], v[216:219], v[36:39]
	s_barrier
	v_mfma_f32_16x16x32_bf16 v[32:35], v[176:179], v[212:215], v[32:35]
	v_mfma_f32_16x16x32_bf16 v[32:35], v[184:187], v[216:219], v[32:35]
	s_setprio 0
	s_add_i32 s64, s79, s68
	v_lshl_add_u64 v[220:221], v[220:221], 0, s[12:13]
	s_mov_b32 m0, s64
	ds_read_b128 v[188:191], v150 offset:49152
	ds_read_b128 v[192:195], v150 offset:50176
	ds_read_b128 v[196:199], v150 offset:51200
	ds_read_b128 v[200:203], v150 offset:52224
	ds_read_b128 v[204:207], v150 offset:53248
	ds_read_b128 v[208:211], v150 offset:54272
	ds_read_b128 v[212:215], v150 offset:55296
	ds_read_b128 v[216:219], v150 offset:56320
	global_load_lds_dwordx4 v[220:221], off
	s_add_i32 m0, s64, 0x2000
	s_add_u32 s62, s62, 0x40080
	v_lshl_add_u64 v[220:221], v[222:223], 0, s[12:13]
	s_addc_u32 s63, s63, 0
	s_add_i32 s64, s88, s68
	global_load_lds_dwordx4 v[220:221], off
	v_lshl_add_u64 v[220:221], s[62:63], 0, v[130:131]
	s_mov_b32 m0, s64
	s_nop 0
	global_load_lds_dwordx4 v[220:221], off
	v_lshl_add_u64 v[220:221], s[62:63], 0, v[134:135]
	s_add_i32 m0, s64, 0x2000
	s_nop 0
	global_load_lds_dwordx4 v[220:221], off
	v_lshl_add_u64 v[220:221], v[224:225], 0, s[12:13]
	s_mov_b32 m0, s75
	s_nop 0
	global_load_lds_dwordx4 v[220:221], off
	v_lshl_add_u64 v[220:221], v[226:227], 0, s[12:13]
	s_mov_b32 m0, s76
	s_nop 0
	global_load_lds_dwordx4 v[220:221], off
	s_waitcnt vmcnt(8)
	s_waitcnt lgkmcnt(0)
	s_barrier
	s_setprio 1
	s_waitcnt lgkmcnt(0)
	v_mfma_f32_16x16x32_bf16 v[92:95], v[152:155], v[188:191], v[92:95]
	v_mfma_f32_16x16x32_bf16 v[92:95], v[156:159], v[192:195], v[92:95]
	v_mfma_f32_16x16x32_bf16 v[88:91], v[160:163], v[188:191], v[88:91]
	v_mfma_f32_16x16x32_bf16 v[88:91], v[164:167], v[192:195], v[88:91]
	v_mfma_f32_16x16x32_bf16 v[84:87], v[152:155], v[196:199], v[84:87]
	v_mfma_f32_16x16x32_bf16 v[84:87], v[156:159], v[200:203], v[84:87]
	v_mfma_f32_16x16x32_bf16 v[80:83], v[160:163], v[196:199], v[80:83]
	v_mfma_f32_16x16x32_bf16 v[80:83], v[164:167], v[200:203], v[80:83]
	v_mfma_f32_16x16x32_bf16 v[76:79], v[152:155], v[204:207], v[76:79]
	v_mfma_f32_16x16x32_bf16 v[76:79], v[156:159], v[208:211], v[76:79]
	v_mfma_f32_16x16x32_bf16 v[72:75], v[160:163], v[204:207], v[72:75]
	v_mfma_f32_16x16x32_bf16 v[72:75], v[164:167], v[208:211], v[72:75]
	v_mfma_f32_16x16x32_bf16 v[60:63], v[152:155], v[212:215], v[60:63]
	v_mfma_f32_16x16x32_bf16 v[60:63], v[156:159], v[216:219], v[60:63]
	v_mfma_f32_16x16x32_bf16 v[56:59], v[160:163], v[212:215], v[56:59]
	v_mfma_f32_16x16x32_bf16 v[56:59], v[164:167], v[216:219], v[56:59]
	s_setprio 0
	s_setprio 1
	v_mfma_f32_16x16x32_bf16 v[28:31], v[168:171], v[188:191], v[28:31]
	v_mfma_f32_16x16x32_bf16 v[28:31], v[172:175], v[192:195], v[28:31]
	v_mfma_f32_16x16x32_bf16 v[24:27], v[176:179], v[188:191], v[24:27]
	v_mfma_f32_16x16x32_bf16 v[24:27], v[184:187], v[192:195], v[24:27]
	v_mfma_f32_16x16x32_bf16 v[20:23], v[168:171], v[196:199], v[20:23]
	v_mfma_f32_16x16x32_bf16 v[20:23], v[172:175], v[200:203], v[20:23]
	v_mfma_f32_16x16x32_bf16 v[16:19], v[176:179], v[196:199], v[16:19]
	v_mfma_f32_16x16x32_bf16 v[16:19], v[184:187], v[200:203], v[16:19]
	v_mfma_f32_16x16x32_bf16 v[12:15], v[168:171], v[204:207], v[12:15]
	v_mfma_f32_16x16x32_bf16 v[12:15], v[172:175], v[208:211], v[12:15]
	v_mfma_f32_16x16x32_bf16 v[8:11], v[176:179], v[204:207], v[8:11]
	v_mfma_f32_16x16x32_bf16 v[8:11], v[184:187], v[208:211], v[8:11]
	v_mfma_f32_16x16x32_bf16 v[4:7], v[168:171], v[212:215], v[4:7]
	v_mfma_f32_16x16x32_bf16 v[4:7], v[172:175], v[216:219], v[4:7]
	s_barrier
	v_mfma_f32_16x16x32_bf16 v[0:3], v[176:179], v[212:215], v[0:3]
	v_mfma_f32_16x16x32_bf16 v[0:3], v[184:187], v[216:219], v[0:3]
	s_setprio 0
	s_add_i32 s87, s87, 2
	s_add_u32 s60, s60, 0x100
	s_addc_u32 s61, s61, 0
	s_add_u32 s85, s85, 0x100
	s_addc_u32 s86, s86, 0
	s_cmp_gt_u32 s87, 13
	s_cbranch_scc0 .LBB0_1162
	s_and_b64 vcc, exec, s[16:17]
	s_cbranch_vccz .LBB0_1165
	s_barrier

.LBB0_1310:
	s_ashr_i32 s49, s48, 31
	s_lshl_b64 s[50:51], s[48:49], 19
	s_add_u32 s50, s38, s50
	s_addc_u32 s51, s39, s51
	s_and_b64 s[52:53], s[10:11], exec
	s_cselect_b32 s49, s51, s57
	s_cselect_b32 s82, s50, s56
	s_ashr_i32 s47, s46, 31
	s_lshl_b64 s[52:53], s[46:47], 19
	s_add_u32 s52, s62, s52
	s_addc_u32 s53, s63, s53
	s_and_b64 s[60:61], s[10:11], exec
	s_cselect_b32 s47, s53, s59
	s_cselect_b32 s83, s52, s58
	s_add_u32 s56, s56, 0x40080
	s_addc_u32 s57, s57, 0
	s_add_u32 s84, s58, 0x100
	s_addc_u32 s85, s59, 0
	s_mov_b32 s86, -2
	ds_read_b128 v[152:155], v149
	ds_read_b128 v[156:159], v149 offset:1024
	ds_read_b128 v[160:163], v149 offset:2048
	ds_read_b128 v[164:167], v149 offset:3072
	ds_read_b128 v[168:171], v150
	ds_read_b128 v[172:175], v150 offset:1024
	ds_read_b128 v[176:179], v150 offset:2048
	ds_read_b128 v[184:187], v150 offset:3072
	s_add_u32 s58, s56, 0xfffc0080
	s_addc_u32 s59, s57, -1
	s_cmp_eq_u32 s86, 12
	s_cselect_b32 s61, s49, s59
	s_cselect_b32 s60, s82, s58
	s_cselect_b32 s59, s47, s85
	s_cselect_b32 s58, s83, s84
	v_lshl_add_u64 v[144:145], s[56:57], 0, v[136:137]
	s_add_i32 m0, s55, 0xc000
	ds_read_b128 v[188:191], v151
	ds_read_b128 v[192:195], v151 offset:1024
	ds_read_b128 v[196:199], v151 offset:2048
	ds_read_b128 v[200:203], v151 offset:3072
	ds_read_b128 v[204:207], v151 offset:4096
	ds_read_b128 v[208:211], v151 offset:5120
	ds_read_b128 v[212:215], v151 offset:6144
	ds_read_b128 v[216:219], v151 offset:7168
	global_load_lds_dwordx4 v[144:145], off
	v_lshl_add_u64 v[144:145], s[56:57], 0, v[138:139]
	s_add_i32 m0, s55, 0xe000
	s_nop 0
	global_load_lds_dwordx4 v[144:145], off
	s_waitcnt vmcnt(8)
	s_waitcnt lgkmcnt(0)
	s_barrier
	s_setprio 1
	s_waitcnt lgkmcnt(0)
	v_mfma_f32_16x16x32_bf16 v[124:127], v[152:155], v[188:191], 0
	v_mfma_f32_16x16x32_bf16 v[124:127], v[156:159], v[192:195], v[124:127]
	v_mfma_f32_16x16x32_bf16 v[120:123], v[160:163], v[188:191], 0
	v_mfma_f32_16x16x32_bf16 v[120:123], v[164:167], v[192:195], v[120:123]
	v_mfma_f32_16x16x32_bf16 v[116:119], v[152:155], v[196:199], 0
	v_mfma_f32_16x16x32_bf16 v[116:119], v[156:159], v[200:203], v[116:119]
	v_mfma_f32_16x16x32_bf16 v[108:111], v[160:163], v[196:199], 0
	v_mfma_f32_16x16x32_bf16 v[108:111], v[164:167], v[200:203], v[108:111]
	v_mfma_f32_16x16x32_bf16 v[100:103], v[152:155], v[204:207], 0
	v_mfma_f32_16x16x32_bf16 v[100:103], v[156:159], v[208:211], v[100:103]
	v_mfma_f32_16x16x32_bf16 v[92:95], v[160:163], v[204:207], 0
	v_mfma_f32_16x16x32_bf16 v[92:95], v[164:167], v[208:211], v[92:95]
	v_mfma_f32_16x16x32_bf16 v[84:87], v[152:155], v[212:215], 0
	v_mfma_f32_16x16x32_bf16 v[84:87], v[156:159], v[216:219], v[84:87]
	v_mfma_f32_16x16x32_bf16 v[76:79], v[160:163], v[212:215], 0
	v_mfma_f32_16x16x32_bf16 v[76:79], v[164:167], v[216:219], v[76:79]
	s_setprio 0
	s_setprio 1
	v_mfma_f32_16x16x32_bf16 v[112:115], v[168:171], v[188:191], 0
	v_mfma_f32_16x16x32_bf16 v[112:115], v[172:175], v[192:195], v[112:115]
	v_mfma_f32_16x16x32_bf16 v[104:107], v[176:179], v[188:191], 0
	v_mfma_f32_16x16x32_bf16 v[104:107], v[184:187], v[192:195], v[104:107]
	v_mfma_f32_16x16x32_bf16 v[96:99], v[168:171], v[196:199], 0
	v_mfma_f32_16x16x32_bf16 v[96:99], v[172:175], v[200:203], v[96:99]
	v_mfma_f32_16x16x32_bf16 v[88:91], v[176:179], v[196:199], 0
	v_mfma_f32_16x16x32_bf16 v[88:91], v[184:187], v[200:203], v[88:91]
	v_mfma_f32_16x16x32_bf16 v[80:83], v[168:171], v[204:207], 0
	v_mfma_f32_16x16x32_bf16 v[80:83], v[172:175], v[208:211], v[80:83]
	v_mfma_f32_16x16x32_bf16 v[72:75], v[176:179], v[204:207], 0
	v_mfma_f32_16x16x32_bf16 v[72:75], v[184:187], v[208:211], v[72:75]
	v_mfma_f32_16x16x32_bf16 v[68:71], v[168:171], v[212:215], 0
	v_mfma_f32_16x16x32_bf16 v[68:71], v[172:175], v[216:219], v[68:71]
	s_barrier
	v_mfma_f32_16x16x32_bf16 v[64:67], v[176:179], v[212:215], 0
	v_mfma_f32_16x16x32_bf16 v[64:67], v[184:187], v[216:219], v[64:67]
	s_setprio 0
	s_add_i32 s79, s71, s64
	v_lshl_add_u64 v[144:145], s[58:59], 0, v[130:131]
	s_mov_b32 m0, s79
	ds_read_b128 v[188:191], v151 offset:16384
	ds_read_b128 v[192:195], v151 offset:17408
	ds_read_b128 v[196:199], v151 offset:18432
	ds_read_b128 v[200:203], v151 offset:19456
	ds_read_b128 v[204:207], v151 offset:20480
	ds_read_b128 v[208:211], v151 offset:21504
	ds_read_b128 v[212:215], v151 offset:22528
	ds_read_b128 v[216:219], v151 offset:23552
	global_load_lds_dwordx4 v[144:145], off
	s_add_i32 m0, s79, 0x2000
	s_add_u32 s88, s58, 0x40000
	v_lshl_add_u64 v[220:221], s[58:59], 0, v[134:135]
	s_addc_u32 s89, s59, 0
	s_add_i32 s79, s72, s64
	global_load_lds_dwordx4 v[220:221], off
	v_lshl_add_u64 v[222:223], s[88:89], 0, v[130:131]
	s_mov_b32 m0, s79
	v_lshl_add_u64 v[224:225], s[60:61], 0, v[132:133]
	global_load_lds_dwordx4 v[222:223], off
	v_lshl_add_u64 v[222:223], s[88:89], 0, v[134:135]
	s_add_i32 m0, s79, 0x2000
	s_nop 0
	global_load_lds_dwordx4 v[222:223], off
	v_lshl_add_u64 v[222:223], s[60:61], 0, v[128:129]
	s_mov_b32 m0, s55
	s_nop 0
	global_load_lds_dwordx4 v[222:223], off
	s_mov_b32 m0, s65
	s_nop 0
	global_load_lds_dwordx4 v[224:225], off
	s_waitcnt vmcnt(8)
	s_waitcnt lgkmcnt(0)
	s_barrier
	s_setprio 1
	s_waitcnt lgkmcnt(0)
	v_mfma_f32_16x16x32_bf16 v[60:63], v[152:155], v[188:191], 0
	v_mfma_f32_16x16x32_bf16 v[60:63], v[156:159], v[192:195], v[60:63]
	v_mfma_f32_16x16x32_bf16 v[56:59], v[160:163], v[188:191], 0
	v_mfma_f32_16x16x32_bf16 v[56:59], v[164:167], v[192:195], v[56:59]
	v_mfma_f32_16x16x32_bf16 v[52:55], v[152:155], v[196:199], 0
	v_mfma_f32_16x16x32_bf16 v[52:55], v[156:159], v[200:203], v[52:55]
	v_mfma_f32_16x16x32_bf16 v[44:47], v[160:163], v[196:199], 0
	v_mfma_f32_16x16x32_bf16 v[44:47], v[164:167], v[200:203], v[44:47]
	v_mfma_f32_16x16x32_bf16 v[36:39], v[152:155], v[204:207], 0
	v_mfma_f32_16x16x32_bf16 v[36:39], v[156:159], v[208:211], v[36:39]
	v_mfma_f32_16x16x32_bf16 v[28:31], v[160:163], v[204:207], 0
	v_mfma_f32_16x16x32_bf16 v[28:31], v[164:167], v[208:211], v[28:31]
	v_mfma_f32_16x16x32_bf16 v[20:23], v[152:155], v[212:215], 0
	v_mfma_f32_16x16x32_bf16 v[20:23], v[156:159], v[216:219], v[20:23]
	v_mfma_f32_16x16x32_bf16 v[12:15], v[160:163], v[212:215], 0
	v_mfma_f32_16x16x32_bf16 v[12:15], v[164:167], v[216:219], v[12:15]
	s_setprio 0
	s_setprio 1
	v_mfma_f32_16x16x32_bf16 v[48:51], v[168:171], v[188:191], 0
	v_mfma_f32_16x16x32_bf16 v[48:51], v[172:175], v[192:195], v[48:51]
	v_mfma_f32_16x16x32_bf16 v[40:43], v[176:179], v[188:191], 0
	v_mfma_f32_16x16x32_bf16 v[40:43], v[184:187], v[192:195], v[40:43]
	v_mfma_f32_16x16x32_bf16 v[32:35], v[168:171], v[196:199], 0
	v_mfma_f32_16x16x32_bf16 v[32:35], v[172:175], v[200:203], v[32:35]
	v_mfma_f32_16x16x32_bf16 v[24:27], v[176:179], v[196:199], 0
	v_mfma_f32_16x16x32_bf16 v[24:27], v[184:187], v[200:203], v[24:27]
	v_mfma_f32_16x16x32_bf16 v[16:19], v[168:171], v[204:207], 0
	v_mfma_f32_16x16x32_bf16 v[16:19], v[172:175], v[208:211], v[16:19]
	v_mfma_f32_16x16x32_bf16 v[8:11], v[176:179], v[204:207], 0
	v_mfma_f32_16x16x32_bf16 v[8:11], v[184:187], v[208:211], v[8:11]
	v_mfma_f32_16x16x32_bf16 v[4:7], v[168:171], v[212:215], 0
	v_mfma_f32_16x16x32_bf16 v[4:7], v[172:175], v[216:219], v[4:7]
	s_barrier
	v_mfma_f32_16x16x32_bf16 v[0:3], v[176:179], v[212:215], 0
	v_mfma_f32_16x16x32_bf16 v[0:3], v[184:187], v[216:219], v[0:3]
	s_setprio 0
	s_branch .Lmid_gemm10
.LBB0_1311:
	ds_read_b128 v[152:155], v149
	ds_read_b128 v[156:159], v149 offset:1024
	ds_read_b128 v[160:163], v149 offset:2048
	ds_read_b128 v[164:167], v149 offset:3072
	ds_read_b128 v[168:171], v150
	ds_read_b128 v[172:175], v150 offset:1024
	ds_read_b128 v[176:179], v150 offset:2048
	ds_read_b128 v[184:187], v150 offset:3072
	s_add_u32 s58, s56, 0xfffc0080
	s_addc_u32 s59, s57, -1
	s_cmp_eq_u32 s86, 12
	s_cselect_b32 s61, s49, s59
	s_cselect_b32 s60, s82, s58
	s_cselect_b32 s59, s47, s85
	s_cselect_b32 s58, s83, s84
	v_lshl_add_u64 v[144:145], s[56:57], 0, v[136:137]
	s_add_i32 m0, s55, 0xc000
	ds_read_b128 v[188:191], v151
	ds_read_b128 v[192:195], v151 offset:1024
	ds_read_b128 v[196:199], v151 offset:2048
	ds_read_b128 v[200:203], v151 offset:3072
	ds_read_b128 v[204:207], v151 offset:4096
	ds_read_b128 v[208:211], v151 offset:5120
	ds_read_b128 v[212:215], v151 offset:6144
	ds_read_b128 v[216:219], v151 offset:7168
	global_load_lds_dwordx4 v[144:145], off
	v_lshl_add_u64 v[144:145], s[56:57], 0, v[138:139]
	s_add_i32 m0, s55, 0xe000
	s_nop 0
	global_load_lds_dwordx4 v[144:145], off
	s_waitcnt vmcnt(8)
	s_waitcnt lgkmcnt(0)
	s_barrier
	s_setprio 1
	s_waitcnt lgkmcnt(0)
	v_mfma_f32_16x16x32_bf16 v[124:127], v[152:155], v[188:191], v[124:127]
	v_mfma_f32_16x16x32_bf16 v[124:127], v[156:159], v[192:195], v[124:127]
	v_mfma_f32_16x16x32_bf16 v[120:123], v[160:163], v[188:191], v[120:123]
	v_mfma_f32_16x16x32_bf16 v[120:123], v[164:167], v[192:195], v[120:123]
	v_mfma_f32_16x16x32_bf16 v[116:119], v[152:155], v[196:199], v[116:119]
	v_mfma_f32_16x16x32_bf16 v[116:119], v[156:159], v[200:203], v[116:119]
	v_mfma_f32_16x16x32_bf16 v[108:111], v[160:163], v[196:199], v[108:111]
	v_mfma_f32_16x16x32_bf16 v[108:111], v[164:167], v[200:203], v[108:111]
	v_mfma_f32_16x16x32_bf16 v[100:103], v[152:155], v[204:207], v[100:103]
	v_mfma_f32_16x16x32_bf16 v[100:103], v[156:159], v[208:211], v[100:103]
	v_mfma_f32_16x16x32_bf16 v[92:95], v[160:163], v[204:207], v[92:95]
	v_mfma_f32_16x16x32_bf16 v[92:95], v[164:167], v[208:211], v[92:95]
	v_mfma_f32_16x16x32_bf16 v[84:87], v[152:155], v[212:215], v[84:87]
	v_mfma_f32_16x16x32_bf16 v[84:87], v[156:159], v[216:219], v[84:87]
	v_mfma_f32_16x16x32_bf16 v[76:79], v[160:163], v[212:215], v[76:79]
	v_mfma_f32_16x16x32_bf16 v[76:79], v[164:167], v[216:219], v[76:79]
	s_setprio 0
	s_setprio 1
	v_mfma_f32_16x16x32_bf16 v[112:115], v[168:171], v[188:191], v[112:115]
	v_mfma_f32_16x16x32_bf16 v[112:115], v[172:175], v[192:195], v[112:115]
	v_mfma_f32_16x16x32_bf16 v[104:107], v[176:179], v[188:191], v[104:107]
	v_mfma_f32_16x16x32_bf16 v[104:107], v[184:187], v[192:195], v[104:107]
	v_mfma_f32_16x16x32_bf16 v[96:99], v[168:171], v[196:199], v[96:99]
	v_mfma_f32_16x16x32_bf16 v[96:99], v[172:175], v[200:203], v[96:99]
	v_mfma_f32_16x16x32_bf16 v[88:91], v[176:179], v[196:199], v[88:91]
	v_mfma_f32_16x16x32_bf16 v[88:91], v[184:187], v[200:203], v[88:91]
	v_mfma_f32_16x16x32_bf16 v[80:83], v[168:171], v[204:207], v[80:83]
	v_mfma_f32_16x16x32_bf16 v[80:83], v[172:175], v[208:211], v[80:83]
	v_mfma_f32_16x16x32_bf16 v[72:75], v[176:179], v[204:207], v[72:75]
	v_mfma_f32_16x16x32_bf16 v[72:75], v[184:187], v[208:211], v[72:75]
	v_mfma_f32_16x16x32_bf16 v[68:71], v[168:171], v[212:215], v[68:71]
	v_mfma_f32_16x16x32_bf16 v[68:71], v[172:175], v[216:219], v[68:71]
	s_barrier
	v_mfma_f32_16x16x32_bf16 v[64:67], v[176:179], v[212:215], v[64:67]
	v_mfma_f32_16x16x32_bf16 v[64:67], v[184:187], v[216:219], v[64:67]
	s_setprio 0
	s_add_i32 s79, s71, s64
	v_lshl_add_u64 v[144:145], s[58:59], 0, v[130:131]
	s_mov_b32 m0, s79
	ds_read_b128 v[188:191], v151 offset:16384
	ds_read_b128 v[192:195], v151 offset:17408
	ds_read_b128 v[196:199], v151 offset:18432
	ds_read_b128 v[200:203], v151 offset:19456
	ds_read_b128 v[204:207], v151 offset:20480
	ds_read_b128 v[208:211], v151 offset:21504
	ds_read_b128 v[212:215], v151 offset:22528
	ds_read_b128 v[216:219], v151 offset:23552
	global_load_lds_dwordx4 v[144:145], off
	s_add_i32 m0, s79, 0x2000
	s_add_u32 s88, s58, 0x40000
	v_lshl_add_u64 v[220:221], s[58:59], 0, v[134:135]
	s_addc_u32 s89, s59, 0
	s_add_i32 s79, s72, s64
	global_load_lds_dwordx4 v[220:221], off
	v_lshl_add_u64 v[222:223], s[88:89], 0, v[130:131]
	s_mov_b32 m0, s79
	v_lshl_add_u64 v[224:225], s[60:61], 0, v[132:133]
	global_load_lds_dwordx4 v[222:223], off
	v_lshl_add_u64 v[222:223], s[88:89], 0, v[134:135]
	s_add_i32 m0, s79, 0x2000
	s_nop 0
	global_load_lds_dwordx4 v[222:223], off
	v_lshl_add_u64 v[222:223], s[60:61], 0, v[128:129]
	s_mov_b32 m0, s55
	s_nop 0
	global_load_lds_dwordx4 v[222:223], off
	s_mov_b32 m0, s65
	s_nop 0
	global_load_lds_dwordx4 v[224:225], off
	s_waitcnt vmcnt(8)
	s_waitcnt lgkmcnt(0)
	s_barrier
	s_setprio 1
	s_waitcnt lgkmcnt(0)
	v_mfma_f32_16x16x32_bf16 v[60:63], v[152:155], v[188:191], v[60:63]
	v_mfma_f32_16x16x32_bf16 v[60:63], v[156:159], v[192:195], v[60:63]
	v_mfma_f32_16x16x32_bf16 v[56:59], v[160:163], v[188:191], v[56:59]
	v_mfma_f32_16x16x32_bf16 v[56:59], v[164:167], v[192:195], v[56:59]
	v_mfma_f32_16x16x32_bf16 v[52:55], v[152:155], v[196:199], v[52:55]
	v_mfma_f32_16x16x32_bf16 v[52:55], v[156:159], v[200:203], v[52:55]
	v_mfma_f32_16x16x32_bf16 v[44:47], v[160:163], v[196:199], v[44:47]
	v_mfma_f32_16x16x32_bf16 v[44:47], v[164:167], v[200:203], v[44:47]
	v_mfma_f32_16x16x32_bf16 v[36:39], v[152:155], v[204:207], v[36:39]
	v_mfma_f32_16x16x32_bf16 v[36:39], v[156:159], v[208:211], v[36:39]
	v_mfma_f32_16x16x32_bf16 v[28:31], v[160:163], v[204:207], v[28:31]
	v_mfma_f32_16x16x32_bf16 v[28:31], v[164:167], v[208:211], v[28:31]
	v_mfma_f32_16x16x32_bf16 v[20:23], v[152:155], v[212:215], v[20:23]
	v_mfma_f32_16x16x32_bf16 v[20:23], v[156:159], v[216:219], v[20:23]
	v_mfma_f32_16x16x32_bf16 v[12:15], v[160:163], v[212:215], v[12:15]
	v_mfma_f32_16x16x32_bf16 v[12:15], v[164:167], v[216:219], v[12:15]
	s_setprio 0
	s_setprio 1
	v_mfma_f32_16x16x32_bf16 v[48:51], v[168:171], v[188:191], v[48:51]
	v_mfma_f32_16x16x32_bf16 v[48:51], v[172:175], v[192:195], v[48:51]
	v_mfma_f32_16x16x32_bf16 v[40:43], v[176:179], v[188:191], v[40:43]
	v_mfma_f32_16x16x32_bf16 v[40:43], v[184:187], v[192:195], v[40:43]
	v_mfma_f32_16x16x32_bf16 v[32:35], v[168:171], v[196:199], v[32:35]
	v_mfma_f32_16x16x32_bf16 v[32:35], v[172:175], v[200:203], v[32:35]
	v_mfma_f32_16x16x32_bf16 v[24:27], v[176:179], v[196:199], v[24:27]
	v_mfma_f32_16x16x32_bf16 v[24:27], v[184:187], v[200:203], v[24:27]
	v_mfma_f32_16x16x32_bf16 v[16:19], v[168:171], v[204:207], v[16:19]
	v_mfma_f32_16x16x32_bf16 v[16:19], v[172:175], v[208:211], v[16:19]
	v_mfma_f32_16x16x32_bf16 v[8:11], v[176:179], v[204:207], v[8:11]
	v_mfma_f32_16x16x32_bf16 v[8:11], v[184:187], v[208:211], v[8:11]
	v_mfma_f32_16x16x32_bf16 v[4:7], v[168:171], v[212:215], v[4:7]
	v_mfma_f32_16x16x32_bf16 v[4:7], v[172:175], v[216:219], v[4:7]
	s_barrier
	v_mfma_f32_16x16x32_bf16 v[0:3], v[176:179], v[212:215], v[0:3]
	v_mfma_f32_16x16x32_bf16 v[0:3], v[184:187], v[216:219], v[0:3]
	s_setprio 0
.Lmid_gemm10:
	s_add_i32 s79, 0, 0x18000
	s_add_i32 s87, 0, 0x1c000
	v_add_u32_e32 v164, s79, v147
	v_add_u32_e32 v181, s87, v147
	ds_read_b128 v[152:155], v164
	ds_read_b128 v[156:159], v164 offset:1024
	ds_read_b128 v[160:163], v164 offset:2048
	ds_read_b128 v[164:167], v164 offset:3072
	ds_read_b128 v[168:171], v181
	ds_read_b128 v[172:175], v181 offset:1024
	ds_read_b128 v[176:179], v181 offset:2048
	ds_read_b128 v[184:187], v181 offset:3072
	s_add_u32 s60, s60, 0x40000
	s_addc_u32 s61, s61, 0
	s_mov_b32 m0, s66
	v_lshl_add_u64 v[226:227], s[60:61], 0, v[128:129]
	ds_read_b128 v[188:191], v151 offset:32768
	ds_read_b128 v[192:195], v151 offset:33792
	ds_read_b128 v[196:199], v151 offset:34816
	ds_read_b128 v[200:203], v151 offset:35840
	ds_read_b128 v[204:207], v151 offset:36864
	ds_read_b128 v[208:211], v151 offset:37888
	ds_read_b128 v[212:215], v151 offset:38912
	ds_read_b128 v[216:219], v151 offset:39936
	global_load_lds_dwordx4 v[226:227], off
	v_lshl_add_u64 v[226:227], s[60:61], 0, v[132:133]
	s_mov_b32 m0, s67
	s_nop 0
	global_load_lds_dwordx4 v[226:227], off
	s_waitcnt vmcnt(8)
	s_waitcnt lgkmcnt(0)
	s_barrier
	s_setprio 1
	s_waitcnt lgkmcnt(0)
	v_mfma_f32_16x16x32_bf16 v[124:127], v[152:155], v[188:191], v[124:127]
	v_mfma_f32_16x16x32_bf16 v[124:127], v[156:159], v[192:195], v[124:127]
	v_mfma_f32_16x16x32_bf16 v[120:123], v[160:163], v[188:191], v[120:123]
	v_mfma_f32_16x16x32_bf16 v[120:123], v[164:167], v[192:195], v[120:123]
	v_mfma_f32_16x16x32_bf16 v[116:119], v[152:155], v[196:199], v[116:119]
	v_mfma_f32_16x16x32_bf16 v[116:119], v[156:159], v[200:203], v[116:119]
	v_mfma_f32_16x16x32_bf16 v[108:111], v[160:163], v[196:199], v[108:111]
	v_mfma_f32_16x16x32_bf16 v[108:111], v[164:167], v[200:203], v[108:111]
	v_mfma_f32_16x16x32_bf16 v[100:103], v[152:155], v[204:207], v[100:103]
	v_mfma_f32_16x16x32_bf16 v[100:103], v[156:159], v[208:211], v[100:103]
	v_mfma_f32_16x16x32_bf16 v[92:95], v[160:163], v[204:207], v[92:95]
	v_mfma_f32_16x16x32_bf16 v[92:95], v[164:167], v[208:211], v[92:95]
	v_mfma_f32_16x16x32_bf16 v[84:87], v[152:155], v[212:215], v[84:87]
	v_mfma_f32_16x16x32_bf16 v[84:87], v[156:159], v[216:219], v[84:87]
	v_mfma_f32_16x16x32_bf16 v[76:79], v[160:163], v[212:215], v[76:79]
	v_mfma_f32_16x16x32_bf16 v[76:79], v[164:167], v[216:219], v[76:79]
	s_setprio 0
	s_setprio 1
	v_mfma_f32_16x16x32_bf16 v[112:115], v[168:171], v[188:191], v[112:115]
	v_mfma_f32_16x16x32_bf16 v[112:115], v[172:175], v[192:195], v[112:115]
	v_mfma_f32_16x16x32_bf16 v[104:107], v[176:179], v[188:191], v[104:107]
	v_mfma_f32_16x16x32_bf16 v[104:107], v[184:187], v[192:195], v[104:107]
	v_mfma_f32_16x16x32_bf16 v[96:99], v[168:171], v[196:199], v[96:99]
	v_mfma_f32_16x16x32_bf16 v[96:99], v[172:175], v[200:203], v[96:99]
	v_mfma_f32_16x16x32_bf16 v[88:91], v[176:179], v[196:199], v[88:91]
	v_mfma_f32_16x16x32_bf16 v[88:91], v[184:187], v[200:203], v[88:91]
	v_mfma_f32_16x16x32_bf16 v[80:83], v[168:171], v[204:207], v[80:83]
	v_mfma_f32_16x16x32_bf16 v[80:83], v[172:175], v[208:211], v[80:83]
	v_mfma_f32_16x16x32_bf16 v[72:75], v[176:179], v[204:207], v[72:75]
	v_mfma_f32_16x16x32_bf16 v[72:75], v[184:187], v[208:211], v[72:75]
	v_mfma_f32_16x16x32_bf16 v[68:71], v[168:171], v[212:215], v[68:71]
	v_mfma_f32_16x16x32_bf16 v[68:71], v[172:175], v[216:219], v[68:71]
	s_barrier
	v_mfma_f32_16x16x32_bf16 v[64:67], v[176:179], v[212:215], v[64:67]
	v_mfma_f32_16x16x32_bf16 v[64:67], v[184:187], v[216:219], v[64:67]
	s_setprio 0
	s_add_i32 s60, s79, s64
	v_lshl_add_u64 v[144:145], v[144:145], 0, s[16:17]
	s_mov_b32 m0, s60
	ds_read_b128 v[188:191], v151 offset:49152
	ds_read_b128 v[192:195], v151 offset:50176
	ds_read_b128 v[196:199], v151 offset:51200
	ds_read_b128 v[200:203], v151 offset:52224
	ds_read_b128 v[204:207], v151 offset:53248
	ds_read_b128 v[208:211], v151 offset:54272
	ds_read_b128 v[212:215], v151 offset:55296
	ds_read_b128 v[216:219], v151 offset:56320
	global_load_lds_dwordx4 v[144:145], off
	s_add_i32 m0, s60, 0x2000
	s_add_u32 s58, s58, 0x40080
	v_lshl_add_u64 v[144:145], v[220:221], 0, s[16:17]
	s_addc_u32 s59, s59, 0
	s_add_i32 s60, s87, s64
	global_load_lds_dwordx4 v[144:145], off
	v_lshl_add_u64 v[144:145], s[58:59], 0, v[130:131]
	s_mov_b32 m0, s60
	s_nop 0
	global_load_lds_dwordx4 v[144:145], off
	v_lshl_add_u64 v[144:145], s[58:59], 0, v[134:135]
	s_add_i32 m0, s60, 0x2000
	s_nop 0
	global_load_lds_dwordx4 v[144:145], off
	v_lshl_add_u64 v[144:145], v[222:223], 0, s[16:17]
	s_mov_b32 m0, s69
	s_nop 0
	global_load_lds_dwordx4 v[144:145], off
	v_lshl_add_u64 v[144:145], v[224:225], 0, s[16:17]
	s_mov_b32 m0, s70
	s_nop 0
	global_load_lds_dwordx4 v[144:145], off
	s_waitcnt vmcnt(8)
	s_waitcnt lgkmcnt(0)
	s_barrier
	s_setprio 1
	s_waitcnt lgkmcnt(0)
	v_mfma_f32_16x16x32_bf16 v[60:63], v[152:155], v[188:191], v[60:63]
	v_mfma_f32_16x16x32_bf16 v[60:63], v[156:159], v[192:195], v[60:63]
	v_mfma_f32_16x16x32_bf16 v[56:59], v[160:163], v[188:191], v[56:59]
	v_mfma_f32_16x16x32_bf16 v[56:59], v[164:167], v[192:195], v[56:59]
	v_mfma_f32_16x16x32_bf16 v[52:55], v[152:155], v[196:199], v[52:55]
	v_mfma_f32_16x16x32_bf16 v[52:55], v[156:159], v[200:203], v[52:55]
	v_mfma_f32_16x16x32_bf16 v[44:47], v[160:163], v[196:199], v[44:47]
	v_mfma_f32_16x16x32_bf16 v[44:47], v[164:167], v[200:203], v[44:47]
	v_mfma_f32_16x16x32_bf16 v[36:39], v[152:155], v[204:207], v[36:39]
	v_mfma_f32_16x16x32_bf16 v[36:39], v[156:159], v[208:211], v[36:39]
	v_mfma_f32_16x16x32_bf16 v[28:31], v[160:163], v[204:207], v[28:31]
	v_mfma_f32_16x16x32_bf16 v[28:31], v[164:167], v[208:211], v[28:31]
	v_mfma_f32_16x16x32_bf16 v[20:23], v[152:155], v[212:215], v[20:23]
	v_mfma_f32_16x16x32_bf16 v[20:23], v[156:159], v[216:219], v[20:23]
	v_mfma_f32_16x16x32_bf16 v[12:15], v[160:163], v[212:215], v[12:15]
	v_mfma_f32_16x16x32_bf16 v[12:15], v[164:167], v[216:219], v[12:15]
	s_setprio 0
	s_setprio 1
	v_mfma_f32_16x16x32_bf16 v[48:51], v[168:171], v[188:191], v[48:51]
	v_mfma_f32_16x16x32_bf16 v[48:51], v[172:175], v[192:195], v[48:51]
	v_mfma_f32_16x16x32_bf16 v[40:43], v[176:179], v[188:191], v[40:43]
	v_mfma_f32_16x16x32_bf16 v[40:43], v[184:187], v[192:195], v[40:43]
	v_mfma_f32_16x16x32_bf16 v[32:35], v[168:171], v[196:199], v[32:35]
	v_mfma_f32_16x16x32_bf16 v[32:35], v[172:175], v[200:203], v[32:35]
	v_mfma_f32_16x16x32_bf16 v[24:27], v[176:179], v[196:199], v[24:27]
	v_mfma_f32_16x16x32_bf16 v[24:27], v[184:187], v[200:203], v[24:27]
	v_mfma_f32_16x16x32_bf16 v[16:19], v[168:171], v[204:207], v[16:19]
	v_mfma_f32_16x16x32_bf16 v[16:19], v[172:175], v[208:211], v[16:19]
	v_mfma_f32_16x16x32_bf16 v[8:11], v[176:179], v[204:207], v[8:11]
	v_mfma_f32_16x16x32_bf16 v[8:11], v[184:187], v[208:211], v[8:11]
	v_mfma_f32_16x16x32_bf16 v[4:7], v[168:171], v[212:215], v[4:7]
	v_mfma_f32_16x16x32_bf16 v[4:7], v[172:175], v[216:219], v[4:7]
	s_barrier
	v_mfma_f32_16x16x32_bf16 v[0:3], v[176:179], v[212:215], v[0:3]
	v_mfma_f32_16x16x32_bf16 v[0:3], v[184:187], v[216:219], v[0:3]
	s_setprio 0
	s_add_i32 s86, s86, 2
	s_add_u32 s56, s56, 0x100
	s_addc_u32 s57, s57, 0
	s_add_u32 s84, s84, 0x100
	s_addc_u32 s85, s85, 0
	s_cmp_gt_u32 s86, 13
	s_cbranch_scc0 .LBB0_1311
	s_and_b64 vcc, exec, s[18:19]
	s_cbranch_vccz .LBB0_1314
	s_barrier

.LBB0_1433:
	s_ashr_i32 s19, s18, 31
	s_lshl_b64 s[30:31], s[18:19], 19
	s_add_u32 s30, s80, s30
	s_addc_u32 s31, s81, s31
	s_and_b64 s[36:37], s[8:9], exec
	s_cselect_b32 s19, s31, s47
	s_cselect_b32 s66, s30, s46
	s_ashr_i32 s17, s16, 31
	s_lshl_b64 s[36:37], s[16:17], 19
	s_add_u32 s36, s52, s36
	s_addc_u32 s37, s53, s37
	s_and_b64 s[50:51], s[8:9], exec
	s_cselect_b32 s17, s37, s49
	s_cselect_b32 s67, s36, s48
	s_add_u32 s46, s46, 0x40080
	s_addc_u32 s47, s47, 0
	s_add_u32 s68, s48, 0x100
	s_addc_u32 s69, s49, 0
	s_mov_b32 s70, -2
	ds_read_b128 v[140:143], v147
	ds_read_b128 v[150:153], v147 offset:1024
	ds_read_b128 v[154:157], v147 offset:2048
	ds_read_b128 v[158:161], v147 offset:3072
	ds_read_b128 v[162:165], v148
	ds_read_b128 v[166:169], v148 offset:1024
	ds_read_b128 v[170:173], v148 offset:2048
	ds_read_b128 v[174:177], v148 offset:3072
	s_add_u32 s48, s46, 0xfffc0080
	s_addc_u32 s49, s47, -1
	s_cmp_eq_u32 s70, 12
	s_cselect_b32 s51, s19, s49
	s_cselect_b32 s50, s66, s48
	s_cselect_b32 s49, s17, s69
	s_cselect_b32 s48, s67, s68
	v_lshl_add_u64 v[178:179], s[46:47], 0, v[132:133]
	s_add_i32 m0, s45, 0xc000
	ds_read_b128 v[184:187], v149
	ds_read_b128 v[188:191], v149 offset:1024
	ds_read_b128 v[192:195], v149 offset:2048
	ds_read_b128 v[196:199], v149 offset:3072
	ds_read_b128 v[200:203], v149 offset:4096
	ds_read_b128 v[204:207], v149 offset:5120
	ds_read_b128 v[208:211], v149 offset:6144
	ds_read_b128 v[212:215], v149 offset:7168
	global_load_lds_dwordx4 v[178:179], off
	v_lshl_add_u64 v[178:179], s[46:47], 0, v[134:135]
	s_add_i32 m0, s45, 0xe000
	s_nop 0
	global_load_lds_dwordx4 v[178:179], off
	s_waitcnt vmcnt(8)
	s_waitcnt lgkmcnt(0)
	s_barrier
	s_setprio 1
	s_waitcnt lgkmcnt(0)
	v_mfma_f32_16x16x32_bf16 v[124:127], v[140:143], v[184:187], 0
	v_mfma_f32_16x16x32_bf16 v[124:127], v[150:153], v[188:191], v[124:127]
	v_mfma_f32_16x16x32_bf16 v[120:123], v[154:157], v[184:187], 0
	v_mfma_f32_16x16x32_bf16 v[120:123], v[158:161], v[188:191], v[120:123]
	v_mfma_f32_16x16x32_bf16 v[108:111], v[140:143], v[192:195], 0
	v_mfma_f32_16x16x32_bf16 v[108:111], v[150:153], v[196:199], v[108:111]
	v_mfma_f32_16x16x32_bf16 v[104:107], v[154:157], v[192:195], 0
	v_mfma_f32_16x16x32_bf16 v[104:107], v[158:161], v[196:199], v[104:107]
	v_mfma_f32_16x16x32_bf16 v[92:95], v[140:143], v[200:203], 0
	v_mfma_f32_16x16x32_bf16 v[92:95], v[150:153], v[204:207], v[92:95]
	v_mfma_f32_16x16x32_bf16 v[88:91], v[154:157], v[200:203], 0
	v_mfma_f32_16x16x32_bf16 v[88:91], v[158:161], v[204:207], v[88:91]
	v_mfma_f32_16x16x32_bf16 v[76:79], v[140:143], v[208:211], 0
	v_mfma_f32_16x16x32_bf16 v[76:79], v[150:153], v[212:215], v[76:79]
	v_mfma_f32_16x16x32_bf16 v[72:75], v[154:157], v[208:211], 0
	v_mfma_f32_16x16x32_bf16 v[72:75], v[158:161], v[212:215], v[72:75]
	s_setprio 0
	s_setprio 1
	v_mfma_f32_16x16x32_bf16 v[116:119], v[162:165], v[184:187], 0
	v_mfma_f32_16x16x32_bf16 v[116:119], v[166:169], v[188:191], v[116:119]
	v_mfma_f32_16x16x32_bf16 v[112:115], v[170:173], v[184:187], 0
	v_mfma_f32_16x16x32_bf16 v[112:115], v[174:177], v[188:191], v[112:115]
	v_mfma_f32_16x16x32_bf16 v[100:103], v[162:165], v[192:195], 0
	v_mfma_f32_16x16x32_bf16 v[100:103], v[166:169], v[196:199], v[100:103]
	v_mfma_f32_16x16x32_bf16 v[96:99], v[170:173], v[192:195], 0
	v_mfma_f32_16x16x32_bf16 v[96:99], v[174:177], v[196:199], v[96:99]
	v_mfma_f32_16x16x32_bf16 v[84:87], v[162:165], v[200:203], 0
	v_mfma_f32_16x16x32_bf16 v[84:87], v[166:169], v[204:207], v[84:87]
	v_mfma_f32_16x16x32_bf16 v[80:83], v[170:173], v[200:203], 0
	v_mfma_f32_16x16x32_bf16 v[80:83], v[174:177], v[204:207], v[80:83]
	v_mfma_f32_16x16x32_bf16 v[68:71], v[162:165], v[208:211], 0
	v_mfma_f32_16x16x32_bf16 v[68:71], v[166:169], v[212:215], v[68:71]
	s_barrier
	v_mfma_f32_16x16x32_bf16 v[64:67], v[170:173], v[208:211], 0
	v_mfma_f32_16x16x32_bf16 v[64:67], v[174:177], v[212:215], v[64:67]
	s_setprio 0
	s_add_i32 s71, s62, s54
	v_lshl_add_u64 v[178:179], s[48:49], 0, v[130:131]
	s_mov_b32 m0, s71
	ds_read_b128 v[184:187], v149 offset:16384
	ds_read_b128 v[188:191], v149 offset:17408
	ds_read_b128 v[192:195], v149 offset:18432
	ds_read_b128 v[196:199], v149 offset:19456
	ds_read_b128 v[200:203], v149 offset:20480
	ds_read_b128 v[204:207], v149 offset:21504
	ds_read_b128 v[208:211], v149 offset:22528
	ds_read_b128 v[212:215], v149 offset:23552
	global_load_lds_dwordx4 v[178:179], off
	s_add_i32 m0, s71, 0x2000
	s_add_u32 s72, s48, 0x40000
	v_lshl_add_u64 v[216:217], s[48:49], 0, v[128:129]
	s_addc_u32 s73, s49, 0
	s_add_i32 s71, s63, s54
	global_load_lds_dwordx4 v[216:217], off
	v_lshl_add_u64 v[218:219], s[72:73], 0, v[130:131]
	s_mov_b32 m0, s71
	v_lshl_add_u64 v[220:221], s[50:51], 0, v[128:129]
	global_load_lds_dwordx4 v[218:219], off
	v_lshl_add_u64 v[218:219], s[72:73], 0, v[128:129]
	s_add_i32 m0, s71, 0x2000
	s_nop 0
	global_load_lds_dwordx4 v[218:219], off
	v_lshl_add_u64 v[218:219], s[50:51], 0, v[130:131]
	s_mov_b32 m0, s45
	s_nop 0
	global_load_lds_dwordx4 v[218:219], off
	s_mov_b32 m0, s56
	s_nop 0
	global_load_lds_dwordx4 v[220:221], off
	s_waitcnt vmcnt(8)
	s_waitcnt lgkmcnt(0)
	s_barrier
	s_setprio 1
	s_waitcnt lgkmcnt(0)
	v_mfma_f32_16x16x32_bf16 v[60:63], v[140:143], v[184:187], 0
	v_mfma_f32_16x16x32_bf16 v[60:63], v[150:153], v[188:191], v[60:63]
	v_mfma_f32_16x16x32_bf16 v[56:59], v[154:157], v[184:187], 0
	v_mfma_f32_16x16x32_bf16 v[56:59], v[158:161], v[188:191], v[56:59]
	v_mfma_f32_16x16x32_bf16 v[44:47], v[140:143], v[192:195], 0
	v_mfma_f32_16x16x32_bf16 v[44:47], v[150:153], v[196:199], v[44:47]
	v_mfma_f32_16x16x32_bf16 v[40:43], v[154:157], v[192:195], 0
	v_mfma_f32_16x16x32_bf16 v[40:43], v[158:161], v[196:199], v[40:43]
	v_mfma_f32_16x16x32_bf16 v[28:31], v[140:143], v[200:203], 0
	v_mfma_f32_16x16x32_bf16 v[28:31], v[150:153], v[204:207], v[28:31]
	v_mfma_f32_16x16x32_bf16 v[24:27], v[154:157], v[200:203], 0
	v_mfma_f32_16x16x32_bf16 v[24:27], v[158:161], v[204:207], v[24:27]
	v_mfma_f32_16x16x32_bf16 v[12:15], v[140:143], v[208:211], 0
	v_mfma_f32_16x16x32_bf16 v[12:15], v[150:153], v[212:215], v[12:15]
	v_mfma_f32_16x16x32_bf16 v[8:11], v[154:157], v[208:211], 0
	v_mfma_f32_16x16x32_bf16 v[8:11], v[158:161], v[212:215], v[8:11]
	s_setprio 0
	s_setprio 1
	v_mfma_f32_16x16x32_bf16 v[52:55], v[162:165], v[184:187], 0
	v_mfma_f32_16x16x32_bf16 v[52:55], v[166:169], v[188:191], v[52:55]
	v_mfma_f32_16x16x32_bf16 v[48:51], v[170:173], v[184:187], 0
	v_mfma_f32_16x16x32_bf16 v[48:51], v[174:177], v[188:191], v[48:51]
	v_mfma_f32_16x16x32_bf16 v[36:39], v[162:165], v[192:195], 0
	v_mfma_f32_16x16x32_bf16 v[36:39], v[166:169], v[196:199], v[36:39]
	v_mfma_f32_16x16x32_bf16 v[32:35], v[170:173], v[192:195], 0
	v_mfma_f32_16x16x32_bf16 v[32:35], v[174:177], v[196:199], v[32:35]
	v_mfma_f32_16x16x32_bf16 v[20:23], v[162:165], v[200:203], 0
	v_mfma_f32_16x16x32_bf16 v[20:23], v[166:169], v[204:207], v[20:23]
	v_mfma_f32_16x16x32_bf16 v[16:19], v[170:173], v[200:203], 0
	v_mfma_f32_16x16x32_bf16 v[16:19], v[174:177], v[204:207], v[16:19]
	v_mfma_f32_16x16x32_bf16 v[4:7], v[162:165], v[208:211], 0
	v_mfma_f32_16x16x32_bf16 v[4:7], v[166:169], v[212:215], v[4:7]
	s_barrier
	v_mfma_f32_16x16x32_bf16 v[0:3], v[170:173], v[208:211], 0
	v_mfma_f32_16x16x32_bf16 v[0:3], v[174:177], v[212:215], v[0:3]
	s_setprio 0
	s_branch .Lmid_gemm11
.LBB0_1434:
	ds_read_b128 v[140:143], v147
	ds_read_b128 v[150:153], v147 offset:1024
	ds_read_b128 v[154:157], v147 offset:2048
	ds_read_b128 v[158:161], v147 offset:3072
	ds_read_b128 v[162:165], v148
	ds_read_b128 v[166:169], v148 offset:1024
	ds_read_b128 v[170:173], v148 offset:2048
	ds_read_b128 v[174:177], v148 offset:3072
	s_add_u32 s48, s46, 0xfffc0080
	s_addc_u32 s49, s47, -1
	s_cmp_eq_u32 s70, 12
	s_cselect_b32 s51, s19, s49
	s_cselect_b32 s50, s66, s48
	s_cselect_b32 s49, s17, s69
	s_cselect_b32 s48, s67, s68
	v_lshl_add_u64 v[178:179], s[46:47], 0, v[132:133]
	s_add_i32 m0, s45, 0xc000
	ds_read_b128 v[184:187], v149
	ds_read_b128 v[188:191], v149 offset:1024
	ds_read_b128 v[192:195], v149 offset:2048
	ds_read_b128 v[196:199], v149 offset:3072
	ds_read_b128 v[200:203], v149 offset:4096
	ds_read_b128 v[204:207], v149 offset:5120
	ds_read_b128 v[208:211], v149 offset:6144
	ds_read_b128 v[212:215], v149 offset:7168
	global_load_lds_dwordx4 v[178:179], off
	v_lshl_add_u64 v[178:179], s[46:47], 0, v[134:135]
	s_add_i32 m0, s45, 0xe000
	s_nop 0
	global_load_lds_dwordx4 v[178:179], off
	s_waitcnt vmcnt(8)
	s_waitcnt lgkmcnt(0)
	s_barrier
	s_setprio 1
	s_waitcnt lgkmcnt(0)
	v_mfma_f32_16x16x32_bf16 v[124:127], v[140:143], v[184:187], v[124:127]
	v_mfma_f32_16x16x32_bf16 v[124:127], v[150:153], v[188:191], v[124:127]
	v_mfma_f32_16x16x32_bf16 v[120:123], v[154:157], v[184:187], v[120:123]
	v_mfma_f32_16x16x32_bf16 v[120:123], v[158:161], v[188:191], v[120:123]
	v_mfma_f32_16x16x32_bf16 v[108:111], v[140:143], v[192:195], v[108:111]
	v_mfma_f32_16x16x32_bf16 v[108:111], v[150:153], v[196:199], v[108:111]
	v_mfma_f32_16x16x32_bf16 v[104:107], v[154:157], v[192:195], v[104:107]
	v_mfma_f32_16x16x32_bf16 v[104:107], v[158:161], v[196:199], v[104:107]
	v_mfma_f32_16x16x32_bf16 v[92:95], v[140:143], v[200:203], v[92:95]
	v_mfma_f32_16x16x32_bf16 v[92:95], v[150:153], v[204:207], v[92:95]
	v_mfma_f32_16x16x32_bf16 v[88:91], v[154:157], v[200:203], v[88:91]
	v_mfma_f32_16x16x32_bf16 v[88:91], v[158:161], v[204:207], v[88:91]
	v_mfma_f32_16x16x32_bf16 v[76:79], v[140:143], v[208:211], v[76:79]
	v_mfma_f32_16x16x32_bf16 v[76:79], v[150:153], v[212:215], v[76:79]
	v_mfma_f32_16x16x32_bf16 v[72:75], v[154:157], v[208:211], v[72:75]
	v_mfma_f32_16x16x32_bf16 v[72:75], v[158:161], v[212:215], v[72:75]
	s_setprio 0
	s_setprio 1
	v_mfma_f32_16x16x32_bf16 v[116:119], v[162:165], v[184:187], v[116:119]
	v_mfma_f32_16x16x32_bf16 v[116:119], v[166:169], v[188:191], v[116:119]
	v_mfma_f32_16x16x32_bf16 v[112:115], v[170:173], v[184:187], v[112:115]
	v_mfma_f32_16x16x32_bf16 v[112:115], v[174:177], v[188:191], v[112:115]
	v_mfma_f32_16x16x32_bf16 v[100:103], v[162:165], v[192:195], v[100:103]
	v_mfma_f32_16x16x32_bf16 v[100:103], v[166:169], v[196:199], v[100:103]
	v_mfma_f32_16x16x32_bf16 v[96:99], v[170:173], v[192:195], v[96:99]
	v_mfma_f32_16x16x32_bf16 v[96:99], v[174:177], v[196:199], v[96:99]
	v_mfma_f32_16x16x32_bf16 v[84:87], v[162:165], v[200:203], v[84:87]
	v_mfma_f32_16x16x32_bf16 v[84:87], v[166:169], v[204:207], v[84:87]
	v_mfma_f32_16x16x32_bf16 v[80:83], v[170:173], v[200:203], v[80:83]
	v_mfma_f32_16x16x32_bf16 v[80:83], v[174:177], v[204:207], v[80:83]
	v_mfma_f32_16x16x32_bf16 v[68:71], v[162:165], v[208:211], v[68:71]
	v_mfma_f32_16x16x32_bf16 v[68:71], v[166:169], v[212:215], v[68:71]
	s_barrier
	v_mfma_f32_16x16x32_bf16 v[64:67], v[170:173], v[208:211], v[64:67]
	v_mfma_f32_16x16x32_bf16 v[64:67], v[174:177], v[212:215], v[64:67]
	s_setprio 0
	s_add_i32 s71, s62, s54
	v_lshl_add_u64 v[178:179], s[48:49], 0, v[130:131]
	s_mov_b32 m0, s71
	ds_read_b128 v[184:187], v149 offset:16384
	ds_read_b128 v[188:191], v149 offset:17408
	ds_read_b128 v[192:195], v149 offset:18432
	ds_read_b128 v[196:199], v149 offset:19456
	ds_read_b128 v[200:203], v149 offset:20480
	ds_read_b128 v[204:207], v149 offset:21504
	ds_read_b128 v[208:211], v149 offset:22528
	ds_read_b128 v[212:215], v149 offset:23552
	global_load_lds_dwordx4 v[178:179], off
	s_add_i32 m0, s71, 0x2000
	s_add_u32 s72, s48, 0x40000
	v_lshl_add_u64 v[216:217], s[48:49], 0, v[128:129]
	s_addc_u32 s73, s49, 0
	s_add_i32 s71, s63, s54
	global_load_lds_dwordx4 v[216:217], off
	v_lshl_add_u64 v[218:219], s[72:73], 0, v[130:131]
	s_mov_b32 m0, s71
	v_lshl_add_u64 v[220:221], s[50:51], 0, v[128:129]
	global_load_lds_dwordx4 v[218:219], off
	v_lshl_add_u64 v[218:219], s[72:73], 0, v[128:129]
	s_add_i32 m0, s71, 0x2000
	s_nop 0
	global_load_lds_dwordx4 v[218:219], off
	v_lshl_add_u64 v[218:219], s[50:51], 0, v[130:131]
	s_mov_b32 m0, s45
	s_nop 0
	global_load_lds_dwordx4 v[218:219], off
	s_mov_b32 m0, s56
	s_nop 0
	global_load_lds_dwordx4 v[220:221], off
	s_waitcnt vmcnt(8)
	s_waitcnt lgkmcnt(0)
	s_barrier
	s_setprio 1
	s_waitcnt lgkmcnt(0)
	v_mfma_f32_16x16x32_bf16 v[60:63], v[140:143], v[184:187], v[60:63]
	v_mfma_f32_16x16x32_bf16 v[60:63], v[150:153], v[188:191], v[60:63]
	v_mfma_f32_16x16x32_bf16 v[56:59], v[154:157], v[184:187], v[56:59]
	v_mfma_f32_16x16x32_bf16 v[56:59], v[158:161], v[188:191], v[56:59]
	v_mfma_f32_16x16x32_bf16 v[44:47], v[140:143], v[192:195], v[44:47]
	v_mfma_f32_16x16x32_bf16 v[44:47], v[150:153], v[196:199], v[44:47]
	v_mfma_f32_16x16x32_bf16 v[40:43], v[154:157], v[192:195], v[40:43]
	v_mfma_f32_16x16x32_bf16 v[40:43], v[158:161], v[196:199], v[40:43]
	v_mfma_f32_16x16x32_bf16 v[28:31], v[140:143], v[200:203], v[28:31]
	v_mfma_f32_16x16x32_bf16 v[28:31], v[150:153], v[204:207], v[28:31]
	v_mfma_f32_16x16x32_bf16 v[24:27], v[154:157], v[200:203], v[24:27]
	v_mfma_f32_16x16x32_bf16 v[24:27], v[158:161], v[204:207], v[24:27]
	v_mfma_f32_16x16x32_bf16 v[12:15], v[140:143], v[208:211], v[12:15]
	v_mfma_f32_16x16x32_bf16 v[12:15], v[150:153], v[212:215], v[12:15]
	v_mfma_f32_16x16x32_bf16 v[8:11], v[154:157], v[208:211], v[8:11]
	v_mfma_f32_16x16x32_bf16 v[8:11], v[158:161], v[212:215], v[8:11]
	s_setprio 0
	s_setprio 1
	v_mfma_f32_16x16x32_bf16 v[52:55], v[162:165], v[184:187], v[52:55]
	v_mfma_f32_16x16x32_bf16 v[52:55], v[166:169], v[188:191], v[52:55]
	v_mfma_f32_16x16x32_bf16 v[48:51], v[170:173], v[184:187], v[48:51]
	v_mfma_f32_16x16x32_bf16 v[48:51], v[174:177], v[188:191], v[48:51]
	v_mfma_f32_16x16x32_bf16 v[36:39], v[162:165], v[192:195], v[36:39]
	v_mfma_f32_16x16x32_bf16 v[36:39], v[166:169], v[196:199], v[36:39]
	v_mfma_f32_16x16x32_bf16 v[32:35], v[170:173], v[192:195], v[32:35]
	v_mfma_f32_16x16x32_bf16 v[32:35], v[174:177], v[196:199], v[32:35]
	v_mfma_f32_16x16x32_bf16 v[20:23], v[162:165], v[200:203], v[20:23]
	v_mfma_f32_16x16x32_bf16 v[20:23], v[166:169], v[204:207], v[20:23]
	v_mfma_f32_16x16x32_bf16 v[16:19], v[170:173], v[200:203], v[16:19]
	v_mfma_f32_16x16x32_bf16 v[16:19], v[174:177], v[204:207], v[16:19]
	v_mfma_f32_16x16x32_bf16 v[4:7], v[162:165], v[208:211], v[4:7]
	v_mfma_f32_16x16x32_bf16 v[4:7], v[166:169], v[212:215], v[4:7]
	s_barrier
	v_mfma_f32_16x16x32_bf16 v[0:3], v[170:173], v[208:211], v[0:3]
	v_mfma_f32_16x16x32_bf16 v[0:3], v[174:177], v[212:215], v[0:3]
	s_setprio 0
.Lmid_gemm11:
	s_add_i32 s71, 0, 0x18000
	s_add_i32 s72, 0, 0x1c000
	v_add_u32_e32 v158, s71, v145
	v_add_u32_e32 v174, s72, v145
	ds_read_b128 v[140:143], v158
	ds_read_b128 v[150:153], v158 offset:1024
	ds_read_b128 v[154:157], v158 offset:2048
	ds_read_b128 v[158:161], v158 offset:3072
	ds_read_b128 v[162:165], v174
	ds_read_b128 v[166:169], v174 offset:1024
	ds_read_b128 v[170:173], v174 offset:2048
	ds_read_b128 v[174:177], v174 offset:3072
	s_add_u32 s50, s50, 0x40000
	s_addc_u32 s51, s51, 0
	s_mov_b32 m0, s57
	v_lshl_add_u64 v[222:223], s[50:51], 0, v[130:131]
	ds_read_b128 v[184:187], v149 offset:32768
	ds_read_b128 v[188:191], v149 offset:33792
	ds_read_b128 v[192:195], v149 offset:34816
	ds_read_b128 v[196:199], v149 offset:35840
	ds_read_b128 v[200:203], v149 offset:36864
	ds_read_b128 v[204:207], v149 offset:37888
	ds_read_b128 v[208:211], v149 offset:38912
	ds_read_b128 v[212:215], v149 offset:39936
	global_load_lds_dwordx4 v[222:223], off
	v_lshl_add_u64 v[222:223], s[50:51], 0, v[128:129]
	s_mov_b32 m0, s58
	s_nop 0
	global_load_lds_dwordx4 v[222:223], off
	s_waitcnt vmcnt(8)
	s_waitcnt lgkmcnt(0)
	s_barrier
	s_setprio 1
	s_waitcnt lgkmcnt(0)
	v_mfma_f32_16x16x32_bf16 v[124:127], v[140:143], v[184:187], v[124:127]
	v_mfma_f32_16x16x32_bf16 v[124:127], v[150:153], v[188:191], v[124:127]
	v_mfma_f32_16x16x32_bf16 v[120:123], v[154:157], v[184:187], v[120:123]
	v_mfma_f32_16x16x32_bf16 v[120:123], v[158:161], v[188:191], v[120:123]
	v_mfma_f32_16x16x32_bf16 v[108:111], v[140:143], v[192:195], v[108:111]
	v_mfma_f32_16x16x32_bf16 v[108:111], v[150:153], v[196:199], v[108:111]
	v_mfma_f32_16x16x32_bf16 v[104:107], v[154:157], v[192:195], v[104:107]
	v_mfma_f32_16x16x32_bf16 v[104:107], v[158:161], v[196:199], v[104:107]
	v_mfma_f32_16x16x32_bf16 v[92:95], v[140:143], v[200:203], v[92:95]
	v_mfma_f32_16x16x32_bf16 v[92:95], v[150:153], v[204:207], v[92:95]
	v_mfma_f32_16x16x32_bf16 v[88:91], v[154:157], v[200:203], v[88:91]
	v_mfma_f32_16x16x32_bf16 v[88:91], v[158:161], v[204:207], v[88:91]
	v_mfma_f32_16x16x32_bf16 v[76:79], v[140:143], v[208:211], v[76:79]
	v_mfma_f32_16x16x32_bf16 v[76:79], v[150:153], v[212:215], v[76:79]
	v_mfma_f32_16x16x32_bf16 v[72:75], v[154:157], v[208:211], v[72:75]
	v_mfma_f32_16x16x32_bf16 v[72:75], v[158:161], v[212:215], v[72:75]
	s_setprio 0
	s_setprio 1
	v_mfma_f32_16x16x32_bf16 v[116:119], v[162:165], v[184:187], v[116:119]
	v_mfma_f32_16x16x32_bf16 v[116:119], v[166:169], v[188:191], v[116:119]
	v_mfma_f32_16x16x32_bf16 v[112:115], v[170:173], v[184:187], v[112:115]
	v_mfma_f32_16x16x32_bf16 v[112:115], v[174:177], v[188:191], v[112:115]
	v_mfma_f32_16x16x32_bf16 v[100:103], v[162:165], v[192:195], v[100:103]
	v_mfma_f32_16x16x32_bf16 v[100:103], v[166:169], v[196:199], v[100:103]
	v_mfma_f32_16x16x32_bf16 v[96:99], v[170:173], v[192:195], v[96:99]
	v_mfma_f32_16x16x32_bf16 v[96:99], v[174:177], v[196:199], v[96:99]
	v_mfma_f32_16x16x32_bf16 v[84:87], v[162:165], v[200:203], v[84:87]
	v_mfma_f32_16x16x32_bf16 v[84:87], v[166:169], v[204:207], v[84:87]
	v_mfma_f32_16x16x32_bf16 v[80:83], v[170:173], v[200:203], v[80:83]
	v_mfma_f32_16x16x32_bf16 v[80:83], v[174:177], v[204:207], v[80:83]
	v_mfma_f32_16x16x32_bf16 v[68:71], v[162:165], v[208:211], v[68:71]
	v_mfma_f32_16x16x32_bf16 v[68:71], v[166:169], v[212:215], v[68:71]
	s_barrier
	v_mfma_f32_16x16x32_bf16 v[64:67], v[170:173], v[208:211], v[64:67]
	v_mfma_f32_16x16x32_bf16 v[64:67], v[174:177], v[212:215], v[64:67]
	s_setprio 0
	s_add_i32 s50, s71, s54
	v_lshl_add_u64 v[178:179], v[178:179], 0, s[10:11]
	s_mov_b32 m0, s50
	ds_read_b128 v[184:187], v149 offset:49152
	ds_read_b128 v[188:191], v149 offset:50176
	ds_read_b128 v[192:195], v149 offset:51200
	ds_read_b128 v[196:199], v149 offset:52224
	ds_read_b128 v[200:203], v149 offset:53248
	ds_read_b128 v[204:207], v149 offset:54272
	ds_read_b128 v[208:211], v149 offset:55296
	ds_read_b128 v[212:215], v149 offset:56320
	global_load_lds_dwordx4 v[178:179], off
	s_add_i32 m0, s50, 0x2000
	s_add_u32 s48, s48, 0x40080
	v_lshl_add_u64 v[178:179], v[216:217], 0, s[10:11]
	s_addc_u32 s49, s49, 0
	s_add_i32 s50, s72, s54
	global_load_lds_dwordx4 v[178:179], off
	v_lshl_add_u64 v[178:179], s[48:49], 0, v[130:131]
	s_mov_b32 m0, s50
	s_nop 0
	global_load_lds_dwordx4 v[178:179], off
	v_lshl_add_u64 v[178:179], s[48:49], 0, v[128:129]
	s_add_i32 m0, s50, 0x2000
	s_nop 0
	global_load_lds_dwordx4 v[178:179], off
	v_lshl_add_u64 v[178:179], v[218:219], 0, s[10:11]
	s_mov_b32 m0, s60
	s_nop 0
	global_load_lds_dwordx4 v[178:179], off
	v_lshl_add_u64 v[178:179], v[220:221], 0, s[10:11]
	s_mov_b32 m0, s61
	s_nop 0
	global_load_lds_dwordx4 v[178:179], off
	s_waitcnt vmcnt(8)
	s_waitcnt lgkmcnt(0)
	s_barrier
	s_setprio 1
	s_waitcnt lgkmcnt(0)
	v_mfma_f32_16x16x32_bf16 v[60:63], v[140:143], v[184:187], v[60:63]
	v_mfma_f32_16x16x32_bf16 v[60:63], v[150:153], v[188:191], v[60:63]
	v_mfma_f32_16x16x32_bf16 v[56:59], v[154:157], v[184:187], v[56:59]
	v_mfma_f32_16x16x32_bf16 v[56:59], v[158:161], v[188:191], v[56:59]
	v_mfma_f32_16x16x32_bf16 v[44:47], v[140:143], v[192:195], v[44:47]
	v_mfma_f32_16x16x32_bf16 v[44:47], v[150:153], v[196:199], v[44:47]
	v_mfma_f32_16x16x32_bf16 v[40:43], v[154:157], v[192:195], v[40:43]
	v_mfma_f32_16x16x32_bf16 v[40:43], v[158:161], v[196:199], v[40:43]
	v_mfma_f32_16x16x32_bf16 v[28:31], v[140:143], v[200:203], v[28:31]
	v_mfma_f32_16x16x32_bf16 v[28:31], v[150:153], v[204:207], v[28:31]
	v_mfma_f32_16x16x32_bf16 v[24:27], v[154:157], v[200:203], v[24:27]
	v_mfma_f32_16x16x32_bf16 v[24:27], v[158:161], v[204:207], v[24:27]
	v_mfma_f32_16x16x32_bf16 v[12:15], v[140:143], v[208:211], v[12:15]
	v_mfma_f32_16x16x32_bf16 v[12:15], v[150:153], v[212:215], v[12:15]
	v_mfma_f32_16x16x32_bf16 v[8:11], v[154:157], v[208:211], v[8:11]
	v_mfma_f32_16x16x32_bf16 v[8:11], v[158:161], v[212:215], v[8:11]
	s_setprio 0
	s_setprio 1
	v_mfma_f32_16x16x32_bf16 v[52:55], v[162:165], v[184:187], v[52:55]
	v_mfma_f32_16x16x32_bf16 v[52:55], v[166:169], v[188:191], v[52:55]
	v_mfma_f32_16x16x32_bf16 v[48:51], v[170:173], v[184:187], v[48:51]
	v_mfma_f32_16x16x32_bf16 v[48:51], v[174:177], v[188:191], v[48:51]
	v_mfma_f32_16x16x32_bf16 v[36:39], v[162:165], v[192:195], v[36:39]
	v_mfma_f32_16x16x32_bf16 v[36:39], v[166:169], v[196:199], v[36:39]
	v_mfma_f32_16x16x32_bf16 v[32:35], v[170:173], v[192:195], v[32:35]
	v_mfma_f32_16x16x32_bf16 v[32:35], v[174:177], v[196:199], v[32:35]
	v_mfma_f32_16x16x32_bf16 v[20:23], v[162:165], v[200:203], v[20:23]
	v_mfma_f32_16x16x32_bf16 v[20:23], v[166:169], v[204:207], v[20:23]
	v_mfma_f32_16x16x32_bf16 v[16:19], v[170:173], v[200:203], v[16:19]
	v_mfma_f32_16x16x32_bf16 v[16:19], v[174:177], v[204:207], v[16:19]
	v_mfma_f32_16x16x32_bf16 v[4:7], v[162:165], v[208:211], v[4:7]
	v_mfma_f32_16x16x32_bf16 v[4:7], v[166:169], v[212:215], v[4:7]
	s_barrier
	v_mfma_f32_16x16x32_bf16 v[0:3], v[170:173], v[208:211], v[0:3]
	v_mfma_f32_16x16x32_bf16 v[0:3], v[174:177], v[212:215], v[0:3]
	s_setprio 0
	s_add_i32 s70, s70, 2
	s_add_u32 s46, s46, 0x100
	s_addc_u32 s47, s47, 0
	s_add_u32 s68, s68, 0x100
	s_addc_u32 s69, s69, 0
	s_cmp_gt_u32 s70, 13
	s_cbranch_scc0 .LBB0_1434
	s_and_b64 vcc, exec, s[12:13]
	s_cbranch_vccz .LBB0_1437
	s_barrier

.LBB0_1513:
	s_add_u32 s74, s48, 0x100
	s_addc_u32 s75, s49, 0
	s_mov_b32 s76, -2
	ds_read_b128 v[152:155], v149
	ds_read_b128 v[156:159], v149 offset:1024
	ds_read_b128 v[160:163], v149 offset:2048
	ds_read_b128 v[164:167], v149 offset:3072
	ds_read_b128 v[168:171], v150
	ds_read_b128 v[172:175], v150 offset:1024
	ds_read_b128 v[176:179], v150 offset:2048
	ds_read_b128 v[184:187], v150 offset:3072
	s_add_u32 s48, s46, 0x100
	s_addc_u32 s49, s47, 0
	s_cmp_eq_u32 s76, 40
	s_cselect_b32 s53, s9, s49
	s_cselect_b32 s52, s8, s48
	s_cselect_b32 s51, s45, s75
	s_cselect_b32 s50, s44, s74
	v_lshl_add_u64 v[144:145], s[46:47], 0, v[136:137]
	s_add_i32 m0, s57, 0xc000
	ds_read_b128 v[188:191], v151
	ds_read_b128 v[192:195], v151 offset:1024
	ds_read_b128 v[196:199], v151 offset:2048
	ds_read_b128 v[200:203], v151 offset:3072
	ds_read_b128 v[204:207], v151 offset:4096
	ds_read_b128 v[208:211], v151 offset:5120
	ds_read_b128 v[212:215], v151 offset:6144
	ds_read_b128 v[216:219], v151 offset:7168
	global_load_lds_dwordx4 v[144:145], off
	v_lshl_add_u64 v[144:145], s[46:47], 0, v[138:139]
	s_add_i32 m0, s57, 0xe000
	s_nop 0
	global_load_lds_dwordx4 v[144:145], off
	s_waitcnt vmcnt(8)
	s_waitcnt lgkmcnt(0)
	s_barrier
	s_setprio 1
	s_waitcnt lgkmcnt(0)
	v_mfma_f32_16x16x32_bf16 v[124:127], v[152:155], v[188:191], 0
	v_mfma_f32_16x16x32_bf16 v[124:127], v[156:159], v[192:195], v[124:127]
	v_mfma_f32_16x16x32_bf16 v[120:123], v[160:163], v[188:191], 0
	v_mfma_f32_16x16x32_bf16 v[120:123], v[164:167], v[192:195], v[120:123]
	v_mfma_f32_16x16x32_bf16 v[116:119], v[152:155], v[196:199], 0
	v_mfma_f32_16x16x32_bf16 v[116:119], v[156:159], v[200:203], v[116:119]
	v_mfma_f32_16x16x32_bf16 v[108:111], v[160:163], v[196:199], 0
	v_mfma_f32_16x16x32_bf16 v[108:111], v[164:167], v[200:203], v[108:111]
	v_mfma_f32_16x16x32_bf16 v[100:103], v[152:155], v[204:207], 0
	v_mfma_f32_16x16x32_bf16 v[100:103], v[156:159], v[208:211], v[100:103]
	v_mfma_f32_16x16x32_bf16 v[92:95], v[160:163], v[204:207], 0
	v_mfma_f32_16x16x32_bf16 v[92:95], v[164:167], v[208:211], v[92:95]
	v_mfma_f32_16x16x32_bf16 v[84:87], v[152:155], v[212:215], 0
	v_mfma_f32_16x16x32_bf16 v[84:87], v[156:159], v[216:219], v[84:87]
	v_mfma_f32_16x16x32_bf16 v[76:79], v[160:163], v[212:215], 0
	v_mfma_f32_16x16x32_bf16 v[76:79], v[164:167], v[216:219], v[76:79]
	s_setprio 0
	s_setprio 1
	v_mfma_f32_16x16x32_bf16 v[112:115], v[168:171], v[188:191], 0
	v_mfma_f32_16x16x32_bf16 v[112:115], v[172:175], v[192:195], v[112:115]
	v_mfma_f32_16x16x32_bf16 v[104:107], v[176:179], v[188:191], 0
	v_mfma_f32_16x16x32_bf16 v[104:107], v[184:187], v[192:195], v[104:107]
	v_mfma_f32_16x16x32_bf16 v[96:99], v[168:171], v[196:199], 0
	v_mfma_f32_16x16x32_bf16 v[96:99], v[172:175], v[200:203], v[96:99]
	v_mfma_f32_16x16x32_bf16 v[88:91], v[176:179], v[196:199], 0
	v_mfma_f32_16x16x32_bf16 v[88:91], v[184:187], v[200:203], v[88:91]
	v_mfma_f32_16x16x32_bf16 v[80:83], v[168:171], v[204:207], 0
	v_mfma_f32_16x16x32_bf16 v[80:83], v[172:175], v[208:211], v[80:83]
	v_mfma_f32_16x16x32_bf16 v[72:75], v[176:179], v[204:207], 0
	v_mfma_f32_16x16x32_bf16 v[72:75], v[184:187], v[208:211], v[72:75]
	v_mfma_f32_16x16x32_bf16 v[68:71], v[168:171], v[212:215], 0
	v_mfma_f32_16x16x32_bf16 v[68:71], v[172:175], v[216:219], v[68:71]
	s_barrier
	v_mfma_f32_16x16x32_bf16 v[64:67], v[176:179], v[212:215], 0
	v_mfma_f32_16x16x32_bf16 v[64:67], v[184:187], v[216:219], v[64:67]
	s_setprio 0
	s_add_i32 s46, s64, s56
	v_lshl_add_u64 v[144:145], s[50:51], 0, v[130:131]
	s_mov_b32 m0, s46
	ds_read_b128 v[188:191], v151 offset:16384
	ds_read_b128 v[192:195], v151 offset:17408
	ds_read_b128 v[196:199], v151 offset:18432
	ds_read_b128 v[200:203], v151 offset:19456
	ds_read_b128 v[204:207], v151 offset:20480
	ds_read_b128 v[208:211], v151 offset:21504
	ds_read_b128 v[212:215], v151 offset:22528
	ds_read_b128 v[216:219], v151 offset:23552
	global_load_lds_dwordx4 v[144:145], off
	s_add_i32 m0, s46, 0x2000
	s_add_u32 s46, s50, 0xb0000
	v_lshl_add_u64 v[220:221], s[50:51], 0, v[134:135]
	s_addc_u32 s47, s51, 0
	s_add_i32 s77, s65, s56
	global_load_lds_dwordx4 v[220:221], off
	v_lshl_add_u64 v[222:223], s[46:47], 0, v[130:131]
	s_mov_b32 m0, s77
	v_lshl_add_u64 v[224:225], s[52:53], 0, v[132:133]
	global_load_lds_dwordx4 v[222:223], off
	v_lshl_add_u64 v[222:223], s[46:47], 0, v[134:135]
	s_add_i32 m0, s77, 0x2000
	s_nop 0
	global_load_lds_dwordx4 v[222:223], off
	v_lshl_add_u64 v[222:223], s[52:53], 0, v[128:129]
	s_mov_b32 m0, s57
	s_nop 0
	global_load_lds_dwordx4 v[222:223], off
	s_mov_b32 m0, s58
	s_nop 0
	global_load_lds_dwordx4 v[224:225], off
	s_waitcnt vmcnt(8)
	s_waitcnt lgkmcnt(0)
	s_barrier
	s_setprio 1
	s_waitcnt lgkmcnt(0)
	v_mfma_f32_16x16x32_bf16 v[60:63], v[152:155], v[188:191], 0
	v_mfma_f32_16x16x32_bf16 v[60:63], v[156:159], v[192:195], v[60:63]
	v_mfma_f32_16x16x32_bf16 v[56:59], v[160:163], v[188:191], 0
	v_mfma_f32_16x16x32_bf16 v[56:59], v[164:167], v[192:195], v[56:59]
	v_mfma_f32_16x16x32_bf16 v[52:55], v[152:155], v[196:199], 0
	v_mfma_f32_16x16x32_bf16 v[52:55], v[156:159], v[200:203], v[52:55]
	v_mfma_f32_16x16x32_bf16 v[44:47], v[160:163], v[196:199], 0
	v_mfma_f32_16x16x32_bf16 v[44:47], v[164:167], v[200:203], v[44:47]
	v_mfma_f32_16x16x32_bf16 v[36:39], v[152:155], v[204:207], 0
	v_mfma_f32_16x16x32_bf16 v[36:39], v[156:159], v[208:211], v[36:39]
	v_mfma_f32_16x16x32_bf16 v[28:31], v[160:163], v[204:207], 0
	v_mfma_f32_16x16x32_bf16 v[28:31], v[164:167], v[208:211], v[28:31]
	v_mfma_f32_16x16x32_bf16 v[20:23], v[152:155], v[212:215], 0
	v_mfma_f32_16x16x32_bf16 v[20:23], v[156:159], v[216:219], v[20:23]
	v_mfma_f32_16x16x32_bf16 v[12:15], v[160:163], v[212:215], 0
	v_mfma_f32_16x16x32_bf16 v[12:15], v[164:167], v[216:219], v[12:15]
	s_setprio 0
	s_setprio 1
	v_mfma_f32_16x16x32_bf16 v[48:51], v[168:171], v[188:191], 0
	v_mfma_f32_16x16x32_bf16 v[48:51], v[172:175], v[192:195], v[48:51]
	v_mfma_f32_16x16x32_bf16 v[40:43], v[176:179], v[188:191], 0
	v_mfma_f32_16x16x32_bf16 v[40:43], v[184:187], v[192:195], v[40:43]
	v_mfma_f32_16x16x32_bf16 v[32:35], v[168:171], v[196:199], 0
	v_mfma_f32_16x16x32_bf16 v[32:35], v[172:175], v[200:203], v[32:35]
	v_mfma_f32_16x16x32_bf16 v[24:27], v[176:179], v[196:199], 0
	v_mfma_f32_16x16x32_bf16 v[24:27], v[184:187], v[200:203], v[24:27]
	v_mfma_f32_16x16x32_bf16 v[16:19], v[168:171], v[204:207], 0
	v_mfma_f32_16x16x32_bf16 v[16:19], v[172:175], v[208:211], v[16:19]
	v_mfma_f32_16x16x32_bf16 v[8:11], v[176:179], v[204:207], 0
	v_mfma_f32_16x16x32_bf16 v[8:11], v[184:187], v[208:211], v[8:11]
	v_mfma_f32_16x16x32_bf16 v[4:7], v[168:171], v[212:215], 0
	v_mfma_f32_16x16x32_bf16 v[4:7], v[172:175], v[216:219], v[4:7]
	s_barrier
	v_mfma_f32_16x16x32_bf16 v[0:3], v[176:179], v[212:215], 0
	v_mfma_f32_16x16x32_bf16 v[0:3], v[184:187], v[216:219], v[0:3]
	s_setprio 0
	s_branch .Lmid_gemm12
.LBB0_1514:
	ds_read_b128 v[152:155], v149
	ds_read_b128 v[156:159], v149 offset:1024
	ds_read_b128 v[160:163], v149 offset:2048
	ds_read_b128 v[164:167], v149 offset:3072
	ds_read_b128 v[168:171], v150
	ds_read_b128 v[172:175], v150 offset:1024
	ds_read_b128 v[176:179], v150 offset:2048
	ds_read_b128 v[184:187], v150 offset:3072
	s_add_u32 s48, s46, 0x100
	s_addc_u32 s49, s47, 0
	s_cmp_eq_u32 s76, 40
	s_cselect_b32 s53, s9, s49
	s_cselect_b32 s52, s8, s48
	s_cselect_b32 s51, s45, s75
	s_cselect_b32 s50, s44, s74
	v_lshl_add_u64 v[144:145], s[46:47], 0, v[136:137]
	s_add_i32 m0, s57, 0xc000
	ds_read_b128 v[188:191], v151
	ds_read_b128 v[192:195], v151 offset:1024
	ds_read_b128 v[196:199], v151 offset:2048
	ds_read_b128 v[200:203], v151 offset:3072
	ds_read_b128 v[204:207], v151 offset:4096
	ds_read_b128 v[208:211], v151 offset:5120
	ds_read_b128 v[212:215], v151 offset:6144
	ds_read_b128 v[216:219], v151 offset:7168
	global_load_lds_dwordx4 v[144:145], off
	v_lshl_add_u64 v[144:145], s[46:47], 0, v[138:139]
	s_add_i32 m0, s57, 0xe000
	s_nop 0
	global_load_lds_dwordx4 v[144:145], off
	s_waitcnt vmcnt(8)
	s_waitcnt lgkmcnt(0)
	s_barrier
	s_setprio 1
	s_waitcnt lgkmcnt(0)
	v_mfma_f32_16x16x32_bf16 v[124:127], v[152:155], v[188:191], v[124:127]
	v_mfma_f32_16x16x32_bf16 v[124:127], v[156:159], v[192:195], v[124:127]
	v_mfma_f32_16x16x32_bf16 v[120:123], v[160:163], v[188:191], v[120:123]
	v_mfma_f32_16x16x32_bf16 v[120:123], v[164:167], v[192:195], v[120:123]
	v_mfma_f32_16x16x32_bf16 v[116:119], v[152:155], v[196:199], v[116:119]
	v_mfma_f32_16x16x32_bf16 v[116:119], v[156:159], v[200:203], v[116:119]
	v_mfma_f32_16x16x32_bf16 v[108:111], v[160:163], v[196:199], v[108:111]
	v_mfma_f32_16x16x32_bf16 v[108:111], v[164:167], v[200:203], v[108:111]
	v_mfma_f32_16x16x32_bf16 v[100:103], v[152:155], v[204:207], v[100:103]
	v_mfma_f32_16x16x32_bf16 v[100:103], v[156:159], v[208:211], v[100:103]
	v_mfma_f32_16x16x32_bf16 v[92:95], v[160:163], v[204:207], v[92:95]
	v_mfma_f32_16x16x32_bf16 v[92:95], v[164:167], v[208:211], v[92:95]
	v_mfma_f32_16x16x32_bf16 v[84:87], v[152:155], v[212:215], v[84:87]
	v_mfma_f32_16x16x32_bf16 v[84:87], v[156:159], v[216:219], v[84:87]
	v_mfma_f32_16x16x32_bf16 v[76:79], v[160:163], v[212:215], v[76:79]
	v_mfma_f32_16x16x32_bf16 v[76:79], v[164:167], v[216:219], v[76:79]
	s_setprio 0
	s_setprio 1
	v_mfma_f32_16x16x32_bf16 v[112:115], v[168:171], v[188:191], v[112:115]
	v_mfma_f32_16x16x32_bf16 v[112:115], v[172:175], v[192:195], v[112:115]
	v_mfma_f32_16x16x32_bf16 v[104:107], v[176:179], v[188:191], v[104:107]
	v_mfma_f32_16x16x32_bf16 v[104:107], v[184:187], v[192:195], v[104:107]
	v_mfma_f32_16x16x32_bf16 v[96:99], v[168:171], v[196:199], v[96:99]
	v_mfma_f32_16x16x32_bf16 v[96:99], v[172:175], v[200:203], v[96:99]
	v_mfma_f32_16x16x32_bf16 v[88:91], v[176:179], v[196:199], v[88:91]
	v_mfma_f32_16x16x32_bf16 v[88:91], v[184:187], v[200:203], v[88:91]
	v_mfma_f32_16x16x32_bf16 v[80:83], v[168:171], v[204:207], v[80:83]
	v_mfma_f32_16x16x32_bf16 v[80:83], v[172:175], v[208:211], v[80:83]
	v_mfma_f32_16x16x32_bf16 v[72:75], v[176:179], v[204:207], v[72:75]
	v_mfma_f32_16x16x32_bf16 v[72:75], v[184:187], v[208:211], v[72:75]
	v_mfma_f32_16x16x32_bf16 v[68:71], v[168:171], v[212:215], v[68:71]
	v_mfma_f32_16x16x32_bf16 v[68:71], v[172:175], v[216:219], v[68:71]
	s_barrier
	v_mfma_f32_16x16x32_bf16 v[64:67], v[176:179], v[212:215], v[64:67]
	v_mfma_f32_16x16x32_bf16 v[64:67], v[184:187], v[216:219], v[64:67]
	s_setprio 0
	s_add_i32 s46, s64, s56
	v_lshl_add_u64 v[144:145], s[50:51], 0, v[130:131]
	s_mov_b32 m0, s46
	ds_read_b128 v[188:191], v151 offset:16384
	ds_read_b128 v[192:195], v151 offset:17408
	ds_read_b128 v[196:199], v151 offset:18432
	ds_read_b128 v[200:203], v151 offset:19456
	ds_read_b128 v[204:207], v151 offset:20480
	ds_read_b128 v[208:211], v151 offset:21504
	ds_read_b128 v[212:215], v151 offset:22528
	ds_read_b128 v[216:219], v151 offset:23552
	global_load_lds_dwordx4 v[144:145], off
	s_add_i32 m0, s46, 0x2000
	s_add_u32 s46, s50, 0xb0000
	v_lshl_add_u64 v[220:221], s[50:51], 0, v[134:135]
	s_addc_u32 s47, s51, 0
	s_add_i32 s77, s65, s56
	global_load_lds_dwordx4 v[220:221], off
	v_lshl_add_u64 v[222:223], s[46:47], 0, v[130:131]
	s_mov_b32 m0, s77
	v_lshl_add_u64 v[224:225], s[52:53], 0, v[132:133]
	global_load_lds_dwordx4 v[222:223], off
	v_lshl_add_u64 v[222:223], s[46:47], 0, v[134:135]
	s_add_i32 m0, s77, 0x2000
	s_nop 0
	global_load_lds_dwordx4 v[222:223], off
	v_lshl_add_u64 v[222:223], s[52:53], 0, v[128:129]
	s_mov_b32 m0, s57
	s_nop 0
	global_load_lds_dwordx4 v[222:223], off
	s_mov_b32 m0, s58
	s_nop 0
	global_load_lds_dwordx4 v[224:225], off
	s_waitcnt vmcnt(8)
	s_waitcnt lgkmcnt(0)
	s_barrier
	s_setprio 1
	s_waitcnt lgkmcnt(0)
	v_mfma_f32_16x16x32_bf16 v[60:63], v[152:155], v[188:191], v[60:63]
	v_mfma_f32_16x16x32_bf16 v[60:63], v[156:159], v[192:195], v[60:63]
	v_mfma_f32_16x16x32_bf16 v[56:59], v[160:163], v[188:191], v[56:59]
	v_mfma_f32_16x16x32_bf16 v[56:59], v[164:167], v[192:195], v[56:59]
	v_mfma_f32_16x16x32_bf16 v[52:55], v[152:155], v[196:199], v[52:55]
	v_mfma_f32_16x16x32_bf16 v[52:55], v[156:159], v[200:203], v[52:55]
	v_mfma_f32_16x16x32_bf16 v[44:47], v[160:163], v[196:199], v[44:47]
	v_mfma_f32_16x16x32_bf16 v[44:47], v[164:167], v[200:203], v[44:47]
	v_mfma_f32_16x16x32_bf16 v[36:39], v[152:155], v[204:207], v[36:39]
	v_mfma_f32_16x16x32_bf16 v[36:39], v[156:159], v[208:211], v[36:39]
	v_mfma_f32_16x16x32_bf16 v[28:31], v[160:163], v[204:207], v[28:31]
	v_mfma_f32_16x16x32_bf16 v[28:31], v[164:167], v[208:211], v[28:31]
	v_mfma_f32_16x16x32_bf16 v[20:23], v[152:155], v[212:215], v[20:23]
	v_mfma_f32_16x16x32_bf16 v[20:23], v[156:159], v[216:219], v[20:23]
	v_mfma_f32_16x16x32_bf16 v[12:15], v[160:163], v[212:215], v[12:15]
	v_mfma_f32_16x16x32_bf16 v[12:15], v[164:167], v[216:219], v[12:15]
	s_setprio 0
	s_setprio 1
	v_mfma_f32_16x16x32_bf16 v[48:51], v[168:171], v[188:191], v[48:51]
	v_mfma_f32_16x16x32_bf16 v[48:51], v[172:175], v[192:195], v[48:51]
	v_mfma_f32_16x16x32_bf16 v[40:43], v[176:179], v[188:191], v[40:43]
	v_mfma_f32_16x16x32_bf16 v[40:43], v[184:187], v[192:195], v[40:43]
	v_mfma_f32_16x16x32_bf16 v[32:35], v[168:171], v[196:199], v[32:35]
	v_mfma_f32_16x16x32_bf16 v[32:35], v[172:175], v[200:203], v[32:35]
	v_mfma_f32_16x16x32_bf16 v[24:27], v[176:179], v[196:199], v[24:27]
	v_mfma_f32_16x16x32_bf16 v[24:27], v[184:187], v[200:203], v[24:27]
	v_mfma_f32_16x16x32_bf16 v[16:19], v[168:171], v[204:207], v[16:19]
	v_mfma_f32_16x16x32_bf16 v[16:19], v[172:175], v[208:211], v[16:19]
	v_mfma_f32_16x16x32_bf16 v[8:11], v[176:179], v[204:207], v[8:11]
	v_mfma_f32_16x16x32_bf16 v[8:11], v[184:187], v[208:211], v[8:11]
	v_mfma_f32_16x16x32_bf16 v[4:7], v[168:171], v[212:215], v[4:7]
	v_mfma_f32_16x16x32_bf16 v[4:7], v[172:175], v[216:219], v[4:7]
	s_barrier
	v_mfma_f32_16x16x32_bf16 v[0:3], v[176:179], v[212:215], v[0:3]
	v_mfma_f32_16x16x32_bf16 v[0:3], v[184:187], v[216:219], v[0:3]
	s_setprio 0
.Lmid_gemm12:
	s_add_i32 s77, 0, 0x18000
	s_add_i32 s79, 0, 0x1c000
	v_add_u32_e32 v164, s77, v147
	v_add_u32_e32 v181, s79, v147
	ds_read_b128 v[152:155], v164
	ds_read_b128 v[156:159], v164 offset:1024
	ds_read_b128 v[160:163], v164 offset:2048
	ds_read_b128 v[164:167], v164 offset:3072
	ds_read_b128 v[168:171], v181
	ds_read_b128 v[172:175], v181 offset:1024
	ds_read_b128 v[176:179], v181 offset:2048
	ds_read_b128 v[184:187], v181 offset:3072
	s_add_u32 s46, s52, 0xb0000
	s_addc_u32 s47, s53, 0
	s_mov_b32 m0, s59
	v_lshl_add_u64 v[226:227], s[46:47], 0, v[128:129]
	ds_read_b128 v[188:191], v151 offset:32768
	ds_read_b128 v[192:195], v151 offset:33792
	ds_read_b128 v[196:199], v151 offset:34816
	ds_read_b128 v[200:203], v151 offset:35840
	ds_read_b128 v[204:207], v151 offset:36864
	ds_read_b128 v[208:211], v151 offset:37888
	ds_read_b128 v[212:215], v151 offset:38912
	ds_read_b128 v[216:219], v151 offset:39936
	global_load_lds_dwordx4 v[226:227], off
	v_lshl_add_u64 v[226:227], s[46:47], 0, v[132:133]
	s_mov_b32 m0, s60
	s_nop 0
	global_load_lds_dwordx4 v[226:227], off
	s_waitcnt vmcnt(8)
	s_waitcnt lgkmcnt(0)
	s_barrier
	s_setprio 1
	s_waitcnt lgkmcnt(0)
	v_mfma_f32_16x16x32_bf16 v[124:127], v[152:155], v[188:191], v[124:127]
	v_mfma_f32_16x16x32_bf16 v[124:127], v[156:159], v[192:195], v[124:127]
	v_mfma_f32_16x16x32_bf16 v[120:123], v[160:163], v[188:191], v[120:123]
	v_mfma_f32_16x16x32_bf16 v[120:123], v[164:167], v[192:195], v[120:123]
	v_mfma_f32_16x16x32_bf16 v[116:119], v[152:155], v[196:199], v[116:119]
	v_mfma_f32_16x16x32_bf16 v[116:119], v[156:159], v[200:203], v[116:119]
	v_mfma_f32_16x16x32_bf16 v[108:111], v[160:163], v[196:199], v[108:111]
	v_mfma_f32_16x16x32_bf16 v[108:111], v[164:167], v[200:203], v[108:111]
	v_mfma_f32_16x16x32_bf16 v[100:103], v[152:155], v[204:207], v[100:103]
	v_mfma_f32_16x16x32_bf16 v[100:103], v[156:159], v[208:211], v[100:103]
	v_mfma_f32_16x16x32_bf16 v[92:95], v[160:163], v[204:207], v[92:95]
	v_mfma_f32_16x16x32_bf16 v[92:95], v[164:167], v[208:211], v[92:95]
	v_mfma_f32_16x16x32_bf16 v[84:87], v[152:155], v[212:215], v[84:87]
	v_mfma_f32_16x16x32_bf16 v[84:87], v[156:159], v[216:219], v[84:87]
	v_mfma_f32_16x16x32_bf16 v[76:79], v[160:163], v[212:215], v[76:79]
	v_mfma_f32_16x16x32_bf16 v[76:79], v[164:167], v[216:219], v[76:79]
	s_setprio 0
	s_setprio 1
	v_mfma_f32_16x16x32_bf16 v[112:115], v[168:171], v[188:191], v[112:115]
	v_mfma_f32_16x16x32_bf16 v[112:115], v[172:175], v[192:195], v[112:115]
	v_mfma_f32_16x16x32_bf16 v[104:107], v[176:179], v[188:191], v[104:107]
	v_mfma_f32_16x16x32_bf16 v[104:107], v[184:187], v[192:195], v[104:107]
	v_mfma_f32_16x16x32_bf16 v[96:99], v[168:171], v[196:199], v[96:99]
	v_mfma_f32_16x16x32_bf16 v[96:99], v[172:175], v[200:203], v[96:99]
	v_mfma_f32_16x16x32_bf16 v[88:91], v[176:179], v[196:199], v[88:91]
	v_mfma_f32_16x16x32_bf16 v[88:91], v[184:187], v[200:203], v[88:91]
	v_mfma_f32_16x16x32_bf16 v[80:83], v[168:171], v[204:207], v[80:83]
	v_mfma_f32_16x16x32_bf16 v[80:83], v[172:175], v[208:211], v[80:83]
	v_mfma_f32_16x16x32_bf16 v[72:75], v[176:179], v[204:207], v[72:75]
	v_mfma_f32_16x16x32_bf16 v[72:75], v[184:187], v[208:211], v[72:75]
	v_mfma_f32_16x16x32_bf16 v[68:71], v[168:171], v[212:215], v[68:71]
	v_mfma_f32_16x16x32_bf16 v[68:71], v[172:175], v[216:219], v[68:71]
	s_barrier
	v_mfma_f32_16x16x32_bf16 v[64:67], v[176:179], v[212:215], v[64:67]
	v_mfma_f32_16x16x32_bf16 v[64:67], v[184:187], v[216:219], v[64:67]
	s_setprio 0
	s_add_i32 s46, s77, s56
	v_lshl_add_u64 v[144:145], v[144:145], 0, s[10:11]
	s_mov_b32 m0, s46
	ds_read_b128 v[188:191], v151 offset:49152
	ds_read_b128 v[192:195], v151 offset:50176
	ds_read_b128 v[196:199], v151 offset:51200
	ds_read_b128 v[200:203], v151 offset:52224
	ds_read_b128 v[204:207], v151 offset:53248
	ds_read_b128 v[208:211], v151 offset:54272
	ds_read_b128 v[212:215], v151 offset:55296
	ds_read_b128 v[216:219], v151 offset:56320
	global_load_lds_dwordx4 v[144:145], off
	s_add_i32 m0, s46, 0x2000
	s_add_u32 s46, s50, 0xb0080
	v_lshl_add_u64 v[144:145], v[220:221], 0, s[10:11]
	s_addc_u32 s47, s51, 0
	s_add_i32 s50, s79, s56
	global_load_lds_dwordx4 v[144:145], off
	v_lshl_add_u64 v[144:145], s[46:47], 0, v[130:131]
	s_mov_b32 m0, s50
	s_nop 0
	global_load_lds_dwordx4 v[144:145], off
	v_lshl_add_u64 v[144:145], s[46:47], 0, v[134:135]
	s_add_i32 m0, s50, 0x2000
	s_nop 0
	global_load_lds_dwordx4 v[144:145], off
	v_lshl_add_u64 v[144:145], v[222:223], 0, s[10:11]
	s_mov_b32 m0, s62
	s_nop 0
	global_load_lds_dwordx4 v[144:145], off
	v_lshl_add_u64 v[144:145], v[224:225], 0, s[10:11]
	s_mov_b32 m0, s63
	s_nop 0
	global_load_lds_dwordx4 v[144:145], off
	s_waitcnt vmcnt(8)
	s_waitcnt lgkmcnt(0)
	s_barrier
	s_setprio 1
	s_waitcnt lgkmcnt(0)
	v_mfma_f32_16x16x32_bf16 v[60:63], v[152:155], v[188:191], v[60:63]
	v_mfma_f32_16x16x32_bf16 v[60:63], v[156:159], v[192:195], v[60:63]
	v_mfma_f32_16x16x32_bf16 v[56:59], v[160:163], v[188:191], v[56:59]
	v_mfma_f32_16x16x32_bf16 v[56:59], v[164:167], v[192:195], v[56:59]
	v_mfma_f32_16x16x32_bf16 v[52:55], v[152:155], v[196:199], v[52:55]
	v_mfma_f32_16x16x32_bf16 v[52:55], v[156:159], v[200:203], v[52:55]
	v_mfma_f32_16x16x32_bf16 v[44:47], v[160:163], v[196:199], v[44:47]
	v_mfma_f32_16x16x32_bf16 v[44:47], v[164:167], v[200:203], v[44:47]
	v_mfma_f32_16x16x32_bf16 v[36:39], v[152:155], v[204:207], v[36:39]
	v_mfma_f32_16x16x32_bf16 v[36:39], v[156:159], v[208:211], v[36:39]
	v_mfma_f32_16x16x32_bf16 v[28:31], v[160:163], v[204:207], v[28:31]
	v_mfma_f32_16x16x32_bf16 v[28:31], v[164:167], v[208:211], v[28:31]
	v_mfma_f32_16x16x32_bf16 v[20:23], v[152:155], v[212:215], v[20:23]
	v_mfma_f32_16x16x32_bf16 v[20:23], v[156:159], v[216:219], v[20:23]
	v_mfma_f32_16x16x32_bf16 v[12:15], v[160:163], v[212:215], v[12:15]
	v_mfma_f32_16x16x32_bf16 v[12:15], v[164:167], v[216:219], v[12:15]
	s_setprio 0
	s_setprio 1
	v_mfma_f32_16x16x32_bf16 v[48:51], v[168:171], v[188:191], v[48:51]
	v_mfma_f32_16x16x32_bf16 v[48:51], v[172:175], v[192:195], v[48:51]
	v_mfma_f32_16x16x32_bf16 v[40:43], v[176:179], v[188:191], v[40:43]
	v_mfma_f32_16x16x32_bf16 v[40:43], v[184:187], v[192:195], v[40:43]
	v_mfma_f32_16x16x32_bf16 v[32:35], v[168:171], v[196:199], v[32:35]
	v_mfma_f32_16x16x32_bf16 v[32:35], v[172:175], v[200:203], v[32:35]
	v_mfma_f32_16x16x32_bf16 v[24:27], v[176:179], v[196:199], v[24:27]
	v_mfma_f32_16x16x32_bf16 v[24:27], v[184:187], v[200:203], v[24:27]
	v_mfma_f32_16x16x32_bf16 v[16:19], v[168:171], v[204:207], v[16:19]
	v_mfma_f32_16x16x32_bf16 v[16:19], v[172:175], v[208:211], v[16:19]
	v_mfma_f32_16x16x32_bf16 v[8:11], v[176:179], v[204:207], v[8:11]
	v_mfma_f32_16x16x32_bf16 v[8:11], v[184:187], v[208:211], v[8:11]
	v_mfma_f32_16x16x32_bf16 v[4:7], v[168:171], v[212:215], v[4:7]
	v_mfma_f32_16x16x32_bf16 v[4:7], v[172:175], v[216:219], v[4:7]
	s_barrier
	v_mfma_f32_16x16x32_bf16 v[0:3], v[176:179], v[212:215], v[0:3]
	v_mfma_f32_16x16x32_bf16 v[0:3], v[184:187], v[216:219], v[0:3]
	s_setprio 0
	s_add_i32 s76, s76, 2
	s_add_u32 s74, s74, 0x100
	s_addc_u32 s75, s75, 0
	s_cmp_gt_u32 s76, 41
	s_mov_b64 s[46:47], s[48:49]
	s_cbranch_scc0 .LBB0_1514
	s_and_b64 vcc, exec, s[12:13]
	s_cbranch_vccz .LBB0_1517
	s_barrier
